# hand-written row-wise phases; fused-branch epilogue with load ring; attn_pass bias lookups batched; permlane-swap max reductions
# speedup vs baseline: 1.0181x; 1.0181x over previous
; #define LAS __attribute__((address_space(3)))
; __global__ void __launch_bounds__(512, 2) mega_fwd(Args a) {
;     ...
;     volatile LAS unsigned* bst = (volatile LAS unsigned*)(lds + LDS_BYTES - 16);
;     if (threadIdx.x < 4) bst[threadIdx.x] = 0u;
;     __syncthreads();
;     const XcdBarrier xbar = xcd_barrier_post((unsigned*)a.ws + 1024, bst);
;     const int G = gridDim.x;
;     const int lo = a.ph_lo, hi = a.ph_hi;
;     unsigned char* ws = a.ws;
;     float* mods = (float*)(ws + WS_MOD); bf16_t* KC = (bf16_t*)(ws + WS_KC); unsigned* selm = (unsigned*)(ws + WS_SEL); const float* hb = (const float*)(ws + WS_HB);
;     bf16_t* Wb = (bf16_t*)(ws + WS_W); bf16_t* H = (bf16_t*)(ws + WS_H); bf16_t* BIG = (bf16_t*)(ws + WS_BIG); bf16_t* Y = (bf16_t*)(ws + WS_Y);
;     bf16_t* Ya = Y; bf16_t* Yb = Y + 512; bf16_t* Yc = Y + (size_t)M * YP; bf16_t* Ycmp = (bf16_t*)(ws + WS_YCMP); bf16_t* WbT = (bf16_t*)(ws + WS_WB); bf16_t* MG = BIG + (size_t)64 * MiB / 2;
;     const float* x_in = a.in[0]; const float* relb = a.in[2]; const float* ln_pre = a.in[5]; const float* ln_post = a.in[6];
.LBB0_5:
	s_or_b64 exec, exec, s[4:5]
	v_writelane_b32 v252, s16, 4
	s_cmp_ge_i32 s22, s23
	s_nop 0
	v_writelane_b32 v252, s17, 5
	v_writelane_b32 v252, s18, 6
	v_writelane_b32 v252, s19, 7
	v_writelane_b32 v252, s20, 8
	v_writelane_b32 v252, s21, 9
	v_writelane_b32 v252, s22, 10
	v_writelane_b32 v252, s23, 11
	s_cbranch_scc1 .Lexit_near
	s_load_dwordx8 s[16:23], s[0:1], 0x80
	s_mov_b32 s10, s2
	s_mov_b32 s37, 0
	s_mov_b32 s11, s37
	s_mul_i32 s6, s15, s14
	s_waitcnt lgkmcnt(0)
	s_add_u32 s16, s20, 0x100000
	s_addc_u32 s17, s21, 0
	s_add_u32 s3, s20, 0x600000
	v_writelane_b32 v252, s3, 12
	s_addc_u32 s3, s21, 0
	v_writelane_b32 v252, s3, 13
	s_add_u32 s3, s20, 0x800000
	v_writelane_b32 v252, s3, 14
	s_addc_u32 s3, s21, 0
	s_add_u32 s4, s20, 0x900000
	v_writelane_b32 v252, s3, 15
	s_addc_u32 s5, s21, 0
	v_writelane_b32 v252, s4, 16
	s_add_u32 s3, s20, 0xa00000
	v_lshrrev_b32_e32 v1, 20, v0
	v_writelane_b32 v252, s5, 17
	v_writelane_b32 v252, s3, 18
	s_addc_u32 s3, s21, 0
	s_add_u32 s4, s20, 0x4000000
	s_addc_u32 s5, s21, 0
	v_writelane_b32 v252, s3, 19
	s_add_u32 s18, s20, 0xc000000
	v_writelane_b32 v252, s4, 20
	s_addc_u32 s19, s21, 0
	v_lshrrev_b32_e32 v0, 10, v0
	v_writelane_b32 v252, s5, 21
	s_add_u32 s4, s20, 0x28400000
	s_addc_u32 s5, s21, 0
	v_writelane_b32 v252, s4, 22
	v_or_b32_e32 v0, v0, v1
	s_load_dwordx16 s[56:71], s[0:1], 0x40
	v_writelane_b32 v252, s5, 23
	s_add_u32 s4, s20, 0x28400400
	s_addc_u32 s5, s21, 0
	v_writelane_b32 v252, s4, 24
	s_add_u32 s3, s20, 0x30400000
	v_mbcnt_lo_u32_b32 v2, -1, 0
	v_writelane_b32 v252, s5, 25
	v_writelane_b32 v252, s3, 26
	s_addc_u32 s3, s21, 0
	s_add_u32 s4, s20, 0x38400000
	v_writelane_b32 v252, s3, 27
	s_addc_u32 s5, s21, 0
	v_writelane_b32 v252, s4, 28
	v_mbcnt_hi_u32_b32 v217, -1, v2
	v_and_b32_e32 v2, 64, v217
	v_writelane_b32 v252, s5, 29
	s_add_u32 s4, s20, 0x3c400000
	s_addc_u32 s5, s21, 0
	v_writelane_b32 v252, s4, 30
	s_add_u32 s3, s20, 0x10000000
	v_mov_b32_e32 v215, 0x358637bd
	v_writelane_b32 v252, s5, 31
	v_writelane_b32 v252, s3, 32
	s_addc_u32 s3, s21, 0
	s_cmpk_lt_i32 s14, 0xc9
	v_writelane_b32 v252, s3, 33
	s_cselect_b64 s[4:5], -1, 0
	v_writelane_b32 v252, s4, 34
	s_cmpk_lt_i32 s2, 0x90
	s_cselect_b64 s[2:3], -1, 0
	v_writelane_b32 v252, s5, 35
	v_writelane_b32 v252, s2, 36
	s_cmpk_gt_i32 s10, 0x8f
	v_mov_b32_e32 v216, 1
	v_writelane_b32 v252, s3, 37
	s_cselect_b64 s[2:3], -1, 0
	v_writelane_b32 v252, s2, 38
	s_lshl_b32 s7, s10, 3
	s_lshl_b32 s24, s14, 3
	v_writelane_b32 v252, s3, 39
	s_add_u32 s2, s20, 0x3e80000
	v_writelane_b32 v252, s2, 40
	s_addc_u32 s2, s21, 0
	v_writelane_b32 v252, s2, 41
	s_add_u32 s2, s20, 0x3d80000
	v_writelane_b32 v252, s2, 42
	s_addc_u32 s2, s21, 0
	v_writelane_b32 v252, s2, 43
	s_add_u32 s2, s20, 0x3b80000
	s_addc_u32 s3, s21, 0
	v_writelane_b32 v252, s2, 44
	v_add_u32_e32 v218, 64, v2
	v_xor_b32_e32 v219, 1, v217
	v_writelane_b32 v252, s3, 45
	s_add_u32 s2, s20, 0x2b00000
	s_addc_u32 s3, s21, 0
	v_writelane_b32 v252, s2, 46
	v_xor_b32_e32 v220, 2, v217
	v_xor_b32_e32 v221, 4, v217
	v_writelane_b32 v252, s3, 47
	s_add_u32 s2, s20, 0x2000000
	v_writelane_b32 v252, s2, 48
	s_addc_u32 s2, s21, 0
	v_writelane_b32 v252, s2, 49
	s_add_i32 s4, s14, 0xffffff70
	s_add_i32 s2, s7, 0xfffffb80
	v_writelane_b32 v252, s2, 50
	s_lshl_b32 s2, s4, 3
	s_lshl_b32 s52, s14, 9
	v_writelane_b32 v252, s2, 51
	s_lshl_b32 s26, s4, 9
	s_lshl_b64 s[4:5], s[10:11], 18
	s_add_u32 s2, s18, s4
	v_writelane_b32 v252, s18, 52
	s_addc_u32 s3, s19, s5
	s_add_u32 s4, s2, 0x20000
	v_writelane_b32 v252, s19, 53
	v_writelane_b32 v252, s2, 54
	s_addc_u32 s5, s3, 0
	v_xor_b32_e32 v222, 8, v217
	v_writelane_b32 v252, s3, 55
	v_writelane_b32 v252, s4, 56
	v_xor_b32_e32 v223, 16, v217
	v_xor_b32_e32 v224, 32, v217
	v_writelane_b32 v252, s5, 57
	s_load_dword s4, s[0:1], 0xa8
	v_mov_b32_e32 v225, 0xffc00000
	v_mov_b32_e32 v226, 0xf149f2ca
	v_mov_b32_e32 v227, 0x3e38aa3b
	v_mov_b32_e32 v4, 0
	s_waitcnt lgkmcnt(0)
	s_mul_i32 s2, s6, s4
	v_writelane_b32 v252, s2, 58
	s_add_u32 s2, s20, 0x3280000
	s_addc_u32 s3, s21, 0
	s_ashr_i32 s11, s10, 31
	v_writelane_b32 v252, s2, 59
	s_cmpk_lt_i32 s10, 0x400
	s_movk_i32 s84, 0x90
	v_writelane_b32 v252, s3, 60
	s_cselect_b64 s[2:3], -1, 0
	v_writelane_b32 v252, s2, 61
	s_movk_i32 s85, 0x1c30
	s_movk_i32 s33, 0x200
	v_writelane_b32 v252, s3, 62
	s_add_u32 s2, s20, 0x8000
	v_writelane_b32 v252, s2, 63
	s_addc_u32 s2, s21, 0
	v_writelane_b32 v253, s2, 0
	s_add_u32 s2, s20, 0x1200
	s_addc_u32 s3, s21, 0
	v_writelane_b32 v253, s2, 1
	s_mov_b32 s86, 0xf149f2ca
	s_mov_b32 s39, 0xefa18f08
	v_writelane_b32 v253, s3, 2
	s_add_u32 s2, s20, 0x1400
	s_addc_u32 s3, s21, 0
	v_writelane_b32 v253, s2, 3
	s_mov_b32 s34, 0x9000
	s_mov_b32 s38, 0x12000
	v_writelane_b32 v253, s3, 4
	s_add_u32 s2, s20, 0x1500
	s_addc_u32 s3, s21, 0
	v_writelane_b32 v253, s2, 5
	s_mov_b32 s35, 0x1b000
	s_mov_b64 s[28:29], 0x8000
	v_writelane_b32 v253, s3, 6
	s_add_u32 s2, s20, 0x1600
	s_addc_u32 s3, s21, 0
	v_writelane_b32 v253, s2, 7
	s_mov_b64 s[30:31], 0x80
	s_nop 0
	v_writelane_b32 v253, s3, 8
	s_add_u32 s2, s20, 0x1700
	s_addc_u32 s3, s21, 0
	v_writelane_b32 v253, s2, 9
	s_nop 1
	v_writelane_b32 v253, s3, 10
	s_add_u32 s2, s20, 0x1800
	s_addc_u32 s3, s21, 0
	v_writelane_b32 v253, s2, 11
	s_nop 1
	v_writelane_b32 v253, s3, 12
	s_add_u32 s2, s20, 0x1900
	s_addc_u32 s3, s21, 0
	v_writelane_b32 v253, s2, 13
	s_nop 1
	v_writelane_b32 v253, s3, 14
	s_add_u32 s2, s20, 0x1a00
	s_addc_u32 s3, s21, 0
	v_writelane_b32 v253, s2, 15
	s_nop 1
	v_writelane_b32 v253, s3, 16
	s_add_u32 s2, s20, 0x1b00
	s_addc_u32 s3, s21, 0
	v_writelane_b32 v253, s2, 17
	s_nop 1
	v_writelane_b32 v253, s3, 18
; __device__ __forceinline__ unsigned xb_ld(unsigned* p)              { return __hip_atomic_load(p, __ATOMIC_RELAXED, __HIP_MEMORY_SCOPE_AGENT); }
; __device__ __forceinline__ void xcd_barrier_complete(unsigned* bar, unsigned x, unsigned& nloc, unsigned& nx) {
;     const unsigned G = gridDim.x * gridDim.y * gridDim.z;
;     unsigned sum, cnt, mine, sp = 0u;
;     for (;;) {
;         sum = 0u; cnt = 0u; mine = 0u;
; #pragma unroll
;         for (unsigned j = 0; j < 16; ++j) { const unsigned c = xb_ld(&bar[XB_XCNT(j)]); sum += c; cnt += (c > 0u) ? 1u : 0u; mine = (j == x) ? c : mine; }
;         if (sum == G) break;
;         __builtin_amdgcn_s_sleep(1);
;         if ((++sp & 255u) == 0u) { if (xb_ld(&bar[XB_TMO])) break; if (sp > XB_SPIN_CAP) { atomicAdd(&bar[XB_TMO], 1u); break; } }
;     }
;     nloc = mine > 0u ? mine : 1u; nx = cnt > 0u ? cnt : 1u;
; }
; __global__ void __launch_bounds__(512, 2) mega_fwd(Args a) {
;     ...
;     float* mods = (float*)(ws + WS_MOD); bf16_t* KC = (bf16_t*)(ws + WS_KC); unsigned* selm = (unsigned*)(ws + WS_SEL); const float* hb = (const float*)(ws + WS_HB);
;     bf16_t* Wb = (bf16_t*)(ws + WS_W); bf16_t* H = (bf16_t*)(ws + WS_H); bf16_t* BIG = (bf16_t*)(ws + WS_BIG); bf16_t* Y = (bf16_t*)(ws + WS_Y);
;     bf16_t* Ya = Y; bf16_t* Yb = Y + 512; bf16_t* Yc = Y + (size_t)M * YP; bf16_t* Ycmp = (bf16_t*)(ws + WS_YCMP); bf16_t* WbT = (bf16_t*)(ws + WS_WB); bf16_t* MG = BIG + (size_t)64 * MiB / 2;
;     const float* x_in = a.in[0]; const float* relb = a.in[2]; const float* ln_pre = a.in[5]; const float* ln_post = a.in[6];
;     enum { K_MODS, K_INIT, K_G1, K_G2, K_ROW, K_GIN, K_ATT1, K_CMP, K_ATTB, K_FUSED, K_OUT };
;     for (int ph = lo; ph < hi; ++ph) {
	s_add_u32 s2, s20, 0x1c00
	s_addc_u32 s3, s21, 0
	v_writelane_b32 v253, s2, 19
	s_nop 1
	v_writelane_b32 v253, s3, 20
	s_add_u32 s2, s20, 0x1d00
	s_addc_u32 s3, s21, 0
	v_writelane_b32 v253, s2, 21
	s_nop 1
	v_writelane_b32 v253, s3, 22
	s_add_u32 s2, s20, 0x1e00
	s_addc_u32 s3, s21, 0
	v_writelane_b32 v253, s2, 23
	s_nop 1
	v_writelane_b32 v253, s3, 24
	s_add_u32 s2, s20, 0x1f00
	s_addc_u32 s3, s21, 0
	v_writelane_b32 v253, s2, 25
	s_nop 1
	v_writelane_b32 v253, s3, 26
	s_add_u32 s2, s20, 0x2000
	s_addc_u32 s3, s21, 0
	v_writelane_b32 v253, s2, 27
	s_nop 1
	v_writelane_b32 v253, s3, 28
	s_add_u32 s2, s20, 0x2100
	s_addc_u32 s3, s21, 0
	v_writelane_b32 v253, s2, 29
	s_nop 1
	v_writelane_b32 v253, s3, 30
	s_add_u32 s2, s20, 0x2200
	s_addc_u32 s3, s21, 0
	v_writelane_b32 v253, s2, 31
	s_nop 1
	v_writelane_b32 v253, s3, 32
	s_add_u32 s2, s20, 0x2300
	s_addc_u32 s3, s21, 0
	v_writelane_b32 v253, s2, 33
	s_cmp_eq_u32 s8, 15
	s_nop 0
	v_writelane_b32 v253, s3, 34
	s_cselect_b64 s[2:3], -1, 0
	v_writelane_b32 v253, s2, 35
	s_cmp_eq_u32 s8, 14
	s_nop 0
	v_writelane_b32 v253, s3, 36
	s_cselect_b64 s[2:3], -1, 0
	v_writelane_b32 v253, s2, 37
	s_cmp_eq_u32 s8, 13
	s_nop 0
	v_writelane_b32 v253, s3, 38
	s_cselect_b64 s[2:3], -1, 0
	v_writelane_b32 v253, s2, 39
	s_cmp_eq_u32 s8, 12
	s_nop 0
	v_writelane_b32 v253, s3, 40
	s_cselect_b64 s[2:3], -1, 0
	v_writelane_b32 v253, s2, 41
	s_cmp_eq_u32 s8, 11
	s_nop 0
	v_writelane_b32 v253, s3, 42
	s_cselect_b64 s[2:3], -1, 0
	v_writelane_b32 v253, s2, 43
	s_cmp_eq_u32 s8, 10
	s_nop 0
	v_writelane_b32 v253, s3, 44
	s_cselect_b64 s[2:3], -1, 0
	v_writelane_b32 v253, s2, 45
	s_cmp_eq_u32 s8, 9
	s_nop 0
	v_writelane_b32 v253, s3, 46
	s_cselect_b64 s[2:3], -1, 0
	v_writelane_b32 v253, s2, 47
	s_cmp_eq_u32 s8, 8
	s_nop 0
	v_writelane_b32 v253, s3, 48
	s_cselect_b64 s[2:3], -1, 0
	v_writelane_b32 v253, s2, 49
	s_cmp_eq_u32 s8, 7
	s_nop 0
	v_writelane_b32 v253, s3, 50
	s_cselect_b64 s[2:3], -1, 0
	v_writelane_b32 v253, s2, 51
	s_cmp_eq_u32 s8, 6
	s_nop 0
	v_writelane_b32 v253, s3, 52
	s_cselect_b64 s[2:3], -1, 0
	v_writelane_b32 v253, s2, 53
	s_cmp_eq_u32 s8, 5
	s_nop 0
	v_writelane_b32 v253, s3, 54
	s_cselect_b64 s[2:3], -1, 0
	v_writelane_b32 v253, s2, 55
	s_cmp_eq_u32 s8, 4
	s_nop 0
	v_writelane_b32 v253, s3, 56
	s_cselect_b64 s[2:3], -1, 0
	v_writelane_b32 v253, s2, 57
	s_cmp_eq_u32 s8, 3
	s_nop 0
	v_writelane_b32 v253, s3, 58
	s_cselect_b64 s[2:3], -1, 0
	v_writelane_b32 v253, s2, 59
	s_cmp_eq_u32 s8, 2
	s_nop 0
	v_writelane_b32 v253, s3, 60
	s_cselect_b64 s[2:3], -1, 0
	v_writelane_b32 v253, s2, 61
	s_cmp_eq_u32 s8, 1
	s_nop 0
	v_writelane_b32 v253, s3, 62
	s_cselect_b64 s[2:3], -1, 0
	v_writelane_b32 v253, s2, 63
	s_cmp_eq_u32 s8, 0
	s_nop 0
	v_writelane_b32 v254, s3, 0
	s_cselect_b64 s[2:3], -1, 0
	v_writelane_b32 v254, s2, 1
	s_lshl_b32 s4, s8, 8
	s_nop 0
	v_writelane_b32 v254, s3, 2
	s_add_u32 s2, s12, s4
	s_addc_u32 s3, s13, 0
	s_add_u32 s8, s2, 0x1400
	s_addc_u32 s9, s3, 0
	v_writelane_b32 v254, s8, 3
	s_add_u32 s2, s2, 0x2400
	s_addc_u32 s3, s3, 0
	v_writelane_b32 v254, s9, 4
	v_writelane_b32 v254, s2, 5
	s_mov_b32 s4, s26
	s_movk_i32 s12, 0x7bf
	v_writelane_b32 v254, s3, 6
	s_add_u32 s2, s20, 0x4400
	s_addc_u32 s3, s21, 0
	v_writelane_b32 v254, s2, 7
	s_nop 1
	v_writelane_b32 v254, s3, 8
	s_add_u32 s2, s20, 0x4500
	s_addc_u32 s3, s21, 0
	v_writelane_b32 v254, s2, 9
	s_nop 1
	v_writelane_b32 v254, s3, 10
	s_movk_i32 s2, 0x3ff
	v_and_or_b32 v1, v0, s2, v214
	s_lshl_b32 s2, s10, 7
	v_writelane_b32 v254, s2, 11
	s_lshl_b32 s2, s14, 7
	v_writelane_b32 v254, s2, 12
	s_add_i32 s2, s7, 0xffffccf0
	v_writelane_b32 v254, s2, 13
	v_writelane_b32 v254, s10, 14
	s_lshl_b32 s2, s10, 8
	v_mov_b32_e32 v0, 0
	v_writelane_b32 v254, s11, 15
	v_writelane_b32 v254, s2, 16
	s_add_i32 s2, s7, 0xffffd1f0
	v_writelane_b32 v254, s2, 17
	s_add_u32 s2, s20, 0x320c000
	s_addc_u32 s3, s21, 0
	v_writelane_b32 v254, s2, 18
	s_ashr_i32 s53, s52, 31
	v_mov_b32_e32 v5, v0
	v_writelane_b32 v254, s3, 19
	s_lshl_b64 s[2:3], s[52:53], 4
	v_writelane_b32 v254, s2, 20
	v_mov_b32_e32 v6, v0
	v_mov_b32_e32 v7, v0
	v_writelane_b32 v254, s3, 21
	s_add_u32 s2, s66, 0x200000
	v_writelane_b32 v254, s2, 22
	s_addc_u32 s2, s67, 0
	v_writelane_b32 v254, s2, 23
	s_add_u32 s2, s64, 0x4000
	v_writelane_b32 v254, s2, 24
	v_writelane_b32 v254, s56, 25
	s_addc_u32 s2, s65, 0
	s_ashr_i32 s5, s26, 31
	v_writelane_b32 v254, s57, 26
	v_writelane_b32 v254, s58, 27
	v_writelane_b32 v254, s59, 28
	v_writelane_b32 v254, s60, 29
	v_writelane_b32 v254, s61, 30
	v_writelane_b32 v254, s62, 31
	v_writelane_b32 v254, s63, 32
	v_writelane_b32 v254, s64, 33
	v_writelane_b32 v254, s65, 34
	v_writelane_b32 v254, s66, 35
	v_writelane_b32 v254, s67, 36
	v_writelane_b32 v254, s68, 37
	v_writelane_b32 v254, s69, 38
	v_writelane_b32 v254, s70, 39
	v_writelane_b32 v254, s71, 40
	v_writelane_b32 v254, s2, 41
	v_writelane_b32 v254, s4, 42
	s_add_i32 s2, s7, 0xffffc770
	s_ashr_i32 s25, s24, 31
	v_writelane_b32 v254, s5, 43
	v_writelane_b32 v254, s2, 44
	s_add_i32 s2, s7, 0xffffc870
	v_writelane_b32 v254, s2, 45
	v_writelane_b32 v254, s7, 46
	s_add_i32 s2, s7, 0xffffcd70
	v_writelane_b32 v254, s2, 47
	s_add_i32 s2, 0, 0x23fe0
	v_writelane_b32 v254, s2, 48
	s_add_i32 s2, 0, 0x9004
	v_writelane_b32 v254, s2, 49
	s_add_i32 s2, 0, 0x9000
	v_writelane_b32 v254, s2, 50
	s_add_i32 s2, 0, 0x12000
	v_writelane_b32 v254, s2, 51
	s_add_i32 s2, 0, 0x12800
	v_writelane_b32 v254, s2, 52
	s_add_i32 s2, 0, 0x20010
	v_writelane_b32 v254, s2, 53
	s_add_i32 s2, 0, 0x23ff0
	v_writelane_b32 v254, s2, 54
	s_add_i32 s2, 0, 0x23ff4
	v_writelane_b32 v254, s2, 55
	v_cmp_eq_u32_e64 s[2:3], 0, v1
	s_load_dwordx16 s[56:71], s[0:1], 0x0
	s_nop 0
	v_writelane_b32 v254, s2, 56
	s_nop 1
	v_writelane_b32 v254, s3, 57
	s_lshl_b64 s[2:3], s[24:25], 16
	v_writelane_b32 v254, s2, 58
	s_nop 1
	v_writelane_b32 v254, s3, 59
	s_mov_b32 s2, s24
	v_writelane_b32 v254, s2, 60
	s_nop 1
	v_writelane_b32 v254, s3, 61
	s_lshl_b64 s[2:3], s[24:25], 17
	v_writelane_b32 v254, s2, 62
	s_nop 1
	v_writelane_b32 v254, s3, 63
	s_lshl_b64 s[2:3], s[4:5], 4
	v_writelane_b32 v255, s2, 0
	s_mov_b32 s4, s22
	s_nop 0
	v_writelane_b32 v255, s3, 1
	v_writelane_b32 v255, s4, 2
	s_mov_b64 s[2:3], 0x100
	s_nop 0
	v_writelane_b32 v255, s5, 3
	s_waitcnt lgkmcnt(0)
	v_writelane_b32 v255, s56, 4
	s_nop 1
	v_writelane_b32 v255, s57, 5
	v_writelane_b32 v255, s58, 6
	v_writelane_b32 v255, s59, 7
	v_writelane_b32 v255, s60, 8
	v_writelane_b32 v255, s61, 9
	v_writelane_b32 v255, s62, 10
	v_writelane_b32 v255, s63, 11
	v_writelane_b32 v255, s64, 12
	v_writelane_b32 v255, s65, 13
	v_writelane_b32 v255, s66, 14
	v_writelane_b32 v255, s67, 15
	v_writelane_b32 v255, s68, 16
	v_writelane_b32 v255, s69, 17
	v_writelane_b32 v255, s70, 18
	v_writelane_b32 v255, s71, 19
	v_writelane_b32 v255, s14, 20
	s_nop 1
	v_writelane_b32 v255, s15, 21
	v_writelane_b32 v255, s16, 22
	s_nop 1
	v_writelane_b32 v255, s17, 23
	v_writelane_b32 v255, s52, 24
	s_nop 1
	v_writelane_b32 v255, s53, 25
	s_branch .LBB0_11
; __global__ void __launch_bounds__(512, 2) mega_fwd(Args a) {
;     ...
;     for (int ph = lo; ph < hi; ++ph) {
;         int kind, l = 0, i = 0;
;         if (ph == 0) kind = K_MODS; else if (ph == 1) kind = K_INIT;
;         else { const int r = ph - 2; l = r / 13; const int q = r - 13 * l;
;             if (q < 3) { i = 0; kind = q == 0 ? K_G1 : q == 1 ? K_G2 : K_ROW; }
;             else if (q < 10) { i = 1; kind = q == 3 ? K_GIN : q == 4 ? K_ATT1 : q == 5 ? K_CMP : q == 6 ? K_ATTB : q == 7 ? K_FUSED : q == 8 ? K_OUT : K_ROW; }
;             else { i = 2; kind = q == 10 ? K_G1 : q == 11 ? K_G2 : K_ROW; } }
.Lexit_near:
	s_endpgm
.LBB0_11:
	v_readlane_b32 s0, v255, 2
	s_cmp_lg_u32 s0, 0
	s_cselect_b64 s[4:5], -1, 0
	v_readlane_b32 s1, v255, 3
	v_writelane_b32 v255, s4, 26
	s_cmp_eq_u32 s0, 0
	s_mov_b64 s[10:11], -1
	v_writelane_b32 v255, s5, 27
	s_mov_b64 s[4:5], 0
	v_writelane_b32 v255, s4, 28
	s_mov_b64 s[8:9], -1
	s_mov_b32 s7, s37
	v_writelane_b32 v255, s5, 29
	s_mov_b32 s4, s37
	v_writelane_b32 v255, s4, 30
	s_mov_b32 s14, s37
	s_nop 0
	v_writelane_b32 v255, s5, 31
	s_cbranch_scc1 .LBB0_38
	s_cmp_eq_u32 s0, 1
	s_mov_b32 s14, 1
	s_cbranch_scc1 .LBB0_37
	s_add_i32 s0, s0, -2
	s_mul_hi_i32 s1, s0, 0x4ec4ec4f
	s_lshr_b32 s4, s1, 31
	s_ashr_i32 s1, s1, 2
	s_add_i32 s6, s1, s4
	s_mov_b32 s4, s6
	s_mul_i32 s6, s6, -13
	v_writelane_b32 v255, s4, 30
	s_add_i32 s6, s6, s0
	s_cmp_gt_i32 s6, 2
	v_writelane_b32 v255, s5, 31
	s_mov_b64 s[0:1], -1
	s_cbranch_scc0 .LBB0_35
	s_mov_b64 s[8:9], -1
	s_cmp_gt_u32 s6, 9
	s_mov_b64 s[4:5], -1
	s_cbranch_scc0 .LBB0_16
	s_cmp_eq_u32 s6, 11
	s_cselect_b32 s0, 3, 4
	s_cmp_lg_u32 s6, 10
	s_cselect_b32 s14, s0, 2
	s_mov_b64 s[4:5], 0

; template <int MODE>
; __device__ __forceinline__ void attn_pass(LAS unsigned char* lds, const bf16_t* base, int gk, int q0, const float* relb_b, const unsigned* selrow, f32x4 (&o)[2][4]) {
;     ...
;                 const int dbase = selb ? (qw0 + 16 * qt + c - k0 - 4 * g) : -(1 << 22);
;                 float mx = -1e30f;
; #pragma unroll
;                 for (int nt = 0; nt < 4; ++nt)
; #pragma unroll
;                     for (int j = 0; j < 4; ++j) { const int dist = dbase - (16 * nt + j); const bool valid = (unsigned)dist < (unsigned)W;
;                         const unsigned di = (unsigned)dist < 127u ? (unsigned)dist : 127u;
;                         const float lg = valid ? (s[qt][nt][j] * C1 + lut[di]) : -1e30f; s[qt][nt][j] = lg; mx = fmaxf(mx, lg); }
;                 mx = fmaxf(mx, __shfl_xor(mx, 16)); mx = fmaxf(mx, __shfl_xor(mx, 32));
;                 mnew = fmaxf(mrun[qt], mx); alpha = __builtin_amdgcn_exp2f(mrun[qt] - mnew);
; #pragma unroll
;                 for (int nt = 0; nt < 4; ++nt)
; #pragma unroll
;                     for (int j = 0; j < 4; ++j) s[qt][nt][j] = __builtin_amdgcn_exp2f(s[qt][nt][j] - mnew);
.LBB0_75:
	v_cndmask_b32_e64 v3, v158, v225, s[0:1]
	s_mov_b32 s15, 0x100000
	v_min_u32_e32 v112, 0x7f, v3
	v_lshl_add_u32 v112, v112, 2, s47
	ds_read_b32 v112, v112 offset:36864
	v_add_u32_e32 v229, -1, v3
	v_min_u32_e32 v2, 0x7f, v229
	v_lshl_add_u32 v2, v2, 2, s47
	ds_read_b32 v2, v2 offset:36864
	v_add_u32_e32 v230, -2, v3
	v_min_u32_e32 v114, 0x7f, v230
	v_lshl_add_u32 v114, v114, 2, s47
	ds_read_b32 v114, v114 offset:36864
	v_add_u32_e32 v231, -3, v3
	v_min_u32_e32 v113, 0x7f, v231
	v_lshl_add_u32 v113, v113, 2, s47
	ds_read_b32 v113, v113 offset:36864
	v_add_u32_e32 v232, -16, v3
	v_min_u32_e32 v115, 0x7f, v232
	v_lshl_add_u32 v115, v115, 2, s47
	ds_read_b32 v115, v115 offset:36864
	v_subrev_u32_e32 v233, 17, v3
	v_min_u32_e32 v117, 0x7f, v233
	v_lshl_add_u32 v117, v117, 2, s47
	ds_read_b32 v117, v117 offset:36864
	v_subrev_u32_e32 v234, 18, v3
	v_min_u32_e32 v118, 0x7f, v234
	v_lshl_add_u32 v118, v118, 2, s47
	ds_read_b32 v118, v118 offset:36864
	v_subrev_u32_e32 v235, 19, v3
	v_min_u32_e32 v119, 0x7f, v235
	v_lshl_add_u32 v119, v119, 2, s47
	ds_read_b32 v119, v119 offset:36864
	v_subrev_u32_e32 v236, 32, v3
	v_min_u32_e32 v120, 0x7f, v236
	v_lshl_add_u32 v120, v120, 2, s47
	ds_read_b32 v120, v120 offset:36864
	v_subrev_u32_e32 v237, 33, v3
	v_min_u32_e32 v121, 0x7f, v237
	v_lshl_add_u32 v121, v121, 2, s47
	ds_read_b32 v121, v121 offset:36864
	v_subrev_u32_e32 v238, 34, v3
	v_min_u32_e32 v122, 0x7f, v238
	v_lshl_add_u32 v122, v122, 2, s47
	ds_read_b32 v122, v122 offset:36864
	v_subrev_u32_e32 v239, 35, v3
	v_min_u32_e32 v123, 0x7f, v239
	v_lshl_add_u32 v123, v123, 2, s47
	ds_read_b32 v123, v123 offset:36864
	v_subrev_u32_e32 v240, 48, v3
	v_min_u32_e32 v124, 0x7f, v240
	v_lshl_add_u32 v124, v124, 2, s47
	ds_read_b32 v124, v124 offset:36864
	v_subrev_u32_e32 v241, 49, v3
	v_min_u32_e32 v125, 0x7f, v241
	v_lshl_add_u32 v125, v125, 2, s47
	ds_read_b32 v125, v125 offset:36864
	v_subrev_u32_e32 v242, 50, v3
	v_min_u32_e32 v126, 0x7f, v242
	v_lshl_add_u32 v126, v126, 2, s47
	ds_read_b32 v126, v126 offset:36864
	v_subrev_u32_e32 v243, 51, v3
	v_min_u32_e32 v127, 0x7f, v243
	v_lshl_add_u32 v127, v127, 2, s47
	ds_read_b32 v127, v127 offset:36864
	s_waitcnt lgkmcnt(0)
	v_cmp_gt_u32_e32 vcc, s15, v3
	v_fmac_f32_e32 v112, 0x3e38aa3b, v140
	s_nop 0
	v_cndmask_b32_e32 v112, v226, v112, vcc
	v_cmp_gt_u32_e32 vcc, s15, v229
	v_fmac_f32_e32 v2, 0x3e38aa3b, v141
	s_nop 0
	v_cndmask_b32_e32 v2, v226, v2, vcc
	v_cmp_gt_u32_e32 vcc, s15, v230
	v_fmac_f32_e32 v114, 0x3e38aa3b, v142
	s_nop 0
	v_cndmask_b32_e32 v114, v226, v114, vcc
	v_cmp_gt_u32_e32 vcc, s15, v231
	v_fmac_f32_e32 v113, 0x3e38aa3b, v143
	s_nop 0
	v_cndmask_b32_e32 v113, v226, v113, vcc
	v_cmp_gt_u32_e32 vcc, s15, v232
	v_fmac_f32_e32 v115, 0x3e38aa3b, v136
	s_nop 0
	v_cndmask_b32_e32 v115, v226, v115, vcc
	v_cmp_gt_u32_e32 vcc, s15, v233
	v_fmac_f32_e32 v117, 0x3e38aa3b, v137
	s_nop 0
	v_cndmask_b32_e32 v117, v226, v117, vcc
	v_cmp_gt_u32_e32 vcc, s15, v234
	v_fmac_f32_e32 v118, 0x3e38aa3b, v138
	s_nop 0
	v_cndmask_b32_e32 v118, v226, v118, vcc
	v_cmp_gt_u32_e32 vcc, s15, v235
	v_fmac_f32_e32 v119, 0x3e38aa3b, v139
	s_nop 0
	v_cndmask_b32_e32 v119, v226, v119, vcc
	v_cmp_gt_u32_e32 vcc, s15, v236
	v_fmac_f32_e32 v120, 0x3e38aa3b, v132
	s_nop 0
	v_cndmask_b32_e32 v120, v226, v120, vcc
	v_cmp_gt_u32_e32 vcc, s15, v237
	v_fmac_f32_e32 v121, 0x3e38aa3b, v133
	s_nop 0
	v_cndmask_b32_e32 v121, v226, v121, vcc
	v_cmp_gt_u32_e32 vcc, s15, v238
	v_fmac_f32_e32 v122, 0x3e38aa3b, v134
	s_nop 0
	v_cndmask_b32_e32 v122, v226, v122, vcc
	v_cmp_gt_u32_e32 vcc, s15, v239
	v_fmac_f32_e32 v123, 0x3e38aa3b, v135
	s_nop 0
	v_cndmask_b32_e32 v123, v226, v123, vcc
	v_cmp_gt_u32_e32 vcc, s15, v240
	v_fmac_f32_e32 v124, 0x3e38aa3b, v128
	s_nop 0
	v_cndmask_b32_e32 v124, v226, v124, vcc
	v_cmp_gt_u32_e32 vcc, s15, v241
	v_fmac_f32_e32 v125, 0x3e38aa3b, v129
	s_nop 0
	v_cndmask_b32_e32 v125, v226, v125, vcc
	v_cmp_gt_u32_e32 vcc, s15, v242
	v_fmac_f32_e32 v126, 0x3e38aa3b, v130
	s_nop 0
	v_cndmask_b32_e32 v126, v226, v126, vcc
	v_cmp_gt_u32_e32 vcc, s15, v243
	v_fmac_f32_e32 v127, 0x3e38aa3b, v131
	s_nop 0
	v_cndmask_b32_e32 v127, v226, v127, vcc
	v_max3_f32 v3, v112, s86, v2
	v_max3_f32 v3, v3, v114, v113
	v_max3_f32 v3, v3, v115, v117
	v_max3_f32 v3, v3, v118, v119
	v_max3_f32 v3, v3, v120, v121
	v_max3_f32 v3, v3, v122, v123
	v_max3_f32 v3, v3, v124, v125
	v_max3_f32 v3, v3, v126, v127
	v_mov_b32_e32 v116, v3
	s_waitcnt lgkmcnt(0)
	s_nop 1
	v_permlane16_swap_b32_e32 v3, v116
	s_nop 0
	v_max_f32_e32 v3, v3, v116
	v_mov_b32_e32 v116, v3
	s_nop 1
	v_permlane32_swap_b32_e32 v3, v116
	s_nop 0
	v_max3_f32 v3, v157, v3, v116
	v_sub_f32_e32 v2, v2, v3
	v_sub_f32_e32 v116, v113, v3
	v_exp_f32_e32 v113, v2
	v_sub_f32_e32 v2, v117, v3
	v_exp_f32_e32 v117, v2
	v_sub_f32_e32 v2, v118, v3
	v_exp_f32_e32 v118, v2
	v_sub_f32_e32 v2, v119, v3
	v_exp_f32_e32 v119, v2
	v_sub_f32_e32 v2, v120, v3
	v_exp_f32_e32 v120, v2
	v_sub_f32_e32 v2, v121, v3
	v_exp_f32_e32 v121, v2
	v_sub_f32_e32 v2, v122, v3
	v_exp_f32_e32 v122, v2
	v_sub_f32_e32 v2, v123, v3
	v_exp_f32_e32 v123, v2
	v_sub_f32_e32 v2, v124, v3
	v_exp_f32_e32 v124, v2
	v_sub_f32_e32 v2, v125, v3
	v_sub_f32_e32 v112, v112, v3
	v_sub_f32_e32 v114, v114, v3
	v_sub_f32_e32 v156, v115, v3
	v_exp_f32_e32 v125, v2
	v_sub_f32_e32 v2, v126, v3
	v_exp_f32_e32 v112, v112
	v_exp_f32_e32 v114, v114
	v_exp_f32_e32 v115, v116
	v_exp_f32_e32 v116, v156
	v_exp_f32_e32 v126, v2
	v_sub_f32_e32 v156, v127, v3
	s_branch .LBB0_65
; template <int MODE>
; __device__ __forceinline__ void attn_pass(LAS unsigned char* lds, const bf16_t* base, int gk, int q0, const float* relb_b, const unsigned* selrow, f32x4 (&o)[2][4]) {
;     ...
;             if (fast) {
;                 float mx = fmaxf(fmaxf(s[qt][0][0], s[qt][0][1]), fmaxf(s[qt][0][2], s[qt][0][3]));
; #pragma unroll
;                 for (int nt = 1; nt < 4; ++nt) mx = fmaxf(mx, fmaxf(fmaxf(s[qt][nt][0], s[qt][nt][1]), fmaxf(s[qt][nt][2], s[qt][nt][3])));
;                 mx = fmaxf(mx, __shfl_xor(mx, 16)); mx = fmaxf(mx, __shfl_xor(mx, 32));
;                 const float mxl = selb ? (mx * C1 + bias_far) : -1e30f;
;                 mnew = fmaxf(mrun[qt], mxl); alpha = __builtin_amdgcn_exp2f(mrun[qt] - mnew);
;                 const float c1 = selb ? C1 : 0.f, c2 = selb ? (bias_far - mnew) : -1e30f;
; #pragma unroll
;                 for (int nt = 0; nt < 4; ++nt)
; #pragma unroll
;                     for (int j = 0; j < 4; ++j) s[qt][nt][j] = __builtin_amdgcn_exp2f(s[qt][nt][j] * c1 + c2);
;             } else {
;                 const int dbase = selb ? (qw0 + 16 * qt + c - k0 - 4 * g) : -(1 << 22);
;                 float mx = -1e30f;
; #pragma unroll
;                 for (int nt = 0; nt < 4; ++nt)
; #pragma unroll
;                     for (int j = 0; j < 4; ++j) { const int dist = dbase - (16 * nt + j); const bool valid = (unsigned)dist < (unsigned)W;
;                         const unsigned di = (unsigned)dist < 127u ? (unsigned)dist : 127u;
;                         const float lg = valid ? (s[qt][nt][j] * C1 + lut[di]) : -1e30f; s[qt][nt][j] = lg; mx = fmaxf(mx, lg); }
.LBB0_108:
	v_max_f32_e32 v2, v141, v141
	v_max_f32_e32 v3, v140, v140
	v_max_f32_e32 v2, v3, v2
	v_max_f32_e32 v3, v143, v143
	v_max_f32_e32 v112, v142, v142
	v_max_f32_e32 v3, v112, v3
	v_max_f32_e32 v112, v139, v139
	v_max_f32_e32 v113, v138, v138
	v_max_f32_e32 v112, v113, v112
	v_max3_f32 v112, v136, v137, v112
	v_max3_f32 v2, v2, v3, v112
	v_max_f32_e32 v3, v135, v135
	v_max_f32_e32 v112, v134, v134
	v_max_f32_e32 v3, v112, v3
	v_max_f32_e32 v112, v131, v131
	v_max_f32_e32 v113, v130, v130
	v_max_f32_e32 v112, v113, v112
	v_max3_f32 v3, v132, v133, v3
	v_max3_f32 v112, v128, v129, v112
	v_max3_f32 v2, v2, v3, v112
	v_mov_b32_e32 v3, v2
	s_waitcnt lgkmcnt(0)
	s_nop 1
	v_permlane16_swap_b32_e32 v2, v3
	s_nop 0
	v_max_f32_e32 v2, v2, v3
	v_mov_b32_e32 v3, v2
	s_nop 1
	v_permlane32_swap_b32_e32 v2, v3
	s_nop 0
	v_max_f32_e32 v2, v2, v3
	v_fmamk_f32 v2, v2, 0x3e38aa3b, v150
	v_cndmask_b32_e64 v2, v2, v226, s[0:1]
	v_max_f32_e32 v3, v157, v157
	v_max_f32_e32 v3, v3, v2
	v_sub_f32_e32 v112, v150, v3
	v_cndmask_b32_e64 v2, v227, 0, s[0:1]
	v_cndmask_b32_e64 v156, v112, v226, s[0:1]
	v_fma_f32 v112, v2, v140, v156
	v_fma_f32 v113, v2, v141, v156
	v_fma_f32 v114, v2, v142, v156
	v_fma_f32 v115, v2, v143, v156
	v_fma_f32 v116, v2, v136, v156
	v_fma_f32 v117, v2, v137, v156
	v_fma_f32 v118, v2, v138, v156
	v_fma_f32 v119, v2, v139, v156
	v_fma_f32 v120, v2, v132, v156
	v_fma_f32 v121, v2, v133, v156
	v_fma_f32 v122, v2, v134, v156
	v_fma_f32 v123, v2, v135, v156
	v_fma_f32 v124, v2, v128, v156
	v_fma_f32 v125, v2, v129, v156
	v_fma_f32 v126, v2, v130, v156
	v_exp_f32_e32 v112, v112
	v_exp_f32_e32 v113, v113
	v_exp_f32_e32 v114, v114
	v_exp_f32_e32 v115, v115
	v_exp_f32_e32 v116, v116
	v_exp_f32_e32 v117, v117
	v_exp_f32_e32 v118, v118
	v_exp_f32_e32 v119, v119
	v_exp_f32_e32 v120, v120
	v_exp_f32_e32 v121, v121
	v_exp_f32_e32 v122, v122
	v_exp_f32_e32 v123, v123
	v_exp_f32_e32 v124, v124
	v_exp_f32_e32 v125, v125
	v_exp_f32_e32 v126, v126
	v_fmac_f32_e32 v156, v2, v131
	v_sub_f32_e32 v2, v157, v3
	v_exp_f32_e32 v2, v2
	v_cmp_gt_f32_e32 vcc, v3, v157
	s_cbranch_vccnz .LBB0_66
	s_branch .LBB0_67
.LBB0_109:
	v_add_u32_e32 v127, 16, v158
	v_cndmask_b32_e64 v127, v127, v225, s[0:1]
	s_mov_b32 s10, 0x100000
	v_min_u32_e32 v129, 0x7f, v127
	v_lshl_add_u32 v129, v129, 2, s47
	ds_read_b32 v129, v129 offset:36864
	v_add_u32_e32 v229, -1, v127
	v_min_u32_e32 v128, 0x7f, v229
	v_lshl_add_u32 v128, v128, 2, s47
	ds_read_b32 v128, v128 offset:36864
	v_add_u32_e32 v230, -2, v127
	v_min_u32_e32 v131, 0x7f, v230
	v_lshl_add_u32 v131, v131, 2, s47
	ds_read_b32 v131, v131 offset:36864
	v_add_u32_e32 v231, -3, v127
	v_min_u32_e32 v130, 0x7f, v231
	v_lshl_add_u32 v130, v130, 2, s47
	ds_read_b32 v130, v130 offset:36864
	v_add_u32_e32 v232, -16, v127
	v_min_u32_e32 v132, 0x7f, v232
	v_lshl_add_u32 v132, v132, 2, s47
	ds_read_b32 v132, v132 offset:36864
	v_subrev_u32_e32 v233, 17, v127
	v_min_u32_e32 v133, 0x7f, v233
	v_lshl_add_u32 v133, v133, 2, s47
	ds_read_b32 v133, v133 offset:36864
	v_subrev_u32_e32 v234, 18, v127
	v_min_u32_e32 v134, 0x7f, v234
	v_lshl_add_u32 v134, v134, 2, s47
	ds_read_b32 v134, v134 offset:36864
	v_subrev_u32_e32 v235, 19, v127
	v_min_u32_e32 v135, 0x7f, v235
	v_lshl_add_u32 v135, v135, 2, s47
	ds_read_b32 v135, v135 offset:36864
	v_subrev_u32_e32 v236, 32, v127
	v_min_u32_e32 v136, 0x7f, v236
	v_lshl_add_u32 v136, v136, 2, s47
	ds_read_b32 v136, v136 offset:36864
	v_subrev_u32_e32 v237, 33, v127
	v_min_u32_e32 v137, 0x7f, v237
	v_lshl_add_u32 v137, v137, 2, s47
	ds_read_b32 v137, v137 offset:36864
	v_subrev_u32_e32 v238, 34, v127
	v_min_u32_e32 v138, 0x7f, v238
	v_lshl_add_u32 v138, v138, 2, s47
	ds_read_b32 v138, v138 offset:36864
	v_subrev_u32_e32 v239, 35, v127
	v_min_u32_e32 v139, 0x7f, v239
	v_lshl_add_u32 v139, v139, 2, s47
	ds_read_b32 v139, v139 offset:36864
	v_subrev_u32_e32 v240, 48, v127
	v_min_u32_e32 v140, 0x7f, v240
	v_lshl_add_u32 v140, v140, 2, s47
	ds_read_b32 v140, v140 offset:36864
	v_subrev_u32_e32 v241, 49, v127
	v_min_u32_e32 v141, 0x7f, v241
	v_lshl_add_u32 v141, v141, 2, s47
	ds_read_b32 v141, v141 offset:36864
	v_subrev_u32_e32 v242, 50, v127
	v_min_u32_e32 v142, 0x7f, v242
	v_lshl_add_u32 v142, v142, 2, s47
	ds_read_b32 v142, v142 offset:36864
	v_subrev_u32_e32 v243, 51, v127
	v_min_u32_e32 v143, 0x7f, v243
	v_lshl_add_u32 v143, v143, 2, s47
	ds_read_b32 v143, v143 offset:36864
	s_waitcnt lgkmcnt(0)
; template <int MODE>
; __device__ __forceinline__ void attn_pass(LAS unsigned char* lds, const bf16_t* base, int gk, int q0, const float* relb_b, const unsigned* selrow, f32x4 (&o)[2][4]) {
;     ...
;             if (fast) {
;                 float mx = fmaxf(fmaxf(s[qt][0][0], s[qt][0][1]), fmaxf(s[qt][0][2], s[qt][0][3]));
; #pragma unroll
;                 for (int nt = 1; nt < 4; ++nt) mx = fmaxf(mx, fmaxf(fmaxf(s[qt][nt][0], s[qt][nt][1]), fmaxf(s[qt][nt][2], s[qt][nt][3])));
;                 mx = fmaxf(mx, __shfl_xor(mx, 16)); mx = fmaxf(mx, __shfl_xor(mx, 32));
;                 const float mxl = selb ? (mx * C1 + bias_far) : -1e30f;
;                 mnew = fmaxf(mrun[qt], mxl); alpha = __builtin_amdgcn_exp2f(mrun[qt] - mnew);
;                 const float c1 = selb ? C1 : 0.f, c2 = selb ? (bias_far - mnew) : -1e30f;
; #pragma unroll
;                 for (int nt = 0; nt < 4; ++nt)
; #pragma unroll
;                     for (int j = 0; j < 4; ++j) s[qt][nt][j] = __builtin_amdgcn_exp2f(s[qt][nt][j] * c1 + c2);
;             } else {
;                 const int dbase = selb ? (qw0 + 16 * qt + c - k0 - 4 * g) : -(1 << 22);
;                 float mx = -1e30f;
; #pragma unroll
;                 for (int nt = 0; nt < 4; ++nt)
; #pragma unroll
;                     for (int j = 0; j < 4; ++j) { const int dist = dbase - (16 * nt + j); const bool valid = (unsigned)dist < (unsigned)W;
;                         const unsigned di = (unsigned)dist < 127u ? (unsigned)dist : 127u;
;                         const float lg = valid ? (s[qt][nt][j] * C1 + lut[di]) : -1e30f; s[qt][nt][j] = lg; mx = fmaxf(mx, lg); }
;                 mx = fmaxf(mx, __shfl_xor(mx, 16)); mx = fmaxf(mx, __shfl_xor(mx, 32));
;                 mnew = fmaxf(mrun[qt], mx); alpha = __builtin_amdgcn_exp2f(mrun[qt] - mnew);
; #pragma unroll
;                 for (int nt = 0; nt < 4; ++nt)
; #pragma unroll
;                     for (int j = 0; j < 4; ++j) s[qt][nt][j] = __builtin_amdgcn_exp2f(s[qt][nt][j] - mnew);
	v_cmp_gt_u32_e32 vcc, s10, v127
	v_fmac_f32_e32 v129, 0x3e38aa3b, v108
	s_nop 0
	v_cndmask_b32_e32 v129, v226, v129, vcc
	v_cmp_gt_u32_e32 vcc, s10, v229
	v_fmac_f32_e32 v128, 0x3e38aa3b, v109
	s_nop 0
	v_cndmask_b32_e32 v128, v226, v128, vcc
	v_cmp_gt_u32_e32 vcc, s10, v230
	v_fmac_f32_e32 v131, 0x3e38aa3b, v110
	s_nop 0
	v_cndmask_b32_e32 v131, v226, v131, vcc
	v_cmp_gt_u32_e32 vcc, s10, v231
	v_fmac_f32_e32 v130, 0x3e38aa3b, v111
	s_nop 0
	v_cndmask_b32_e32 v130, v226, v130, vcc
	v_cmp_gt_u32_e32 vcc, s10, v232
	v_fmac_f32_e32 v132, 0x3e38aa3b, v104
	s_nop 0
	v_cndmask_b32_e32 v132, v226, v132, vcc
	v_cmp_gt_u32_e32 vcc, s10, v233
	v_fmac_f32_e32 v133, 0x3e38aa3b, v105
	s_nop 0
	v_cndmask_b32_e32 v133, v226, v133, vcc
	v_cmp_gt_u32_e32 vcc, s10, v234
	v_fmac_f32_e32 v134, 0x3e38aa3b, v106
	s_nop 0
	v_cndmask_b32_e32 v134, v226, v134, vcc
	v_cmp_gt_u32_e32 vcc, s10, v235
	v_fmac_f32_e32 v135, 0x3e38aa3b, v107
	s_nop 0
	v_cndmask_b32_e32 v135, v226, v135, vcc
	v_cmp_gt_u32_e32 vcc, s10, v236
	v_fmac_f32_e32 v136, 0x3e38aa3b, v100
	s_nop 0
	v_cndmask_b32_e32 v136, v226, v136, vcc
	v_cmp_gt_u32_e32 vcc, s10, v237
	v_fmac_f32_e32 v137, 0x3e38aa3b, v101
	s_nop 0
	v_cndmask_b32_e32 v137, v226, v137, vcc
	v_cmp_gt_u32_e32 vcc, s10, v238
	v_fmac_f32_e32 v138, 0x3e38aa3b, v102
	s_nop 0
	v_cndmask_b32_e32 v138, v226, v138, vcc
	v_cmp_gt_u32_e32 vcc, s10, v239
	v_fmac_f32_e32 v139, 0x3e38aa3b, v103
	s_nop 0
	v_cndmask_b32_e32 v139, v226, v139, vcc
	v_cmp_gt_u32_e32 vcc, s10, v240
	v_fmac_f32_e32 v140, 0x3e38aa3b, v96
	s_nop 0
	v_cndmask_b32_e32 v140, v226, v140, vcc
	v_cmp_gt_u32_e32 vcc, s10, v241
	v_fmac_f32_e32 v141, 0x3e38aa3b, v97
	s_nop 0
	v_cndmask_b32_e32 v141, v226, v141, vcc
	v_cmp_gt_u32_e32 vcc, s10, v242
	v_fmac_f32_e32 v142, 0x3e38aa3b, v98
	s_nop 0
	v_cndmask_b32_e32 v142, v226, v142, vcc
	v_cmp_gt_u32_e32 vcc, s10, v243
	v_fmac_f32_e32 v143, 0x3e38aa3b, v99
	s_nop 0
	v_cndmask_b32_e32 v143, v226, v143, vcc
	v_max3_f32 v127, v129, s86, v128
	v_max3_f32 v127, v127, v131, v130
	v_max3_f32 v127, v127, v132, v133
	v_max3_f32 v127, v127, v134, v135
	v_max3_f32 v127, v127, v136, v137
	v_max3_f32 v127, v127, v138, v139
	v_max3_f32 v127, v127, v140, v141
	v_max3_f32 v127, v127, v142, v143
	v_mov_b32_e32 v157, v127
	s_waitcnt lgkmcnt(0)
	s_nop 1
	v_permlane16_swap_b32_e32 v127, v157
	s_nop 0
	v_max_f32_e32 v127, v127, v157
	v_mov_b32_e32 v157, v127
	s_nop 1
	v_permlane32_swap_b32_e32 v127, v157
	s_nop 0
	v_max3_f32 v127, v155, v127, v157
	v_sub_f32_e32 v129, v129, v127
	v_sub_f32_e32 v157, v128, v127
	v_sub_f32_e32 v131, v131, v127
	v_sub_f32_e32 v158, v130, v127
	v_sub_f32_e32 v132, v132, v127
	v_sub_f32_e32 v133, v133, v127
	v_sub_f32_e32 v134, v134, v127
	v_sub_f32_e32 v135, v135, v127
	v_sub_f32_e32 v136, v136, v127
	v_sub_f32_e32 v137, v137, v127
	v_sub_f32_e32 v138, v138, v127
	v_sub_f32_e32 v139, v139, v127
	v_sub_f32_e32 v140, v140, v127
	v_sub_f32_e32 v141, v141, v127
	v_sub_f32_e32 v142, v142, v127
	v_exp_f32_e32 v128, v129
	v_exp_f32_e32 v129, v157
	v_exp_f32_e32 v130, v131
	v_exp_f32_e32 v131, v158
	v_exp_f32_e32 v132, v132
	v_exp_f32_e32 v133, v133
	v_exp_f32_e32 v134, v134
	v_exp_f32_e32 v135, v135
	v_exp_f32_e32 v136, v136
	v_exp_f32_e32 v137, v137
	v_exp_f32_e32 v138, v138
	v_exp_f32_e32 v139, v139
	v_exp_f32_e32 v140, v140
	v_exp_f32_e32 v141, v141
	v_exp_f32_e32 v142, v142
	v_sub_f32_e32 v157, v143, v127
	s_branch .LBB0_69
.LBB0_142:
	v_max_f32_e32 v127, v109, v109
	v_max_f32_e32 v128, v108, v108
	v_max_f32_e32 v127, v128, v127
	v_max_f32_e32 v128, v111, v111
	v_max_f32_e32 v129, v110, v110
	v_max_f32_e32 v128, v129, v128
	v_max_f32_e32 v129, v107, v107
	v_max_f32_e32 v130, v106, v106
	v_max_f32_e32 v129, v130, v129
	v_max3_f32 v129, v104, v105, v129
	v_max3_f32 v127, v127, v128, v129
	v_max_f32_e32 v128, v103, v103
	v_max_f32_e32 v129, v102, v102
	v_max_f32_e32 v128, v129, v128
	v_max_f32_e32 v129, v99, v99
	v_max_f32_e32 v130, v98, v98
	v_max_f32_e32 v129, v130, v129
	v_max3_f32 v128, v100, v101, v128
	v_max3_f32 v129, v96, v97, v129
	v_max3_f32 v127, v127, v128, v129
	v_mov_b32_e32 v128, v127
	v_cndmask_b32_e64 v143, v227, 0, s[0:1]
	s_waitcnt lgkmcnt(0)
	s_nop 1
	v_permlane16_swap_b32_e32 v127, v128
	s_nop 0
	v_max_f32_e32 v127, v127, v128
	v_mov_b32_e32 v128, v127
	s_nop 1
	v_permlane32_swap_b32_e32 v127, v128
	s_nop 0
	v_max_f32_e32 v127, v127, v128
	v_fmamk_f32 v127, v127, 0x3e38aa3b, v150
	v_cndmask_b32_e64 v127, v127, v226, s[0:1]
	v_max_f32_e32 v128, v155, v155
	v_max_f32_e32 v127, v128, v127
	v_sub_f32_e32 v128, v150, v127
	v_cndmask_b32_e64 v157, v128, v226, s[0:1]
	v_fma_f32 v108, v143, v108, v157
	v_fma_f32 v104, v143, v104, v157
	v_fma_f32 v100, v143, v100, v157
	v_exp_f32_e32 v128, v108
	v_fma_f32 v108, v143, v109, v157
	v_exp_f32_e32 v132, v104
	v_fma_f32 v104, v143, v105, v157
	v_exp_f32_e32 v136, v100
	v_fma_f32 v100, v143, v101, v157
	v_fma_f32 v96, v143, v96, v157
	v_exp_f32_e32 v129, v108
	v_fma_f32 v108, v143, v110, v157
	v_exp_f32_e32 v133, v104
	v_fma_f32 v104, v143, v106, v157
	v_exp_f32_e32 v137, v100
	v_fma_f32 v100, v143, v102, v157
	v_exp_f32_e32 v140, v96
	v_fma_f32 v96, v143, v97, v157
	v_exp_f32_e32 v130, v108
	v_fma_f32 v108, v143, v111, v157
	v_exp_f32_e32 v134, v104
	v_fma_f32 v104, v143, v107, v157
	v_exp_f32_e32 v138, v100
	v_fma_f32 v100, v143, v103, v157
	v_exp_f32_e32 v141, v96
	v_fma_f32 v96, v143, v98, v157
	v_exp_f32_e32 v131, v108
	v_exp_f32_e32 v135, v104
	v_exp_f32_e32 v139, v100
	v_exp_f32_e32 v142, v96
	v_fmac_f32_e32 v157, v143, v99
	v_sub_f32_e32 v96, v155, v127
	v_exp_f32_e32 v96, v96
	v_cmp_gt_f32_e32 vcc, v127, v155
	s_cbranch_vccnz .LBB0_70
	s_branch .LBB0_71

; template <int MODE>
; __device__ __forceinline__ void attn_pass(LAS unsigned char* lds, const bf16_t* base, int gk, int q0, const float* relb_b, const unsigned* selrow, f32x4 (&o)[2][4]) {
;     ...
;                 const int dbase = selb ? (qw0 + 16 * qt + c - k0 - 4 * g) : -(1 << 22);
;                 float mx = -1e30f;
; #pragma unroll
;                 for (int nt = 0; nt < 4; ++nt)
; #pragma unroll
;                     for (int j = 0; j < 4; ++j) { const int dist = dbase - (16 * nt + j); const bool valid = (unsigned)dist < (unsigned)W;
;                         const unsigned di = (unsigned)dist < 127u ? (unsigned)dist : 127u;
;                         const float lg = valid ? (s[qt][nt][j] * C1 + lut[di]) : -1e30f; s[qt][nt][j] = lg; mx = fmaxf(mx, lg); }
;                 mx = fmaxf(mx, __shfl_xor(mx, 16)); mx = fmaxf(mx, __shfl_xor(mx, 32));
;                 mnew = fmaxf(mrun[qt], mx); alpha = __builtin_amdgcn_exp2f(mrun[qt] - mnew);
; #pragma unroll
;                 for (int nt = 0; nt < 4; ++nt)
; #pragma unroll
;                     for (int j = 0; j < 4; ++j) s[qt][nt][j] = __builtin_amdgcn_exp2f(s[qt][nt][j] - mnew);
.LBB0_161:
	v_min_u32_e32 v144, 0x7f, v198
	v_lshl_add_u32 v144, v144, 2, s42
	ds_read_b32 v144, v144 offset:36864
	v_sub_u32_e32 v229, v199, v191
	v_min_u32_e32 v2, 0x7f, v229
	v_lshl_add_u32 v2, v2, 2, s42
	ds_read_b32 v2, v2 offset:36864
	v_sub_u32_e32 v230, v199, v192
	v_min_u32_e32 v146, 0x7f, v230
	v_lshl_add_u32 v146, v146, 2, s42
	ds_read_b32 v146, v146 offset:36864
	v_sub_u32_e32 v231, v199, v193
	v_min_u32_e32 v145, 0x7f, v231
	v_lshl_add_u32 v145, v145, 2, s42
	ds_read_b32 v145, v145 offset:36864
	v_add_u32_e32 v232, -16, v198
	v_min_u32_e32 v147, 0x7f, v232
	v_lshl_add_u32 v147, v147, 2, s42
	ds_read_b32 v147, v147 offset:36864
	v_add_u32_e32 v233, -16, v229
	v_min_u32_e32 v149, 0x7f, v233
	v_lshl_add_u32 v149, v149, 2, s42
	ds_read_b32 v149, v149 offset:36864
	v_add_u32_e32 v234, -16, v230
	v_min_u32_e32 v152, 0x7f, v234
	v_lshl_add_u32 v152, v152, 2, s42
	ds_read_b32 v152, v152 offset:36864
	v_add_u32_e32 v235, -16, v231
	v_min_u32_e32 v151, 0x7f, v235
	v_lshl_add_u32 v151, v151, 2, s42
	ds_read_b32 v151, v151 offset:36864
	v_subrev_u32_e32 v236, 32, v198
	v_min_u32_e32 v154, 0x7f, v236
	v_lshl_add_u32 v154, v154, 2, s42
	ds_read_b32 v154, v154 offset:36864
	v_subrev_u32_e32 v237, 32, v229
	v_min_u32_e32 v153, 0x7f, v237
	v_lshl_add_u32 v153, v153, 2, s42
	ds_read_b32 v153, v153 offset:36864
	v_subrev_u32_e32 v238, 32, v230
	v_min_u32_e32 v156, 0x7f, v238
	v_lshl_add_u32 v156, v156, 2, s42
	ds_read_b32 v156, v156 offset:36864
	v_subrev_u32_e32 v239, 32, v231
	v_min_u32_e32 v155, 0x7f, v239
	v_lshl_add_u32 v155, v155, 2, s42
	ds_read_b32 v155, v155 offset:36864
	v_subrev_u32_e32 v240, 48, v198
	v_min_u32_e32 v158, 0x7f, v240
	v_lshl_add_u32 v158, v158, 2, s42
	ds_read_b32 v158, v158 offset:36864
	v_subrev_u32_e32 v241, 48, v229
	v_min_u32_e32 v157, 0x7f, v241
	v_lshl_add_u32 v157, v157, 2, s42
	ds_read_b32 v157, v157 offset:36864
	v_subrev_u32_e32 v242, 48, v230
	v_min_u32_e32 v197, 0x7f, v242
	v_lshl_add_u32 v197, v197, 2, s42
	ds_read_b32 v197, v197 offset:36864
	v_subrev_u32_e32 v243, 48, v231
	v_min_u32_e32 v159, 0x7f, v243
	v_lshl_add_u32 v159, v159, 2, s42
	ds_read_b32 v159, v159 offset:36864
	s_waitcnt lgkmcnt(0)
	v_fmac_f32_e32 v144, 0x3e38aa3b, v172
	v_cndmask_b32_e64 v144, v226, v144, s[0:1]
	v_cmp_gt_u32_e32 vcc, s33, v229
	v_fmac_f32_e32 v2, 0x3e38aa3b, v173
	s_nop 0
	v_cndmask_b32_e32 v2, v226, v2, vcc
	v_cmp_gt_u32_e32 vcc, s33, v230
	v_fmac_f32_e32 v146, 0x3e38aa3b, v174
	s_nop 0
	v_cndmask_b32_e32 v146, v226, v146, vcc
	v_cmp_gt_u32_e32 vcc, s33, v231
	v_fmac_f32_e32 v145, 0x3e38aa3b, v175
	s_nop 0
	v_cndmask_b32_e32 v145, v226, v145, vcc
	v_cmp_gt_u32_e32 vcc, s33, v232
	v_fmac_f32_e32 v147, 0x3e38aa3b, v168
	s_nop 0
	v_cndmask_b32_e32 v147, v226, v147, vcc
	v_cmp_gt_u32_e32 vcc, s33, v233
	v_fmac_f32_e32 v149, 0x3e38aa3b, v169
	s_nop 0
	v_cndmask_b32_e32 v149, v226, v149, vcc
	v_cmp_gt_u32_e32 vcc, s33, v234
	v_fmac_f32_e32 v152, 0x3e38aa3b, v170
	s_nop 0
	v_cndmask_b32_e32 v152, v226, v152, vcc
	v_cmp_gt_u32_e32 vcc, s33, v235
	v_fmac_f32_e32 v151, 0x3e38aa3b, v171
	s_nop 0
	v_cndmask_b32_e32 v151, v226, v151, vcc
	v_cmp_gt_u32_e32 vcc, s33, v236
	v_fmac_f32_e32 v154, 0x3e38aa3b, v164
	s_nop 0
	v_cndmask_b32_e32 v154, v226, v154, vcc
	v_cmp_gt_u32_e32 vcc, s33, v237
	v_fmac_f32_e32 v153, 0x3e38aa3b, v165
	s_nop 0
	v_cndmask_b32_e32 v153, v226, v153, vcc
	v_cmp_gt_u32_e32 vcc, s33, v238
	v_fmac_f32_e32 v156, 0x3e38aa3b, v166
	s_nop 0
	v_cndmask_b32_e32 v156, v226, v156, vcc
	v_cmp_gt_u32_e32 vcc, s33, v239
	v_fmac_f32_e32 v155, 0x3e38aa3b, v167
	s_nop 0
	v_cndmask_b32_e32 v155, v226, v155, vcc
	v_cmp_gt_u32_e32 vcc, s33, v240
	v_fmac_f32_e32 v158, 0x3e38aa3b, v160
	s_nop 0
	v_cndmask_b32_e32 v158, v226, v158, vcc
	v_cmp_gt_u32_e32 vcc, s33, v241
	v_fmac_f32_e32 v157, 0x3e38aa3b, v161
	s_nop 0
	v_cndmask_b32_e32 v157, v226, v157, vcc
	v_cmp_gt_u32_e32 vcc, s33, v242
	v_fmac_f32_e32 v197, 0x3e38aa3b, v162
	s_nop 0
	v_cndmask_b32_e32 v197, v226, v197, vcc
	v_cmp_gt_u32_e32 vcc, s33, v243
	v_fmac_f32_e32 v159, 0x3e38aa3b, v163
	s_nop 0
	v_cndmask_b32_e32 v159, v226, v159, vcc
	v_max3_f32 v3, v144, s86, v2
	v_max3_f32 v3, v3, v146, v145
	v_max3_f32 v3, v3, v147, v149
	v_max3_f32 v3, v3, v152, v151
	v_max3_f32 v3, v3, v154, v153
	v_max3_f32 v3, v3, v156, v155
	v_max3_f32 v3, v3, v158, v157
	v_max3_f32 v3, v3, v197, v159
	v_mov_b32_e32 v148, v3
	s_waitcnt lgkmcnt(0)
	s_nop 1
	v_permlane16_swap_b32_e32 v3, v148
	s_nop 0
	v_max_f32_e32 v3, v3, v148
	v_mov_b32_e32 v148, v3
	s_nop 1
	v_permlane32_swap_b32_e32 v3, v148
	s_nop 0
	v_max3_f32 v3, v200, v3, v148
	v_sub_f32_e32 v2, v2, v3
	v_sub_f32_e32 v148, v145, v3
	v_exp_f32_e32 v145, v2
	v_sub_f32_e32 v2, v149, v3
	v_sub_f32_e32 v150, v147, v3
	v_exp_f32_e32 v149, v2
	v_sub_f32_e32 v2, v152, v3
	v_exp_f32_e32 v147, v148
	v_exp_f32_e32 v148, v150
	v_exp_f32_e32 v150, v2
	v_sub_f32_e32 v2, v151, v3
	v_exp_f32_e32 v151, v2
	v_sub_f32_e32 v2, v154, v3
	v_exp_f32_e32 v152, v2
	v_sub_f32_e32 v2, v153, v3
	v_exp_f32_e32 v153, v2
	v_sub_f32_e32 v2, v156, v3
	v_exp_f32_e32 v154, v2
	v_sub_f32_e32 v2, v155, v3
	v_exp_f32_e32 v155, v2
	v_sub_f32_e32 v2, v158, v3
	v_exp_f32_e32 v156, v2
	v_sub_f32_e32 v2, v157, v3
	v_sub_f32_e32 v144, v144, v3
	v_sub_f32_e32 v146, v146, v3
	v_exp_f32_e32 v157, v2
	v_sub_f32_e32 v2, v197, v3
	v_exp_f32_e32 v144, v144
	v_exp_f32_e32 v146, v146
	v_exp_f32_e32 v158, v2
	v_sub_f32_e32 v197, v159, v3
	s_branch .LBB0_153
; template <int MODE>
; __device__ __forceinline__ void attn_pass(LAS unsigned char* lds, const bf16_t* base, int gk, int q0, const float* relb_b, const unsigned* selrow, f32x4 (&o)[2][4]) {
;     ...
;             if (fast) {
;                 float mx = fmaxf(fmaxf(s[qt][0][0], s[qt][0][1]), fmaxf(s[qt][0][2], s[qt][0][3]));
; #pragma unroll
;                 for (int nt = 1; nt < 4; ++nt) mx = fmaxf(mx, fmaxf(fmaxf(s[qt][nt][0], s[qt][nt][1]), fmaxf(s[qt][nt][2], s[qt][nt][3])));
;                 mx = fmaxf(mx, __shfl_xor(mx, 16)); mx = fmaxf(mx, __shfl_xor(mx, 32));
;                 const float mxl = selb ? (mx * C1 + bias_far) : -1e30f;
;                 mnew = fmaxf(mrun[qt], mxl); alpha = __builtin_amdgcn_exp2f(mrun[qt] - mnew);
;                 const float c1 = selb ? C1 : 0.f, c2 = selb ? (bias_far - mnew) : -1e30f;
; #pragma unroll
;                 for (int nt = 0; nt < 4; ++nt)
; #pragma unroll
;                     for (int j = 0; j < 4; ++j) s[qt][nt][j] = __builtin_amdgcn_exp2f(s[qt][nt][j] * c1 + c2);
;             } else {
;                 const int dbase = selb ? (qw0 + 16 * qt + c - k0 - 4 * g) : -(1 << 22);
;                 float mx = -1e30f;
; #pragma unroll
;                 for (int nt = 0; nt < 4; ++nt)
; #pragma unroll
;                     for (int j = 0; j < 4; ++j) { const int dist = dbase - (16 * nt + j); const bool valid = (unsigned)dist < (unsigned)W;
;                         const unsigned di = (unsigned)dist < 127u ? (unsigned)dist : 127u;
;                         const float lg = valid ? (s[qt][nt][j] * C1 + lut[di]) : -1e30f; s[qt][nt][j] = lg; mx = fmaxf(mx, lg); }
.LBB0_194:
	v_max_f32_e32 v2, v173, v173
	v_max_f32_e32 v3, v172, v172
	v_max_f32_e32 v2, v3, v2
	v_max_f32_e32 v3, v175, v175
	v_max_f32_e32 v144, v174, v174
	v_max_f32_e32 v3, v144, v3
	v_max_f32_e32 v144, v171, v171
	v_max_f32_e32 v145, v170, v170
	v_max_f32_e32 v144, v145, v144
	v_max3_f32 v144, v168, v169, v144
	v_max3_f32 v2, v2, v3, v144
	v_max_f32_e32 v3, v167, v167
	v_max_f32_e32 v144, v166, v166
	v_max_f32_e32 v3, v144, v3
	v_max_f32_e32 v144, v163, v163
	v_max_f32_e32 v145, v162, v162
	v_max_f32_e32 v144, v145, v144
	v_max3_f32 v3, v164, v165, v3
	v_max3_f32 v144, v160, v161, v144
	v_max3_f32 v2, v2, v3, v144
	v_mov_b32_e32 v3, v2
	s_waitcnt lgkmcnt(0)
	s_nop 1
	v_permlane16_swap_b32_e32 v2, v3
	s_nop 0
	v_max_f32_e32 v2, v2, v3
	v_mov_b32_e32 v3, v2
	s_nop 1
	v_permlane32_swap_b32_e32 v2, v3
	s_nop 0
	v_max_f32_e32 v2, v2, v3
	v_fmamk_f32 v2, v2, 0x3e38aa3b, v188
	v_max_f32_e32 v3, v200, v200
	v_max_f32_e32 v3, v3, v2
	v_sub_f32_e32 v197, v188, v3
	v_fmamk_f32 v2, v172, 0x3e38aa3b, v197
	v_exp_f32_e32 v144, v2
	v_fmamk_f32 v2, v173, 0x3e38aa3b, v197
	v_exp_f32_e32 v145, v2
	v_fmamk_f32 v2, v174, 0x3e38aa3b, v197
	v_exp_f32_e32 v146, v2
	v_fmamk_f32 v2, v175, 0x3e38aa3b, v197
	v_exp_f32_e32 v147, v2
	v_fmamk_f32 v2, v168, 0x3e38aa3b, v197
	v_exp_f32_e32 v148, v2
	v_fmamk_f32 v2, v169, 0x3e38aa3b, v197
	v_exp_f32_e32 v149, v2
	v_fmamk_f32 v2, v170, 0x3e38aa3b, v197
	v_exp_f32_e32 v150, v2
	v_fmamk_f32 v2, v171, 0x3e38aa3b, v197
	v_exp_f32_e32 v151, v2
	v_fmamk_f32 v2, v164, 0x3e38aa3b, v197
	v_exp_f32_e32 v152, v2
	v_fmamk_f32 v2, v165, 0x3e38aa3b, v197
	v_exp_f32_e32 v153, v2
	v_fmamk_f32 v2, v166, 0x3e38aa3b, v197
	v_exp_f32_e32 v154, v2
	v_fmamk_f32 v2, v167, 0x3e38aa3b, v197
	v_exp_f32_e32 v155, v2
	v_fmamk_f32 v2, v160, 0x3e38aa3b, v197
	v_exp_f32_e32 v156, v2
	v_fmamk_f32 v2, v161, 0x3e38aa3b, v197
	v_exp_f32_e32 v157, v2
	v_fmamk_f32 v2, v162, 0x3e38aa3b, v197
	v_exp_f32_e32 v158, v2
	v_fmac_f32_e32 v197, 0x3e38aa3b, v163
	v_sub_f32_e32 v2, v200, v3
	v_exp_f32_e32 v2, v2
	v_cmp_gt_f32_e32 vcc, v3, v200
	s_cbranch_vccnz .LBB0_154
	s_branch .LBB0_155
.LBB0_195:
	v_or_b32_e32 v159, 16, v199
	v_sub_u32_e32 v228, v159, v189
	v_min_u32_e32 v161, 0x7f, v228
	v_lshl_add_u32 v161, v161, 2, s42
	ds_read_b32 v161, v161 offset:36864
	v_sub_u32_e32 v229, v159, v191
	v_min_u32_e32 v160, 0x7f, v229
	v_lshl_add_u32 v160, v160, 2, s42
	ds_read_b32 v160, v160 offset:36864
	v_sub_u32_e32 v230, v159, v192
	v_min_u32_e32 v163, 0x7f, v230
	v_lshl_add_u32 v163, v163, 2, s42
	ds_read_b32 v163, v163 offset:36864
	v_sub_u32_e32 v231, v159, v193
	v_min_u32_e32 v162, 0x7f, v231
	v_lshl_add_u32 v162, v162, 2, s42
	ds_read_b32 v162, v162 offset:36864
	v_mov_b32_e32 v232, v198
	v_min_u32_e32 v164, 0x7f, v232
	v_lshl_add_u32 v164, v164, 2, s42
	ds_read_b32 v164, v164 offset:36864
	v_sub_u32_e32 v233, v199, v191
	v_min_u32_e32 v165, 0x7f, v233
	v_lshl_add_u32 v165, v165, 2, s42
	ds_read_b32 v165, v165 offset:36864
	v_sub_u32_e32 v234, v199, v192
	v_min_u32_e32 v166, 0x7f, v234
	v_lshl_add_u32 v166, v166, 2, s42
	ds_read_b32 v166, v166 offset:36864
	v_sub_u32_e32 v235, v199, v193
	v_min_u32_e32 v167, 0x7f, v235
	v_lshl_add_u32 v167, v167, 2, s42
	ds_read_b32 v167, v167 offset:36864
	v_add_u32_e32 v236, -16, v198
	v_min_u32_e32 v168, 0x7f, v236
	v_lshl_add_u32 v168, v168, 2, s42
	ds_read_b32 v168, v168 offset:36864
	v_add_u32_e32 v237, -16, v233
	v_min_u32_e32 v169, 0x7f, v237
	v_lshl_add_u32 v169, v169, 2, s42
	ds_read_b32 v169, v169 offset:36864
	v_add_u32_e32 v238, -16, v234
	v_min_u32_e32 v170, 0x7f, v238
	v_lshl_add_u32 v170, v170, 2, s42
	ds_read_b32 v170, v170 offset:36864
	v_add_u32_e32 v239, -16, v235
	v_min_u32_e32 v171, 0x7f, v239
	v_lshl_add_u32 v171, v171, 2, s42
	ds_read_b32 v171, v171 offset:36864
	v_subrev_u32_e32 v240, 32, v198
	v_min_u32_e32 v175, 0x7f, v240
	v_lshl_add_u32 v175, v175, 2, s42
	ds_read_b32 v175, v175 offset:36864
	v_subrev_u32_e32 v241, 32, v233
	v_min_u32_e32 v174, 0x7f, v241
	v_lshl_add_u32 v174, v174, 2, s42
	ds_read_b32 v174, v174 offset:36864
	v_subrev_u32_e32 v242, 32, v234
	v_min_u32_e32 v199, 0x7f, v242
	v_lshl_add_u32 v199, v199, 2, s42
	ds_read_b32 v199, v199 offset:36864
	v_subrev_u32_e32 v243, 32, v235
	v_min_u32_e32 v198, 0x7f, v243
	v_lshl_add_u32 v198, v198, 2, s42
	ds_read_b32 v198, v198 offset:36864
	s_waitcnt lgkmcnt(0)
; template <int MODE>
; __device__ __forceinline__ void attn_pass(LAS unsigned char* lds, const bf16_t* base, int gk, int q0, const float* relb_b, const unsigned* selrow, f32x4 (&o)[2][4]) {
;     ...
;             if (fast) {
;                 float mx = fmaxf(fmaxf(s[qt][0][0], s[qt][0][1]), fmaxf(s[qt][0][2], s[qt][0][3]));
; #pragma unroll
;                 for (int nt = 1; nt < 4; ++nt) mx = fmaxf(mx, fmaxf(fmaxf(s[qt][nt][0], s[qt][nt][1]), fmaxf(s[qt][nt][2], s[qt][nt][3])));
;                 mx = fmaxf(mx, __shfl_xor(mx, 16)); mx = fmaxf(mx, __shfl_xor(mx, 32));
;                 const float mxl = selb ? (mx * C1 + bias_far) : -1e30f;
;                 mnew = fmaxf(mrun[qt], mxl); alpha = __builtin_amdgcn_exp2f(mrun[qt] - mnew);
;                 const float c1 = selb ? C1 : 0.f, c2 = selb ? (bias_far - mnew) : -1e30f;
; #pragma unroll
;                 for (int nt = 0; nt < 4; ++nt)
; #pragma unroll
;                     for (int j = 0; j < 4; ++j) s[qt][nt][j] = __builtin_amdgcn_exp2f(s[qt][nt][j] * c1 + c2);
;             } else {
;                 const int dbase = selb ? (qw0 + 16 * qt + c - k0 - 4 * g) : -(1 << 22);
;                 float mx = -1e30f;
; #pragma unroll
;                 for (int nt = 0; nt < 4; ++nt)
; #pragma unroll
;                     for (int j = 0; j < 4; ++j) { const int dist = dbase - (16 * nt + j); const bool valid = (unsigned)dist < (unsigned)W;
;                         const unsigned di = (unsigned)dist < 127u ? (unsigned)dist : 127u;
;                         const float lg = valid ? (s[qt][nt][j] * C1 + lut[di]) : -1e30f; s[qt][nt][j] = lg; mx = fmaxf(mx, lg); }
;                 mx = fmaxf(mx, __shfl_xor(mx, 16)); mx = fmaxf(mx, __shfl_xor(mx, 32));
;                 mnew = fmaxf(mrun[qt], mx); alpha = __builtin_amdgcn_exp2f(mrun[qt] - mnew);
; #pragma unroll
;                 for (int nt = 0; nt < 4; ++nt)
; #pragma unroll
;                     for (int j = 0; j < 4; ++j) s[qt][nt][j] = __builtin_amdgcn_exp2f(s[qt][nt][j] - mnew);
	v_cmp_gt_u32_e32 vcc, s33, v228
	v_fmac_f32_e32 v161, 0x3e38aa3b, v140
	s_nop 0
	v_cndmask_b32_e32 v161, v226, v161, vcc
	v_cmp_gt_u32_e32 vcc, s33, v229
	v_fmac_f32_e32 v160, 0x3e38aa3b, v141
	s_nop 0
	v_cndmask_b32_e32 v160, v226, v160, vcc
	v_cmp_gt_u32_e32 vcc, s33, v230
	v_fmac_f32_e32 v163, 0x3e38aa3b, v142
	s_nop 0
	v_cndmask_b32_e32 v163, v226, v163, vcc
	v_cmp_gt_u32_e32 vcc, s33, v231
	v_fmac_f32_e32 v162, 0x3e38aa3b, v143
	s_nop 0
	v_cndmask_b32_e32 v162, v226, v162, vcc
	v_cmp_gt_u32_e32 vcc, s33, v232
	v_fmac_f32_e32 v164, 0x3e38aa3b, v136
	s_nop 0
	v_cndmask_b32_e32 v164, v226, v164, vcc
	v_cmp_gt_u32_e32 vcc, s33, v233
	v_fmac_f32_e32 v165, 0x3e38aa3b, v137
	s_nop 0
	v_cndmask_b32_e32 v165, v226, v165, vcc
	v_cmp_gt_u32_e32 vcc, s33, v234
	v_fmac_f32_e32 v166, 0x3e38aa3b, v138
	s_nop 0
	v_cndmask_b32_e32 v166, v226, v166, vcc
	v_cmp_gt_u32_e32 vcc, s33, v235
	v_fmac_f32_e32 v167, 0x3e38aa3b, v139
	s_nop 0
	v_cndmask_b32_e32 v167, v226, v167, vcc
	v_cmp_gt_u32_e32 vcc, s33, v236
	v_fmac_f32_e32 v168, 0x3e38aa3b, v132
	s_nop 0
	v_cndmask_b32_e32 v168, v226, v168, vcc
	v_cmp_gt_u32_e32 vcc, s33, v237
	v_fmac_f32_e32 v169, 0x3e38aa3b, v133
	s_nop 0
	v_cndmask_b32_e32 v169, v226, v169, vcc
	v_cmp_gt_u32_e32 vcc, s33, v238
	v_fmac_f32_e32 v170, 0x3e38aa3b, v134
	s_nop 0
	v_cndmask_b32_e32 v170, v226, v170, vcc
	v_cmp_gt_u32_e32 vcc, s33, v239
	v_fmac_f32_e32 v171, 0x3e38aa3b, v135
	s_nop 0
	v_cndmask_b32_e32 v171, v226, v171, vcc
	v_cmp_gt_u32_e32 vcc, s33, v240
	v_fmac_f32_e32 v175, 0x3e38aa3b, v128
	s_nop 0
	v_cndmask_b32_e32 v175, v226, v175, vcc
	v_cmp_gt_u32_e32 vcc, s33, v241
	v_fmac_f32_e32 v174, 0x3e38aa3b, v129
	s_nop 0
	v_cndmask_b32_e32 v174, v226, v174, vcc
	v_cmp_gt_u32_e32 vcc, s33, v242
	v_fmac_f32_e32 v199, 0x3e38aa3b, v130
	s_nop 0
	v_cndmask_b32_e32 v199, v226, v199, vcc
	v_cmp_gt_u32_e32 vcc, s33, v243
	v_fmac_f32_e32 v198, 0x3e38aa3b, v131
	s_nop 0
	v_cndmask_b32_e32 v198, v226, v198, vcc
	v_max3_f32 v159, v161, s86, v160
	v_max3_f32 v159, v159, v163, v162
	v_max3_f32 v159, v159, v164, v165
	v_max3_f32 v159, v159, v166, v167
	v_max3_f32 v159, v159, v168, v169
	v_max3_f32 v159, v159, v170, v171
	v_max3_f32 v159, v159, v175, v174
	v_max3_f32 v159, v159, v199, v198
	v_mov_b32_e32 v172, v159
	s_waitcnt lgkmcnt(0)
	s_nop 1
	v_permlane16_swap_b32_e32 v159, v172
	s_nop 0
	v_max_f32_e32 v159, v159, v172
	v_mov_b32_e32 v172, v159
	s_nop 1
	v_permlane32_swap_b32_e32 v159, v172
	s_nop 0
	v_max3_f32 v159, v196, v159, v172
	v_sub_f32_e32 v161, v161, v159
	v_sub_f32_e32 v172, v160, v159
	v_sub_f32_e32 v163, v163, v159
	v_sub_f32_e32 v173, v162, v159
	v_sub_f32_e32 v164, v164, v159
	v_exp_f32_e32 v160, v161
	v_exp_f32_e32 v161, v172
	v_exp_f32_e32 v162, v163
	v_exp_f32_e32 v163, v173
	v_sub_f32_e32 v165, v165, v159
	v_sub_f32_e32 v166, v166, v159
	v_sub_f32_e32 v167, v167, v159
	v_sub_f32_e32 v168, v168, v159
	v_sub_f32_e32 v169, v169, v159
	v_sub_f32_e32 v170, v170, v159
	v_sub_f32_e32 v171, v171, v159
	v_sub_f32_e32 v172, v175, v159
	v_sub_f32_e32 v173, v174, v159
	v_sub_f32_e32 v174, v199, v159
	v_exp_f32_e32 v164, v164
	v_exp_f32_e32 v165, v165
	v_exp_f32_e32 v166, v166
	v_exp_f32_e32 v167, v167
	v_exp_f32_e32 v168, v168
	v_exp_f32_e32 v169, v169
	v_exp_f32_e32 v170, v170
	v_exp_f32_e32 v171, v171
	v_exp_f32_e32 v172, v172
	v_exp_f32_e32 v173, v173
	v_exp_f32_e32 v174, v174
	v_sub_f32_e32 v200, v198, v159
	s_branch .LBB0_157
.LBB0_228:
	v_max_f32_e32 v159, v141, v141
	v_max_f32_e32 v160, v140, v140
	v_max_f32_e32 v159, v160, v159
	v_max_f32_e32 v160, v143, v143
	v_max_f32_e32 v161, v142, v142
	v_max_f32_e32 v160, v161, v160
	v_max_f32_e32 v161, v139, v139
	v_max_f32_e32 v162, v138, v138
	v_max_f32_e32 v161, v162, v161
	v_max3_f32 v161, v136, v137, v161
	v_max3_f32 v159, v159, v160, v161
	v_max_f32_e32 v160, v135, v135
	v_max_f32_e32 v161, v134, v134
	v_max_f32_e32 v160, v161, v160
	v_max_f32_e32 v161, v131, v131
	v_max_f32_e32 v162, v130, v130
	v_max_f32_e32 v161, v162, v161
	v_max3_f32 v160, v132, v133, v160
	v_max3_f32 v161, v128, v129, v161
	v_max3_f32 v159, v159, v160, v161
	v_mov_b32_e32 v160, v159
	s_waitcnt lgkmcnt(0)
	s_nop 1
	v_permlane16_swap_b32_e32 v159, v160
	s_nop 0
	v_max_f32_e32 v159, v159, v160
	v_mov_b32_e32 v160, v159
	s_nop 1
	v_permlane32_swap_b32_e32 v159, v160
	s_nop 0
	v_max_f32_e32 v159, v159, v160
	v_fmamk_f32 v159, v159, 0x3e38aa3b, v188
	v_max_f32_e32 v160, v196, v196
	v_max_f32_e32 v159, v160, v159
	v_sub_f32_e32 v200, v188, v159
	v_fmamk_f32 v140, v140, 0x3e38aa3b, v200
	v_fmamk_f32 v136, v136, 0x3e38aa3b, v200
	v_fmamk_f32 v132, v132, 0x3e38aa3b, v200
	v_exp_f32_e32 v160, v140
	v_fmamk_f32 v140, v141, 0x3e38aa3b, v200
	v_exp_f32_e32 v164, v136
	v_fmamk_f32 v136, v137, 0x3e38aa3b, v200
	v_exp_f32_e32 v168, v132
	v_fmamk_f32 v132, v133, 0x3e38aa3b, v200
	v_fmamk_f32 v128, v128, 0x3e38aa3b, v200
	v_exp_f32_e32 v161, v140
	v_fmamk_f32 v140, v142, 0x3e38aa3b, v200
	v_exp_f32_e32 v165, v136
	v_fmamk_f32 v136, v138, 0x3e38aa3b, v200
	v_exp_f32_e32 v169, v132
	v_fmamk_f32 v132, v134, 0x3e38aa3b, v200
	v_exp_f32_e32 v172, v128
	v_fmamk_f32 v128, v129, 0x3e38aa3b, v200
	v_exp_f32_e32 v162, v140
	v_fmamk_f32 v140, v143, 0x3e38aa3b, v200
	v_exp_f32_e32 v166, v136
	v_fmamk_f32 v136, v139, 0x3e38aa3b, v200
	v_exp_f32_e32 v170, v132
	v_fmamk_f32 v132, v135, 0x3e38aa3b, v200
	v_exp_f32_e32 v173, v128
	v_fmamk_f32 v128, v130, 0x3e38aa3b, v200
	v_exp_f32_e32 v163, v140
	v_exp_f32_e32 v167, v136
	v_exp_f32_e32 v171, v132
	v_exp_f32_e32 v174, v128
	v_fmac_f32_e32 v200, 0x3e38aa3b, v131
	v_sub_f32_e32 v128, v196, v159
	v_exp_f32_e32 v128, v128
	v_cmp_gt_f32_e32 vcc, v159, v196
	s_cbranch_vccnz .LBB0_158
	s_branch .LBB0_159

; __device__ __forceinline__ unsigned cvtpk(float lo, float hi) { f32x2 v = {lo, hi}; bf16x2_t b = __builtin_convertvector(v, bf16x2_t); return __builtin_bit_cast(unsigned, b); }
; __device__ __forceinline__ float bflo(unsigned u) { return __uint_as_float(u << 16); }
; __device__ __forceinline__ float bfhi(unsigned u) { return __uint_as_float(u & 0xffff0000u); }
; __device__ __forceinline__ float sigmoidf_(float x) { return fast_rcp(1.f + __expf(-x)); }
;     __device__ __forceinline__ void operator()(const f32x4 (&acc)[2][2][4][2], const Unit& u, int wr, int wc, int fr, int fq) const {
;     ...
;                         if (mode == 1 || mode == 5) {
; #pragma unroll
;                             for (int e = 0; e < 4; ++e) { v0[e] = sigmoidf_(v0[e]); v1[e] = sigmoidf_(v1[e]); } }
;                         if (mode == 6) {
;                             const u32x4 gq = *(const u32x4*)(sG + rl * 256 + cl);
;                             v0[0] *= bflo(gq.x); v0[1] *= bfhi(gq.x); v0[2] *= bflo(gq.y); v0[3] *= bfhi(gq.y); v1[0] *= bflo(gq.z); v1[1] *= bfhi(gq.z); v1[2] *= bflo(gq.w); v1[3] *= bfhi(gq.w);
;                             if (u.br > 0) { const u32x4 mo = *(const u32x4*)(sM + rl * 256 + cl);
;                                 v0[0] += bflo(mo.x); v0[1] += bfhi(mo.x); v0[2] += bflo(mo.y); v0[3] += bfhi(mo.y); v1[0] += bflo(mo.z); v1[1] += bfhi(mo.z); v1[2] += bflo(mo.w); v1[3] += bfhi(mo.w); } }
;                         u32x4 w; w.x = cvtpk(v0[0], v0[1]); w.y = cvtpk(v0[2], v0[3]); w.z = cvtpk(v1[0], v1[1]); w.w = cvtpk(v1[2], v1[3]);
;                         if (mode == 5) *(u32x4*)(sG + rl * 256 + cl) = w;
;                         else if (mode == 6 && u.br < 2) *(u32x4*)(sM + rl * 256 + cl) = w;
;                         else if (col0 < ncols) *(u32x4*)(rowp + col0) = w; } } }
.LBB0_423:
	s_cmp_eq_u32 s71, 6
	s_cbranch_scc1 .Lepi6
	s_cmp_lt_i32 s71, 5
	s_cbranch_scc1 .LBB0_426
	s_cmp_eq_u32 s71, 5
	s_cselect_b64 s[26:27], -1, 0
	s_cbranch_execz .LBB0_427
	s_branch .LBB0_428

; __device__ __forceinline__ unsigned cvtpk(float lo, float hi) { f32x2 v = {lo, hi}; bf16x2_t b = __builtin_convertvector(v, bf16x2_t); return __builtin_bit_cast(unsigned, b); }
; __device__ __forceinline__ float bflo(unsigned u) { return __uint_as_float(u << 16); }
; __device__ __forceinline__ float bfhi(unsigned u) { return __uint_as_float(u & 0xffff0000u); }
;     __device__ __forceinline__ void operator()(const f32x4 (&acc)[2][2][4][2], const Unit& u, int wr, int wc, int fr, int fq) const {
;     ...
;                         if (mode == 6) {
;                             const u32x4 gq = *(const u32x4*)(sG + rl * 256 + cl);
;                             v0[0] *= bflo(gq.x); v0[1] *= bfhi(gq.x); v0[2] *= bflo(gq.y); v0[3] *= bfhi(gq.y); v1[0] *= bflo(gq.z); v1[1] *= bfhi(gq.z); v1[2] *= bflo(gq.w); v1[3] *= bfhi(gq.w);
;                             if (u.br > 0) { const u32x4 mo = *(const u32x4*)(sM + rl * 256 + cl);
;                                 v0[0] += bflo(mo.x); v0[1] += bfhi(mo.x); v0[2] += bflo(mo.y); v0[3] += bfhi(mo.y); v1[0] += bflo(mo.z); v1[1] += bfhi(mo.z); v1[2] += bflo(mo.w); v1[3] += bfhi(mo.w); } }
;                         u32x4 w; w.x = cvtpk(v0[0], v0[1]); w.y = cvtpk(v0[2], v0[3]); w.z = cvtpk(v1[0], v1[1]); w.w = cvtpk(v1[2], v1[3]);
;                         if (mode == 5) *(u32x4*)(sG + rl * 256 + cl) = w;
;                         else if (mode == 6 && u.br < 2) *(u32x4*)(sM + rl * 256 + cl) = w;
;                         else if (col0 < ncols) *(u32x4*)(rowp + col0) = w; } } }
.Lepi6:
	v_lshlrev_b32_e32 v228, 9, v184
	v_lshl_add_u32 v228, v150, 1, v228
	v_readlane_b32 s74, v252, 54
	v_readlane_b32 s75, v252, 55
	v_readlane_b32 s76, v252, 56
	v_readlane_b32 s77, v252, 57
	s_cmp_lt_i32 s70, 2
	s_cbranch_scc0 .Lepi6_out
	v_mov_b32_e32 v229, v228
	s_mov_b32 s78, s76
	s_mov_b32 s79, s77
	s_mov_b32 s80, 0x10000
	s_movk_i32 s81, 0x2000
	s_branch .Lepi6_go
.Lepi6_out:
	v_lshlrev_b32_e32 v229, 11, v184
	v_lshl_add_u32 v229, v150, 1, v229
	s_lshl_b32 s78, s68, 19
	s_lshl_b32 s79, s69, 9
	s_add_u32 s78, s78, s79
	s_add_u32 s78, s24, s78
	s_addc_u32 s79, s25, 0
	s_mov_b32 s80, 0x40000
	s_mov_b32 s81, 0x8000
.Lepi6_go:
	s_mov_b32 s90, s78
	s_mov_b32 s91, s79
	s_mov_b32 s82, s74
	s_mov_b32 s83, s75
	s_mov_b32 s88, s76
	s_mov_b32 s89, s77
	global_load_dwordx4 v[136:139], v228, s[82:83]
	global_load_dwordx4 v[194:197], v228, s[88:89]
	global_load_dwordx4 v[140:143], v228, s[82:83] offset:256
	global_load_dwordx4 v[198:201], v228, s[88:89] offset:256
	s_add_u32 s82, s74, 0x2000
	s_addc_u32 s83, s75, 0
	s_add_u32 s88, s76, 0x2000
	s_addc_u32 s89, s77, 0
	global_load_dwordx4 v[162:165], v228, s[82:83]
	global_load_dwordx4 v[202:205], v228, s[88:89]
	global_load_dwordx4 v[166:169], v228, s[82:83] offset:256
	global_load_dwordx4 v[206:209], v228, s[88:89] offset:256
	s_add_u32 s82, s74, 0x4000
	s_addc_u32 s83, s75, 0
	s_add_u32 s88, s76, 0x4000
	s_addc_u32 s89, s77, 0
	global_load_dwordx4 v[170:173], v228, s[82:83]
	global_load_dwordx4 v[230:233], v228, s[88:89]
	global_load_dwordx4 v[174:177], v228, s[82:83] offset:256
	global_load_dwordx4 v[234:237], v228, s[88:89] offset:256
	s_add_u32 s82, s74, 0x6000
	s_addc_u32 s83, s75, 0
	s_add_u32 s88, s76, 0x6000
	s_addc_u32 s89, s77, 0
	global_load_dwordx4 v[186:189], v228, s[82:83]
	global_load_dwordx4 v[238:241], v228, s[88:89]
	global_load_dwordx4 v[190:193], v228, s[82:83] offset:256
	global_load_dwordx4 v[242:245], v228, s[88:89] offset:256
	s_waitcnt vmcnt(14)
	v_lshlrev_b32_e32 v250, 16, v136
	v_and_b32_e32 v251, 0xffff0000, v136
	v_pk_mul_f32 v[132:133], v[132:133], v[250:251]
	v_lshlrev_b32_e32 v250, 16, v137
	v_and_b32_e32 v251, 0xffff0000, v137
	v_pk_mul_f32 v[134:135], v[134:135], v[250:251]
	v_lshlrev_b32_e32 v250, 16, v138
	v_and_b32_e32 v251, 0xffff0000, v138
	v_pk_mul_f32 v[128:129], v[128:129], v[250:251]
	v_lshlrev_b32_e32 v250, 16, v139
	v_and_b32_e32 v251, 0xffff0000, v139
	v_pk_mul_f32 v[130:131], v[130:131], v[250:251]
	s_cmp_eq_u32 s70, 0
	s_cbranch_scc1 .Lepi6_na0
	v_lshlrev_b32_e32 v250, 16, v194
	v_and_b32_e32 v251, 0xffff0000, v194
	v_pk_add_f32 v[132:133], v[132:133], v[250:251]
	v_lshlrev_b32_e32 v250, 16, v195
	v_and_b32_e32 v251, 0xffff0000, v195
	v_pk_add_f32 v[134:135], v[134:135], v[250:251]
	v_lshlrev_b32_e32 v250, 16, v196
	v_and_b32_e32 v251, 0xffff0000, v196
	v_pk_add_f32 v[128:129], v[128:129], v[250:251]
	v_lshlrev_b32_e32 v250, 16, v197
	v_and_b32_e32 v251, 0xffff0000, v197
	v_pk_add_f32 v[130:131], v[130:131], v[250:251]
.Lepi6_na0:
	v_cvt_pk_bf16_f32 v246, v132, v133
	v_cvt_pk_bf16_f32 v247, v134, v135
	v_cvt_pk_bf16_f32 v248, v128, v129
	v_cvt_pk_bf16_f32 v249, v130, v131
	global_store_dwordx4 v229, v[246:249], s[90:91]
	s_add_u32 s82, s74, 0x10000
	s_addc_u32 s83, s75, 0
	s_add_u32 s88, s76, 0x10000
	s_addc_u32 s89, s77, 0
	global_load_dwordx4 v[136:139], v228, s[82:83]
	global_load_dwordx4 v[194:197], v228, s[88:89]
	s_waitcnt vmcnt(15)
	v_lshlrev_b32_e32 v250, 16, v140
	v_and_b32_e32 v251, 0xffff0000, v140
	v_pk_mul_f32 v[100:101], v[100:101], v[250:251]
	v_lshlrev_b32_e32 v250, 16, v141
	v_and_b32_e32 v251, 0xffff0000, v141
	v_pk_mul_f32 v[102:103], v[102:103], v[250:251]
	v_lshlrev_b32_e32 v250, 16, v142
	v_and_b32_e32 v251, 0xffff0000, v142
	v_pk_mul_f32 v[96:97], v[96:97], v[250:251]
	v_lshlrev_b32_e32 v250, 16, v143
	v_and_b32_e32 v251, 0xffff0000, v143
	v_pk_mul_f32 v[98:99], v[98:99], v[250:251]
	s_cmp_eq_u32 s70, 0
	s_cbranch_scc1 .Lepi6_na1
	v_lshlrev_b32_e32 v250, 16, v198
	v_and_b32_e32 v251, 0xffff0000, v198
	v_pk_add_f32 v[100:101], v[100:101], v[250:251]
	v_lshlrev_b32_e32 v250, 16, v199
	v_and_b32_e32 v251, 0xffff0000, v199
	v_pk_add_f32 v[102:103], v[102:103], v[250:251]
	v_lshlrev_b32_e32 v250, 16, v200
	v_and_b32_e32 v251, 0xffff0000, v200
	v_pk_add_f32 v[96:97], v[96:97], v[250:251]
	v_lshlrev_b32_e32 v250, 16, v201
	v_and_b32_e32 v251, 0xffff0000, v201
	v_pk_add_f32 v[98:99], v[98:99], v[250:251]
.Lepi6_na1:
	v_cvt_pk_bf16_f32 v210, v100, v101
	v_cvt_pk_bf16_f32 v211, v102, v103
	v_cvt_pk_bf16_f32 v212, v96, v97
	v_cvt_pk_bf16_f32 v213, v98, v99
	global_store_dwordx4 v229, v[210:213], s[90:91] offset:256
	s_add_u32 s90, s90, s81
	s_addc_u32 s91, s91, 0
	global_load_dwordx4 v[140:143], v228, s[82:83] offset:256
	global_load_dwordx4 v[198:201], v228, s[88:89] offset:256
	s_waitcnt vmcnt(16)
	v_lshlrev_b32_e32 v250, 16, v162
	v_and_b32_e32 v251, 0xffff0000, v162
	v_pk_mul_f32 v[124:125], v[124:125], v[250:251]
	v_lshlrev_b32_e32 v250, 16, v163
	v_and_b32_e32 v251, 0xffff0000, v163
	v_pk_mul_f32 v[126:127], v[126:127], v[250:251]
	v_lshlrev_b32_e32 v250, 16, v164
	v_and_b32_e32 v251, 0xffff0000, v164
	v_pk_mul_f32 v[120:121], v[120:121], v[250:251]
	v_lshlrev_b32_e32 v250, 16, v165
	v_and_b32_e32 v251, 0xffff0000, v165
	v_pk_mul_f32 v[122:123], v[122:123], v[250:251]
	s_cmp_eq_u32 s70, 0
	s_cbranch_scc1 .Lepi6_na2
	v_lshlrev_b32_e32 v250, 16, v202
	v_and_b32_e32 v251, 0xffff0000, v202
	v_pk_add_f32 v[124:125], v[124:125], v[250:251]
	v_lshlrev_b32_e32 v250, 16, v203
	v_and_b32_e32 v251, 0xffff0000, v203
	v_pk_add_f32 v[126:127], v[126:127], v[250:251]
	v_lshlrev_b32_e32 v250, 16, v204
	v_and_b32_e32 v251, 0xffff0000, v204
	v_pk_add_f32 v[120:121], v[120:121], v[250:251]
	v_lshlrev_b32_e32 v250, 16, v205
	v_and_b32_e32 v251, 0xffff0000, v205
	v_pk_add_f32 v[122:123], v[122:123], v[250:251]
; __device__ __forceinline__ unsigned cvtpk(float lo, float hi) { f32x2 v = {lo, hi}; bf16x2_t b = __builtin_convertvector(v, bf16x2_t); return __builtin_bit_cast(unsigned, b); }
; __device__ __forceinline__ float bflo(unsigned u) { return __uint_as_float(u << 16); }
; __device__ __forceinline__ float bfhi(unsigned u) { return __uint_as_float(u & 0xffff0000u); }
;     __device__ __forceinline__ void operator()(const f32x4 (&acc)[2][2][4][2], const Unit& u, int wr, int wc, int fr, int fq) const {
;     ...
;                         if (mode == 6) {
;                             const u32x4 gq = *(const u32x4*)(sG + rl * 256 + cl);
;                             v0[0] *= bflo(gq.x); v0[1] *= bfhi(gq.x); v0[2] *= bflo(gq.y); v0[3] *= bfhi(gq.y); v1[0] *= bflo(gq.z); v1[1] *= bfhi(gq.z); v1[2] *= bflo(gq.w); v1[3] *= bfhi(gq.w);
;                             if (u.br > 0) { const u32x4 mo = *(const u32x4*)(sM + rl * 256 + cl);
;                                 v0[0] += bflo(mo.x); v0[1] += bfhi(mo.x); v0[2] += bflo(mo.y); v0[3] += bfhi(mo.y); v1[0] += bflo(mo.z); v1[1] += bfhi(mo.z); v1[2] += bflo(mo.w); v1[3] += bfhi(mo.w); } }
;                         u32x4 w; w.x = cvtpk(v0[0], v0[1]); w.y = cvtpk(v0[2], v0[3]); w.z = cvtpk(v1[0], v1[1]); w.w = cvtpk(v1[2], v1[3]);
;                         if (mode == 5) *(u32x4*)(sG + rl * 256 + cl) = w;
;                         else if (mode == 6 && u.br < 2) *(u32x4*)(sM + rl * 256 + cl) = w;
;                         else if (col0 < ncols) *(u32x4*)(rowp + col0) = w; } } }
.Lepi6_na2:
	v_cvt_pk_bf16_f32 v246, v124, v125
	v_cvt_pk_bf16_f32 v247, v126, v127
	v_cvt_pk_bf16_f32 v248, v120, v121
	v_cvt_pk_bf16_f32 v249, v122, v123
	global_store_dwordx4 v229, v[246:249], s[90:91]
	s_add_u32 s82, s74, 0x12000
	s_addc_u32 s83, s75, 0
	s_add_u32 s88, s76, 0x12000
	s_addc_u32 s89, s77, 0
	global_load_dwordx4 v[162:165], v228, s[82:83]
	global_load_dwordx4 v[202:205], v228, s[88:89]
	s_waitcnt vmcnt(17)
	v_lshlrev_b32_e32 v250, 16, v166
	v_and_b32_e32 v251, 0xffff0000, v166
	v_pk_mul_f32 v[92:93], v[92:93], v[250:251]
	v_lshlrev_b32_e32 v250, 16, v167
	v_and_b32_e32 v251, 0xffff0000, v167
	v_pk_mul_f32 v[94:95], v[94:95], v[250:251]
	v_lshlrev_b32_e32 v250, 16, v168
	v_and_b32_e32 v251, 0xffff0000, v168
	v_pk_mul_f32 v[88:89], v[88:89], v[250:251]
	v_lshlrev_b32_e32 v250, 16, v169
	v_and_b32_e32 v251, 0xffff0000, v169
	v_pk_mul_f32 v[90:91], v[90:91], v[250:251]
	s_cmp_eq_u32 s70, 0
	s_cbranch_scc1 .Lepi6_na3
	v_lshlrev_b32_e32 v250, 16, v206
	v_and_b32_e32 v251, 0xffff0000, v206
	v_pk_add_f32 v[92:93], v[92:93], v[250:251]
	v_lshlrev_b32_e32 v250, 16, v207
	v_and_b32_e32 v251, 0xffff0000, v207
	v_pk_add_f32 v[94:95], v[94:95], v[250:251]
	v_lshlrev_b32_e32 v250, 16, v208
	v_and_b32_e32 v251, 0xffff0000, v208
	v_pk_add_f32 v[88:89], v[88:89], v[250:251]
	v_lshlrev_b32_e32 v250, 16, v209
	v_and_b32_e32 v251, 0xffff0000, v209
	v_pk_add_f32 v[90:91], v[90:91], v[250:251]
.Lepi6_na3:
	v_cvt_pk_bf16_f32 v210, v92, v93
	v_cvt_pk_bf16_f32 v211, v94, v95
	v_cvt_pk_bf16_f32 v212, v88, v89
	v_cvt_pk_bf16_f32 v213, v90, v91
	global_store_dwordx4 v229, v[210:213], s[90:91] offset:256
	s_add_u32 s90, s90, s81
	s_addc_u32 s91, s91, 0
	global_load_dwordx4 v[166:169], v228, s[82:83] offset:256
	global_load_dwordx4 v[206:209], v228, s[88:89] offset:256
	s_waitcnt vmcnt(18)
	v_lshlrev_b32_e32 v250, 16, v170
	v_and_b32_e32 v251, 0xffff0000, v170
	v_pk_mul_f32 v[116:117], v[116:117], v[250:251]
	v_lshlrev_b32_e32 v250, 16, v171
	v_and_b32_e32 v251, 0xffff0000, v171
	v_pk_mul_f32 v[118:119], v[118:119], v[250:251]
	v_lshlrev_b32_e32 v250, 16, v172
	v_and_b32_e32 v251, 0xffff0000, v172
	v_pk_mul_f32 v[112:113], v[112:113], v[250:251]
	v_lshlrev_b32_e32 v250, 16, v173
	v_and_b32_e32 v251, 0xffff0000, v173
	v_pk_mul_f32 v[114:115], v[114:115], v[250:251]
	s_cmp_eq_u32 s70, 0
	s_cbranch_scc1 .Lepi6_na4
	v_lshlrev_b32_e32 v250, 16, v230
	v_and_b32_e32 v251, 0xffff0000, v230
	v_pk_add_f32 v[116:117], v[116:117], v[250:251]
	v_lshlrev_b32_e32 v250, 16, v231
	v_and_b32_e32 v251, 0xffff0000, v231
	v_pk_add_f32 v[118:119], v[118:119], v[250:251]
	v_lshlrev_b32_e32 v250, 16, v232
	v_and_b32_e32 v251, 0xffff0000, v232
	v_pk_add_f32 v[112:113], v[112:113], v[250:251]
	v_lshlrev_b32_e32 v250, 16, v233
	v_and_b32_e32 v251, 0xffff0000, v233
	v_pk_add_f32 v[114:115], v[114:115], v[250:251]
.Lepi6_na4:
	v_cvt_pk_bf16_f32 v246, v116, v117
	v_cvt_pk_bf16_f32 v247, v118, v119
	v_cvt_pk_bf16_f32 v248, v112, v113
	v_cvt_pk_bf16_f32 v249, v114, v115
	global_store_dwordx4 v229, v[246:249], s[90:91]
	s_add_u32 s82, s74, 0x14000
	s_addc_u32 s83, s75, 0
	s_add_u32 s88, s76, 0x14000
	s_addc_u32 s89, s77, 0
	global_load_dwordx4 v[170:173], v228, s[82:83]
	global_load_dwordx4 v[230:233], v228, s[88:89]
	s_waitcnt vmcnt(19)
	v_lshlrev_b32_e32 v250, 16, v174
	v_and_b32_e32 v251, 0xffff0000, v174
	v_pk_mul_f32 v[84:85], v[84:85], v[250:251]
	v_lshlrev_b32_e32 v250, 16, v175
	v_and_b32_e32 v251, 0xffff0000, v175
	v_pk_mul_f32 v[86:87], v[86:87], v[250:251]
	v_lshlrev_b32_e32 v250, 16, v176
	v_and_b32_e32 v251, 0xffff0000, v176
	v_pk_mul_f32 v[80:81], v[80:81], v[250:251]
	v_lshlrev_b32_e32 v250, 16, v177
	v_and_b32_e32 v251, 0xffff0000, v177
	v_pk_mul_f32 v[82:83], v[82:83], v[250:251]
	s_cmp_eq_u32 s70, 0
	s_cbranch_scc1 .Lepi6_na5
	v_lshlrev_b32_e32 v250, 16, v234
	v_and_b32_e32 v251, 0xffff0000, v234
	v_pk_add_f32 v[84:85], v[84:85], v[250:251]
	v_lshlrev_b32_e32 v250, 16, v235
	v_and_b32_e32 v251, 0xffff0000, v235
	v_pk_add_f32 v[86:87], v[86:87], v[250:251]
	v_lshlrev_b32_e32 v250, 16, v236
	v_and_b32_e32 v251, 0xffff0000, v236
	v_pk_add_f32 v[80:81], v[80:81], v[250:251]
	v_lshlrev_b32_e32 v250, 16, v237
	v_and_b32_e32 v251, 0xffff0000, v237
	v_pk_add_f32 v[82:83], v[82:83], v[250:251]
.Lepi6_na5:
	v_cvt_pk_bf16_f32 v210, v84, v85
	v_cvt_pk_bf16_f32 v211, v86, v87
	v_cvt_pk_bf16_f32 v212, v80, v81
	v_cvt_pk_bf16_f32 v213, v82, v83
	global_store_dwordx4 v229, v[210:213], s[90:91] offset:256
	s_add_u32 s90, s90, s81
	s_addc_u32 s91, s91, 0
	global_load_dwordx4 v[174:177], v228, s[82:83] offset:256
	global_load_dwordx4 v[234:237], v228, s[88:89] offset:256
	s_waitcnt vmcnt(20)
	v_lshlrev_b32_e32 v250, 16, v186
	v_and_b32_e32 v251, 0xffff0000, v186
	v_pk_mul_f32 v[108:109], v[108:109], v[250:251]
	v_lshlrev_b32_e32 v250, 16, v187
	v_and_b32_e32 v251, 0xffff0000, v187
	v_pk_mul_f32 v[110:111], v[110:111], v[250:251]
	v_lshlrev_b32_e32 v250, 16, v188
	v_and_b32_e32 v251, 0xffff0000, v188
	v_pk_mul_f32 v[104:105], v[104:105], v[250:251]
	v_lshlrev_b32_e32 v250, 16, v189
	v_and_b32_e32 v251, 0xffff0000, v189
	v_pk_mul_f32 v[106:107], v[106:107], v[250:251]
	s_cmp_eq_u32 s70, 0
	s_cbranch_scc1 .Lepi6_na6
	v_lshlrev_b32_e32 v250, 16, v238
	v_and_b32_e32 v251, 0xffff0000, v238
	v_pk_add_f32 v[108:109], v[108:109], v[250:251]
	v_lshlrev_b32_e32 v250, 16, v239
	v_and_b32_e32 v251, 0xffff0000, v239
	v_pk_add_f32 v[110:111], v[110:111], v[250:251]
	v_lshlrev_b32_e32 v250, 16, v240
	v_and_b32_e32 v251, 0xffff0000, v240
	v_pk_add_f32 v[104:105], v[104:105], v[250:251]
	v_lshlrev_b32_e32 v250, 16, v241
	v_and_b32_e32 v251, 0xffff0000, v241
	v_pk_add_f32 v[106:107], v[106:107], v[250:251]
; __device__ __forceinline__ unsigned cvtpk(float lo, float hi) { f32x2 v = {lo, hi}; bf16x2_t b = __builtin_convertvector(v, bf16x2_t); return __builtin_bit_cast(unsigned, b); }
; __device__ __forceinline__ float bflo(unsigned u) { return __uint_as_float(u << 16); }
; __device__ __forceinline__ float bfhi(unsigned u) { return __uint_as_float(u & 0xffff0000u); }
;     __device__ __forceinline__ void operator()(const f32x4 (&acc)[2][2][4][2], const Unit& u, int wr, int wc, int fr, int fq) const {
;     ...
;                         if (mode == 6) {
;                             const u32x4 gq = *(const u32x4*)(sG + rl * 256 + cl);
;                             v0[0] *= bflo(gq.x); v0[1] *= bfhi(gq.x); v0[2] *= bflo(gq.y); v0[3] *= bfhi(gq.y); v1[0] *= bflo(gq.z); v1[1] *= bfhi(gq.z); v1[2] *= bflo(gq.w); v1[3] *= bfhi(gq.w);
;                             if (u.br > 0) { const u32x4 mo = *(const u32x4*)(sM + rl * 256 + cl);
;                                 v0[0] += bflo(mo.x); v0[1] += bfhi(mo.x); v0[2] += bflo(mo.y); v0[3] += bfhi(mo.y); v1[0] += bflo(mo.z); v1[1] += bfhi(mo.z); v1[2] += bflo(mo.w); v1[3] += bfhi(mo.w); } }
;                         u32x4 w; w.x = cvtpk(v0[0], v0[1]); w.y = cvtpk(v0[2], v0[3]); w.z = cvtpk(v1[0], v1[1]); w.w = cvtpk(v1[2], v1[3]);
;                         if (mode == 5) *(u32x4*)(sG + rl * 256 + cl) = w;
;                         else if (mode == 6 && u.br < 2) *(u32x4*)(sM + rl * 256 + cl) = w;
;                         else if (col0 < ncols) *(u32x4*)(rowp + col0) = w; } } }
.Lepi6_na6:
	v_cvt_pk_bf16_f32 v246, v108, v109
	v_cvt_pk_bf16_f32 v247, v110, v111
	v_cvt_pk_bf16_f32 v248, v104, v105
	v_cvt_pk_bf16_f32 v249, v106, v107
	global_store_dwordx4 v229, v[246:249], s[90:91]
	s_add_u32 s82, s74, 0x16000
	s_addc_u32 s83, s75, 0
	s_add_u32 s88, s76, 0x16000
	s_addc_u32 s89, s77, 0
	global_load_dwordx4 v[186:189], v228, s[82:83]
	global_load_dwordx4 v[238:241], v228, s[88:89]
	s_waitcnt vmcnt(21)
	v_lshlrev_b32_e32 v250, 16, v190
	v_and_b32_e32 v251, 0xffff0000, v190
	v_pk_mul_f32 v[76:77], v[76:77], v[250:251]
	v_lshlrev_b32_e32 v250, 16, v191
	v_and_b32_e32 v251, 0xffff0000, v191
	v_pk_mul_f32 v[78:79], v[78:79], v[250:251]
	v_lshlrev_b32_e32 v250, 16, v192
	v_and_b32_e32 v251, 0xffff0000, v192
	v_pk_mul_f32 v[72:73], v[72:73], v[250:251]
	v_lshlrev_b32_e32 v250, 16, v193
	v_and_b32_e32 v251, 0xffff0000, v193
	v_pk_mul_f32 v[74:75], v[74:75], v[250:251]
	s_cmp_eq_u32 s70, 0
	s_cbranch_scc1 .Lepi6_na7
	v_lshlrev_b32_e32 v250, 16, v242
	v_and_b32_e32 v251, 0xffff0000, v242
	v_pk_add_f32 v[76:77], v[76:77], v[250:251]
	v_lshlrev_b32_e32 v250, 16, v243
	v_and_b32_e32 v251, 0xffff0000, v243
	v_pk_add_f32 v[78:79], v[78:79], v[250:251]
	v_lshlrev_b32_e32 v250, 16, v244
	v_and_b32_e32 v251, 0xffff0000, v244
	v_pk_add_f32 v[72:73], v[72:73], v[250:251]
	v_lshlrev_b32_e32 v250, 16, v245
	v_and_b32_e32 v251, 0xffff0000, v245
	v_pk_add_f32 v[74:75], v[74:75], v[250:251]
.Lepi6_na7:
	v_cvt_pk_bf16_f32 v210, v76, v77
	v_cvt_pk_bf16_f32 v211, v78, v79
	v_cvt_pk_bf16_f32 v212, v72, v73
	v_cvt_pk_bf16_f32 v213, v74, v75
	global_store_dwordx4 v229, v[210:213], s[90:91] offset:256
	s_add_u32 s90, s78, s80
	s_addc_u32 s91, s79, 0
	global_load_dwordx4 v[190:193], v228, s[82:83] offset:256
	global_load_dwordx4 v[242:245], v228, s[88:89] offset:256
	s_waitcnt vmcnt(21)
	v_lshlrev_b32_e32 v250, 16, v136
	v_and_b32_e32 v251, 0xffff0000, v136
	v_pk_mul_f32 v[68:69], v[68:69], v[250:251]
	v_lshlrev_b32_e32 v250, 16, v137
	v_and_b32_e32 v251, 0xffff0000, v137
	v_pk_mul_f32 v[70:71], v[70:71], v[250:251]
	v_lshlrev_b32_e32 v250, 16, v138
	v_and_b32_e32 v251, 0xffff0000, v138
	v_pk_mul_f32 v[64:65], v[64:65], v[250:251]
	v_lshlrev_b32_e32 v250, 16, v139
	v_and_b32_e32 v251, 0xffff0000, v139
	v_pk_mul_f32 v[66:67], v[66:67], v[250:251]
	s_cmp_eq_u32 s70, 0
	s_cbranch_scc1 .Lepi6_na8
	v_lshlrev_b32_e32 v250, 16, v194
	v_and_b32_e32 v251, 0xffff0000, v194
	v_pk_add_f32 v[68:69], v[68:69], v[250:251]
	v_lshlrev_b32_e32 v250, 16, v195
	v_and_b32_e32 v251, 0xffff0000, v195
	v_pk_add_f32 v[70:71], v[70:71], v[250:251]
	v_lshlrev_b32_e32 v250, 16, v196
	v_and_b32_e32 v251, 0xffff0000, v196
	v_pk_add_f32 v[64:65], v[64:65], v[250:251]
	v_lshlrev_b32_e32 v250, 16, v197
	v_and_b32_e32 v251, 0xffff0000, v197
	v_pk_add_f32 v[66:67], v[66:67], v[250:251]
.Lepi6_na8:
	v_cvt_pk_bf16_f32 v246, v68, v69
	v_cvt_pk_bf16_f32 v247, v70, v71
	v_cvt_pk_bf16_f32 v248, v64, v65
	v_cvt_pk_bf16_f32 v249, v66, v67
	global_store_dwordx4 v229, v[246:249], s[90:91]
	s_waitcnt vmcnt(19)
	v_lshlrev_b32_e32 v250, 16, v140
	v_and_b32_e32 v251, 0xffff0000, v140
	v_pk_mul_f32 v[36:37], v[36:37], v[250:251]
	v_lshlrev_b32_e32 v250, 16, v141
	v_and_b32_e32 v251, 0xffff0000, v141
	v_pk_mul_f32 v[38:39], v[38:39], v[250:251]
	v_lshlrev_b32_e32 v250, 16, v142
	v_and_b32_e32 v251, 0xffff0000, v142
	v_pk_mul_f32 v[32:33], v[32:33], v[250:251]
	v_lshlrev_b32_e32 v250, 16, v143
	v_and_b32_e32 v251, 0xffff0000, v143
	v_pk_mul_f32 v[34:35], v[34:35], v[250:251]
	s_cmp_eq_u32 s70, 0
	s_cbranch_scc1 .Lepi6_na9
	v_lshlrev_b32_e32 v250, 16, v198
	v_and_b32_e32 v251, 0xffff0000, v198
	v_pk_add_f32 v[36:37], v[36:37], v[250:251]
	v_lshlrev_b32_e32 v250, 16, v199
	v_and_b32_e32 v251, 0xffff0000, v199
	v_pk_add_f32 v[38:39], v[38:39], v[250:251]
	v_lshlrev_b32_e32 v250, 16, v200
	v_and_b32_e32 v251, 0xffff0000, v200
	v_pk_add_f32 v[32:33], v[32:33], v[250:251]
	v_lshlrev_b32_e32 v250, 16, v201
	v_and_b32_e32 v251, 0xffff0000, v201
	v_pk_add_f32 v[34:35], v[34:35], v[250:251]
.Lepi6_na9:
	v_cvt_pk_bf16_f32 v210, v36, v37
	v_cvt_pk_bf16_f32 v211, v38, v39
	v_cvt_pk_bf16_f32 v212, v32, v33
	v_cvt_pk_bf16_f32 v213, v34, v35
	global_store_dwordx4 v229, v[210:213], s[90:91] offset:256
	s_add_u32 s90, s90, s81
	s_addc_u32 s91, s91, 0
	s_waitcnt vmcnt(17)
	v_lshlrev_b32_e32 v250, 16, v162
	v_and_b32_e32 v251, 0xffff0000, v162
	v_pk_mul_f32 v[60:61], v[60:61], v[250:251]
	v_lshlrev_b32_e32 v250, 16, v163
	v_and_b32_e32 v251, 0xffff0000, v163
	v_pk_mul_f32 v[62:63], v[62:63], v[250:251]
	v_lshlrev_b32_e32 v250, 16, v164
	v_and_b32_e32 v251, 0xffff0000, v164
	v_pk_mul_f32 v[56:57], v[56:57], v[250:251]
	v_lshlrev_b32_e32 v250, 16, v165
	v_and_b32_e32 v251, 0xffff0000, v165
	v_pk_mul_f32 v[58:59], v[58:59], v[250:251]
	s_cmp_eq_u32 s70, 0
	s_cbranch_scc1 .Lepi6_na10
	v_lshlrev_b32_e32 v250, 16, v202
	v_and_b32_e32 v251, 0xffff0000, v202
	v_pk_add_f32 v[60:61], v[60:61], v[250:251]
	v_lshlrev_b32_e32 v250, 16, v203
	v_and_b32_e32 v251, 0xffff0000, v203
	v_pk_add_f32 v[62:63], v[62:63], v[250:251]
	v_lshlrev_b32_e32 v250, 16, v204
	v_and_b32_e32 v251, 0xffff0000, v204
	v_pk_add_f32 v[56:57], v[56:57], v[250:251]
	v_lshlrev_b32_e32 v250, 16, v205
	v_and_b32_e32 v251, 0xffff0000, v205
	v_pk_add_f32 v[58:59], v[58:59], v[250:251]
; __device__ __forceinline__ unsigned cvtpk(float lo, float hi) { f32x2 v = {lo, hi}; bf16x2_t b = __builtin_convertvector(v, bf16x2_t); return __builtin_bit_cast(unsigned, b); }
; __device__ __forceinline__ float bflo(unsigned u) { return __uint_as_float(u << 16); }
; __device__ __forceinline__ float bfhi(unsigned u) { return __uint_as_float(u & 0xffff0000u); }
;     __device__ __forceinline__ void operator()(const f32x4 (&acc)[2][2][4][2], const Unit& u, int wr, int wc, int fr, int fq) const {
;     ...
;                         if (mode == 6) {
;                             const u32x4 gq = *(const u32x4*)(sG + rl * 256 + cl);
;                             v0[0] *= bflo(gq.x); v0[1] *= bfhi(gq.x); v0[2] *= bflo(gq.y); v0[3] *= bfhi(gq.y); v1[0] *= bflo(gq.z); v1[1] *= bfhi(gq.z); v1[2] *= bflo(gq.w); v1[3] *= bfhi(gq.w);
;                             if (u.br > 0) { const u32x4 mo = *(const u32x4*)(sM + rl * 256 + cl);
;                                 v0[0] += bflo(mo.x); v0[1] += bfhi(mo.x); v0[2] += bflo(mo.y); v0[3] += bfhi(mo.y); v1[0] += bflo(mo.z); v1[1] += bfhi(mo.z); v1[2] += bflo(mo.w); v1[3] += bfhi(mo.w); } }
;                         u32x4 w; w.x = cvtpk(v0[0], v0[1]); w.y = cvtpk(v0[2], v0[3]); w.z = cvtpk(v1[0], v1[1]); w.w = cvtpk(v1[2], v1[3]);
;                         if (mode == 5) *(u32x4*)(sG + rl * 256 + cl) = w;
;                         else if (mode == 6 && u.br < 2) *(u32x4*)(sM + rl * 256 + cl) = w;
;                         else if (col0 < ncols) *(u32x4*)(rowp + col0) = w; } } }
.Lepi6_na10:
	v_cvt_pk_bf16_f32 v246, v60, v61
	v_cvt_pk_bf16_f32 v247, v62, v63
	v_cvt_pk_bf16_f32 v248, v56, v57
	v_cvt_pk_bf16_f32 v249, v58, v59
	global_store_dwordx4 v229, v[246:249], s[90:91]
	s_waitcnt vmcnt(15)
	v_lshlrev_b32_e32 v250, 16, v166
	v_and_b32_e32 v251, 0xffff0000, v166
	v_pk_mul_f32 v[28:29], v[28:29], v[250:251]
	v_lshlrev_b32_e32 v250, 16, v167
	v_and_b32_e32 v251, 0xffff0000, v167
	v_pk_mul_f32 v[30:31], v[30:31], v[250:251]
	v_lshlrev_b32_e32 v250, 16, v168
	v_and_b32_e32 v251, 0xffff0000, v168
	v_pk_mul_f32 v[24:25], v[24:25], v[250:251]
	v_lshlrev_b32_e32 v250, 16, v169
	v_and_b32_e32 v251, 0xffff0000, v169
	v_pk_mul_f32 v[26:27], v[26:27], v[250:251]
	s_cmp_eq_u32 s70, 0
	s_cbranch_scc1 .Lepi6_na11
	v_lshlrev_b32_e32 v250, 16, v206
	v_and_b32_e32 v251, 0xffff0000, v206
	v_pk_add_f32 v[28:29], v[28:29], v[250:251]
	v_lshlrev_b32_e32 v250, 16, v207
	v_and_b32_e32 v251, 0xffff0000, v207
	v_pk_add_f32 v[30:31], v[30:31], v[250:251]
	v_lshlrev_b32_e32 v250, 16, v208
	v_and_b32_e32 v251, 0xffff0000, v208
	v_pk_add_f32 v[24:25], v[24:25], v[250:251]
	v_lshlrev_b32_e32 v250, 16, v209
	v_and_b32_e32 v251, 0xffff0000, v209
	v_pk_add_f32 v[26:27], v[26:27], v[250:251]
.Lepi6_na11:
	v_cvt_pk_bf16_f32 v210, v28, v29
	v_cvt_pk_bf16_f32 v211, v30, v31
	v_cvt_pk_bf16_f32 v212, v24, v25
	v_cvt_pk_bf16_f32 v213, v26, v27
	global_store_dwordx4 v229, v[210:213], s[90:91] offset:256
	s_add_u32 s90, s90, s81
	s_addc_u32 s91, s91, 0
	s_waitcnt vmcnt(13)
	v_lshlrev_b32_e32 v250, 16, v170
	v_and_b32_e32 v251, 0xffff0000, v170
	v_pk_mul_f32 v[52:53], v[52:53], v[250:251]
	v_lshlrev_b32_e32 v250, 16, v171
	v_and_b32_e32 v251, 0xffff0000, v171
	v_pk_mul_f32 v[54:55], v[54:55], v[250:251]
	v_lshlrev_b32_e32 v250, 16, v172
	v_and_b32_e32 v251, 0xffff0000, v172
	v_pk_mul_f32 v[48:49], v[48:49], v[250:251]
	v_lshlrev_b32_e32 v250, 16, v173
	v_and_b32_e32 v251, 0xffff0000, v173
	v_pk_mul_f32 v[50:51], v[50:51], v[250:251]
	s_cmp_eq_u32 s70, 0
	s_cbranch_scc1 .Lepi6_na12
	v_lshlrev_b32_e32 v250, 16, v230
	v_and_b32_e32 v251, 0xffff0000, v230
	v_pk_add_f32 v[52:53], v[52:53], v[250:251]
	v_lshlrev_b32_e32 v250, 16, v231
	v_and_b32_e32 v251, 0xffff0000, v231
	v_pk_add_f32 v[54:55], v[54:55], v[250:251]
	v_lshlrev_b32_e32 v250, 16, v232
	v_and_b32_e32 v251, 0xffff0000, v232
	v_pk_add_f32 v[48:49], v[48:49], v[250:251]
	v_lshlrev_b32_e32 v250, 16, v233
	v_and_b32_e32 v251, 0xffff0000, v233
	v_pk_add_f32 v[50:51], v[50:51], v[250:251]
.Lepi6_na12:
	v_cvt_pk_bf16_f32 v246, v52, v53
	v_cvt_pk_bf16_f32 v247, v54, v55
	v_cvt_pk_bf16_f32 v248, v48, v49
	v_cvt_pk_bf16_f32 v249, v50, v51
	global_store_dwordx4 v229, v[246:249], s[90:91]
	s_waitcnt vmcnt(11)
	v_lshlrev_b32_e32 v250, 16, v174
	v_and_b32_e32 v251, 0xffff0000, v174
	v_pk_mul_f32 v[20:21], v[20:21], v[250:251]
	v_lshlrev_b32_e32 v250, 16, v175
	v_and_b32_e32 v251, 0xffff0000, v175
	v_pk_mul_f32 v[22:23], v[22:23], v[250:251]
	v_lshlrev_b32_e32 v250, 16, v176
	v_and_b32_e32 v251, 0xffff0000, v176
	v_pk_mul_f32 v[16:17], v[16:17], v[250:251]
	v_lshlrev_b32_e32 v250, 16, v177
	v_and_b32_e32 v251, 0xffff0000, v177
	v_pk_mul_f32 v[18:19], v[18:19], v[250:251]
	s_cmp_eq_u32 s70, 0
	s_cbranch_scc1 .Lepi6_na13
	v_lshlrev_b32_e32 v250, 16, v234
	v_and_b32_e32 v251, 0xffff0000, v234
	v_pk_add_f32 v[20:21], v[20:21], v[250:251]
	v_lshlrev_b32_e32 v250, 16, v235
	v_and_b32_e32 v251, 0xffff0000, v235
	v_pk_add_f32 v[22:23], v[22:23], v[250:251]
	v_lshlrev_b32_e32 v250, 16, v236
	v_and_b32_e32 v251, 0xffff0000, v236
	v_pk_add_f32 v[16:17], v[16:17], v[250:251]
	v_lshlrev_b32_e32 v250, 16, v237
	v_and_b32_e32 v251, 0xffff0000, v237
	v_pk_add_f32 v[18:19], v[18:19], v[250:251]
.Lepi6_na13:
	v_cvt_pk_bf16_f32 v210, v20, v21
	v_cvt_pk_bf16_f32 v211, v22, v23
	v_cvt_pk_bf16_f32 v212, v16, v17
	v_cvt_pk_bf16_f32 v213, v18, v19
	global_store_dwordx4 v229, v[210:213], s[90:91] offset:256
	s_add_u32 s90, s90, s81
	s_addc_u32 s91, s91, 0
	s_waitcnt vmcnt(9)
	v_lshlrev_b32_e32 v250, 16, v186
	v_and_b32_e32 v251, 0xffff0000, v186
	v_pk_mul_f32 v[44:45], v[44:45], v[250:251]
	v_lshlrev_b32_e32 v250, 16, v187
	v_and_b32_e32 v251, 0xffff0000, v187
	v_pk_mul_f32 v[46:47], v[46:47], v[250:251]
	v_lshlrev_b32_e32 v250, 16, v188
	v_and_b32_e32 v251, 0xffff0000, v188
	v_pk_mul_f32 v[40:41], v[40:41], v[250:251]
	v_lshlrev_b32_e32 v250, 16, v189
	v_and_b32_e32 v251, 0xffff0000, v189
	v_pk_mul_f32 v[42:43], v[42:43], v[250:251]
	s_cmp_eq_u32 s70, 0
	s_cbranch_scc1 .Lepi6_na14
	v_lshlrev_b32_e32 v250, 16, v238
	v_and_b32_e32 v251, 0xffff0000, v238
	v_pk_add_f32 v[44:45], v[44:45], v[250:251]
	v_lshlrev_b32_e32 v250, 16, v239
	v_and_b32_e32 v251, 0xffff0000, v239
	v_pk_add_f32 v[46:47], v[46:47], v[250:251]
	v_lshlrev_b32_e32 v250, 16, v240
	v_and_b32_e32 v251, 0xffff0000, v240
	v_pk_add_f32 v[40:41], v[40:41], v[250:251]
	v_lshlrev_b32_e32 v250, 16, v241
	v_and_b32_e32 v251, 0xffff0000, v241
	v_pk_add_f32 v[42:43], v[42:43], v[250:251]
.Lepi6_na14:
	v_cvt_pk_bf16_f32 v246, v44, v45
	v_cvt_pk_bf16_f32 v247, v46, v47
	v_cvt_pk_bf16_f32 v248, v40, v41
	v_cvt_pk_bf16_f32 v249, v42, v43
	global_store_dwordx4 v229, v[246:249], s[90:91]
	s_waitcnt vmcnt(7)
	v_lshlrev_b32_e32 v250, 16, v190
	v_and_b32_e32 v251, 0xffff0000, v190
	v_pk_mul_f32 v[12:13], v[12:13], v[250:251]
	v_lshlrev_b32_e32 v250, 16, v191
	v_and_b32_e32 v251, 0xffff0000, v191
	v_pk_mul_f32 v[14:15], v[14:15], v[250:251]
	v_lshlrev_b32_e32 v250, 16, v192
	v_and_b32_e32 v251, 0xffff0000, v192
	v_pk_mul_f32 v[8:9], v[8:9], v[250:251]
	v_lshlrev_b32_e32 v250, 16, v193
	v_and_b32_e32 v251, 0xffff0000, v193
	v_pk_mul_f32 v[10:11], v[10:11], v[250:251]
	s_cmp_eq_u32 s70, 0
	s_cbranch_scc1 .Lepi6_na15
	v_lshlrev_b32_e32 v250, 16, v242
	v_and_b32_e32 v251, 0xffff0000, v242
	v_pk_add_f32 v[12:13], v[12:13], v[250:251]
	v_lshlrev_b32_e32 v250, 16, v243
	v_and_b32_e32 v251, 0xffff0000, v243
	v_pk_add_f32 v[14:15], v[14:15], v[250:251]
	v_lshlrev_b32_e32 v250, 16, v244
	v_and_b32_e32 v251, 0xffff0000, v244
	v_pk_add_f32 v[8:9], v[8:9], v[250:251]
	v_lshlrev_b32_e32 v250, 16, v245
	v_and_b32_e32 v251, 0xffff0000, v245
	v_pk_add_f32 v[10:11], v[10:11], v[250:251]
.Lepi6_na15:
	v_cvt_pk_bf16_f32 v210, v12, v13
	v_cvt_pk_bf16_f32 v211, v14, v15
	v_cvt_pk_bf16_f32 v212, v8, v9
	v_cvt_pk_bf16_f32 v213, v10, v11
	global_store_dwordx4 v229, v[210:213], s[90:91] offset:256
	s_branch .LBB0_422

; __device__ __forceinline__ void phase_rowwise(const void* xsrc_, bool sbf, void* xdst_, bool dbf, const bf16_t* Y, bf16_t* H, const float* mods, int lprev, int iprev, const float* lnpost, float resw, ...
;     ...
;     const int lane = tid_ & 63, wid = __builtin_amdgcn_readfirstlane(tid_ >> 6), gw = blockIdx.x * 8 + wid, NGW = gridDim.x * 8;
;     const float* xsrc = (const float*)xsrc_; const bf16_t* xsrcb = (const bf16_t*)xsrc_; float* xdst = (float*)xdst_; bf16_t* xdstb = (bf16_t*)xdst_;
;     for (int ch = gw; ch < M / 32; ch += NGW) {
;         const int b = ch >> 6;
;         f32x4 gp[4], na[4], ns[4];
; #pragma unroll
;         for (int j = 0; j < 4; ++j) { const int c = 4 * lane + 256 * j;
;             if (hasprev) { const f32x4 g = *(const f32x4*)(mods + ((size_t)lprev * 32 + b) * 9216 + iprev * 3072 + 2048 + c); const f32x4 lp = *(const f32x4*)(lnpost + c); gp[j] = g * lp * resw; }
;             else gp[j] = (f32x4){0.f, 0.f, 0.f, 0.f};
;             if (hasnext) { const f32x4 sh = *(const f32x4*)(mods + ((size_t)lnext * 32 + b) * 9216 + inext * 3072 + c); const f32x4 scl = *(const f32x4*)(mods + ((size_t)lnext * 32 + b) * 9216 + inext * 3072 + 1024 + c);
;                 const f32x4 lp = *(const f32x4*)(lnpre + c); na[j] = lp * (scl + 1.0f); ns[j] = sh; }
;             else { na[j] = (f32x4){0.f, 0.f, 0.f, 0.f}; ns[j] = na[j]; } }
;         f32x4 xn[2][4]; u32x2 xnb[2][4]; u32x2 yn[2][4];
;         { const size_t m0 = (size_t)ch * 32;
; #pragma unroll
;           for (int r = 0; r < 2; ++r)
; #pragma unroll
;             for (int j = 0; j < 4; ++j) { if (sbf) { xnb[r][j] = *(const u32x2*)(xsrcb + (m0 + r) * DM + 4 * lane + 256 * j); xn[r][j] = (f32x4){0.f, 0.f, 0.f, 0.f}; } else { xn[r][j] = *(const f32x4*)(xsrc + (m0 + r) * DM + 4 * lane + 256 * j); xnb[r][j] = (u32x2){0u, 0u}; }
;                 yn[r][j] = hasprev ? *(const u32x2*)(Y + (m0 + r) * DM + 4 * lane + 256 * j) : (u32x2){0u, 0u}; } }
.LBB0_866:
	v_readlane_b32 s72, v255, 2
	v_readlane_b32 s73, v255, 30
	v_readlane_b32 s74, v255, 34
	s_cmp_eq_u32 s72, 1
	s_cbranch_scc1 .Lrw_INIT
	s_cmp_eq_u32 s72, 4
	s_cbranch_scc1 .Lrw_FIRST
	s_cmp_eq_u32 s72, 53
	s_cbranch_scc1 .Lrw_LAST
	s_branch .Lrw_MID
.Lrw_MID:
	v_readfirstlane_b32 s40, v214
	v_readlane_b32 s41, v254, 46
	s_lshr_b32 s40, s40, 6
	s_add_i32 s40, s40, s41
	s_lshr_b32 s41, s40, 6
	v_and_b32_e32 v1, 63, v214
	v_lshlrev_b32_e32 v3, 5, v1
	v_lshlrev_b32_e32 v1, 4, v1
	v_mov_b32_e32 v212, 0x3a800000
	s_cmp_eq_u32 s74, 2
	s_cselect_b32 s42, 1, 0
	s_add_i32 s42, s73, s42
	s_add_i32 s43, s74, 1
	s_cmp_eq_u32 s74, 2
	s_cselect_b32 s43, 0, s43
	s_cmp_eq_u32 s74, 1
	s_cselect_b32 s90, 1.0, 0.5
	s_mov_b32 s91, s90
	v_readlane_b32 s44, v255, 22
	v_readlane_b32 s45, v255, 23
	s_lshl_b32 s46, s73, 5
	s_add_i32 s46, s46, s41
	s_mul_i32 s46, s46, 0x9000
	s_mul_i32 s47, s74, 0x3000
	s_add_i32 s46, s46, s47
	s_add_i32 s46, s46, 0x2000
	s_add_u32 s48, s44, s46
	s_addc_u32 s49, s45, 0
	v_readlane_b32 s52, v255, 16
	v_readlane_b32 s53, v255, 17
	s_mul_i32 s46, s73, 3
	s_add_i32 s46, s46, s74
	s_lshl_b32 s46, s46, 12
	s_add_u32 s52, s52, s46
	s_addc_u32 s53, s53, 0
	global_load_dwordx4 v[8:11], v3, s[48:49]
	global_load_dwordx4 v[12:15], v3, s[48:49] offset:16
	global_load_dwordx4 v[16:19], v3, s[48:49] offset:2048
	global_load_dwordx4 v[20:23], v3, s[48:49] offset:2064
	global_load_dwordx4 v[56:59], v3, s[52:53]
	global_load_dwordx4 v[60:63], v3, s[52:53] offset:16
	global_load_dwordx4 v[64:67], v3, s[52:53] offset:2048
	global_load_dwordx4 v[68:71], v3, s[52:53] offset:2064
	s_lshl_b32 s46, s42, 5
	s_add_i32 s46, s46, s41
	s_mul_i32 s46, s46, 0x9000
	s_mul_i32 s47, s43, 0x3000
	s_add_i32 s46, s46, s47
	s_add_u32 s50, s44, s46
	s_addc_u32 s51, s45, 0
	s_add_u32 s56, s50, 0x1000
	s_addc_u32 s57, s51, 0
	v_readlane_b32 s54, v255, 14
	v_readlane_b32 s55, v255, 15
	s_mul_i32 s46, s42, 3
	s_add_i32 s46, s46, s43
	s_lshl_b32 s46, s46, 12
	s_add_u32 s54, s54, s46
	s_addc_u32 s55, s55, 0
	global_load_dwordx4 v[24:27], v3, s[56:57]
	global_load_dwordx4 v[28:31], v3, s[56:57] offset:16
	global_load_dwordx4 v[32:35], v3, s[56:57] offset:2048
	global_load_dwordx4 v[36:39], v3, s[56:57] offset:2064
	global_load_dwordx4 v[72:75], v3, s[54:55]
	global_load_dwordx4 v[76:79], v3, s[54:55] offset:16
	global_load_dwordx4 v[80:83], v3, s[54:55] offset:2048
	global_load_dwordx4 v[84:87], v3, s[54:55] offset:2064
	global_load_dwordx4 v[40:43], v3, s[50:51]
	global_load_dwordx4 v[44:47], v3, s[50:51] offset:16
	global_load_dwordx4 v[48:51], v3, s[50:51] offset:2048
	global_load_dwordx4 v[52:55], v3, s[50:51] offset:2064
	s_lshl_b32 s46, s40, 16
	s_lshl_b32 s47, s40, 17
	v_readlane_b32 s72, v252, 6
	v_readlane_b32 s73, v252, 7
	s_add_u32 s72, s72, s46
	s_addc_u32 s73, s73, 0
	v_readlane_b32 s74, v252, 22
	v_readlane_b32 s75, v252, 23
	s_add_u32 s74, s74, s46
	s_addc_u32 s75, s75, 0
	v_readlane_b32 s76, v252, 6
	v_readlane_b32 s77, v252, 7
	s_add_u32 s76, s76, s46
	s_addc_u32 s77, s77, 0
	v_readlane_b32 s58, v252, 26
	v_readlane_b32 s59, v252, 27
	v_readlane_b32 s83, v255, 2
	s_add_u32 s58, s58, s46
	s_addc_u32 s59, s59, 0
	s_cmp_eq_u32 s83, 50
	s_cselect_b32 s76, s58, s76
	s_cselect_b32 s77, s59, s77
	v_readlane_b32 s78, v252, 20
	v_readlane_b32 s79, v252, 21
	s_add_u32 s78, s78, s46
	s_addc_u32 s79, s79, 0
	s_and_b32 s80, s40, 15
	s_lshl_b32 s80, s80, 1
	s_waitcnt vmcnt(12)
	v_pk_mul_f32 v[8:9], v[8:9], v[56:57]
	v_pk_mul_f32 v[10:11], v[10:11], v[58:59]
	v_pk_mul_f32 v[12:13], v[12:13], v[60:61]
	v_pk_mul_f32 v[14:15], v[14:15], v[62:63]
	v_pk_mul_f32 v[16:17], v[16:17], v[64:65]
	v_pk_mul_f32 v[18:19], v[18:19], v[66:67]
	v_pk_mul_f32 v[20:21], v[20:21], v[68:69]
	v_pk_mul_f32 v[22:23], v[22:23], v[70:71]
	v_pk_mul_f32 v[8:9], v[8:9], s[90:91]
	v_pk_mul_f32 v[10:11], v[10:11], s[90:91]
	v_pk_mul_f32 v[12:13], v[12:13], s[90:91]
	v_pk_mul_f32 v[14:15], v[14:15], s[90:91]
	v_pk_mul_f32 v[16:17], v[16:17], s[90:91]
	v_pk_mul_f32 v[18:19], v[18:19], s[90:91]
	v_pk_mul_f32 v[20:21], v[20:21], s[90:91]
	v_pk_mul_f32 v[22:23], v[22:23], s[90:91]
	s_waitcnt vmcnt(4)
	v_pk_add_f32 v[24:25], v[24:25], 1.0 op_sel_hi:[1,0]
	v_pk_add_f32 v[26:27], v[26:27], 1.0 op_sel_hi:[1,0]
	v_pk_add_f32 v[28:29], v[28:29], 1.0 op_sel_hi:[1,0]
	v_pk_add_f32 v[30:31], v[30:31], 1.0 op_sel_hi:[1,0]
	v_pk_add_f32 v[32:33], v[32:33], 1.0 op_sel_hi:[1,0]
	v_pk_add_f32 v[34:35], v[34:35], 1.0 op_sel_hi:[1,0]
	v_pk_add_f32 v[36:37], v[36:37], 1.0 op_sel_hi:[1,0]
	v_pk_add_f32 v[38:39], v[38:39], 1.0 op_sel_hi:[1,0]
	v_pk_mul_f32 v[24:25], v[72:73], v[24:25]
	v_pk_mul_f32 v[26:27], v[74:75], v[26:27]
	v_pk_mul_f32 v[28:29], v[76:77], v[28:29]
	v_pk_mul_f32 v[30:31], v[78:79], v[30:31]
	v_pk_mul_f32 v[32:33], v[80:81], v[32:33]
	v_pk_mul_f32 v[34:35], v[82:83], v[34:35]
	v_pk_mul_f32 v[36:37], v[84:85], v[36:37]
	v_pk_mul_f32 v[38:39], v[86:87], v[38:39]
	s_waitcnt vmcnt(0)
; __device__ __forceinline__ float bflo(unsigned u) { return __uint_as_float(u << 16); }
; __device__ __forceinline__ void phase_rowwise(const void* xsrc_, bool sbf, void* xdst_, bool dbf, const bf16_t* Y, bf16_t* H, const float* mods, int lprev, int iprev, const float* lnpost, float resw, ...
;     ...
;         for (int rr = 0; rr < 32; rr += 2) {
;             const size_t m = (size_t)ch * 32 + rr;
;             f32x4 x[2][4]; u32x2 yr[2][4];
; #pragma unroll
;             for (int r = 0; r < 2; ++r)
; #pragma unroll
;                 for (int j = 0; j < 4; ++j) { if (sbf) { const u32x2 u = xnb[r][j]; x[r][j] = (f32x4){bflo(u.x), bfhi(u.x), bflo(u.y), bfhi(u.y)}; } else x[r][j] = xn[r][j]; yr[r][j] = yn[r][j]; }
;             if (rr + 2 < 32) {
; #pragma unroll
;                 for (int r = 0; r < 2; ++r)
; #pragma unroll
;                     for (int j = 0; j < 4; ++j) { if (sbf) xnb[r][j] = *(const u32x2*)(xsrcb + (m + 2 + r) * DM + 4 * lane + 256 * j); else xn[r][j] = *(const f32x4*)(xsrc + (m + 2 + r) * DM + 4 * lane + 256 * j); if (hasprev) yn[r][j] = *(const u32x2*)(Y + (m + 2 + r) * DM + 4 * lane + 256 * j); } }
;             if (hasprev) {
;                 f32x4 y[2][4]; float ss[2] = {0.f, 0.f};
; #pragma unroll
;                 for (int r = 0; r < 2; ++r)
; #pragma unroll
;                     for (int j = 0; j < 4; ++j) { const u32x2 u = yr[r][j]; y[r][j] = (f32x4){bflo(u.x), bfhi(u.x), bflo(u.y), bfhi(u.y)};
;                         ss[r] += (y[r][j].x * y[r][j].x + y[r][j].y * y[r][j].y) + (y[r][j].z * y[r][j].z + y[r][j].w * y[r][j].w); }
; #pragma unroll
;                 for (int off = 1; off < 64; off <<= 1) { ss[0] += __shfl_xor(ss[0], off); ss[1] += __shfl_xor(ss[1], off); }
; #pragma unroll
;                 for (int r = 0; r < 2; ++r) { const float rs = __builtin_amdgcn_rsqf(ss[r] * (1.f / DM) + EPS);
; #pragma unroll
;                     for (int j = 0; j < 4; ++j) x[r][j] = x[r][j] + gp[j] * (y[r][j] * rs); }
;             }
; #pragma unroll
;             for (int r = 0; r < 2; ++r)
; #pragma unroll
;                 for (int j = 0; j < 4; ++j) { if (hasprev) { if (dbf) { u32x2 w; w.x = cvtpk(x[r][j].x, x[r][j].y); w.y = cvtpk(x[r][j].z, x[r][j].w); *(u32x2*)(xdstb + (m + r) * DM + 4 * lane + 256 * j) = w; } else *(f32x4*)(xdst + (m + r) * DM + 4 * lane + 256 * j) = x[r][j]; } }
	s_mov_b32 s82, 0
	s_add_i32 s81, s80, 0
	s_add_i32 s81, s81, s82
	s_and_b32 s81, s81, 31
	s_lshl_b32 s83, s81, 11
	v_add_u32_e32 v2, s83, v1
	global_load_dwordx4 v[56:59], v2, s[72:73]
	global_load_dwordx4 v[60:63], v2, s[72:73] offset:1024
	global_load_dwordx4 v[64:67], v2, s[74:75]
	global_load_dwordx4 v[68:71], v2, s[74:75] offset:1024
	s_add_i32 s81, s80, 1
	s_add_i32 s81, s81, s82
	s_and_b32 s81, s81, 31
	s_lshl_b32 s83, s81, 11
	v_add_u32_e32 v2, s83, v1
	global_load_dwordx4 v[72:75], v2, s[72:73]
	global_load_dwordx4 v[76:79], v2, s[72:73] offset:1024
	global_load_dwordx4 v[80:83], v2, s[74:75]
	global_load_dwordx4 v[84:87], v2, s[74:75] offset:1024
	s_add_i32 s81, s80, 2
	s_add_i32 s81, s81, s82
	s_and_b32 s81, s81, 31
	s_lshl_b32 s83, s81, 11
	v_add_u32_e32 v2, s83, v1
	global_load_dwordx4 v[88:91], v2, s[72:73]
	global_load_dwordx4 v[92:95], v2, s[72:73] offset:1024
	global_load_dwordx4 v[96:99], v2, s[74:75]
	global_load_dwordx4 v[100:103], v2, s[74:75] offset:1024
	s_add_i32 s81, s80, 3
	s_add_i32 s81, s81, s82
	s_and_b32 s81, s81, 31
	s_lshl_b32 s83, s81, 11
	v_add_u32_e32 v2, s83, v1
	global_load_dwordx4 v[104:107], v2, s[72:73]
	global_load_dwordx4 v[108:111], v2, s[72:73] offset:1024
	global_load_dwordx4 v[112:115], v2, s[74:75]
	global_load_dwordx4 v[116:119], v2, s[74:75] offset:1024
	s_add_i32 s81, s80, 4
	s_add_i32 s81, s81, s82
	s_and_b32 s81, s81, 31
	s_lshl_b32 s83, s81, 11
	v_add_u32_e32 v2, s83, v1
	global_load_dwordx4 v[120:123], v2, s[72:73]
	global_load_dwordx4 v[124:127], v2, s[72:73] offset:1024
	global_load_dwordx4 v[128:131], v2, s[74:75]
	global_load_dwordx4 v[132:135], v2, s[74:75] offset:1024
	s_waitcnt vmcnt(16)
	v_lshlrev_b32_e32 v200, 16, v64
	v_and_b32_e32 v201, 0xffff0000, v64
	v_pk_mul_f32 v[204:205], v[200:201], v[200:201]
	v_lshlrev_b32_e32 v202, 16, v65
	v_and_b32_e32 v203, 0xffff0000, v65
	v_pk_mul_f32 v[206:207], v[202:203], v[202:203]
	v_lshlrev_b32_e32 v200, 16, v66
	v_and_b32_e32 v201, 0xffff0000, v66
	v_pk_fma_f32 v[204:205], v[200:201], v[200:201], v[204:205]
	v_lshlrev_b32_e32 v202, 16, v67
	v_and_b32_e32 v203, 0xffff0000, v67
	v_pk_fma_f32 v[206:207], v[202:203], v[202:203], v[206:207]
	v_lshlrev_b32_e32 v200, 16, v68
	v_and_b32_e32 v201, 0xffff0000, v68
	v_pk_fma_f32 v[204:205], v[200:201], v[200:201], v[204:205]
	v_lshlrev_b32_e32 v202, 16, v69
	v_and_b32_e32 v203, 0xffff0000, v69
	v_pk_fma_f32 v[206:207], v[202:203], v[202:203], v[206:207]
	v_lshlrev_b32_e32 v200, 16, v70
	v_and_b32_e32 v201, 0xffff0000, v70
	v_pk_fma_f32 v[204:205], v[200:201], v[200:201], v[204:205]
	v_lshlrev_b32_e32 v202, 16, v71
	v_and_b32_e32 v203, 0xffff0000, v71
	v_pk_fma_f32 v[206:207], v[202:203], v[202:203], v[206:207]
	v_pk_add_f32 v[204:205], v[204:205], v[206:207]
	v_add_f32_e32 v208, v204, v205
	v_lshlrev_b32_e32 v184, 16, v56
	v_and_b32_e32 v185, 0xffff0000, v56
	v_add_f32_dpp v208, v208, v208 quad_perm:[1,0,3,2] row_mask:0xf bank_mask:0xf
	v_lshlrev_b32_e32 v186, 16, v57
	v_and_b32_e32 v187, 0xffff0000, v57
	v_add_f32_dpp v208, v208, v208 quad_perm:[2,3,0,1] row_mask:0xf bank_mask:0xf
	v_lshlrev_b32_e32 v188, 16, v58
	v_and_b32_e32 v189, 0xffff0000, v58
	v_add_f32_dpp v208, v208, v208 row_half_mirror row_mask:0xf bank_mask:0xf
	v_lshlrev_b32_e32 v190, 16, v59
	v_and_b32_e32 v191, 0xffff0000, v59
	v_add_f32_dpp v208, v208, v208 row_mirror row_mask:0xf bank_mask:0xf
	v_lshlrev_b32_e32 v192, 16, v60
	v_and_b32_e32 v193, 0xffff0000, v60
	v_add_f32_dpp v208, v208, v208 row_bcast:15 row_mask:0xa bank_mask:0xf
	v_lshlrev_b32_e32 v194, 16, v61
	v_and_b32_e32 v195, 0xffff0000, v61
	v_add_f32_dpp v208, v208, v208 row_bcast:31 row_mask:0xc bank_mask:0xf
	v_lshlrev_b32_e32 v196, 16, v62
	v_and_b32_e32 v197, 0xffff0000, v62
	v_readlane_b32 s60, v208, 63
	s_nop 1
	v_lshlrev_b32_e32 v198, 16, v63
	v_and_b32_e32 v199, 0xffff0000, v63
	v_mov_b32_e32 v210, s60
	v_fmaak_f32 v210, v210, v212, 0x358637bd
	v_rsq_f32_e32 v210, v210
	s_nop 0
	v_lshlrev_b32_e32 v200, 16, v64
	v_and_b32_e32 v201, 0xffff0000, v64
	v_pk_mul_f32 v[200:201], v[200:201], v[210:211] op_sel_hi:[1,0]
	v_pk_fma_f32 v[184:185], v[8:9], v[200:201], v[184:185]
	v_lshlrev_b32_e32 v202, 16, v65
	v_and_b32_e32 v203, 0xffff0000, v65
	v_pk_mul_f32 v[202:203], v[202:203], v[210:211] op_sel_hi:[1,0]
	v_pk_fma_f32 v[186:187], v[10:11], v[202:203], v[186:187]
	v_lshlrev_b32_e32 v200, 16, v66
	v_and_b32_e32 v201, 0xffff0000, v66
	v_pk_mul_f32 v[200:201], v[200:201], v[210:211] op_sel_hi:[1,0]
	v_pk_fma_f32 v[188:189], v[12:13], v[200:201], v[188:189]
	v_lshlrev_b32_e32 v202, 16, v67
	v_and_b32_e32 v203, 0xffff0000, v67
	v_pk_mul_f32 v[202:203], v[202:203], v[210:211] op_sel_hi:[1,0]
	v_pk_fma_f32 v[190:191], v[14:15], v[202:203], v[190:191]
	v_lshlrev_b32_e32 v200, 16, v68
	v_and_b32_e32 v201, 0xffff0000, v68
	v_pk_mul_f32 v[200:201], v[200:201], v[210:211] op_sel_hi:[1,0]
	v_pk_fma_f32 v[192:193], v[16:17], v[200:201], v[192:193]
	v_lshlrev_b32_e32 v202, 16, v69
	v_and_b32_e32 v203, 0xffff0000, v69
	v_pk_mul_f32 v[202:203], v[202:203], v[210:211] op_sel_hi:[1,0]
	v_pk_fma_f32 v[194:195], v[18:19], v[202:203], v[194:195]
	v_lshlrev_b32_e32 v200, 16, v70
	v_and_b32_e32 v201, 0xffff0000, v70
	v_pk_mul_f32 v[200:201], v[200:201], v[210:211] op_sel_hi:[1,0]
	v_pk_fma_f32 v[196:197], v[20:21], v[200:201], v[196:197]
	v_lshlrev_b32_e32 v202, 16, v71
	v_and_b32_e32 v203, 0xffff0000, v71
	v_pk_mul_f32 v[202:203], v[202:203], v[210:211] op_sel_hi:[1,0]
	v_pk_fma_f32 v[198:199], v[22:23], v[202:203], v[198:199]
	s_add_i32 s81, s80, 0
	s_add_i32 s81, s81, s82
	s_and_b32 s81, s81, 31
	s_lshl_b32 s83, s81, 11
	v_add_u32_e32 v2, s83, v1
	v_cvt_pk_bf16_f32 v64, v184, v185
; __device__ __forceinline__ unsigned cvtpk(float lo, float hi) { f32x2 v = {lo, hi}; bf16x2_t b = __builtin_convertvector(v, bf16x2_t); return __builtin_bit_cast(unsigned, b); }
; __device__ __forceinline__ void phase_rowwise(const void* xsrc_, bool sbf, void* xdst_, bool dbf, const bf16_t* Y, bf16_t* H, const float* mods, int lprev, int iprev, const float* lnpost, float resw, ...
;     ...
; #pragma unroll
;             for (int r = 0; r < 2; ++r)
; #pragma unroll
;                 for (int j = 0; j < 4; ++j) { if (hasprev) { if (dbf) { u32x2 w; w.x = cvtpk(x[r][j].x, x[r][j].y); w.y = cvtpk(x[r][j].z, x[r][j].w); *(u32x2*)(xdstb + (m + r) * DM + 4 * lane + 256 * j) = w; } else *(f32x4*)(xdst + (m + r) * DM + 4 * lane + 256 * j) = x[r][j]; } }
;             if (hasnext) {
;                 float ss[2] = {0.f, 0.f};
; #pragma unroll
;                 for (int r = 0; r < 2; ++r)
; #pragma unroll
;                     for (int j = 0; j < 4; ++j) ss[r] += (x[r][j].x * x[r][j].x + x[r][j].y * x[r][j].y) + (x[r][j].z * x[r][j].z + x[r][j].w * x[r][j].w);
; #pragma unroll
;                 for (int off = 1; off < 64; off <<= 1) { ss[0] += __shfl_xor(ss[0], off); ss[1] += __shfl_xor(ss[1], off); }
; #pragma unroll
;                 for (int r = 0; r < 2; ++r) { const float rs = __builtin_amdgcn_rsqf(ss[r] * (1.f / DM) + EPS);
; #pragma unroll
;                     for (int j = 0; j < 4; ++j) { const f32x4 h = (x[r][j] * rs) * na[j] + ns[j]; u32x2 w; w.x = cvtpk(h.x, h.y); w.y = cvtpk(h.z, h.w); *(u32x2*)(H + (m + r) * DM + 4 * lane + 256 * j) = w; } }
	v_cvt_pk_bf16_f32 v65, v186, v187
	v_cvt_pk_bf16_f32 v66, v188, v189
	v_cvt_pk_bf16_f32 v67, v190, v191
	v_cvt_pk_bf16_f32 v68, v192, v193
	v_cvt_pk_bf16_f32 v69, v194, v195
	v_cvt_pk_bf16_f32 v70, v196, v197
	v_cvt_pk_bf16_f32 v71, v198, v199
	global_store_dwordx4 v2, v[64:67], s[76:77]
	global_store_dwordx4 v2, v[68:71], s[76:77] offset:1024
	v_pk_mul_f32 v[204:205], v[184:185], v[184:185]
	v_pk_mul_f32 v[206:207], v[186:187], v[186:187]
	v_pk_fma_f32 v[204:205], v[188:189], v[188:189], v[204:205]
	v_pk_fma_f32 v[206:207], v[190:191], v[190:191], v[206:207]
	v_pk_fma_f32 v[204:205], v[192:193], v[192:193], v[204:205]
	v_pk_fma_f32 v[206:207], v[194:195], v[194:195], v[206:207]
	v_pk_fma_f32 v[204:205], v[196:197], v[196:197], v[204:205]
	v_pk_fma_f32 v[206:207], v[198:199], v[198:199], v[206:207]
	v_pk_add_f32 v[204:205], v[204:205], v[206:207]
	v_add_f32_e32 v208, v204, v205
	s_nop 0
	s_nop 0
	v_add_f32_dpp v208, v208, v208 quad_perm:[1,0,3,2] row_mask:0xf bank_mask:0xf
	s_nop 0
	s_nop 0
	v_add_f32_dpp v208, v208, v208 quad_perm:[2,3,0,1] row_mask:0xf bank_mask:0xf
	s_nop 0
	s_nop 0
	v_add_f32_dpp v208, v208, v208 row_half_mirror row_mask:0xf bank_mask:0xf
	s_nop 0
	s_nop 0
	v_add_f32_dpp v208, v208, v208 row_mirror row_mask:0xf bank_mask:0xf
	s_nop 0
	s_nop 0
	v_add_f32_dpp v208, v208, v208 row_bcast:15 row_mask:0xa bank_mask:0xf
	s_nop 0
	s_nop 0
	v_add_f32_dpp v208, v208, v208 row_bcast:31 row_mask:0xc bank_mask:0xf
	s_nop 0
	s_nop 0
	v_readlane_b32 s60, v208, 63
	s_nop 1
	v_mov_b32_e32 v210, s60
	v_fmaak_f32 v210, v210, v212, 0x358637bd
	v_rsq_f32_e32 v210, v210
	s_nop 0
	v_pk_mul_f32 v[200:201], v[184:185], v[210:211] op_sel_hi:[1,0]
	v_pk_fma_f32 v[200:201], v[200:201], v[24:25], v[40:41]
	v_cvt_pk_bf16_f32 v56, v200, v201
	v_pk_mul_f32 v[202:203], v[186:187], v[210:211] op_sel_hi:[1,0]
	v_pk_fma_f32 v[202:203], v[202:203], v[26:27], v[42:43]
	v_cvt_pk_bf16_f32 v57, v202, v203
	v_pk_mul_f32 v[200:201], v[188:189], v[210:211] op_sel_hi:[1,0]
	v_pk_fma_f32 v[200:201], v[200:201], v[28:29], v[44:45]
	v_cvt_pk_bf16_f32 v58, v200, v201
	v_pk_mul_f32 v[202:203], v[190:191], v[210:211] op_sel_hi:[1,0]
	v_pk_fma_f32 v[202:203], v[202:203], v[30:31], v[46:47]
	v_cvt_pk_bf16_f32 v59, v202, v203
	v_pk_mul_f32 v[200:201], v[192:193], v[210:211] op_sel_hi:[1,0]
	v_pk_fma_f32 v[200:201], v[200:201], v[32:33], v[48:49]
	v_cvt_pk_bf16_f32 v60, v200, v201
	v_pk_mul_f32 v[202:203], v[194:195], v[210:211] op_sel_hi:[1,0]
	v_pk_fma_f32 v[202:203], v[202:203], v[34:35], v[50:51]
	v_cvt_pk_bf16_f32 v61, v202, v203
	v_pk_mul_f32 v[200:201], v[196:197], v[210:211] op_sel_hi:[1,0]
	v_pk_fma_f32 v[200:201], v[200:201], v[36:37], v[52:53]
	v_cvt_pk_bf16_f32 v62, v200, v201
	v_pk_mul_f32 v[202:203], v[198:199], v[210:211] op_sel_hi:[1,0]
	v_pk_fma_f32 v[202:203], v[202:203], v[38:39], v[54:55]
	v_cvt_pk_bf16_f32 v63, v202, v203
	global_store_dwordx4 v2, v[56:59], s[78:79]
	global_store_dwordx4 v2, v[60:63], s[78:79] offset:1024
	s_add_i32 s81, s80, 5
	s_add_i32 s81, s81, s82
	s_and_b32 s81, s81, 31
	s_lshl_b32 s83, s81, 11
	v_add_u32_e32 v2, s83, v1
	global_load_dwordx4 v[136:139], v2, s[72:73]
	global_load_dwordx4 v[140:143], v2, s[72:73] offset:1024
	global_load_dwordx4 v[144:147], v2, s[74:75]
	global_load_dwordx4 v[148:151], v2, s[74:75] offset:1024
	s_waitcnt vmcnt(20)
	v_lshlrev_b32_e32 v200, 16, v80
	v_and_b32_e32 v201, 0xffff0000, v80
	v_pk_mul_f32 v[204:205], v[200:201], v[200:201]
	v_lshlrev_b32_e32 v202, 16, v81
	v_and_b32_e32 v203, 0xffff0000, v81
	v_pk_mul_f32 v[206:207], v[202:203], v[202:203]
	v_lshlrev_b32_e32 v200, 16, v82
	v_and_b32_e32 v201, 0xffff0000, v82
	v_pk_fma_f32 v[204:205], v[200:201], v[200:201], v[204:205]
	v_lshlrev_b32_e32 v202, 16, v83
	v_and_b32_e32 v203, 0xffff0000, v83
	v_pk_fma_f32 v[206:207], v[202:203], v[202:203], v[206:207]
	v_lshlrev_b32_e32 v200, 16, v84
	v_and_b32_e32 v201, 0xffff0000, v84
	v_pk_fma_f32 v[204:205], v[200:201], v[200:201], v[204:205]
	v_lshlrev_b32_e32 v202, 16, v85
	v_and_b32_e32 v203, 0xffff0000, v85
	v_pk_fma_f32 v[206:207], v[202:203], v[202:203], v[206:207]
	v_lshlrev_b32_e32 v200, 16, v86
	v_and_b32_e32 v201, 0xffff0000, v86
	v_pk_fma_f32 v[204:205], v[200:201], v[200:201], v[204:205]
	v_lshlrev_b32_e32 v202, 16, v87
	v_and_b32_e32 v203, 0xffff0000, v87
	v_pk_fma_f32 v[206:207], v[202:203], v[202:203], v[206:207]
	v_pk_add_f32 v[204:205], v[204:205], v[206:207]
	v_add_f32_e32 v208, v204, v205
	v_lshlrev_b32_e32 v184, 16, v72
	v_and_b32_e32 v185, 0xffff0000, v72
	v_add_f32_dpp v208, v208, v208 quad_perm:[1,0,3,2] row_mask:0xf bank_mask:0xf
	v_lshlrev_b32_e32 v186, 16, v73
	v_and_b32_e32 v187, 0xffff0000, v73
	v_add_f32_dpp v208, v208, v208 quad_perm:[2,3,0,1] row_mask:0xf bank_mask:0xf
	v_lshlrev_b32_e32 v188, 16, v74
	v_and_b32_e32 v189, 0xffff0000, v74
	v_add_f32_dpp v208, v208, v208 row_half_mirror row_mask:0xf bank_mask:0xf
	v_lshlrev_b32_e32 v190, 16, v75
	v_and_b32_e32 v191, 0xffff0000, v75
	v_add_f32_dpp v208, v208, v208 row_mirror row_mask:0xf bank_mask:0xf
	v_lshlrev_b32_e32 v192, 16, v76
	v_and_b32_e32 v193, 0xffff0000, v76
	v_add_f32_dpp v208, v208, v208 row_bcast:15 row_mask:0xa bank_mask:0xf
	v_lshlrev_b32_e32 v194, 16, v77
	v_and_b32_e32 v195, 0xffff0000, v77
	v_add_f32_dpp v208, v208, v208 row_bcast:31 row_mask:0xc bank_mask:0xf
	v_lshlrev_b32_e32 v196, 16, v78
	v_and_b32_e32 v197, 0xffff0000, v78
	v_readlane_b32 s60, v208, 63
	s_nop 1
	v_lshlrev_b32_e32 v198, 16, v79
	v_and_b32_e32 v199, 0xffff0000, v79
	v_mov_b32_e32 v210, s60
	v_fmaak_f32 v210, v210, v212, 0x358637bd
	v_rsq_f32_e32 v210, v210
	s_nop 0
	v_lshlrev_b32_e32 v200, 16, v80
	v_and_b32_e32 v201, 0xffff0000, v80
; __device__ __forceinline__ unsigned cvtpk(float lo, float hi) { f32x2 v = {lo, hi}; bf16x2_t b = __builtin_convertvector(v, bf16x2_t); return __builtin_bit_cast(unsigned, b); }
; __device__ __forceinline__ void phase_rowwise(const void* xsrc_, bool sbf, void* xdst_, bool dbf, const bf16_t* Y, bf16_t* H, const float* mods, int lprev, int iprev, const float* lnpost, float resw, ...
;     ...
;                     for (int j = 0; j < 4; ++j) x[r][j] = x[r][j] + gp[j] * (y[r][j] * rs); }
;             }
; #pragma unroll
;             for (int r = 0; r < 2; ++r)
; #pragma unroll
;                 for (int j = 0; j < 4; ++j) { if (hasprev) { if (dbf) { u32x2 w; w.x = cvtpk(x[r][j].x, x[r][j].y); w.y = cvtpk(x[r][j].z, x[r][j].w); *(u32x2*)(xdstb + (m + r) * DM + 4 * lane + 256 * j) = w; } else *(f32x4*)(xdst + (m + r) * DM + 4 * lane + 256 * j) = x[r][j]; } }
;             if (hasnext) {
;                 float ss[2] = {0.f, 0.f};
; #pragma unroll
;                 for (int r = 0; r < 2; ++r)
; #pragma unroll
;                     for (int j = 0; j < 4; ++j) ss[r] += (x[r][j].x * x[r][j].x + x[r][j].y * x[r][j].y) + (x[r][j].z * x[r][j].z + x[r][j].w * x[r][j].w);
; #pragma unroll
;                 for (int off = 1; off < 64; off <<= 1) { ss[0] += __shfl_xor(ss[0], off); ss[1] += __shfl_xor(ss[1], off); }
; #pragma unroll
;                 for (int r = 0; r < 2; ++r) { const float rs = __builtin_amdgcn_rsqf(ss[r] * (1.f / DM) + EPS);
; #pragma unroll
;                     for (int j = 0; j < 4; ++j) { const f32x4 h = (x[r][j] * rs) * na[j] + ns[j]; u32x2 w; w.x = cvtpk(h.x, h.y); w.y = cvtpk(h.z, h.w); *(u32x2*)(H + (m + r) * DM + 4 * lane + 256 * j) = w; } }
	v_pk_mul_f32 v[200:201], v[200:201], v[210:211] op_sel_hi:[1,0]
	v_pk_fma_f32 v[184:185], v[8:9], v[200:201], v[184:185]
	v_lshlrev_b32_e32 v202, 16, v81
	v_and_b32_e32 v203, 0xffff0000, v81
	v_pk_mul_f32 v[202:203], v[202:203], v[210:211] op_sel_hi:[1,0]
	v_pk_fma_f32 v[186:187], v[10:11], v[202:203], v[186:187]
	v_lshlrev_b32_e32 v200, 16, v82
	v_and_b32_e32 v201, 0xffff0000, v82
	v_pk_mul_f32 v[200:201], v[200:201], v[210:211] op_sel_hi:[1,0]
	v_pk_fma_f32 v[188:189], v[12:13], v[200:201], v[188:189]
	v_lshlrev_b32_e32 v202, 16, v83
	v_and_b32_e32 v203, 0xffff0000, v83
	v_pk_mul_f32 v[202:203], v[202:203], v[210:211] op_sel_hi:[1,0]
	v_pk_fma_f32 v[190:191], v[14:15], v[202:203], v[190:191]
	v_lshlrev_b32_e32 v200, 16, v84
	v_and_b32_e32 v201, 0xffff0000, v84
	v_pk_mul_f32 v[200:201], v[200:201], v[210:211] op_sel_hi:[1,0]
	v_pk_fma_f32 v[192:193], v[16:17], v[200:201], v[192:193]
	v_lshlrev_b32_e32 v202, 16, v85
	v_and_b32_e32 v203, 0xffff0000, v85
	v_pk_mul_f32 v[202:203], v[202:203], v[210:211] op_sel_hi:[1,0]
	v_pk_fma_f32 v[194:195], v[18:19], v[202:203], v[194:195]
	v_lshlrev_b32_e32 v200, 16, v86
	v_and_b32_e32 v201, 0xffff0000, v86
	v_pk_mul_f32 v[200:201], v[200:201], v[210:211] op_sel_hi:[1,0]
	v_pk_fma_f32 v[196:197], v[20:21], v[200:201], v[196:197]
	v_lshlrev_b32_e32 v202, 16, v87
	v_and_b32_e32 v203, 0xffff0000, v87
	v_pk_mul_f32 v[202:203], v[202:203], v[210:211] op_sel_hi:[1,0]
	v_pk_fma_f32 v[198:199], v[22:23], v[202:203], v[198:199]
	s_add_i32 s81, s80, 1
	s_add_i32 s81, s81, s82
	s_and_b32 s81, s81, 31
	s_lshl_b32 s83, s81, 11
	v_add_u32_e32 v2, s83, v1
	v_cvt_pk_bf16_f32 v80, v184, v185
	v_cvt_pk_bf16_f32 v81, v186, v187
	v_cvt_pk_bf16_f32 v82, v188, v189
	v_cvt_pk_bf16_f32 v83, v190, v191
	v_cvt_pk_bf16_f32 v84, v192, v193
	v_cvt_pk_bf16_f32 v85, v194, v195
	v_cvt_pk_bf16_f32 v86, v196, v197
	v_cvt_pk_bf16_f32 v87, v198, v199
	global_store_dwordx4 v2, v[80:83], s[76:77]
	global_store_dwordx4 v2, v[84:87], s[76:77] offset:1024
	v_pk_mul_f32 v[204:205], v[184:185], v[184:185]
	v_pk_mul_f32 v[206:207], v[186:187], v[186:187]
	v_pk_fma_f32 v[204:205], v[188:189], v[188:189], v[204:205]
	v_pk_fma_f32 v[206:207], v[190:191], v[190:191], v[206:207]
	v_pk_fma_f32 v[204:205], v[192:193], v[192:193], v[204:205]
	v_pk_fma_f32 v[206:207], v[194:195], v[194:195], v[206:207]
	v_pk_fma_f32 v[204:205], v[196:197], v[196:197], v[204:205]
	v_pk_fma_f32 v[206:207], v[198:199], v[198:199], v[206:207]
	v_pk_add_f32 v[204:205], v[204:205], v[206:207]
	v_add_f32_e32 v208, v204, v205
	s_nop 0
	s_nop 0
	v_add_f32_dpp v208, v208, v208 quad_perm:[1,0,3,2] row_mask:0xf bank_mask:0xf
	s_nop 0
	s_nop 0
	v_add_f32_dpp v208, v208, v208 quad_perm:[2,3,0,1] row_mask:0xf bank_mask:0xf
	s_nop 0
	s_nop 0
	v_add_f32_dpp v208, v208, v208 row_half_mirror row_mask:0xf bank_mask:0xf
	s_nop 0
	s_nop 0
	v_add_f32_dpp v208, v208, v208 row_mirror row_mask:0xf bank_mask:0xf
	s_nop 0
	s_nop 0
	v_add_f32_dpp v208, v208, v208 row_bcast:15 row_mask:0xa bank_mask:0xf
	s_nop 0
	s_nop 0
	v_add_f32_dpp v208, v208, v208 row_bcast:31 row_mask:0xc bank_mask:0xf
	s_nop 0
	s_nop 0
	v_readlane_b32 s60, v208, 63
	s_nop 1
	v_mov_b32_e32 v210, s60
	v_fmaak_f32 v210, v210, v212, 0x358637bd
	v_rsq_f32_e32 v210, v210
	s_nop 0
	v_pk_mul_f32 v[200:201], v[184:185], v[210:211] op_sel_hi:[1,0]
	v_pk_fma_f32 v[200:201], v[200:201], v[24:25], v[40:41]
	v_cvt_pk_bf16_f32 v72, v200, v201
	v_pk_mul_f32 v[202:203], v[186:187], v[210:211] op_sel_hi:[1,0]
	v_pk_fma_f32 v[202:203], v[202:203], v[26:27], v[42:43]
	v_cvt_pk_bf16_f32 v73, v202, v203
	v_pk_mul_f32 v[200:201], v[188:189], v[210:211] op_sel_hi:[1,0]
	v_pk_fma_f32 v[200:201], v[200:201], v[28:29], v[44:45]
	v_cvt_pk_bf16_f32 v74, v200, v201
	v_pk_mul_f32 v[202:203], v[190:191], v[210:211] op_sel_hi:[1,0]
	v_pk_fma_f32 v[202:203], v[202:203], v[30:31], v[46:47]
	v_cvt_pk_bf16_f32 v75, v202, v203
	v_pk_mul_f32 v[200:201], v[192:193], v[210:211] op_sel_hi:[1,0]
	v_pk_fma_f32 v[200:201], v[200:201], v[32:33], v[48:49]
	v_cvt_pk_bf16_f32 v76, v200, v201
	v_pk_mul_f32 v[202:203], v[194:195], v[210:211] op_sel_hi:[1,0]
	v_pk_fma_f32 v[202:203], v[202:203], v[34:35], v[50:51]
	v_cvt_pk_bf16_f32 v77, v202, v203
	v_pk_mul_f32 v[200:201], v[196:197], v[210:211] op_sel_hi:[1,0]
	v_pk_fma_f32 v[200:201], v[200:201], v[36:37], v[52:53]
	v_cvt_pk_bf16_f32 v78, v200, v201
	v_pk_mul_f32 v[202:203], v[198:199], v[210:211] op_sel_hi:[1,0]
	v_pk_fma_f32 v[202:203], v[202:203], v[38:39], v[54:55]
	v_cvt_pk_bf16_f32 v79, v202, v203
	global_store_dwordx4 v2, v[72:75], s[78:79]
	global_store_dwordx4 v2, v[76:79], s[78:79] offset:1024
	s_add_i32 s81, s80, 6
	s_add_i32 s81, s81, s82
	s_and_b32 s81, s81, 31
	s_lshl_b32 s83, s81, 11
	v_add_u32_e32 v2, s83, v1
	global_load_dwordx4 v[152:155], v2, s[72:73]
	global_load_dwordx4 v[156:159], v2, s[72:73] offset:1024
	global_load_dwordx4 v[160:163], v2, s[74:75]
	global_load_dwordx4 v[164:167], v2, s[74:75] offset:1024
	s_waitcnt vmcnt(24)
; __device__ __forceinline__ unsigned cvtpk(float lo, float hi) { f32x2 v = {lo, hi}; bf16x2_t b = __builtin_convertvector(v, bf16x2_t); return __builtin_bit_cast(unsigned, b); }
; __device__ __forceinline__ float bflo(unsigned u) { return __uint_as_float(u << 16); }
; __device__ __forceinline__ float bfhi(unsigned u) { return __uint_as_float(u & 0xffff0000u); }
; __device__ __forceinline__ void phase_rowwise(const void* xsrc_, bool sbf, void* xdst_, bool dbf, const bf16_t* Y, bf16_t* H, const float* mods, int lprev, int iprev, const float* lnpost, float resw, ...
;     ...
;             if (hasprev) {
;                 f32x4 y[2][4]; float ss[2] = {0.f, 0.f};
; #pragma unroll
;                 for (int r = 0; r < 2; ++r)
; #pragma unroll
;                     for (int j = 0; j < 4; ++j) { const u32x2 u = yr[r][j]; y[r][j] = (f32x4){bflo(u.x), bfhi(u.x), bflo(u.y), bfhi(u.y)};
;                         ss[r] += (y[r][j].x * y[r][j].x + y[r][j].y * y[r][j].y) + (y[r][j].z * y[r][j].z + y[r][j].w * y[r][j].w); }
; #pragma unroll
;                 for (int off = 1; off < 64; off <<= 1) { ss[0] += __shfl_xor(ss[0], off); ss[1] += __shfl_xor(ss[1], off); }
; #pragma unroll
;                 for (int r = 0; r < 2; ++r) { const float rs = __builtin_amdgcn_rsqf(ss[r] * (1.f / DM) + EPS);
; #pragma unroll
;                     for (int j = 0; j < 4; ++j) x[r][j] = x[r][j] + gp[j] * (y[r][j] * rs); }
;             }
; #pragma unroll
;             for (int r = 0; r < 2; ++r)
; #pragma unroll
;                 for (int j = 0; j < 4; ++j) { if (hasprev) { if (dbf) { u32x2 w; w.x = cvtpk(x[r][j].x, x[r][j].y); w.y = cvtpk(x[r][j].z, x[r][j].w); *(u32x2*)(xdstb + (m + r) * DM + 4 * lane + 256 * j) = w; } else *(f32x4*)(xdst + (m + r) * DM + 4 * lane + 256 * j) = x[r][j]; } }
	v_lshlrev_b32_e32 v200, 16, v96
	v_and_b32_e32 v201, 0xffff0000, v96
	v_pk_mul_f32 v[204:205], v[200:201], v[200:201]
	v_lshlrev_b32_e32 v202, 16, v97
	v_and_b32_e32 v203, 0xffff0000, v97
	v_pk_mul_f32 v[206:207], v[202:203], v[202:203]
	v_lshlrev_b32_e32 v200, 16, v98
	v_and_b32_e32 v201, 0xffff0000, v98
	v_pk_fma_f32 v[204:205], v[200:201], v[200:201], v[204:205]
	v_lshlrev_b32_e32 v202, 16, v99
	v_and_b32_e32 v203, 0xffff0000, v99
	v_pk_fma_f32 v[206:207], v[202:203], v[202:203], v[206:207]
	v_lshlrev_b32_e32 v200, 16, v100
	v_and_b32_e32 v201, 0xffff0000, v100
	v_pk_fma_f32 v[204:205], v[200:201], v[200:201], v[204:205]
	v_lshlrev_b32_e32 v202, 16, v101
	v_and_b32_e32 v203, 0xffff0000, v101
	v_pk_fma_f32 v[206:207], v[202:203], v[202:203], v[206:207]
	v_lshlrev_b32_e32 v200, 16, v102
	v_and_b32_e32 v201, 0xffff0000, v102
	v_pk_fma_f32 v[204:205], v[200:201], v[200:201], v[204:205]
	v_lshlrev_b32_e32 v202, 16, v103
	v_and_b32_e32 v203, 0xffff0000, v103
	v_pk_fma_f32 v[206:207], v[202:203], v[202:203], v[206:207]
	v_pk_add_f32 v[204:205], v[204:205], v[206:207]
	v_add_f32_e32 v208, v204, v205
	v_lshlrev_b32_e32 v184, 16, v88
	v_and_b32_e32 v185, 0xffff0000, v88
	v_add_f32_dpp v208, v208, v208 quad_perm:[1,0,3,2] row_mask:0xf bank_mask:0xf
	v_lshlrev_b32_e32 v186, 16, v89
	v_and_b32_e32 v187, 0xffff0000, v89
	v_add_f32_dpp v208, v208, v208 quad_perm:[2,3,0,1] row_mask:0xf bank_mask:0xf
	v_lshlrev_b32_e32 v188, 16, v90
	v_and_b32_e32 v189, 0xffff0000, v90
	v_add_f32_dpp v208, v208, v208 row_half_mirror row_mask:0xf bank_mask:0xf
	v_lshlrev_b32_e32 v190, 16, v91
	v_and_b32_e32 v191, 0xffff0000, v91
	v_add_f32_dpp v208, v208, v208 row_mirror row_mask:0xf bank_mask:0xf
	v_lshlrev_b32_e32 v192, 16, v92
	v_and_b32_e32 v193, 0xffff0000, v92
	v_add_f32_dpp v208, v208, v208 row_bcast:15 row_mask:0xa bank_mask:0xf
	v_lshlrev_b32_e32 v194, 16, v93
	v_and_b32_e32 v195, 0xffff0000, v93
	v_add_f32_dpp v208, v208, v208 row_bcast:31 row_mask:0xc bank_mask:0xf
	v_lshlrev_b32_e32 v196, 16, v94
	v_and_b32_e32 v197, 0xffff0000, v94
	v_readlane_b32 s60, v208, 63
	s_nop 1
	v_lshlrev_b32_e32 v198, 16, v95
	v_and_b32_e32 v199, 0xffff0000, v95
	v_mov_b32_e32 v210, s60
	v_fmaak_f32 v210, v210, v212, 0x358637bd
	v_rsq_f32_e32 v210, v210
	s_nop 0
	v_lshlrev_b32_e32 v200, 16, v96
	v_and_b32_e32 v201, 0xffff0000, v96
	v_pk_mul_f32 v[200:201], v[200:201], v[210:211] op_sel_hi:[1,0]
	v_pk_fma_f32 v[184:185], v[8:9], v[200:201], v[184:185]
	v_lshlrev_b32_e32 v202, 16, v97
	v_and_b32_e32 v203, 0xffff0000, v97
	v_pk_mul_f32 v[202:203], v[202:203], v[210:211] op_sel_hi:[1,0]
	v_pk_fma_f32 v[186:187], v[10:11], v[202:203], v[186:187]
	v_lshlrev_b32_e32 v200, 16, v98
	v_and_b32_e32 v201, 0xffff0000, v98
	v_pk_mul_f32 v[200:201], v[200:201], v[210:211] op_sel_hi:[1,0]
	v_pk_fma_f32 v[188:189], v[12:13], v[200:201], v[188:189]
	v_lshlrev_b32_e32 v202, 16, v99
	v_and_b32_e32 v203, 0xffff0000, v99
	v_pk_mul_f32 v[202:203], v[202:203], v[210:211] op_sel_hi:[1,0]
	v_pk_fma_f32 v[190:191], v[14:15], v[202:203], v[190:191]
	v_lshlrev_b32_e32 v200, 16, v100
	v_and_b32_e32 v201, 0xffff0000, v100
	v_pk_mul_f32 v[200:201], v[200:201], v[210:211] op_sel_hi:[1,0]
	v_pk_fma_f32 v[192:193], v[16:17], v[200:201], v[192:193]
	v_lshlrev_b32_e32 v202, 16, v101
	v_and_b32_e32 v203, 0xffff0000, v101
	v_pk_mul_f32 v[202:203], v[202:203], v[210:211] op_sel_hi:[1,0]
	v_pk_fma_f32 v[194:195], v[18:19], v[202:203], v[194:195]
	v_lshlrev_b32_e32 v200, 16, v102
	v_and_b32_e32 v201, 0xffff0000, v102
	v_pk_mul_f32 v[200:201], v[200:201], v[210:211] op_sel_hi:[1,0]
	v_pk_fma_f32 v[196:197], v[20:21], v[200:201], v[196:197]
	v_lshlrev_b32_e32 v202, 16, v103
	v_and_b32_e32 v203, 0xffff0000, v103
	v_pk_mul_f32 v[202:203], v[202:203], v[210:211] op_sel_hi:[1,0]
	v_pk_fma_f32 v[198:199], v[22:23], v[202:203], v[198:199]
	s_add_i32 s81, s80, 2
	s_add_i32 s81, s81, s82
	s_and_b32 s81, s81, 31
	s_lshl_b32 s83, s81, 11
	v_add_u32_e32 v2, s83, v1
	v_cvt_pk_bf16_f32 v96, v184, v185
	v_cvt_pk_bf16_f32 v97, v186, v187
	v_cvt_pk_bf16_f32 v98, v188, v189
	v_cvt_pk_bf16_f32 v99, v190, v191
	v_cvt_pk_bf16_f32 v100, v192, v193
	v_cvt_pk_bf16_f32 v101, v194, v195
	v_cvt_pk_bf16_f32 v102, v196, v197
	v_cvt_pk_bf16_f32 v103, v198, v199
	global_store_dwordx4 v2, v[96:99], s[76:77]
	global_store_dwordx4 v2, v[100:103], s[76:77] offset:1024
	v_pk_mul_f32 v[204:205], v[184:185], v[184:185]
	v_pk_mul_f32 v[206:207], v[186:187], v[186:187]
	v_pk_fma_f32 v[204:205], v[188:189], v[188:189], v[204:205]
	v_pk_fma_f32 v[206:207], v[190:191], v[190:191], v[206:207]
	v_pk_fma_f32 v[204:205], v[192:193], v[192:193], v[204:205]
	v_pk_fma_f32 v[206:207], v[194:195], v[194:195], v[206:207]
	v_pk_fma_f32 v[204:205], v[196:197], v[196:197], v[204:205]
	v_pk_fma_f32 v[206:207], v[198:199], v[198:199], v[206:207]
	v_pk_add_f32 v[204:205], v[204:205], v[206:207]
	v_add_f32_e32 v208, v204, v205
	s_nop 0
	s_nop 0
	v_add_f32_dpp v208, v208, v208 quad_perm:[1,0,3,2] row_mask:0xf bank_mask:0xf
	s_nop 0
	s_nop 0
	v_add_f32_dpp v208, v208, v208 quad_perm:[2,3,0,1] row_mask:0xf bank_mask:0xf
	s_nop 0
	s_nop 0
	v_add_f32_dpp v208, v208, v208 row_half_mirror row_mask:0xf bank_mask:0xf
	s_nop 0
	s_nop 0
	v_add_f32_dpp v208, v208, v208 row_mirror row_mask:0xf bank_mask:0xf
	s_nop 0
	s_nop 0
	v_add_f32_dpp v208, v208, v208 row_bcast:15 row_mask:0xa bank_mask:0xf
	s_nop 0
	s_nop 0
	v_add_f32_dpp v208, v208, v208 row_bcast:31 row_mask:0xc bank_mask:0xf
	s_nop 0
	s_nop 0
	v_readlane_b32 s60, v208, 63
	s_nop 1
	v_mov_b32_e32 v210, s60
	v_fmaak_f32 v210, v210, v212, 0x358637bd
	v_rsq_f32_e32 v210, v210
	s_nop 0
	v_pk_mul_f32 v[200:201], v[184:185], v[210:211] op_sel_hi:[1,0]
; __device__ __forceinline__ float bflo(unsigned u) { return __uint_as_float(u << 16); }
; __device__ __forceinline__ void phase_rowwise(const void* xsrc_, bool sbf, void* xdst_, bool dbf, const bf16_t* Y, bf16_t* H, const float* mods, int lprev, int iprev, const float* lnpost, float resw, ...
;     ...
;             if (hasprev) {
;                 f32x4 y[2][4]; float ss[2] = {0.f, 0.f};
; #pragma unroll
;                 for (int r = 0; r < 2; ++r)
; #pragma unroll
;                     for (int j = 0; j < 4; ++j) { const u32x2 u = yr[r][j]; y[r][j] = (f32x4){bflo(u.x), bfhi(u.x), bflo(u.y), bfhi(u.y)};
;                         ss[r] += (y[r][j].x * y[r][j].x + y[r][j].y * y[r][j].y) + (y[r][j].z * y[r][j].z + y[r][j].w * y[r][j].w); }
; #pragma unroll
;                 for (int off = 1; off < 64; off <<= 1) { ss[0] += __shfl_xor(ss[0], off); ss[1] += __shfl_xor(ss[1], off); }
; #pragma unroll
;                 for (int r = 0; r < 2; ++r) { const float rs = __builtin_amdgcn_rsqf(ss[r] * (1.f / DM) + EPS);
; #pragma unroll
;                     for (int j = 0; j < 4; ++j) x[r][j] = x[r][j] + gp[j] * (y[r][j] * rs); }
;             }
; #pragma unroll
;             for (int r = 0; r < 2; ++r)
; #pragma unroll
;                 for (int j = 0; j < 4; ++j) { if (hasprev) { if (dbf) { u32x2 w; w.x = cvtpk(x[r][j].x, x[r][j].y); w.y = cvtpk(x[r][j].z, x[r][j].w); *(u32x2*)(xdstb + (m + r) * DM + 4 * lane + 256 * j) = w; } else *(f32x4*)(xdst + (m + r) * DM + 4 * lane + 256 * j) = x[r][j]; } }
;             if (hasnext) {
;                 float ss[2] = {0.f, 0.f};
; #pragma unroll
;                 for (int r = 0; r < 2; ++r)
; #pragma unroll
;                     for (int j = 0; j < 4; ++j) ss[r] += (x[r][j].x * x[r][j].x + x[r][j].y * x[r][j].y) + (x[r][j].z * x[r][j].z + x[r][j].w * x[r][j].w);
; #pragma unroll
;                 for (int off = 1; off < 64; off <<= 1) { ss[0] += __shfl_xor(ss[0], off); ss[1] += __shfl_xor(ss[1], off); }
; #pragma unroll
;                 for (int r = 0; r < 2; ++r) { const float rs = __builtin_amdgcn_rsqf(ss[r] * (1.f / DM) + EPS);
; #pragma unroll
;                     for (int j = 0; j < 4; ++j) { const f32x4 h = (x[r][j] * rs) * na[j] + ns[j]; u32x2 w; w.x = cvtpk(h.x, h.y); w.y = cvtpk(h.z, h.w); *(u32x2*)(H + (m + r) * DM + 4 * lane + 256 * j) = w; } }
	v_pk_fma_f32 v[200:201], v[200:201], v[24:25], v[40:41]
	v_cvt_pk_bf16_f32 v88, v200, v201
	v_pk_mul_f32 v[202:203], v[186:187], v[210:211] op_sel_hi:[1,0]
	v_pk_fma_f32 v[202:203], v[202:203], v[26:27], v[42:43]
	v_cvt_pk_bf16_f32 v89, v202, v203
	v_pk_mul_f32 v[200:201], v[188:189], v[210:211] op_sel_hi:[1,0]
	v_pk_fma_f32 v[200:201], v[200:201], v[28:29], v[44:45]
	v_cvt_pk_bf16_f32 v90, v200, v201
	v_pk_mul_f32 v[202:203], v[190:191], v[210:211] op_sel_hi:[1,0]
	v_pk_fma_f32 v[202:203], v[202:203], v[30:31], v[46:47]
	v_cvt_pk_bf16_f32 v91, v202, v203
	v_pk_mul_f32 v[200:201], v[192:193], v[210:211] op_sel_hi:[1,0]
	v_pk_fma_f32 v[200:201], v[200:201], v[32:33], v[48:49]
	v_cvt_pk_bf16_f32 v92, v200, v201
	v_pk_mul_f32 v[202:203], v[194:195], v[210:211] op_sel_hi:[1,0]
	v_pk_fma_f32 v[202:203], v[202:203], v[34:35], v[50:51]
	v_cvt_pk_bf16_f32 v93, v202, v203
	v_pk_mul_f32 v[200:201], v[196:197], v[210:211] op_sel_hi:[1,0]
	v_pk_fma_f32 v[200:201], v[200:201], v[36:37], v[52:53]
	v_cvt_pk_bf16_f32 v94, v200, v201
	v_pk_mul_f32 v[202:203], v[198:199], v[210:211] op_sel_hi:[1,0]
	v_pk_fma_f32 v[202:203], v[202:203], v[38:39], v[54:55]
	v_cvt_pk_bf16_f32 v95, v202, v203
	global_store_dwordx4 v2, v[88:91], s[78:79]
	global_store_dwordx4 v2, v[92:95], s[78:79] offset:1024
	s_add_i32 s81, s80, 7
	s_add_i32 s81, s81, s82
	s_and_b32 s81, s81, 31
	s_lshl_b32 s83, s81, 11
	v_add_u32_e32 v2, s83, v1
	global_load_dwordx4 v[56:59], v2, s[72:73]
	global_load_dwordx4 v[60:63], v2, s[72:73] offset:1024
	global_load_dwordx4 v[64:67], v2, s[74:75]
	global_load_dwordx4 v[68:71], v2, s[74:75] offset:1024
	s_waitcnt vmcnt(28)
	v_lshlrev_b32_e32 v200, 16, v112
	v_and_b32_e32 v201, 0xffff0000, v112
	v_pk_mul_f32 v[204:205], v[200:201], v[200:201]
	v_lshlrev_b32_e32 v202, 16, v113
	v_and_b32_e32 v203, 0xffff0000, v113
	v_pk_mul_f32 v[206:207], v[202:203], v[202:203]
	v_lshlrev_b32_e32 v200, 16, v114
	v_and_b32_e32 v201, 0xffff0000, v114
	v_pk_fma_f32 v[204:205], v[200:201], v[200:201], v[204:205]
	v_lshlrev_b32_e32 v202, 16, v115
	v_and_b32_e32 v203, 0xffff0000, v115
	v_pk_fma_f32 v[206:207], v[202:203], v[202:203], v[206:207]
	v_lshlrev_b32_e32 v200, 16, v116
	v_and_b32_e32 v201, 0xffff0000, v116
	v_pk_fma_f32 v[204:205], v[200:201], v[200:201], v[204:205]
	v_lshlrev_b32_e32 v202, 16, v117
	v_and_b32_e32 v203, 0xffff0000, v117
	v_pk_fma_f32 v[206:207], v[202:203], v[202:203], v[206:207]
	v_lshlrev_b32_e32 v200, 16, v118
	v_and_b32_e32 v201, 0xffff0000, v118
	v_pk_fma_f32 v[204:205], v[200:201], v[200:201], v[204:205]
	v_lshlrev_b32_e32 v202, 16, v119
	v_and_b32_e32 v203, 0xffff0000, v119
	v_pk_fma_f32 v[206:207], v[202:203], v[202:203], v[206:207]
	v_pk_add_f32 v[204:205], v[204:205], v[206:207]
	v_add_f32_e32 v208, v204, v205
	v_lshlrev_b32_e32 v184, 16, v104
	v_and_b32_e32 v185, 0xffff0000, v104
	v_add_f32_dpp v208, v208, v208 quad_perm:[1,0,3,2] row_mask:0xf bank_mask:0xf
	v_lshlrev_b32_e32 v186, 16, v105
	v_and_b32_e32 v187, 0xffff0000, v105
	v_add_f32_dpp v208, v208, v208 quad_perm:[2,3,0,1] row_mask:0xf bank_mask:0xf
	v_lshlrev_b32_e32 v188, 16, v106
	v_and_b32_e32 v189, 0xffff0000, v106
	v_add_f32_dpp v208, v208, v208 row_half_mirror row_mask:0xf bank_mask:0xf
	v_lshlrev_b32_e32 v190, 16, v107
	v_and_b32_e32 v191, 0xffff0000, v107
	v_add_f32_dpp v208, v208, v208 row_mirror row_mask:0xf bank_mask:0xf
	v_lshlrev_b32_e32 v192, 16, v108
	v_and_b32_e32 v193, 0xffff0000, v108
	v_add_f32_dpp v208, v208, v208 row_bcast:15 row_mask:0xa bank_mask:0xf
	v_lshlrev_b32_e32 v194, 16, v109
	v_and_b32_e32 v195, 0xffff0000, v109
	v_add_f32_dpp v208, v208, v208 row_bcast:31 row_mask:0xc bank_mask:0xf
	v_lshlrev_b32_e32 v196, 16, v110
	v_and_b32_e32 v197, 0xffff0000, v110
	v_readlane_b32 s60, v208, 63
	s_nop 1
	v_lshlrev_b32_e32 v198, 16, v111
	v_and_b32_e32 v199, 0xffff0000, v111
	v_mov_b32_e32 v210, s60
	v_fmaak_f32 v210, v210, v212, 0x358637bd
	v_rsq_f32_e32 v210, v210
	s_nop 0
	v_lshlrev_b32_e32 v200, 16, v112
	v_and_b32_e32 v201, 0xffff0000, v112
	v_pk_mul_f32 v[200:201], v[200:201], v[210:211] op_sel_hi:[1,0]
	v_pk_fma_f32 v[184:185], v[8:9], v[200:201], v[184:185]
	v_lshlrev_b32_e32 v202, 16, v113
	v_and_b32_e32 v203, 0xffff0000, v113
	v_pk_mul_f32 v[202:203], v[202:203], v[210:211] op_sel_hi:[1,0]
	v_pk_fma_f32 v[186:187], v[10:11], v[202:203], v[186:187]
	v_lshlrev_b32_e32 v200, 16, v114
	v_and_b32_e32 v201, 0xffff0000, v114
	v_pk_mul_f32 v[200:201], v[200:201], v[210:211] op_sel_hi:[1,0]
	v_pk_fma_f32 v[188:189], v[12:13], v[200:201], v[188:189]
	v_lshlrev_b32_e32 v202, 16, v115
	v_and_b32_e32 v203, 0xffff0000, v115
	v_pk_mul_f32 v[202:203], v[202:203], v[210:211] op_sel_hi:[1,0]
	v_pk_fma_f32 v[190:191], v[14:15], v[202:203], v[190:191]
	v_lshlrev_b32_e32 v200, 16, v116
	v_and_b32_e32 v201, 0xffff0000, v116
	v_pk_mul_f32 v[200:201], v[200:201], v[210:211] op_sel_hi:[1,0]
	v_pk_fma_f32 v[192:193], v[16:17], v[200:201], v[192:193]
	v_lshlrev_b32_e32 v202, 16, v117
	v_and_b32_e32 v203, 0xffff0000, v117
	v_pk_mul_f32 v[202:203], v[202:203], v[210:211] op_sel_hi:[1,0]
	v_pk_fma_f32 v[194:195], v[18:19], v[202:203], v[194:195]
	v_lshlrev_b32_e32 v200, 16, v118
	v_and_b32_e32 v201, 0xffff0000, v118
	v_pk_mul_f32 v[200:201], v[200:201], v[210:211] op_sel_hi:[1,0]
	v_pk_fma_f32 v[196:197], v[20:21], v[200:201], v[196:197]
	v_lshlrev_b32_e32 v202, 16, v119
	v_and_b32_e32 v203, 0xffff0000, v119
	v_pk_mul_f32 v[202:203], v[202:203], v[210:211] op_sel_hi:[1,0]
	v_pk_fma_f32 v[198:199], v[22:23], v[202:203], v[198:199]
	s_add_i32 s81, s80, 3
	s_add_i32 s81, s81, s82
	s_and_b32 s81, s81, 31
	s_lshl_b32 s83, s81, 11
	v_add_u32_e32 v2, s83, v1
	v_cvt_pk_bf16_f32 v112, v184, v185
; __device__ __forceinline__ void phase_rowwise(const void* xsrc_, bool sbf, void* xdst_, bool dbf, const bf16_t* Y, bf16_t* H, const float* mods, int lprev, int iprev, const float* lnpost, float resw, ...
;     ...
;         for (int rr = 0; rr < 32; rr += 2) {
;             const size_t m = (size_t)ch * 32 + rr;
;             f32x4 x[2][4]; u32x2 yr[2][4];
; #pragma unroll
;             for (int r = 0; r < 2; ++r)
; #pragma unroll
;                 for (int j = 0; j < 4; ++j) { if (sbf) { const u32x2 u = xnb[r][j]; x[r][j] = (f32x4){bflo(u.x), bfhi(u.x), bflo(u.y), bfhi(u.y)}; } else x[r][j] = xn[r][j]; yr[r][j] = yn[r][j]; }
;             if (rr + 2 < 32) {
; #pragma unroll
;                 for (int r = 0; r < 2; ++r)
; #pragma unroll
;                     for (int j = 0; j < 4; ++j) { if (sbf) xnb[r][j] = *(const u32x2*)(xsrcb + (m + 2 + r) * DM + 4 * lane + 256 * j); else xn[r][j] = *(const f32x4*)(xsrc + (m + 2 + r) * DM + 4 * lane + 256 * j); if (hasprev) yn[r][j] = *(const u32x2*)(Y + (m + 2 + r) * DM + 4 * lane + 256 * j); } }
;             if (hasprev) {
;                 f32x4 y[2][4]; float ss[2] = {0.f, 0.f};
; #pragma unroll
;                 for (int r = 0; r < 2; ++r)
; #pragma unroll
;                     for (int j = 0; j < 4; ++j) { const u32x2 u = yr[r][j]; y[r][j] = (f32x4){bflo(u.x), bfhi(u.x), bflo(u.y), bfhi(u.y)};
;                         ss[r] += (y[r][j].x * y[r][j].x + y[r][j].y * y[r][j].y) + (y[r][j].z * y[r][j].z + y[r][j].w * y[r][j].w); }
; #pragma unroll
;                 for (int off = 1; off < 64; off <<= 1) { ss[0] += __shfl_xor(ss[0], off); ss[1] += __shfl_xor(ss[1], off); }
; #pragma unroll
;                 for (int r = 0; r < 2; ++r) { const float rs = __builtin_amdgcn_rsqf(ss[r] * (1.f / DM) + EPS);
; #pragma unroll
;                     for (int j = 0; j < 4; ++j) x[r][j] = x[r][j] + gp[j] * (y[r][j] * rs); }
;             }
; #pragma unroll
;             for (int r = 0; r < 2; ++r)
; #pragma unroll
;                 for (int j = 0; j < 4; ++j) { if (hasprev) { if (dbf) { u32x2 w; w.x = cvtpk(x[r][j].x, x[r][j].y); w.y = cvtpk(x[r][j].z, x[r][j].w); *(u32x2*)(xdstb + (m + r) * DM + 4 * lane + 256 * j) = w; } else *(f32x4*)(xdst + (m + r) * DM + 4 * lane + 256 * j) = x[r][j]; } }
;             if (hasnext) {
;                 float ss[2] = {0.f, 0.f};
; #pragma unroll
;                 for (int r = 0; r < 2; ++r)
	v_cvt_pk_bf16_f32 v113, v186, v187
	v_cvt_pk_bf16_f32 v114, v188, v189
	v_cvt_pk_bf16_f32 v115, v190, v191
	v_cvt_pk_bf16_f32 v116, v192, v193
	v_cvt_pk_bf16_f32 v117, v194, v195
	v_cvt_pk_bf16_f32 v118, v196, v197
	v_cvt_pk_bf16_f32 v119, v198, v199
	global_store_dwordx4 v2, v[112:115], s[76:77]
	global_store_dwordx4 v2, v[116:119], s[76:77] offset:1024
	v_pk_mul_f32 v[204:205], v[184:185], v[184:185]
	v_pk_mul_f32 v[206:207], v[186:187], v[186:187]
	v_pk_fma_f32 v[204:205], v[188:189], v[188:189], v[204:205]
	v_pk_fma_f32 v[206:207], v[190:191], v[190:191], v[206:207]
	v_pk_fma_f32 v[204:205], v[192:193], v[192:193], v[204:205]
	v_pk_fma_f32 v[206:207], v[194:195], v[194:195], v[206:207]
	v_pk_fma_f32 v[204:205], v[196:197], v[196:197], v[204:205]
	v_pk_fma_f32 v[206:207], v[198:199], v[198:199], v[206:207]
	v_pk_add_f32 v[204:205], v[204:205], v[206:207]
	v_add_f32_e32 v208, v204, v205
	s_nop 0
	s_nop 0
	v_add_f32_dpp v208, v208, v208 quad_perm:[1,0,3,2] row_mask:0xf bank_mask:0xf
	s_nop 0
	s_nop 0
	v_add_f32_dpp v208, v208, v208 quad_perm:[2,3,0,1] row_mask:0xf bank_mask:0xf
	s_nop 0
	s_nop 0
	v_add_f32_dpp v208, v208, v208 row_half_mirror row_mask:0xf bank_mask:0xf
	s_nop 0
	s_nop 0
	v_add_f32_dpp v208, v208, v208 row_mirror row_mask:0xf bank_mask:0xf
	s_nop 0
	s_nop 0
	v_add_f32_dpp v208, v208, v208 row_bcast:15 row_mask:0xa bank_mask:0xf
	s_nop 0
	s_nop 0
	v_add_f32_dpp v208, v208, v208 row_bcast:31 row_mask:0xc bank_mask:0xf
	s_nop 0
	s_nop 0
	v_readlane_b32 s60, v208, 63
	s_nop 1
	v_mov_b32_e32 v210, s60
	v_fmaak_f32 v210, v210, v212, 0x358637bd
	v_rsq_f32_e32 v210, v210
	s_nop 0
	v_pk_mul_f32 v[200:201], v[184:185], v[210:211] op_sel_hi:[1,0]
	v_pk_fma_f32 v[200:201], v[200:201], v[24:25], v[40:41]
	v_cvt_pk_bf16_f32 v104, v200, v201
	v_pk_mul_f32 v[202:203], v[186:187], v[210:211] op_sel_hi:[1,0]
	v_pk_fma_f32 v[202:203], v[202:203], v[26:27], v[42:43]
	v_cvt_pk_bf16_f32 v105, v202, v203
	v_pk_mul_f32 v[200:201], v[188:189], v[210:211] op_sel_hi:[1,0]
	v_pk_fma_f32 v[200:201], v[200:201], v[28:29], v[44:45]
	v_cvt_pk_bf16_f32 v106, v200, v201
	v_pk_mul_f32 v[202:203], v[190:191], v[210:211] op_sel_hi:[1,0]
	v_pk_fma_f32 v[202:203], v[202:203], v[30:31], v[46:47]
	v_cvt_pk_bf16_f32 v107, v202, v203
	v_pk_mul_f32 v[200:201], v[192:193], v[210:211] op_sel_hi:[1,0]
	v_pk_fma_f32 v[200:201], v[200:201], v[32:33], v[48:49]
	v_cvt_pk_bf16_f32 v108, v200, v201
	v_pk_mul_f32 v[202:203], v[194:195], v[210:211] op_sel_hi:[1,0]
	v_pk_fma_f32 v[202:203], v[202:203], v[34:35], v[50:51]
	v_cvt_pk_bf16_f32 v109, v202, v203
	v_pk_mul_f32 v[200:201], v[196:197], v[210:211] op_sel_hi:[1,0]
	v_pk_fma_f32 v[200:201], v[200:201], v[36:37], v[52:53]
	v_cvt_pk_bf16_f32 v110, v200, v201
	v_pk_mul_f32 v[202:203], v[198:199], v[210:211] op_sel_hi:[1,0]
	v_pk_fma_f32 v[202:203], v[202:203], v[38:39], v[54:55]
	v_cvt_pk_bf16_f32 v111, v202, v203
	global_store_dwordx4 v2, v[104:107], s[78:79]
	global_store_dwordx4 v2, v[108:111], s[78:79] offset:1024
	s_mov_b32 s82, 4
.Lrw_MID_loop:
	s_add_i32 s81, s82, 4
	s_cmp_lt_u32 s81, 32
	s_cbranch_scc0 .Lrw_MID_l0_d
	s_add_i32 s81, s80, 4
	s_add_i32 s81, s81, s82
	s_and_b32 s81, s81, 31
	s_lshl_b32 s83, s81, 11
	v_add_u32_e32 v2, s83, v1
	global_load_dwordx4 v[72:75], v2, s[72:73]
	global_load_dwordx4 v[76:79], v2, s[72:73] offset:1024
	global_load_dwordx4 v[80:83], v2, s[74:75]
	global_load_dwordx4 v[84:87], v2, s[74:75] offset:1024
	s_branch .Lrw_MID_l0_e
.Lrw_MID_l0_d:
	global_load_dword v209, v1, s[72:73]
	global_load_dword v209, v1, s[72:73]
	global_load_dword v209, v1, s[72:73]
	global_load_dword v209, v1, s[72:73]
.Lrw_MID_l0_e:
	s_waitcnt vmcnt(32)
	v_lshlrev_b32_e32 v200, 16, v128
	v_and_b32_e32 v201, 0xffff0000, v128
	v_pk_mul_f32 v[204:205], v[200:201], v[200:201]
	v_lshlrev_b32_e32 v202, 16, v129
	v_and_b32_e32 v203, 0xffff0000, v129
	v_pk_mul_f32 v[206:207], v[202:203], v[202:203]
	v_lshlrev_b32_e32 v200, 16, v130
	v_and_b32_e32 v201, 0xffff0000, v130
	v_pk_fma_f32 v[204:205], v[200:201], v[200:201], v[204:205]
	v_lshlrev_b32_e32 v202, 16, v131
	v_and_b32_e32 v203, 0xffff0000, v131
	v_pk_fma_f32 v[206:207], v[202:203], v[202:203], v[206:207]
	v_lshlrev_b32_e32 v200, 16, v132
	v_and_b32_e32 v201, 0xffff0000, v132
	v_pk_fma_f32 v[204:205], v[200:201], v[200:201], v[204:205]
	v_lshlrev_b32_e32 v202, 16, v133
	v_and_b32_e32 v203, 0xffff0000, v133
	v_pk_fma_f32 v[206:207], v[202:203], v[202:203], v[206:207]
	v_lshlrev_b32_e32 v200, 16, v134
	v_and_b32_e32 v201, 0xffff0000, v134
	v_pk_fma_f32 v[204:205], v[200:201], v[200:201], v[204:205]
	v_lshlrev_b32_e32 v202, 16, v135
	v_and_b32_e32 v203, 0xffff0000, v135
	v_pk_fma_f32 v[206:207], v[202:203], v[202:203], v[206:207]
	v_pk_add_f32 v[204:205], v[204:205], v[206:207]
	v_add_f32_e32 v208, v204, v205
	v_lshlrev_b32_e32 v184, 16, v120
	v_and_b32_e32 v185, 0xffff0000, v120
	v_add_f32_dpp v208, v208, v208 quad_perm:[1,0,3,2] row_mask:0xf bank_mask:0xf
	v_lshlrev_b32_e32 v186, 16, v121
	v_and_b32_e32 v187, 0xffff0000, v121
	v_add_f32_dpp v208, v208, v208 quad_perm:[2,3,0,1] row_mask:0xf bank_mask:0xf
	v_lshlrev_b32_e32 v188, 16, v122
	v_and_b32_e32 v189, 0xffff0000, v122
	v_add_f32_dpp v208, v208, v208 row_half_mirror row_mask:0xf bank_mask:0xf
	v_lshlrev_b32_e32 v190, 16, v123
	v_and_b32_e32 v191, 0xffff0000, v123
	v_add_f32_dpp v208, v208, v208 row_mirror row_mask:0xf bank_mask:0xf
	v_lshlrev_b32_e32 v192, 16, v124
	v_and_b32_e32 v193, 0xffff0000, v124
	v_add_f32_dpp v208, v208, v208 row_bcast:15 row_mask:0xa bank_mask:0xf
	v_lshlrev_b32_e32 v194, 16, v125
; __device__ __forceinline__ void phase_rowwise(const void* xsrc_, bool sbf, void* xdst_, bool dbf, const bf16_t* Y, bf16_t* H, const float* mods, int lprev, int iprev, const float* lnpost, float resw, ...
;     ...
;         for (int rr = 0; rr < 32; rr += 2) {
;             const size_t m = (size_t)ch * 32 + rr;
;             f32x4 x[2][4]; u32x2 yr[2][4];
; #pragma unroll
;             for (int r = 0; r < 2; ++r)
; #pragma unroll
;                 for (int j = 0; j < 4; ++j) { if (sbf) { const u32x2 u = xnb[r][j]; x[r][j] = (f32x4){bflo(u.x), bfhi(u.x), bflo(u.y), bfhi(u.y)}; } else x[r][j] = xn[r][j]; yr[r][j] = yn[r][j]; }
;             if (rr + 2 < 32) {
; #pragma unroll
;                 for (int r = 0; r < 2; ++r)
; #pragma unroll
;                     for (int j = 0; j < 4; ++j) { if (sbf) xnb[r][j] = *(const u32x2*)(xsrcb + (m + 2 + r) * DM + 4 * lane + 256 * j); else xn[r][j] = *(const f32x4*)(xsrc + (m + 2 + r) * DM + 4 * lane + 256 * j); if (hasprev) yn[r][j] = *(const u32x2*)(Y + (m + 2 + r) * DM + 4 * lane + 256 * j); } }
;             if (hasprev) {
;                 f32x4 y[2][4]; float ss[2] = {0.f, 0.f};
; #pragma unroll
;                 for (int r = 0; r < 2; ++r)
; #pragma unroll
;                     for (int j = 0; j < 4; ++j) { const u32x2 u = yr[r][j]; y[r][j] = (f32x4){bflo(u.x), bfhi(u.x), bflo(u.y), bfhi(u.y)};
;                         ss[r] += (y[r][j].x * y[r][j].x + y[r][j].y * y[r][j].y) + (y[r][j].z * y[r][j].z + y[r][j].w * y[r][j].w); }
; #pragma unroll
;                 for (int off = 1; off < 64; off <<= 1) { ss[0] += __shfl_xor(ss[0], off); ss[1] += __shfl_xor(ss[1], off); }
; #pragma unroll
;                 for (int r = 0; r < 2; ++r) { const float rs = __builtin_amdgcn_rsqf(ss[r] * (1.f / DM) + EPS);
; #pragma unroll
;                     for (int j = 0; j < 4; ++j) x[r][j] = x[r][j] + gp[j] * (y[r][j] * rs); }
;             }
; #pragma unroll
;             for (int r = 0; r < 2; ++r)
; #pragma unroll
;                 for (int j = 0; j < 4; ++j) { if (hasprev) { if (dbf) { u32x2 w; w.x = cvtpk(x[r][j].x, x[r][j].y); w.y = cvtpk(x[r][j].z, x[r][j].w); *(u32x2*)(xdstb + (m + r) * DM + 4 * lane + 256 * j) = w; } else *(f32x4*)(xdst + (m + r) * DM + 4 * lane + 256 * j) = x[r][j]; } }
;             if (hasnext) {
;                 float ss[2] = {0.f, 0.f};
; #pragma unroll
;                 for (int r = 0; r < 2; ++r)
	v_and_b32_e32 v195, 0xffff0000, v125
	v_add_f32_dpp v208, v208, v208 row_bcast:31 row_mask:0xc bank_mask:0xf
	v_lshlrev_b32_e32 v196, 16, v126
	v_and_b32_e32 v197, 0xffff0000, v126
	v_readlane_b32 s60, v208, 63
	s_nop 1
	v_lshlrev_b32_e32 v198, 16, v127
	v_and_b32_e32 v199, 0xffff0000, v127
	v_mov_b32_e32 v210, s60
	v_fmaak_f32 v210, v210, v212, 0x358637bd
	v_rsq_f32_e32 v210, v210
	s_nop 0
	v_lshlrev_b32_e32 v200, 16, v128
	v_and_b32_e32 v201, 0xffff0000, v128
	v_pk_mul_f32 v[200:201], v[200:201], v[210:211] op_sel_hi:[1,0]
	v_pk_fma_f32 v[184:185], v[8:9], v[200:201], v[184:185]
	v_lshlrev_b32_e32 v202, 16, v129
	v_and_b32_e32 v203, 0xffff0000, v129
	v_pk_mul_f32 v[202:203], v[202:203], v[210:211] op_sel_hi:[1,0]
	v_pk_fma_f32 v[186:187], v[10:11], v[202:203], v[186:187]
	v_lshlrev_b32_e32 v200, 16, v130
	v_and_b32_e32 v201, 0xffff0000, v130
	v_pk_mul_f32 v[200:201], v[200:201], v[210:211] op_sel_hi:[1,0]
	v_pk_fma_f32 v[188:189], v[12:13], v[200:201], v[188:189]
	v_lshlrev_b32_e32 v202, 16, v131
	v_and_b32_e32 v203, 0xffff0000, v131
	v_pk_mul_f32 v[202:203], v[202:203], v[210:211] op_sel_hi:[1,0]
	v_pk_fma_f32 v[190:191], v[14:15], v[202:203], v[190:191]
	v_lshlrev_b32_e32 v200, 16, v132
	v_and_b32_e32 v201, 0xffff0000, v132
	v_pk_mul_f32 v[200:201], v[200:201], v[210:211] op_sel_hi:[1,0]
	v_pk_fma_f32 v[192:193], v[16:17], v[200:201], v[192:193]
	v_lshlrev_b32_e32 v202, 16, v133
	v_and_b32_e32 v203, 0xffff0000, v133
	v_pk_mul_f32 v[202:203], v[202:203], v[210:211] op_sel_hi:[1,0]
	v_pk_fma_f32 v[194:195], v[18:19], v[202:203], v[194:195]
	v_lshlrev_b32_e32 v200, 16, v134
	v_and_b32_e32 v201, 0xffff0000, v134
	v_pk_mul_f32 v[200:201], v[200:201], v[210:211] op_sel_hi:[1,0]
	v_pk_fma_f32 v[196:197], v[20:21], v[200:201], v[196:197]
	v_lshlrev_b32_e32 v202, 16, v135
	v_and_b32_e32 v203, 0xffff0000, v135
	v_pk_mul_f32 v[202:203], v[202:203], v[210:211] op_sel_hi:[1,0]
	v_pk_fma_f32 v[198:199], v[22:23], v[202:203], v[198:199]
	s_add_i32 s81, s80, 0
	s_add_i32 s81, s81, s82
	s_and_b32 s81, s81, 31
	s_lshl_b32 s83, s81, 11
	v_add_u32_e32 v2, s83, v1
	v_cvt_pk_bf16_f32 v128, v184, v185
	v_cvt_pk_bf16_f32 v129, v186, v187
	v_cvt_pk_bf16_f32 v130, v188, v189
	v_cvt_pk_bf16_f32 v131, v190, v191
	v_cvt_pk_bf16_f32 v132, v192, v193
	v_cvt_pk_bf16_f32 v133, v194, v195
	v_cvt_pk_bf16_f32 v134, v196, v197
	v_cvt_pk_bf16_f32 v135, v198, v199
	global_store_dwordx4 v2, v[128:131], s[76:77]
	global_store_dwordx4 v2, v[132:135], s[76:77] offset:1024
	v_pk_mul_f32 v[204:205], v[184:185], v[184:185]
	v_pk_mul_f32 v[206:207], v[186:187], v[186:187]
	v_pk_fma_f32 v[204:205], v[188:189], v[188:189], v[204:205]
	v_pk_fma_f32 v[206:207], v[190:191], v[190:191], v[206:207]
	v_pk_fma_f32 v[204:205], v[192:193], v[192:193], v[204:205]
	v_pk_fma_f32 v[206:207], v[194:195], v[194:195], v[206:207]
	v_pk_fma_f32 v[204:205], v[196:197], v[196:197], v[204:205]
	v_pk_fma_f32 v[206:207], v[198:199], v[198:199], v[206:207]
	v_pk_add_f32 v[204:205], v[204:205], v[206:207]
	v_add_f32_e32 v208, v204, v205
	s_nop 0
	s_nop 0
	v_add_f32_dpp v208, v208, v208 quad_perm:[1,0,3,2] row_mask:0xf bank_mask:0xf
	s_nop 0
	s_nop 0
	v_add_f32_dpp v208, v208, v208 quad_perm:[2,3,0,1] row_mask:0xf bank_mask:0xf
	s_nop 0
	s_nop 0
	v_add_f32_dpp v208, v208, v208 row_half_mirror row_mask:0xf bank_mask:0xf
	s_nop 0
	s_nop 0
	v_add_f32_dpp v208, v208, v208 row_mirror row_mask:0xf bank_mask:0xf
	s_nop 0
	s_nop 0
	v_add_f32_dpp v208, v208, v208 row_bcast:15 row_mask:0xa bank_mask:0xf
	s_nop 0
	s_nop 0
	v_add_f32_dpp v208, v208, v208 row_bcast:31 row_mask:0xc bank_mask:0xf
	s_nop 0
	s_nop 0
	v_readlane_b32 s60, v208, 63
	s_nop 1
	v_mov_b32_e32 v210, s60
	v_fmaak_f32 v210, v210, v212, 0x358637bd
	v_rsq_f32_e32 v210, v210
	s_nop 0
	v_pk_mul_f32 v[200:201], v[184:185], v[210:211] op_sel_hi:[1,0]
	v_pk_fma_f32 v[200:201], v[200:201], v[24:25], v[40:41]
	v_cvt_pk_bf16_f32 v120, v200, v201
	v_pk_mul_f32 v[202:203], v[186:187], v[210:211] op_sel_hi:[1,0]
	v_pk_fma_f32 v[202:203], v[202:203], v[26:27], v[42:43]
	v_cvt_pk_bf16_f32 v121, v202, v203
	v_pk_mul_f32 v[200:201], v[188:189], v[210:211] op_sel_hi:[1,0]
	v_pk_fma_f32 v[200:201], v[200:201], v[28:29], v[44:45]
	v_cvt_pk_bf16_f32 v122, v200, v201
	v_pk_mul_f32 v[202:203], v[190:191], v[210:211] op_sel_hi:[1,0]
	v_pk_fma_f32 v[202:203], v[202:203], v[30:31], v[46:47]
	v_cvt_pk_bf16_f32 v123, v202, v203
	v_pk_mul_f32 v[200:201], v[192:193], v[210:211] op_sel_hi:[1,0]
	v_pk_fma_f32 v[200:201], v[200:201], v[32:33], v[48:49]
	v_cvt_pk_bf16_f32 v124, v200, v201
	v_pk_mul_f32 v[202:203], v[194:195], v[210:211] op_sel_hi:[1,0]
	v_pk_fma_f32 v[202:203], v[202:203], v[34:35], v[50:51]
	v_cvt_pk_bf16_f32 v125, v202, v203
	v_pk_mul_f32 v[200:201], v[196:197], v[210:211] op_sel_hi:[1,0]
	v_pk_fma_f32 v[200:201], v[200:201], v[36:37], v[52:53]
	v_cvt_pk_bf16_f32 v126, v200, v201
	v_pk_mul_f32 v[202:203], v[198:199], v[210:211] op_sel_hi:[1,0]
	v_pk_fma_f32 v[202:203], v[202:203], v[38:39], v[54:55]
	v_cvt_pk_bf16_f32 v127, v202, v203
	global_store_dwordx4 v2, v[120:123], s[78:79]
	global_store_dwordx4 v2, v[124:127], s[78:79] offset:1024
	s_add_i32 s81, s82, 5
	s_cmp_lt_u32 s81, 32
	s_cbranch_scc0 .Lrw_MID_l1_d
	s_add_i32 s81, s80, 5
	s_add_i32 s81, s81, s82
	s_and_b32 s81, s81, 31
	s_lshl_b32 s83, s81, 11
	v_add_u32_e32 v2, s83, v1
	global_load_dwordx4 v[88:91], v2, s[72:73]
	global_load_dwordx4 v[92:95], v2, s[72:73] offset:1024
	global_load_dwordx4 v[96:99], v2, s[74:75]
	global_load_dwordx4 v[100:103], v2, s[74:75] offset:1024
	s_branch .Lrw_MID_l1_e

; __device__ __forceinline__ float bflo(unsigned u) { return __uint_as_float(u << 16); }
; __device__ __forceinline__ float bfhi(unsigned u) { return __uint_as_float(u & 0xffff0000u); }
; __device__ __forceinline__ void phase_rowwise(const void* xsrc_, bool sbf, void* xdst_, bool dbf, const bf16_t* Y, bf16_t* H, const float* mods, int lprev, int iprev, const float* lnpost, float resw, ...
;     ...
;         for (int rr = 0; rr < 32; rr += 2) {
;             const size_t m = (size_t)ch * 32 + rr;
;             f32x4 x[2][4]; u32x2 yr[2][4];
; #pragma unroll
;             for (int r = 0; r < 2; ++r)
; #pragma unroll
;                 for (int j = 0; j < 4; ++j) { if (sbf) { const u32x2 u = xnb[r][j]; x[r][j] = (f32x4){bflo(u.x), bfhi(u.x), bflo(u.y), bfhi(u.y)}; } else x[r][j] = xn[r][j]; yr[r][j] = yn[r][j]; }
;             if (rr + 2 < 32) {
; #pragma unroll
;                 for (int r = 0; r < 2; ++r)
; #pragma unroll
;                     for (int j = 0; j < 4; ++j) { if (sbf) xnb[r][j] = *(const u32x2*)(xsrcb + (m + 2 + r) * DM + 4 * lane + 256 * j); else xn[r][j] = *(const f32x4*)(xsrc + (m + 2 + r) * DM + 4 * lane + 256 * j); if (hasprev) yn[r][j] = *(const u32x2*)(Y + (m + 2 + r) * DM + 4 * lane + 256 * j); } }
;             if (hasprev) {
;                 f32x4 y[2][4]; float ss[2] = {0.f, 0.f};
; #pragma unroll
;                 for (int r = 0; r < 2; ++r)
; #pragma unroll
;                     for (int j = 0; j < 4; ++j) { const u32x2 u = yr[r][j]; y[r][j] = (f32x4){bflo(u.x), bfhi(u.x), bflo(u.y), bfhi(u.y)};
;                         ss[r] += (y[r][j].x * y[r][j].x + y[r][j].y * y[r][j].y) + (y[r][j].z * y[r][j].z + y[r][j].w * y[r][j].w); }
; #pragma unroll
;                 for (int off = 1; off < 64; off <<= 1) { ss[0] += __shfl_xor(ss[0], off); ss[1] += __shfl_xor(ss[1], off); }
; #pragma unroll
;                 for (int r = 0; r < 2; ++r) { const float rs = __builtin_amdgcn_rsqf(ss[r] * (1.f / DM) + EPS);
; #pragma unroll
;                     for (int j = 0; j < 4; ++j) x[r][j] = x[r][j] + gp[j] * (y[r][j] * rs); }
.Lrw_MID_l1_e:
	s_waitcnt vmcnt(32)
	v_lshlrev_b32_e32 v200, 16, v144
	v_and_b32_e32 v201, 0xffff0000, v144
	v_pk_mul_f32 v[204:205], v[200:201], v[200:201]
	v_lshlrev_b32_e32 v202, 16, v145
	v_and_b32_e32 v203, 0xffff0000, v145
	v_pk_mul_f32 v[206:207], v[202:203], v[202:203]
	v_lshlrev_b32_e32 v200, 16, v146
	v_and_b32_e32 v201, 0xffff0000, v146
	v_pk_fma_f32 v[204:205], v[200:201], v[200:201], v[204:205]
	v_lshlrev_b32_e32 v202, 16, v147
	v_and_b32_e32 v203, 0xffff0000, v147
	v_pk_fma_f32 v[206:207], v[202:203], v[202:203], v[206:207]
	v_lshlrev_b32_e32 v200, 16, v148
	v_and_b32_e32 v201, 0xffff0000, v148
	v_pk_fma_f32 v[204:205], v[200:201], v[200:201], v[204:205]
	v_lshlrev_b32_e32 v202, 16, v149
	v_and_b32_e32 v203, 0xffff0000, v149
	v_pk_fma_f32 v[206:207], v[202:203], v[202:203], v[206:207]
	v_lshlrev_b32_e32 v200, 16, v150
	v_and_b32_e32 v201, 0xffff0000, v150
	v_pk_fma_f32 v[204:205], v[200:201], v[200:201], v[204:205]
	v_lshlrev_b32_e32 v202, 16, v151
	v_and_b32_e32 v203, 0xffff0000, v151
	v_pk_fma_f32 v[206:207], v[202:203], v[202:203], v[206:207]
	v_pk_add_f32 v[204:205], v[204:205], v[206:207]
	v_add_f32_e32 v208, v204, v205
	v_lshlrev_b32_e32 v184, 16, v136
	v_and_b32_e32 v185, 0xffff0000, v136
	v_add_f32_dpp v208, v208, v208 quad_perm:[1,0,3,2] row_mask:0xf bank_mask:0xf
	v_lshlrev_b32_e32 v186, 16, v137
	v_and_b32_e32 v187, 0xffff0000, v137
	v_add_f32_dpp v208, v208, v208 quad_perm:[2,3,0,1] row_mask:0xf bank_mask:0xf
	v_lshlrev_b32_e32 v188, 16, v138
	v_and_b32_e32 v189, 0xffff0000, v138
	v_add_f32_dpp v208, v208, v208 row_half_mirror row_mask:0xf bank_mask:0xf
	v_lshlrev_b32_e32 v190, 16, v139
	v_and_b32_e32 v191, 0xffff0000, v139
	v_add_f32_dpp v208, v208, v208 row_mirror row_mask:0xf bank_mask:0xf
	v_lshlrev_b32_e32 v192, 16, v140
	v_and_b32_e32 v193, 0xffff0000, v140
	v_add_f32_dpp v208, v208, v208 row_bcast:15 row_mask:0xa bank_mask:0xf
	v_lshlrev_b32_e32 v194, 16, v141
	v_and_b32_e32 v195, 0xffff0000, v141
	v_add_f32_dpp v208, v208, v208 row_bcast:31 row_mask:0xc bank_mask:0xf
	v_lshlrev_b32_e32 v196, 16, v142
	v_and_b32_e32 v197, 0xffff0000, v142
	v_readlane_b32 s60, v208, 63
	s_nop 1
	v_lshlrev_b32_e32 v198, 16, v143
	v_and_b32_e32 v199, 0xffff0000, v143
	v_mov_b32_e32 v210, s60
	v_fmaak_f32 v210, v210, v212, 0x358637bd
	v_rsq_f32_e32 v210, v210
	s_nop 0
	v_lshlrev_b32_e32 v200, 16, v144
	v_and_b32_e32 v201, 0xffff0000, v144
	v_pk_mul_f32 v[200:201], v[200:201], v[210:211] op_sel_hi:[1,0]
	v_pk_fma_f32 v[184:185], v[8:9], v[200:201], v[184:185]
	v_lshlrev_b32_e32 v202, 16, v145
	v_and_b32_e32 v203, 0xffff0000, v145
	v_pk_mul_f32 v[202:203], v[202:203], v[210:211] op_sel_hi:[1,0]
	v_pk_fma_f32 v[186:187], v[10:11], v[202:203], v[186:187]
	v_lshlrev_b32_e32 v200, 16, v146
	v_and_b32_e32 v201, 0xffff0000, v146
	v_pk_mul_f32 v[200:201], v[200:201], v[210:211] op_sel_hi:[1,0]
	v_pk_fma_f32 v[188:189], v[12:13], v[200:201], v[188:189]
	v_lshlrev_b32_e32 v202, 16, v147
	v_and_b32_e32 v203, 0xffff0000, v147
	v_pk_mul_f32 v[202:203], v[202:203], v[210:211] op_sel_hi:[1,0]
	v_pk_fma_f32 v[190:191], v[14:15], v[202:203], v[190:191]
	v_lshlrev_b32_e32 v200, 16, v148
	v_and_b32_e32 v201, 0xffff0000, v148
	v_pk_mul_f32 v[200:201], v[200:201], v[210:211] op_sel_hi:[1,0]
	v_pk_fma_f32 v[192:193], v[16:17], v[200:201], v[192:193]
	v_lshlrev_b32_e32 v202, 16, v149
	v_and_b32_e32 v203, 0xffff0000, v149
	v_pk_mul_f32 v[202:203], v[202:203], v[210:211] op_sel_hi:[1,0]
	v_pk_fma_f32 v[194:195], v[18:19], v[202:203], v[194:195]
	v_lshlrev_b32_e32 v200, 16, v150
	v_and_b32_e32 v201, 0xffff0000, v150
	v_pk_mul_f32 v[200:201], v[200:201], v[210:211] op_sel_hi:[1,0]
	v_pk_fma_f32 v[196:197], v[20:21], v[200:201], v[196:197]
	v_lshlrev_b32_e32 v202, 16, v151
; __device__ __forceinline__ unsigned cvtpk(float lo, float hi) { f32x2 v = {lo, hi}; bf16x2_t b = __builtin_convertvector(v, bf16x2_t); return __builtin_bit_cast(unsigned, b); }
; __device__ __forceinline__ void phase_rowwise(const void* xsrc_, bool sbf, void* xdst_, bool dbf, const bf16_t* Y, bf16_t* H, const float* mods, int lprev, int iprev, const float* lnpost, float resw, ...
;     ...
;                     for (int j = 0; j < 4; ++j) { if (sbf) xnb[r][j] = *(const u32x2*)(xsrcb + (m + 2 + r) * DM + 4 * lane + 256 * j); else xn[r][j] = *(const f32x4*)(xsrc + (m + 2 + r) * DM + 4 * lane + 256 * j); if (hasprev) yn[r][j] = *(const u32x2*)(Y + (m + 2 + r) * DM + 4 * lane + 256 * j); } }
;     ...
; #pragma unroll
;             for (int r = 0; r < 2; ++r)
; #pragma unroll
;                 for (int j = 0; j < 4; ++j) { if (hasprev) { if (dbf) { u32x2 w; w.x = cvtpk(x[r][j].x, x[r][j].y); w.y = cvtpk(x[r][j].z, x[r][j].w); *(u32x2*)(xdstb + (m + r) * DM + 4 * lane + 256 * j) = w; } else *(f32x4*)(xdst + (m + r) * DM + 4 * lane + 256 * j) = x[r][j]; } }
;             if (hasnext) {
;                 float ss[2] = {0.f, 0.f};
; #pragma unroll
;                 for (int r = 0; r < 2; ++r)
; #pragma unroll
;                     for (int j = 0; j < 4; ++j) ss[r] += (x[r][j].x * x[r][j].x + x[r][j].y * x[r][j].y) + (x[r][j].z * x[r][j].z + x[r][j].w * x[r][j].w);
; #pragma unroll
;                 for (int off = 1; off < 64; off <<= 1) { ss[0] += __shfl_xor(ss[0], off); ss[1] += __shfl_xor(ss[1], off); }
; #pragma unroll
;                 for (int r = 0; r < 2; ++r) { const float rs = __builtin_amdgcn_rsqf(ss[r] * (1.f / DM) + EPS);
; #pragma unroll
;                     for (int j = 0; j < 4; ++j) { const f32x4 h = (x[r][j] * rs) * na[j] + ns[j]; u32x2 w; w.x = cvtpk(h.x, h.y); w.y = cvtpk(h.z, h.w); *(u32x2*)(H + (m + r) * DM + 4 * lane + 256 * j) = w; } }
;             }
	v_and_b32_e32 v203, 0xffff0000, v151
	v_pk_mul_f32 v[202:203], v[202:203], v[210:211] op_sel_hi:[1,0]
	v_pk_fma_f32 v[198:199], v[22:23], v[202:203], v[198:199]
	s_add_i32 s81, s80, 1
	s_add_i32 s81, s81, s82
	s_and_b32 s81, s81, 31
	s_lshl_b32 s83, s81, 11
	v_add_u32_e32 v2, s83, v1
	v_cvt_pk_bf16_f32 v144, v184, v185
	v_cvt_pk_bf16_f32 v145, v186, v187
	v_cvt_pk_bf16_f32 v146, v188, v189
	v_cvt_pk_bf16_f32 v147, v190, v191
	v_cvt_pk_bf16_f32 v148, v192, v193
	v_cvt_pk_bf16_f32 v149, v194, v195
	v_cvt_pk_bf16_f32 v150, v196, v197
	v_cvt_pk_bf16_f32 v151, v198, v199
	global_store_dwordx4 v2, v[144:147], s[76:77]
	global_store_dwordx4 v2, v[148:151], s[76:77] offset:1024
	v_pk_mul_f32 v[204:205], v[184:185], v[184:185]
	v_pk_mul_f32 v[206:207], v[186:187], v[186:187]
	v_pk_fma_f32 v[204:205], v[188:189], v[188:189], v[204:205]
	v_pk_fma_f32 v[206:207], v[190:191], v[190:191], v[206:207]
	v_pk_fma_f32 v[204:205], v[192:193], v[192:193], v[204:205]
	v_pk_fma_f32 v[206:207], v[194:195], v[194:195], v[206:207]
	v_pk_fma_f32 v[204:205], v[196:197], v[196:197], v[204:205]
	v_pk_fma_f32 v[206:207], v[198:199], v[198:199], v[206:207]
	v_pk_add_f32 v[204:205], v[204:205], v[206:207]
	v_add_f32_e32 v208, v204, v205
	s_nop 0
	s_nop 0
	v_add_f32_dpp v208, v208, v208 quad_perm:[1,0,3,2] row_mask:0xf bank_mask:0xf
	s_nop 0
	s_nop 0
	v_add_f32_dpp v208, v208, v208 quad_perm:[2,3,0,1] row_mask:0xf bank_mask:0xf
	s_nop 0
	s_nop 0
	v_add_f32_dpp v208, v208, v208 row_half_mirror row_mask:0xf bank_mask:0xf
	s_nop 0
	s_nop 0
	v_add_f32_dpp v208, v208, v208 row_mirror row_mask:0xf bank_mask:0xf
	s_nop 0
	s_nop 0
	v_add_f32_dpp v208, v208, v208 row_bcast:15 row_mask:0xa bank_mask:0xf
	s_nop 0
	s_nop 0
	v_add_f32_dpp v208, v208, v208 row_bcast:31 row_mask:0xc bank_mask:0xf
	s_nop 0
	s_nop 0
	v_readlane_b32 s60, v208, 63
	s_nop 1
	v_mov_b32_e32 v210, s60
	v_fmaak_f32 v210, v210, v212, 0x358637bd
	v_rsq_f32_e32 v210, v210
	s_nop 0
	v_pk_mul_f32 v[200:201], v[184:185], v[210:211] op_sel_hi:[1,0]
	v_pk_fma_f32 v[200:201], v[200:201], v[24:25], v[40:41]
	v_cvt_pk_bf16_f32 v136, v200, v201
	v_pk_mul_f32 v[202:203], v[186:187], v[210:211] op_sel_hi:[1,0]
	v_pk_fma_f32 v[202:203], v[202:203], v[26:27], v[42:43]
	v_cvt_pk_bf16_f32 v137, v202, v203
	v_pk_mul_f32 v[200:201], v[188:189], v[210:211] op_sel_hi:[1,0]
	v_pk_fma_f32 v[200:201], v[200:201], v[28:29], v[44:45]
	v_cvt_pk_bf16_f32 v138, v200, v201
	v_pk_mul_f32 v[202:203], v[190:191], v[210:211] op_sel_hi:[1,0]
	v_pk_fma_f32 v[202:203], v[202:203], v[30:31], v[46:47]
	v_cvt_pk_bf16_f32 v139, v202, v203
	v_pk_mul_f32 v[200:201], v[192:193], v[210:211] op_sel_hi:[1,0]
	v_pk_fma_f32 v[200:201], v[200:201], v[32:33], v[48:49]
	v_cvt_pk_bf16_f32 v140, v200, v201
	v_pk_mul_f32 v[202:203], v[194:195], v[210:211] op_sel_hi:[1,0]
	v_pk_fma_f32 v[202:203], v[202:203], v[34:35], v[50:51]
	v_cvt_pk_bf16_f32 v141, v202, v203
	v_pk_mul_f32 v[200:201], v[196:197], v[210:211] op_sel_hi:[1,0]
	v_pk_fma_f32 v[200:201], v[200:201], v[36:37], v[52:53]
	v_cvt_pk_bf16_f32 v142, v200, v201
	v_pk_mul_f32 v[202:203], v[198:199], v[210:211] op_sel_hi:[1,0]
	v_pk_fma_f32 v[202:203], v[202:203], v[38:39], v[54:55]
	v_cvt_pk_bf16_f32 v143, v202, v203
	global_store_dwordx4 v2, v[136:139], s[78:79]
	global_store_dwordx4 v2, v[140:143], s[78:79] offset:1024
	s_add_i32 s81, s82, 6
	s_cmp_lt_u32 s81, 32
	s_cbranch_scc0 .Lrw_MID_l2_d
	s_add_i32 s81, s80, 6
	s_add_i32 s81, s81, s82
	s_and_b32 s81, s81, 31
	s_lshl_b32 s83, s81, 11
	v_add_u32_e32 v2, s83, v1
	global_load_dwordx4 v[104:107], v2, s[72:73]
	global_load_dwordx4 v[108:111], v2, s[72:73] offset:1024
	global_load_dwordx4 v[112:115], v2, s[74:75]
	global_load_dwordx4 v[116:119], v2, s[74:75] offset:1024
	s_branch .Lrw_MID_l2_e

; __device__ __forceinline__ float bflo(unsigned u) { return __uint_as_float(u << 16); }
; __device__ __forceinline__ float bfhi(unsigned u) { return __uint_as_float(u & 0xffff0000u); }
; __device__ __forceinline__ void phase_rowwise(const void* xsrc_, bool sbf, void* xdst_, bool dbf, const bf16_t* Y, bf16_t* H, const float* mods, int lprev, int iprev, const float* lnpost, float resw, ...
;     ...
;         for (int rr = 0; rr < 32; rr += 2) {
;             const size_t m = (size_t)ch * 32 + rr;
;             f32x4 x[2][4]; u32x2 yr[2][4];
; #pragma unroll
;             for (int r = 0; r < 2; ++r)
; #pragma unroll
;                 for (int j = 0; j < 4; ++j) { if (sbf) { const u32x2 u = xnb[r][j]; x[r][j] = (f32x4){bflo(u.x), bfhi(u.x), bflo(u.y), bfhi(u.y)}; } else x[r][j] = xn[r][j]; yr[r][j] = yn[r][j]; }
;             if (rr + 2 < 32) {
; #pragma unroll
;                 for (int r = 0; r < 2; ++r)
; #pragma unroll
;                     for (int j = 0; j < 4; ++j) { if (sbf) xnb[r][j] = *(const u32x2*)(xsrcb + (m + 2 + r) * DM + 4 * lane + 256 * j); else xn[r][j] = *(const f32x4*)(xsrc + (m + 2 + r) * DM + 4 * lane + 256 * j); if (hasprev) yn[r][j] = *(const u32x2*)(Y + (m + 2 + r) * DM + 4 * lane + 256 * j); } }
;             if (hasprev) {
;                 f32x4 y[2][4]; float ss[2] = {0.f, 0.f};
; #pragma unroll
;                 for (int r = 0; r < 2; ++r)
; #pragma unroll
;                     for (int j = 0; j < 4; ++j) { const u32x2 u = yr[r][j]; y[r][j] = (f32x4){bflo(u.x), bfhi(u.x), bflo(u.y), bfhi(u.y)};
;                         ss[r] += (y[r][j].x * y[r][j].x + y[r][j].y * y[r][j].y) + (y[r][j].z * y[r][j].z + y[r][j].w * y[r][j].w); }
; #pragma unroll
;                 for (int off = 1; off < 64; off <<= 1) { ss[0] += __shfl_xor(ss[0], off); ss[1] += __shfl_xor(ss[1], off); }
; #pragma unroll
;                 for (int r = 0; r < 2; ++r) { const float rs = __builtin_amdgcn_rsqf(ss[r] * (1.f / DM) + EPS);
; #pragma unroll
;                     for (int j = 0; j < 4; ++j) x[r][j] = x[r][j] + gp[j] * (y[r][j] * rs); }
.Lrw_MID_l2_e:
	s_waitcnt vmcnt(32)
	v_lshlrev_b32_e32 v200, 16, v160
	v_and_b32_e32 v201, 0xffff0000, v160
	v_pk_mul_f32 v[204:205], v[200:201], v[200:201]
	v_lshlrev_b32_e32 v202, 16, v161
	v_and_b32_e32 v203, 0xffff0000, v161
	v_pk_mul_f32 v[206:207], v[202:203], v[202:203]
	v_lshlrev_b32_e32 v200, 16, v162
	v_and_b32_e32 v201, 0xffff0000, v162
	v_pk_fma_f32 v[204:205], v[200:201], v[200:201], v[204:205]
	v_lshlrev_b32_e32 v202, 16, v163
	v_and_b32_e32 v203, 0xffff0000, v163
	v_pk_fma_f32 v[206:207], v[202:203], v[202:203], v[206:207]
	v_lshlrev_b32_e32 v200, 16, v164
	v_and_b32_e32 v201, 0xffff0000, v164
	v_pk_fma_f32 v[204:205], v[200:201], v[200:201], v[204:205]
	v_lshlrev_b32_e32 v202, 16, v165
	v_and_b32_e32 v203, 0xffff0000, v165
	v_pk_fma_f32 v[206:207], v[202:203], v[202:203], v[206:207]
	v_lshlrev_b32_e32 v200, 16, v166
	v_and_b32_e32 v201, 0xffff0000, v166
	v_pk_fma_f32 v[204:205], v[200:201], v[200:201], v[204:205]
	v_lshlrev_b32_e32 v202, 16, v167
	v_and_b32_e32 v203, 0xffff0000, v167
	v_pk_fma_f32 v[206:207], v[202:203], v[202:203], v[206:207]
	v_pk_add_f32 v[204:205], v[204:205], v[206:207]
	v_add_f32_e32 v208, v204, v205
	v_lshlrev_b32_e32 v184, 16, v152
	v_and_b32_e32 v185, 0xffff0000, v152
	v_add_f32_dpp v208, v208, v208 quad_perm:[1,0,3,2] row_mask:0xf bank_mask:0xf
	v_lshlrev_b32_e32 v186, 16, v153
	v_and_b32_e32 v187, 0xffff0000, v153
	v_add_f32_dpp v208, v208, v208 quad_perm:[2,3,0,1] row_mask:0xf bank_mask:0xf
	v_lshlrev_b32_e32 v188, 16, v154
	v_and_b32_e32 v189, 0xffff0000, v154
	v_add_f32_dpp v208, v208, v208 row_half_mirror row_mask:0xf bank_mask:0xf
	v_lshlrev_b32_e32 v190, 16, v155
	v_and_b32_e32 v191, 0xffff0000, v155
	v_add_f32_dpp v208, v208, v208 row_mirror row_mask:0xf bank_mask:0xf
	v_lshlrev_b32_e32 v192, 16, v156
	v_and_b32_e32 v193, 0xffff0000, v156
	v_add_f32_dpp v208, v208, v208 row_bcast:15 row_mask:0xa bank_mask:0xf
	v_lshlrev_b32_e32 v194, 16, v157
	v_and_b32_e32 v195, 0xffff0000, v157
	v_add_f32_dpp v208, v208, v208 row_bcast:31 row_mask:0xc bank_mask:0xf
	v_lshlrev_b32_e32 v196, 16, v158
	v_and_b32_e32 v197, 0xffff0000, v158
	v_readlane_b32 s60, v208, 63
	s_nop 1
	v_lshlrev_b32_e32 v198, 16, v159
	v_and_b32_e32 v199, 0xffff0000, v159
	v_mov_b32_e32 v210, s60
	v_fmaak_f32 v210, v210, v212, 0x358637bd
	v_rsq_f32_e32 v210, v210
	s_nop 0
	v_lshlrev_b32_e32 v200, 16, v160
	v_and_b32_e32 v201, 0xffff0000, v160
	v_pk_mul_f32 v[200:201], v[200:201], v[210:211] op_sel_hi:[1,0]
	v_pk_fma_f32 v[184:185], v[8:9], v[200:201], v[184:185]
	v_lshlrev_b32_e32 v202, 16, v161
	v_and_b32_e32 v203, 0xffff0000, v161
	v_pk_mul_f32 v[202:203], v[202:203], v[210:211] op_sel_hi:[1,0]
	v_pk_fma_f32 v[186:187], v[10:11], v[202:203], v[186:187]
	v_lshlrev_b32_e32 v200, 16, v162
	v_and_b32_e32 v201, 0xffff0000, v162
	v_pk_mul_f32 v[200:201], v[200:201], v[210:211] op_sel_hi:[1,0]
	v_pk_fma_f32 v[188:189], v[12:13], v[200:201], v[188:189]
	v_lshlrev_b32_e32 v202, 16, v163
	v_and_b32_e32 v203, 0xffff0000, v163
	v_pk_mul_f32 v[202:203], v[202:203], v[210:211] op_sel_hi:[1,0]
	v_pk_fma_f32 v[190:191], v[14:15], v[202:203], v[190:191]
	v_lshlrev_b32_e32 v200, 16, v164
	v_and_b32_e32 v201, 0xffff0000, v164
	v_pk_mul_f32 v[200:201], v[200:201], v[210:211] op_sel_hi:[1,0]
	v_pk_fma_f32 v[192:193], v[16:17], v[200:201], v[192:193]
	v_lshlrev_b32_e32 v202, 16, v165
	v_and_b32_e32 v203, 0xffff0000, v165
	v_pk_mul_f32 v[202:203], v[202:203], v[210:211] op_sel_hi:[1,0]
	v_pk_fma_f32 v[194:195], v[18:19], v[202:203], v[194:195]
	v_lshlrev_b32_e32 v200, 16, v166
	v_and_b32_e32 v201, 0xffff0000, v166
	v_pk_mul_f32 v[200:201], v[200:201], v[210:211] op_sel_hi:[1,0]
	v_pk_fma_f32 v[196:197], v[20:21], v[200:201], v[196:197]
	v_lshlrev_b32_e32 v202, 16, v167
; __device__ __forceinline__ unsigned cvtpk(float lo, float hi) { f32x2 v = {lo, hi}; bf16x2_t b = __builtin_convertvector(v, bf16x2_t); return __builtin_bit_cast(unsigned, b); }
; __device__ __forceinline__ void phase_rowwise(const void* xsrc_, bool sbf, void* xdst_, bool dbf, const bf16_t* Y, bf16_t* H, const float* mods, int lprev, int iprev, const float* lnpost, float resw, ...
;     ...
;                     for (int j = 0; j < 4; ++j) { if (sbf) xnb[r][j] = *(const u32x2*)(xsrcb + (m + 2 + r) * DM + 4 * lane + 256 * j); else xn[r][j] = *(const f32x4*)(xsrc + (m + 2 + r) * DM + 4 * lane + 256 * j); if (hasprev) yn[r][j] = *(const u32x2*)(Y + (m + 2 + r) * DM + 4 * lane + 256 * j); } }
;     ...
; #pragma unroll
;             for (int r = 0; r < 2; ++r)
; #pragma unroll
;                 for (int j = 0; j < 4; ++j) { if (hasprev) { if (dbf) { u32x2 w; w.x = cvtpk(x[r][j].x, x[r][j].y); w.y = cvtpk(x[r][j].z, x[r][j].w); *(u32x2*)(xdstb + (m + r) * DM + 4 * lane + 256 * j) = w; } else *(f32x4*)(xdst + (m + r) * DM + 4 * lane + 256 * j) = x[r][j]; } }
;             if (hasnext) {
;                 float ss[2] = {0.f, 0.f};
; #pragma unroll
;                 for (int r = 0; r < 2; ++r)
; #pragma unroll
;                     for (int j = 0; j < 4; ++j) ss[r] += (x[r][j].x * x[r][j].x + x[r][j].y * x[r][j].y) + (x[r][j].z * x[r][j].z + x[r][j].w * x[r][j].w);
; #pragma unroll
;                 for (int off = 1; off < 64; off <<= 1) { ss[0] += __shfl_xor(ss[0], off); ss[1] += __shfl_xor(ss[1], off); }
; #pragma unroll
;                 for (int r = 0; r < 2; ++r) { const float rs = __builtin_amdgcn_rsqf(ss[r] * (1.f / DM) + EPS);
; #pragma unroll
;                     for (int j = 0; j < 4; ++j) { const f32x4 h = (x[r][j] * rs) * na[j] + ns[j]; u32x2 w; w.x = cvtpk(h.x, h.y); w.y = cvtpk(h.z, h.w); *(u32x2*)(H + (m + r) * DM + 4 * lane + 256 * j) = w; } }
;             }
	v_and_b32_e32 v203, 0xffff0000, v167
	v_pk_mul_f32 v[202:203], v[202:203], v[210:211] op_sel_hi:[1,0]
	v_pk_fma_f32 v[198:199], v[22:23], v[202:203], v[198:199]
	s_add_i32 s81, s80, 2
	s_add_i32 s81, s81, s82
	s_and_b32 s81, s81, 31
	s_lshl_b32 s83, s81, 11
	v_add_u32_e32 v2, s83, v1
	v_cvt_pk_bf16_f32 v160, v184, v185
	v_cvt_pk_bf16_f32 v161, v186, v187
	v_cvt_pk_bf16_f32 v162, v188, v189
	v_cvt_pk_bf16_f32 v163, v190, v191
	v_cvt_pk_bf16_f32 v164, v192, v193
	v_cvt_pk_bf16_f32 v165, v194, v195
	v_cvt_pk_bf16_f32 v166, v196, v197
	v_cvt_pk_bf16_f32 v167, v198, v199
	global_store_dwordx4 v2, v[160:163], s[76:77]
	global_store_dwordx4 v2, v[164:167], s[76:77] offset:1024
	v_pk_mul_f32 v[204:205], v[184:185], v[184:185]
	v_pk_mul_f32 v[206:207], v[186:187], v[186:187]
	v_pk_fma_f32 v[204:205], v[188:189], v[188:189], v[204:205]
	v_pk_fma_f32 v[206:207], v[190:191], v[190:191], v[206:207]
	v_pk_fma_f32 v[204:205], v[192:193], v[192:193], v[204:205]
	v_pk_fma_f32 v[206:207], v[194:195], v[194:195], v[206:207]
	v_pk_fma_f32 v[204:205], v[196:197], v[196:197], v[204:205]
	v_pk_fma_f32 v[206:207], v[198:199], v[198:199], v[206:207]
	v_pk_add_f32 v[204:205], v[204:205], v[206:207]
	v_add_f32_e32 v208, v204, v205
	s_nop 0
	s_nop 0
	v_add_f32_dpp v208, v208, v208 quad_perm:[1,0,3,2] row_mask:0xf bank_mask:0xf
	s_nop 0
	s_nop 0
	v_add_f32_dpp v208, v208, v208 quad_perm:[2,3,0,1] row_mask:0xf bank_mask:0xf
	s_nop 0
	s_nop 0
	v_add_f32_dpp v208, v208, v208 row_half_mirror row_mask:0xf bank_mask:0xf
	s_nop 0
	s_nop 0
	v_add_f32_dpp v208, v208, v208 row_mirror row_mask:0xf bank_mask:0xf
	s_nop 0
	s_nop 0
	v_add_f32_dpp v208, v208, v208 row_bcast:15 row_mask:0xa bank_mask:0xf
	s_nop 0
	s_nop 0
	v_add_f32_dpp v208, v208, v208 row_bcast:31 row_mask:0xc bank_mask:0xf
	s_nop 0
	s_nop 0
	v_readlane_b32 s60, v208, 63
	s_nop 1
	v_mov_b32_e32 v210, s60
	v_fmaak_f32 v210, v210, v212, 0x358637bd
	v_rsq_f32_e32 v210, v210
	s_nop 0
	v_pk_mul_f32 v[200:201], v[184:185], v[210:211] op_sel_hi:[1,0]
	v_pk_fma_f32 v[200:201], v[200:201], v[24:25], v[40:41]
	v_cvt_pk_bf16_f32 v152, v200, v201
	v_pk_mul_f32 v[202:203], v[186:187], v[210:211] op_sel_hi:[1,0]
	v_pk_fma_f32 v[202:203], v[202:203], v[26:27], v[42:43]
	v_cvt_pk_bf16_f32 v153, v202, v203
	v_pk_mul_f32 v[200:201], v[188:189], v[210:211] op_sel_hi:[1,0]
	v_pk_fma_f32 v[200:201], v[200:201], v[28:29], v[44:45]
	v_cvt_pk_bf16_f32 v154, v200, v201
	v_pk_mul_f32 v[202:203], v[190:191], v[210:211] op_sel_hi:[1,0]
	v_pk_fma_f32 v[202:203], v[202:203], v[30:31], v[46:47]
	v_cvt_pk_bf16_f32 v155, v202, v203
	v_pk_mul_f32 v[200:201], v[192:193], v[210:211] op_sel_hi:[1,0]
	v_pk_fma_f32 v[200:201], v[200:201], v[32:33], v[48:49]
	v_cvt_pk_bf16_f32 v156, v200, v201
	v_pk_mul_f32 v[202:203], v[194:195], v[210:211] op_sel_hi:[1,0]
	v_pk_fma_f32 v[202:203], v[202:203], v[34:35], v[50:51]
	v_cvt_pk_bf16_f32 v157, v202, v203
	v_pk_mul_f32 v[200:201], v[196:197], v[210:211] op_sel_hi:[1,0]
	v_pk_fma_f32 v[200:201], v[200:201], v[36:37], v[52:53]
	v_cvt_pk_bf16_f32 v158, v200, v201
	v_pk_mul_f32 v[202:203], v[198:199], v[210:211] op_sel_hi:[1,0]
	v_pk_fma_f32 v[202:203], v[202:203], v[38:39], v[54:55]
	v_cvt_pk_bf16_f32 v159, v202, v203
	global_store_dwordx4 v2, v[152:155], s[78:79]
	global_store_dwordx4 v2, v[156:159], s[78:79] offset:1024
	s_add_i32 s81, s82, 7
	s_cmp_lt_u32 s81, 32
	s_cbranch_scc0 .Lrw_MID_l3_d
	s_add_i32 s81, s80, 7
	s_add_i32 s81, s81, s82
	s_and_b32 s81, s81, 31
	s_lshl_b32 s83, s81, 11
	v_add_u32_e32 v2, s83, v1
	global_load_dwordx4 v[120:123], v2, s[72:73]
	global_load_dwordx4 v[124:127], v2, s[72:73] offset:1024
	global_load_dwordx4 v[128:131], v2, s[74:75]
	global_load_dwordx4 v[132:135], v2, s[74:75] offset:1024
	s_branch .Lrw_MID_l3_e

; __device__ __forceinline__ void phase_rowwise(const void* xsrc_, bool sbf, void* xdst_, bool dbf, const bf16_t* Y, bf16_t* H, const float* mods, int lprev, int iprev, const float* lnpost, float resw, ...
;     ...
;         for (int rr = 0; rr < 32; rr += 2) {
;             const size_t m = (size_t)ch * 32 + rr;
;             f32x4 x[2][4]; u32x2 yr[2][4];
; #pragma unroll
;             for (int r = 0; r < 2; ++r)
; #pragma unroll
;                 for (int j = 0; j < 4; ++j) { if (sbf) { const u32x2 u = xnb[r][j]; x[r][j] = (f32x4){bflo(u.x), bfhi(u.x), bflo(u.y), bfhi(u.y)}; } else x[r][j] = xn[r][j]; yr[r][j] = yn[r][j]; }
;             if (rr + 2 < 32) {
; #pragma unroll
;                 for (int r = 0; r < 2; ++r)
; #pragma unroll
;                     for (int j = 0; j < 4; ++j) { if (sbf) xnb[r][j] = *(const u32x2*)(xsrcb + (m + 2 + r) * DM + 4 * lane + 256 * j); else xn[r][j] = *(const f32x4*)(xsrc + (m + 2 + r) * DM + 4 * lane + 256 * j); if (hasprev) yn[r][j] = *(const u32x2*)(Y + (m + 2 + r) * DM + 4 * lane + 256 * j); } }
;             if (hasprev) {
;                 f32x4 y[2][4]; float ss[2] = {0.f, 0.f};
; #pragma unroll
;                 for (int r = 0; r < 2; ++r)
; #pragma unroll
;                     for (int j = 0; j < 4; ++j) { const u32x2 u = yr[r][j]; y[r][j] = (f32x4){bflo(u.x), bfhi(u.x), bflo(u.y), bfhi(u.y)};
;                         ss[r] += (y[r][j].x * y[r][j].x + y[r][j].y * y[r][j].y) + (y[r][j].z * y[r][j].z + y[r][j].w * y[r][j].w); }
; #pragma unroll
;                 for (int off = 1; off < 64; off <<= 1) { ss[0] += __shfl_xor(ss[0], off); ss[1] += __shfl_xor(ss[1], off); }
; #pragma unroll
;                 for (int r = 0; r < 2; ++r) { const float rs = __builtin_amdgcn_rsqf(ss[r] * (1.f / DM) + EPS);
; #pragma unroll
;                     for (int j = 0; j < 4; ++j) x[r][j] = x[r][j] + gp[j] * (y[r][j] * rs); }
;             }
; #pragma unroll
;             for (int r = 0; r < 2; ++r)
; #pragma unroll
;                 for (int j = 0; j < 4; ++j) { if (hasprev) { if (dbf) { u32x2 w; w.x = cvtpk(x[r][j].x, x[r][j].y); w.y = cvtpk(x[r][j].z, x[r][j].w); *(u32x2*)(xdstb + (m + r) * DM + 4 * lane + 256 * j) = w; } else *(f32x4*)(xdst + (m + r) * DM + 4 * lane + 256 * j) = x[r][j]; } }
;             if (hasnext) {
;                 float ss[2] = {0.f, 0.f};
; #pragma unroll
;                 for (int r = 0; r < 2; ++r)
.Lrw_MID_l3_e:
	s_waitcnt vmcnt(32)
	v_lshlrev_b32_e32 v200, 16, v64
	v_and_b32_e32 v201, 0xffff0000, v64
	v_pk_mul_f32 v[204:205], v[200:201], v[200:201]
	v_lshlrev_b32_e32 v202, 16, v65
	v_and_b32_e32 v203, 0xffff0000, v65
	v_pk_mul_f32 v[206:207], v[202:203], v[202:203]
	v_lshlrev_b32_e32 v200, 16, v66
	v_and_b32_e32 v201, 0xffff0000, v66
	v_pk_fma_f32 v[204:205], v[200:201], v[200:201], v[204:205]
	v_lshlrev_b32_e32 v202, 16, v67
	v_and_b32_e32 v203, 0xffff0000, v67
	v_pk_fma_f32 v[206:207], v[202:203], v[202:203], v[206:207]
	v_lshlrev_b32_e32 v200, 16, v68
	v_and_b32_e32 v201, 0xffff0000, v68
	v_pk_fma_f32 v[204:205], v[200:201], v[200:201], v[204:205]
	v_lshlrev_b32_e32 v202, 16, v69
	v_and_b32_e32 v203, 0xffff0000, v69
	v_pk_fma_f32 v[206:207], v[202:203], v[202:203], v[206:207]
	v_lshlrev_b32_e32 v200, 16, v70
	v_and_b32_e32 v201, 0xffff0000, v70
	v_pk_fma_f32 v[204:205], v[200:201], v[200:201], v[204:205]
	v_lshlrev_b32_e32 v202, 16, v71
	v_and_b32_e32 v203, 0xffff0000, v71
	v_pk_fma_f32 v[206:207], v[202:203], v[202:203], v[206:207]
	v_pk_add_f32 v[204:205], v[204:205], v[206:207]
	v_add_f32_e32 v208, v204, v205
	v_lshlrev_b32_e32 v184, 16, v56
	v_and_b32_e32 v185, 0xffff0000, v56
	v_add_f32_dpp v208, v208, v208 quad_perm:[1,0,3,2] row_mask:0xf bank_mask:0xf
	v_lshlrev_b32_e32 v186, 16, v57
	v_and_b32_e32 v187, 0xffff0000, v57
	v_add_f32_dpp v208, v208, v208 quad_perm:[2,3,0,1] row_mask:0xf bank_mask:0xf
	v_lshlrev_b32_e32 v188, 16, v58
	v_and_b32_e32 v189, 0xffff0000, v58
	v_add_f32_dpp v208, v208, v208 row_half_mirror row_mask:0xf bank_mask:0xf
	v_lshlrev_b32_e32 v190, 16, v59
	v_and_b32_e32 v191, 0xffff0000, v59
	v_add_f32_dpp v208, v208, v208 row_mirror row_mask:0xf bank_mask:0xf
	v_lshlrev_b32_e32 v192, 16, v60
	v_and_b32_e32 v193, 0xffff0000, v60
	v_add_f32_dpp v208, v208, v208 row_bcast:15 row_mask:0xa bank_mask:0xf
	v_lshlrev_b32_e32 v194, 16, v61
	v_and_b32_e32 v195, 0xffff0000, v61
	v_add_f32_dpp v208, v208, v208 row_bcast:31 row_mask:0xc bank_mask:0xf
	v_lshlrev_b32_e32 v196, 16, v62
	v_and_b32_e32 v197, 0xffff0000, v62
	v_readlane_b32 s60, v208, 63
	s_nop 1
	v_lshlrev_b32_e32 v198, 16, v63
	v_and_b32_e32 v199, 0xffff0000, v63
	v_mov_b32_e32 v210, s60
	v_fmaak_f32 v210, v210, v212, 0x358637bd
	v_rsq_f32_e32 v210, v210
	s_nop 0
	v_lshlrev_b32_e32 v200, 16, v64
	v_and_b32_e32 v201, 0xffff0000, v64
	v_pk_mul_f32 v[200:201], v[200:201], v[210:211] op_sel_hi:[1,0]
	v_pk_fma_f32 v[184:185], v[8:9], v[200:201], v[184:185]
	v_lshlrev_b32_e32 v202, 16, v65
	v_and_b32_e32 v203, 0xffff0000, v65
	v_pk_mul_f32 v[202:203], v[202:203], v[210:211] op_sel_hi:[1,0]
	v_pk_fma_f32 v[186:187], v[10:11], v[202:203], v[186:187]
	v_lshlrev_b32_e32 v200, 16, v66
	v_and_b32_e32 v201, 0xffff0000, v66
	v_pk_mul_f32 v[200:201], v[200:201], v[210:211] op_sel_hi:[1,0]
	v_pk_fma_f32 v[188:189], v[12:13], v[200:201], v[188:189]
	v_lshlrev_b32_e32 v202, 16, v67
	v_and_b32_e32 v203, 0xffff0000, v67
	v_pk_mul_f32 v[202:203], v[202:203], v[210:211] op_sel_hi:[1,0]
	v_pk_fma_f32 v[190:191], v[14:15], v[202:203], v[190:191]
	v_lshlrev_b32_e32 v200, 16, v68
	v_and_b32_e32 v201, 0xffff0000, v68
	v_pk_mul_f32 v[200:201], v[200:201], v[210:211] op_sel_hi:[1,0]
	v_pk_fma_f32 v[192:193], v[16:17], v[200:201], v[192:193]
	v_lshlrev_b32_e32 v202, 16, v69
	v_and_b32_e32 v203, 0xffff0000, v69
	v_pk_mul_f32 v[202:203], v[202:203], v[210:211] op_sel_hi:[1,0]
	v_pk_fma_f32 v[194:195], v[18:19], v[202:203], v[194:195]
	v_lshlrev_b32_e32 v200, 16, v70
	v_and_b32_e32 v201, 0xffff0000, v70
	v_pk_mul_f32 v[200:201], v[200:201], v[210:211] op_sel_hi:[1,0]
	v_pk_fma_f32 v[196:197], v[20:21], v[200:201], v[196:197]
	v_lshlrev_b32_e32 v202, 16, v71
	v_and_b32_e32 v203, 0xffff0000, v71
	v_pk_mul_f32 v[202:203], v[202:203], v[210:211] op_sel_hi:[1,0]
	v_pk_fma_f32 v[198:199], v[22:23], v[202:203], v[198:199]
	s_add_i32 s81, s80, 3
	s_add_i32 s81, s81, s82
	s_and_b32 s81, s81, 31
	s_lshl_b32 s83, s81, 11
	v_add_u32_e32 v2, s83, v1
	v_cvt_pk_bf16_f32 v64, v184, v185
	v_cvt_pk_bf16_f32 v65, v186, v187
	v_cvt_pk_bf16_f32 v66, v188, v189
	v_cvt_pk_bf16_f32 v67, v190, v191
	v_cvt_pk_bf16_f32 v68, v192, v193
	v_cvt_pk_bf16_f32 v69, v194, v195
	v_cvt_pk_bf16_f32 v70, v196, v197
	v_cvt_pk_bf16_f32 v71, v198, v199
	global_store_dwordx4 v2, v[64:67], s[76:77]
	global_store_dwordx4 v2, v[68:71], s[76:77] offset:1024
	v_pk_mul_f32 v[204:205], v[184:185], v[184:185]
	v_pk_mul_f32 v[206:207], v[186:187], v[186:187]
	v_pk_fma_f32 v[204:205], v[188:189], v[188:189], v[204:205]
	v_pk_fma_f32 v[206:207], v[190:191], v[190:191], v[206:207]
	v_pk_fma_f32 v[204:205], v[192:193], v[192:193], v[204:205]
	v_pk_fma_f32 v[206:207], v[194:195], v[194:195], v[206:207]
	v_pk_fma_f32 v[204:205], v[196:197], v[196:197], v[204:205]
	v_pk_fma_f32 v[206:207], v[198:199], v[198:199], v[206:207]
	v_pk_add_f32 v[204:205], v[204:205], v[206:207]
	v_add_f32_e32 v208, v204, v205
	s_nop 0
	s_nop 0
	v_add_f32_dpp v208, v208, v208 quad_perm:[1,0,3,2] row_mask:0xf bank_mask:0xf
	s_nop 0
	s_nop 0
	v_add_f32_dpp v208, v208, v208 quad_perm:[2,3,0,1] row_mask:0xf bank_mask:0xf
	s_nop 0
	s_nop 0
	v_add_f32_dpp v208, v208, v208 row_half_mirror row_mask:0xf bank_mask:0xf
	s_nop 0
	s_nop 0
	v_add_f32_dpp v208, v208, v208 row_mirror row_mask:0xf bank_mask:0xf
	s_nop 0
	s_nop 0
	v_add_f32_dpp v208, v208, v208 row_bcast:15 row_mask:0xa bank_mask:0xf
	s_nop 0
	s_nop 0
	v_add_f32_dpp v208, v208, v208 row_bcast:31 row_mask:0xc bank_mask:0xf
	s_nop 0
	s_nop 0
	v_readlane_b32 s60, v208, 63
	s_nop 1
	v_mov_b32_e32 v210, s60
	v_fmaak_f32 v210, v210, v212, 0x358637bd
	v_rsq_f32_e32 v210, v210
	s_nop 0
	v_pk_mul_f32 v[200:201], v[184:185], v[210:211] op_sel_hi:[1,0]
	v_pk_fma_f32 v[200:201], v[200:201], v[24:25], v[40:41]
	v_cvt_pk_bf16_f32 v56, v200, v201
	v_pk_mul_f32 v[202:203], v[186:187], v[210:211] op_sel_hi:[1,0]
	v_pk_fma_f32 v[202:203], v[202:203], v[26:27], v[42:43]
	v_cvt_pk_bf16_f32 v57, v202, v203
	v_pk_mul_f32 v[200:201], v[188:189], v[210:211] op_sel_hi:[1,0]
	v_pk_fma_f32 v[200:201], v[200:201], v[28:29], v[44:45]
	v_cvt_pk_bf16_f32 v58, v200, v201
	v_pk_mul_f32 v[202:203], v[190:191], v[210:211] op_sel_hi:[1,0]
	v_pk_fma_f32 v[202:203], v[202:203], v[30:31], v[46:47]
	v_cvt_pk_bf16_f32 v59, v202, v203
	v_pk_mul_f32 v[200:201], v[192:193], v[210:211] op_sel_hi:[1,0]
	v_pk_fma_f32 v[200:201], v[200:201], v[32:33], v[48:49]
	v_cvt_pk_bf16_f32 v60, v200, v201
	v_pk_mul_f32 v[202:203], v[194:195], v[210:211] op_sel_hi:[1,0]
	v_pk_fma_f32 v[202:203], v[202:203], v[34:35], v[50:51]
	v_cvt_pk_bf16_f32 v61, v202, v203
	v_pk_mul_f32 v[200:201], v[196:197], v[210:211] op_sel_hi:[1,0]
	v_pk_fma_f32 v[200:201], v[200:201], v[36:37], v[52:53]
	v_cvt_pk_bf16_f32 v62, v200, v201
	v_pk_mul_f32 v[202:203], v[198:199], v[210:211] op_sel_hi:[1,0]
	v_pk_fma_f32 v[202:203], v[202:203], v[38:39], v[54:55]
	v_cvt_pk_bf16_f32 v63, v202, v203
	global_store_dwordx4 v2, v[56:59], s[78:79]
	global_store_dwordx4 v2, v[60:63], s[78:79] offset:1024
	s_add_i32 s81, s82, 8
	s_cmp_lt_u32 s81, 32
	s_cbranch_scc0 .Lrw_MID_l4_d
; __device__ __forceinline__ void phase_rowwise(const void* xsrc_, bool sbf, void* xdst_, bool dbf, const bf16_t* Y, bf16_t* H, const float* mods, int lprev, int iprev, const float* lnpost, float resw, ...
;     ...
;                     for (int j = 0; j < 4; ++j) { if (sbf) xnb[r][j] = *(const u32x2*)(xsrcb + (m + 2 + r) * DM + 4 * lane + 256 * j); else xn[r][j] = *(const f32x4*)(xsrc + (m + 2 + r) * DM + 4 * lane + 256 * j); if (hasprev) yn[r][j] = *(const u32x2*)(Y + (m + 2 + r) * DM + 4 * lane + 256 * j); } }
	s_add_i32 s81, s80, 8
	s_add_i32 s81, s81, s82
	s_and_b32 s81, s81, 31
	s_lshl_b32 s83, s81, 11
	v_add_u32_e32 v2, s83, v1
	global_load_dwordx4 v[136:139], v2, s[72:73]
	global_load_dwordx4 v[140:143], v2, s[72:73] offset:1024
	global_load_dwordx4 v[144:147], v2, s[74:75]
	global_load_dwordx4 v[148:151], v2, s[74:75] offset:1024
	s_branch .Lrw_MID_l4_e

; __device__ __forceinline__ void phase_rowwise(const void* xsrc_, bool sbf, void* xdst_, bool dbf, const bf16_t* Y, bf16_t* H, const float* mods, int lprev, int iprev, const float* lnpost, float resw, ...
;     ...
;         for (int rr = 0; rr < 32; rr += 2) {
;             const size_t m = (size_t)ch * 32 + rr;
;             f32x4 x[2][4]; u32x2 yr[2][4];
; #pragma unroll
;             for (int r = 0; r < 2; ++r)
; #pragma unroll
;                 for (int j = 0; j < 4; ++j) { if (sbf) { const u32x2 u = xnb[r][j]; x[r][j] = (f32x4){bflo(u.x), bfhi(u.x), bflo(u.y), bfhi(u.y)}; } else x[r][j] = xn[r][j]; yr[r][j] = yn[r][j]; }
;             if (rr + 2 < 32) {
; #pragma unroll
;                 for (int r = 0; r < 2; ++r)
; #pragma unroll
;                     for (int j = 0; j < 4; ++j) { if (sbf) xnb[r][j] = *(const u32x2*)(xsrcb + (m + 2 + r) * DM + 4 * lane + 256 * j); else xn[r][j] = *(const f32x4*)(xsrc + (m + 2 + r) * DM + 4 * lane + 256 * j); if (hasprev) yn[r][j] = *(const u32x2*)(Y + (m + 2 + r) * DM + 4 * lane + 256 * j); } }
;             if (hasprev) {
;                 f32x4 y[2][4]; float ss[2] = {0.f, 0.f};
; #pragma unroll
;                 for (int r = 0; r < 2; ++r)
; #pragma unroll
;                     for (int j = 0; j < 4; ++j) { const u32x2 u = yr[r][j]; y[r][j] = (f32x4){bflo(u.x), bfhi(u.x), bflo(u.y), bfhi(u.y)};
;                         ss[r] += (y[r][j].x * y[r][j].x + y[r][j].y * y[r][j].y) + (y[r][j].z * y[r][j].z + y[r][j].w * y[r][j].w); }
; #pragma unroll
;                 for (int off = 1; off < 64; off <<= 1) { ss[0] += __shfl_xor(ss[0], off); ss[1] += __shfl_xor(ss[1], off); }
; #pragma unroll
;                 for (int r = 0; r < 2; ++r) { const float rs = __builtin_amdgcn_rsqf(ss[r] * (1.f / DM) + EPS);
; #pragma unroll
;                     for (int j = 0; j < 4; ++j) x[r][j] = x[r][j] + gp[j] * (y[r][j] * rs); }
;             }
; #pragma unroll
;             for (int r = 0; r < 2; ++r)
; #pragma unroll
;                 for (int j = 0; j < 4; ++j) { if (hasprev) { if (dbf) { u32x2 w; w.x = cvtpk(x[r][j].x, x[r][j].y); w.y = cvtpk(x[r][j].z, x[r][j].w); *(u32x2*)(xdstb + (m + r) * DM + 4 * lane + 256 * j) = w; } else *(f32x4*)(xdst + (m + r) * DM + 4 * lane + 256 * j) = x[r][j]; } }
;             if (hasnext) {
;                 float ss[2] = {0.f, 0.f};
; #pragma unroll
;                 for (int r = 0; r < 2; ++r)
.Lrw_MID_l4_e:
	s_waitcnt vmcnt(32)
	v_lshlrev_b32_e32 v200, 16, v80
	v_and_b32_e32 v201, 0xffff0000, v80
	v_pk_mul_f32 v[204:205], v[200:201], v[200:201]
	v_lshlrev_b32_e32 v202, 16, v81
	v_and_b32_e32 v203, 0xffff0000, v81
	v_pk_mul_f32 v[206:207], v[202:203], v[202:203]
	v_lshlrev_b32_e32 v200, 16, v82
	v_and_b32_e32 v201, 0xffff0000, v82
	v_pk_fma_f32 v[204:205], v[200:201], v[200:201], v[204:205]
	v_lshlrev_b32_e32 v202, 16, v83
	v_and_b32_e32 v203, 0xffff0000, v83
	v_pk_fma_f32 v[206:207], v[202:203], v[202:203], v[206:207]
	v_lshlrev_b32_e32 v200, 16, v84
	v_and_b32_e32 v201, 0xffff0000, v84
	v_pk_fma_f32 v[204:205], v[200:201], v[200:201], v[204:205]
	v_lshlrev_b32_e32 v202, 16, v85
	v_and_b32_e32 v203, 0xffff0000, v85
	v_pk_fma_f32 v[206:207], v[202:203], v[202:203], v[206:207]
	v_lshlrev_b32_e32 v200, 16, v86
	v_and_b32_e32 v201, 0xffff0000, v86
	v_pk_fma_f32 v[204:205], v[200:201], v[200:201], v[204:205]
	v_lshlrev_b32_e32 v202, 16, v87
	v_and_b32_e32 v203, 0xffff0000, v87
	v_pk_fma_f32 v[206:207], v[202:203], v[202:203], v[206:207]
	v_pk_add_f32 v[204:205], v[204:205], v[206:207]
	v_add_f32_e32 v208, v204, v205
	v_lshlrev_b32_e32 v184, 16, v72
	v_and_b32_e32 v185, 0xffff0000, v72
	v_add_f32_dpp v208, v208, v208 quad_perm:[1,0,3,2] row_mask:0xf bank_mask:0xf
	v_lshlrev_b32_e32 v186, 16, v73
	v_and_b32_e32 v187, 0xffff0000, v73
	v_add_f32_dpp v208, v208, v208 quad_perm:[2,3,0,1] row_mask:0xf bank_mask:0xf
	v_lshlrev_b32_e32 v188, 16, v74
	v_and_b32_e32 v189, 0xffff0000, v74
	v_add_f32_dpp v208, v208, v208 row_half_mirror row_mask:0xf bank_mask:0xf
	v_lshlrev_b32_e32 v190, 16, v75
	v_and_b32_e32 v191, 0xffff0000, v75
	v_add_f32_dpp v208, v208, v208 row_mirror row_mask:0xf bank_mask:0xf
	v_lshlrev_b32_e32 v192, 16, v76
	v_and_b32_e32 v193, 0xffff0000, v76
	v_add_f32_dpp v208, v208, v208 row_bcast:15 row_mask:0xa bank_mask:0xf
	v_lshlrev_b32_e32 v194, 16, v77
	v_and_b32_e32 v195, 0xffff0000, v77
	v_add_f32_dpp v208, v208, v208 row_bcast:31 row_mask:0xc bank_mask:0xf
	v_lshlrev_b32_e32 v196, 16, v78
	v_and_b32_e32 v197, 0xffff0000, v78
	v_readlane_b32 s60, v208, 63
	s_nop 1
	v_lshlrev_b32_e32 v198, 16, v79
	v_and_b32_e32 v199, 0xffff0000, v79
	v_mov_b32_e32 v210, s60
	v_fmaak_f32 v210, v210, v212, 0x358637bd
	v_rsq_f32_e32 v210, v210
	s_nop 0
	v_lshlrev_b32_e32 v200, 16, v80
	v_and_b32_e32 v201, 0xffff0000, v80
	v_pk_mul_f32 v[200:201], v[200:201], v[210:211] op_sel_hi:[1,0]
	v_pk_fma_f32 v[184:185], v[8:9], v[200:201], v[184:185]
	v_lshlrev_b32_e32 v202, 16, v81
	v_and_b32_e32 v203, 0xffff0000, v81
	v_pk_mul_f32 v[202:203], v[202:203], v[210:211] op_sel_hi:[1,0]
	v_pk_fma_f32 v[186:187], v[10:11], v[202:203], v[186:187]
	v_lshlrev_b32_e32 v200, 16, v82
	v_and_b32_e32 v201, 0xffff0000, v82
	v_pk_mul_f32 v[200:201], v[200:201], v[210:211] op_sel_hi:[1,0]
	v_pk_fma_f32 v[188:189], v[12:13], v[200:201], v[188:189]
	v_lshlrev_b32_e32 v202, 16, v83
	v_and_b32_e32 v203, 0xffff0000, v83
	v_pk_mul_f32 v[202:203], v[202:203], v[210:211] op_sel_hi:[1,0]
	v_pk_fma_f32 v[190:191], v[14:15], v[202:203], v[190:191]
	v_lshlrev_b32_e32 v200, 16, v84
	v_and_b32_e32 v201, 0xffff0000, v84
	v_pk_mul_f32 v[200:201], v[200:201], v[210:211] op_sel_hi:[1,0]
	v_pk_fma_f32 v[192:193], v[16:17], v[200:201], v[192:193]
	v_lshlrev_b32_e32 v202, 16, v85
	v_and_b32_e32 v203, 0xffff0000, v85
	v_pk_mul_f32 v[202:203], v[202:203], v[210:211] op_sel_hi:[1,0]
	v_pk_fma_f32 v[194:195], v[18:19], v[202:203], v[194:195]
	v_lshlrev_b32_e32 v200, 16, v86
	v_and_b32_e32 v201, 0xffff0000, v86
	v_pk_mul_f32 v[200:201], v[200:201], v[210:211] op_sel_hi:[1,0]
	v_pk_fma_f32 v[196:197], v[20:21], v[200:201], v[196:197]
	v_lshlrev_b32_e32 v202, 16, v87
	v_and_b32_e32 v203, 0xffff0000, v87
	v_pk_mul_f32 v[202:203], v[202:203], v[210:211] op_sel_hi:[1,0]
	v_pk_fma_f32 v[198:199], v[22:23], v[202:203], v[198:199]
	s_add_i32 s81, s80, 4
	s_add_i32 s81, s81, s82
	s_and_b32 s81, s81, 31
	s_lshl_b32 s83, s81, 11
	v_add_u32_e32 v2, s83, v1
	v_cvt_pk_bf16_f32 v80, v184, v185
	v_cvt_pk_bf16_f32 v81, v186, v187
	v_cvt_pk_bf16_f32 v82, v188, v189
	v_cvt_pk_bf16_f32 v83, v190, v191
	v_cvt_pk_bf16_f32 v84, v192, v193
	v_cvt_pk_bf16_f32 v85, v194, v195
	v_cvt_pk_bf16_f32 v86, v196, v197
	v_cvt_pk_bf16_f32 v87, v198, v199
	global_store_dwordx4 v2, v[80:83], s[76:77]
	global_store_dwordx4 v2, v[84:87], s[76:77] offset:1024
	v_pk_mul_f32 v[204:205], v[184:185], v[184:185]
	v_pk_mul_f32 v[206:207], v[186:187], v[186:187]
	v_pk_fma_f32 v[204:205], v[188:189], v[188:189], v[204:205]
	v_pk_fma_f32 v[206:207], v[190:191], v[190:191], v[206:207]
	v_pk_fma_f32 v[204:205], v[192:193], v[192:193], v[204:205]
	v_pk_fma_f32 v[206:207], v[194:195], v[194:195], v[206:207]
	v_pk_fma_f32 v[204:205], v[196:197], v[196:197], v[204:205]
	v_pk_fma_f32 v[206:207], v[198:199], v[198:199], v[206:207]
	v_pk_add_f32 v[204:205], v[204:205], v[206:207]
	v_add_f32_e32 v208, v204, v205
	s_nop 0
	s_nop 0
	v_add_f32_dpp v208, v208, v208 quad_perm:[1,0,3,2] row_mask:0xf bank_mask:0xf
	s_nop 0
	s_nop 0
	v_add_f32_dpp v208, v208, v208 quad_perm:[2,3,0,1] row_mask:0xf bank_mask:0xf
	s_nop 0
	s_nop 0
	v_add_f32_dpp v208, v208, v208 row_half_mirror row_mask:0xf bank_mask:0xf
	s_nop 0
	s_nop 0
	v_add_f32_dpp v208, v208, v208 row_mirror row_mask:0xf bank_mask:0xf
	s_nop 0
	s_nop 0
	v_add_f32_dpp v208, v208, v208 row_bcast:15 row_mask:0xa bank_mask:0xf
	s_nop 0
	s_nop 0
	v_add_f32_dpp v208, v208, v208 row_bcast:31 row_mask:0xc bank_mask:0xf
	s_nop 0
	s_nop 0
	v_readlane_b32 s60, v208, 63
	s_nop 1
	v_mov_b32_e32 v210, s60
	v_fmaak_f32 v210, v210, v212, 0x358637bd
	v_rsq_f32_e32 v210, v210
	s_nop 0
	v_pk_mul_f32 v[200:201], v[184:185], v[210:211] op_sel_hi:[1,0]
	v_pk_fma_f32 v[200:201], v[200:201], v[24:25], v[40:41]
	v_cvt_pk_bf16_f32 v72, v200, v201
	v_pk_mul_f32 v[202:203], v[186:187], v[210:211] op_sel_hi:[1,0]
	v_pk_fma_f32 v[202:203], v[202:203], v[26:27], v[42:43]
	v_cvt_pk_bf16_f32 v73, v202, v203
	v_pk_mul_f32 v[200:201], v[188:189], v[210:211] op_sel_hi:[1,0]
	v_pk_fma_f32 v[200:201], v[200:201], v[28:29], v[44:45]
	v_cvt_pk_bf16_f32 v74, v200, v201
	v_pk_mul_f32 v[202:203], v[190:191], v[210:211] op_sel_hi:[1,0]
	v_pk_fma_f32 v[202:203], v[202:203], v[30:31], v[46:47]
	v_cvt_pk_bf16_f32 v75, v202, v203
	v_pk_mul_f32 v[200:201], v[192:193], v[210:211] op_sel_hi:[1,0]
	v_pk_fma_f32 v[200:201], v[200:201], v[32:33], v[48:49]
	v_cvt_pk_bf16_f32 v76, v200, v201
	v_pk_mul_f32 v[202:203], v[194:195], v[210:211] op_sel_hi:[1,0]
	v_pk_fma_f32 v[202:203], v[202:203], v[34:35], v[50:51]
	v_cvt_pk_bf16_f32 v77, v202, v203
	v_pk_mul_f32 v[200:201], v[196:197], v[210:211] op_sel_hi:[1,0]
	v_pk_fma_f32 v[200:201], v[200:201], v[36:37], v[52:53]
	v_cvt_pk_bf16_f32 v78, v200, v201
	v_pk_mul_f32 v[202:203], v[198:199], v[210:211] op_sel_hi:[1,0]
	v_pk_fma_f32 v[202:203], v[202:203], v[38:39], v[54:55]
	v_cvt_pk_bf16_f32 v79, v202, v203
	global_store_dwordx4 v2, v[72:75], s[78:79]
	global_store_dwordx4 v2, v[76:79], s[78:79] offset:1024
	s_add_i32 s81, s82, 9
	s_cmp_lt_u32 s81, 32
	s_cbranch_scc0 .Lrw_MID_l5_d
; __device__ __forceinline__ void phase_rowwise(const void* xsrc_, bool sbf, void* xdst_, bool dbf, const bf16_t* Y, bf16_t* H, const float* mods, int lprev, int iprev, const float* lnpost, float resw, ...
;     ...
;                     for (int j = 0; j < 4; ++j) { if (sbf) xnb[r][j] = *(const u32x2*)(xsrcb + (m + 2 + r) * DM + 4 * lane + 256 * j); else xn[r][j] = *(const f32x4*)(xsrc + (m + 2 + r) * DM + 4 * lane + 256 * j); if (hasprev) yn[r][j] = *(const u32x2*)(Y + (m + 2 + r) * DM + 4 * lane + 256 * j); } }
	s_add_i32 s81, s80, 9
	s_add_i32 s81, s81, s82
	s_and_b32 s81, s81, 31
	s_lshl_b32 s83, s81, 11
	v_add_u32_e32 v2, s83, v1
	global_load_dwordx4 v[152:155], v2, s[72:73]
	global_load_dwordx4 v[156:159], v2, s[72:73] offset:1024
	global_load_dwordx4 v[160:163], v2, s[74:75]
	global_load_dwordx4 v[164:167], v2, s[74:75] offset:1024
	s_branch .Lrw_MID_l5_e

; __device__ __forceinline__ float bflo(unsigned u) { return __uint_as_float(u << 16); }
; __device__ __forceinline__ float bfhi(unsigned u) { return __uint_as_float(u & 0xffff0000u); }
; __device__ __forceinline__ void phase_rowwise(const void* xsrc_, bool sbf, void* xdst_, bool dbf, const bf16_t* Y, bf16_t* H, const float* mods, int lprev, int iprev, const float* lnpost, float resw, ...
;     ...
;         for (int rr = 0; rr < 32; rr += 2) {
;             const size_t m = (size_t)ch * 32 + rr;
;             f32x4 x[2][4]; u32x2 yr[2][4];
; #pragma unroll
;             for (int r = 0; r < 2; ++r)
; #pragma unroll
;                 for (int j = 0; j < 4; ++j) { if (sbf) { const u32x2 u = xnb[r][j]; x[r][j] = (f32x4){bflo(u.x), bfhi(u.x), bflo(u.y), bfhi(u.y)}; } else x[r][j] = xn[r][j]; yr[r][j] = yn[r][j]; }
;             if (rr + 2 < 32) {
; #pragma unroll
;                 for (int r = 0; r < 2; ++r)
; #pragma unroll
;                     for (int j = 0; j < 4; ++j) { if (sbf) xnb[r][j] = *(const u32x2*)(xsrcb + (m + 2 + r) * DM + 4 * lane + 256 * j); else xn[r][j] = *(const f32x4*)(xsrc + (m + 2 + r) * DM + 4 * lane + 256 * j); if (hasprev) yn[r][j] = *(const u32x2*)(Y + (m + 2 + r) * DM + 4 * lane + 256 * j); } }
;             if (hasprev) {
;                 f32x4 y[2][4]; float ss[2] = {0.f, 0.f};
; #pragma unroll
;                 for (int r = 0; r < 2; ++r)
; #pragma unroll
;                     for (int j = 0; j < 4; ++j) { const u32x2 u = yr[r][j]; y[r][j] = (f32x4){bflo(u.x), bfhi(u.x), bflo(u.y), bfhi(u.y)};
;                         ss[r] += (y[r][j].x * y[r][j].x + y[r][j].y * y[r][j].y) + (y[r][j].z * y[r][j].z + y[r][j].w * y[r][j].w); }
; #pragma unroll
;                 for (int off = 1; off < 64; off <<= 1) { ss[0] += __shfl_xor(ss[0], off); ss[1] += __shfl_xor(ss[1], off); }
; #pragma unroll
;                 for (int r = 0; r < 2; ++r) { const float rs = __builtin_amdgcn_rsqf(ss[r] * (1.f / DM) + EPS);
; #pragma unroll
;                     for (int j = 0; j < 4; ++j) x[r][j] = x[r][j] + gp[j] * (y[r][j] * rs); }
.Lrw_MID_l5_e:
	s_waitcnt vmcnt(32)
	v_lshlrev_b32_e32 v200, 16, v96
	v_and_b32_e32 v201, 0xffff0000, v96
	v_pk_mul_f32 v[204:205], v[200:201], v[200:201]
	v_lshlrev_b32_e32 v202, 16, v97
	v_and_b32_e32 v203, 0xffff0000, v97
	v_pk_mul_f32 v[206:207], v[202:203], v[202:203]
	v_lshlrev_b32_e32 v200, 16, v98
	v_and_b32_e32 v201, 0xffff0000, v98
	v_pk_fma_f32 v[204:205], v[200:201], v[200:201], v[204:205]
	v_lshlrev_b32_e32 v202, 16, v99
	v_and_b32_e32 v203, 0xffff0000, v99
	v_pk_fma_f32 v[206:207], v[202:203], v[202:203], v[206:207]
	v_lshlrev_b32_e32 v200, 16, v100
	v_and_b32_e32 v201, 0xffff0000, v100
	v_pk_fma_f32 v[204:205], v[200:201], v[200:201], v[204:205]
	v_lshlrev_b32_e32 v202, 16, v101
	v_and_b32_e32 v203, 0xffff0000, v101
	v_pk_fma_f32 v[206:207], v[202:203], v[202:203], v[206:207]
	v_lshlrev_b32_e32 v200, 16, v102
	v_and_b32_e32 v201, 0xffff0000, v102
	v_pk_fma_f32 v[204:205], v[200:201], v[200:201], v[204:205]
	v_lshlrev_b32_e32 v202, 16, v103
	v_and_b32_e32 v203, 0xffff0000, v103
	v_pk_fma_f32 v[206:207], v[202:203], v[202:203], v[206:207]
	v_pk_add_f32 v[204:205], v[204:205], v[206:207]
	v_add_f32_e32 v208, v204, v205
	v_lshlrev_b32_e32 v184, 16, v88
	v_and_b32_e32 v185, 0xffff0000, v88
	v_add_f32_dpp v208, v208, v208 quad_perm:[1,0,3,2] row_mask:0xf bank_mask:0xf
	v_lshlrev_b32_e32 v186, 16, v89
	v_and_b32_e32 v187, 0xffff0000, v89
	v_add_f32_dpp v208, v208, v208 quad_perm:[2,3,0,1] row_mask:0xf bank_mask:0xf
	v_lshlrev_b32_e32 v188, 16, v90
	v_and_b32_e32 v189, 0xffff0000, v90
	v_add_f32_dpp v208, v208, v208 row_half_mirror row_mask:0xf bank_mask:0xf
	v_lshlrev_b32_e32 v190, 16, v91
	v_and_b32_e32 v191, 0xffff0000, v91
	v_add_f32_dpp v208, v208, v208 row_mirror row_mask:0xf bank_mask:0xf
	v_lshlrev_b32_e32 v192, 16, v92
	v_and_b32_e32 v193, 0xffff0000, v92
	v_add_f32_dpp v208, v208, v208 row_bcast:15 row_mask:0xa bank_mask:0xf
	v_lshlrev_b32_e32 v194, 16, v93
	v_and_b32_e32 v195, 0xffff0000, v93
	v_add_f32_dpp v208, v208, v208 row_bcast:31 row_mask:0xc bank_mask:0xf
	v_lshlrev_b32_e32 v196, 16, v94
	v_and_b32_e32 v197, 0xffff0000, v94
	v_readlane_b32 s60, v208, 63
	s_nop 1
	v_lshlrev_b32_e32 v198, 16, v95
	v_and_b32_e32 v199, 0xffff0000, v95
	v_mov_b32_e32 v210, s60
	v_fmaak_f32 v210, v210, v212, 0x358637bd
	v_rsq_f32_e32 v210, v210
	s_nop 0
	v_lshlrev_b32_e32 v200, 16, v96
	v_and_b32_e32 v201, 0xffff0000, v96
	v_pk_mul_f32 v[200:201], v[200:201], v[210:211] op_sel_hi:[1,0]
	v_pk_fma_f32 v[184:185], v[8:9], v[200:201], v[184:185]
	v_lshlrev_b32_e32 v202, 16, v97
	v_and_b32_e32 v203, 0xffff0000, v97
	v_pk_mul_f32 v[202:203], v[202:203], v[210:211] op_sel_hi:[1,0]
	v_pk_fma_f32 v[186:187], v[10:11], v[202:203], v[186:187]
	v_lshlrev_b32_e32 v200, 16, v98
	v_and_b32_e32 v201, 0xffff0000, v98
	v_pk_mul_f32 v[200:201], v[200:201], v[210:211] op_sel_hi:[1,0]
	v_pk_fma_f32 v[188:189], v[12:13], v[200:201], v[188:189]
	v_lshlrev_b32_e32 v202, 16, v99
	v_and_b32_e32 v203, 0xffff0000, v99
	v_pk_mul_f32 v[202:203], v[202:203], v[210:211] op_sel_hi:[1,0]
	v_pk_fma_f32 v[190:191], v[14:15], v[202:203], v[190:191]
	v_lshlrev_b32_e32 v200, 16, v100
	v_and_b32_e32 v201, 0xffff0000, v100
	v_pk_mul_f32 v[200:201], v[200:201], v[210:211] op_sel_hi:[1,0]
	v_pk_fma_f32 v[192:193], v[16:17], v[200:201], v[192:193]
	v_lshlrev_b32_e32 v202, 16, v101
	v_and_b32_e32 v203, 0xffff0000, v101
	v_pk_mul_f32 v[202:203], v[202:203], v[210:211] op_sel_hi:[1,0]
	v_pk_fma_f32 v[194:195], v[18:19], v[202:203], v[194:195]
	v_lshlrev_b32_e32 v200, 16, v102
	v_and_b32_e32 v201, 0xffff0000, v102
	v_pk_mul_f32 v[200:201], v[200:201], v[210:211] op_sel_hi:[1,0]
	v_pk_fma_f32 v[196:197], v[20:21], v[200:201], v[196:197]
	v_lshlrev_b32_e32 v202, 16, v103
; __device__ __forceinline__ unsigned cvtpk(float lo, float hi) { f32x2 v = {lo, hi}; bf16x2_t b = __builtin_convertvector(v, bf16x2_t); return __builtin_bit_cast(unsigned, b); }
; __device__ __forceinline__ void phase_rowwise(const void* xsrc_, bool sbf, void* xdst_, bool dbf, const bf16_t* Y, bf16_t* H, const float* mods, int lprev, int iprev, const float* lnpost, float resw, ...
;     ...
;                     for (int j = 0; j < 4; ++j) { if (sbf) xnb[r][j] = *(const u32x2*)(xsrcb + (m + 2 + r) * DM + 4 * lane + 256 * j); else xn[r][j] = *(const f32x4*)(xsrc + (m + 2 + r) * DM + 4 * lane + 256 * j); if (hasprev) yn[r][j] = *(const u32x2*)(Y + (m + 2 + r) * DM + 4 * lane + 256 * j); } }
;     ...
; #pragma unroll
;             for (int r = 0; r < 2; ++r)
; #pragma unroll
;                 for (int j = 0; j < 4; ++j) { if (hasprev) { if (dbf) { u32x2 w; w.x = cvtpk(x[r][j].x, x[r][j].y); w.y = cvtpk(x[r][j].z, x[r][j].w); *(u32x2*)(xdstb + (m + r) * DM + 4 * lane + 256 * j) = w; } else *(f32x4*)(xdst + (m + r) * DM + 4 * lane + 256 * j) = x[r][j]; } }
;             if (hasnext) {
;                 float ss[2] = {0.f, 0.f};
; #pragma unroll
;                 for (int r = 0; r < 2; ++r)
; #pragma unroll
;                     for (int j = 0; j < 4; ++j) ss[r] += (x[r][j].x * x[r][j].x + x[r][j].y * x[r][j].y) + (x[r][j].z * x[r][j].z + x[r][j].w * x[r][j].w);
; #pragma unroll
;                 for (int off = 1; off < 64; off <<= 1) { ss[0] += __shfl_xor(ss[0], off); ss[1] += __shfl_xor(ss[1], off); }
; #pragma unroll
;                 for (int r = 0; r < 2; ++r) { const float rs = __builtin_amdgcn_rsqf(ss[r] * (1.f / DM) + EPS);
; #pragma unroll
;                     for (int j = 0; j < 4; ++j) { const f32x4 h = (x[r][j] * rs) * na[j] + ns[j]; u32x2 w; w.x = cvtpk(h.x, h.y); w.y = cvtpk(h.z, h.w); *(u32x2*)(H + (m + r) * DM + 4 * lane + 256 * j) = w; } }
;             }
	v_and_b32_e32 v203, 0xffff0000, v103
	v_pk_mul_f32 v[202:203], v[202:203], v[210:211] op_sel_hi:[1,0]
	v_pk_fma_f32 v[198:199], v[22:23], v[202:203], v[198:199]
	s_add_i32 s81, s80, 5
	s_add_i32 s81, s81, s82
	s_and_b32 s81, s81, 31
	s_lshl_b32 s83, s81, 11
	v_add_u32_e32 v2, s83, v1
	v_cvt_pk_bf16_f32 v96, v184, v185
	v_cvt_pk_bf16_f32 v97, v186, v187
	v_cvt_pk_bf16_f32 v98, v188, v189
	v_cvt_pk_bf16_f32 v99, v190, v191
	v_cvt_pk_bf16_f32 v100, v192, v193
	v_cvt_pk_bf16_f32 v101, v194, v195
	v_cvt_pk_bf16_f32 v102, v196, v197
	v_cvt_pk_bf16_f32 v103, v198, v199
	global_store_dwordx4 v2, v[96:99], s[76:77]
	global_store_dwordx4 v2, v[100:103], s[76:77] offset:1024
	v_pk_mul_f32 v[204:205], v[184:185], v[184:185]
	v_pk_mul_f32 v[206:207], v[186:187], v[186:187]
	v_pk_fma_f32 v[204:205], v[188:189], v[188:189], v[204:205]
	v_pk_fma_f32 v[206:207], v[190:191], v[190:191], v[206:207]
	v_pk_fma_f32 v[204:205], v[192:193], v[192:193], v[204:205]
	v_pk_fma_f32 v[206:207], v[194:195], v[194:195], v[206:207]
	v_pk_fma_f32 v[204:205], v[196:197], v[196:197], v[204:205]
	v_pk_fma_f32 v[206:207], v[198:199], v[198:199], v[206:207]
	v_pk_add_f32 v[204:205], v[204:205], v[206:207]
	v_add_f32_e32 v208, v204, v205
	s_nop 0
	s_nop 0
	v_add_f32_dpp v208, v208, v208 quad_perm:[1,0,3,2] row_mask:0xf bank_mask:0xf
	s_nop 0
	s_nop 0
	v_add_f32_dpp v208, v208, v208 quad_perm:[2,3,0,1] row_mask:0xf bank_mask:0xf
	s_nop 0
	s_nop 0
	v_add_f32_dpp v208, v208, v208 row_half_mirror row_mask:0xf bank_mask:0xf
	s_nop 0
	s_nop 0
	v_add_f32_dpp v208, v208, v208 row_mirror row_mask:0xf bank_mask:0xf
	s_nop 0
	s_nop 0
	v_add_f32_dpp v208, v208, v208 row_bcast:15 row_mask:0xa bank_mask:0xf
	s_nop 0
	s_nop 0
	v_add_f32_dpp v208, v208, v208 row_bcast:31 row_mask:0xc bank_mask:0xf
	s_nop 0
	s_nop 0
	v_readlane_b32 s60, v208, 63
	s_nop 1
	v_mov_b32_e32 v210, s60
	v_fmaak_f32 v210, v210, v212, 0x358637bd
	v_rsq_f32_e32 v210, v210
	s_nop 0
	v_pk_mul_f32 v[200:201], v[184:185], v[210:211] op_sel_hi:[1,0]
	v_pk_fma_f32 v[200:201], v[200:201], v[24:25], v[40:41]
	v_cvt_pk_bf16_f32 v88, v200, v201
	v_pk_mul_f32 v[202:203], v[186:187], v[210:211] op_sel_hi:[1,0]
	v_pk_fma_f32 v[202:203], v[202:203], v[26:27], v[42:43]
	v_cvt_pk_bf16_f32 v89, v202, v203
	v_pk_mul_f32 v[200:201], v[188:189], v[210:211] op_sel_hi:[1,0]
	v_pk_fma_f32 v[200:201], v[200:201], v[28:29], v[44:45]
	v_cvt_pk_bf16_f32 v90, v200, v201
	v_pk_mul_f32 v[202:203], v[190:191], v[210:211] op_sel_hi:[1,0]
	v_pk_fma_f32 v[202:203], v[202:203], v[30:31], v[46:47]
	v_cvt_pk_bf16_f32 v91, v202, v203
	v_pk_mul_f32 v[200:201], v[192:193], v[210:211] op_sel_hi:[1,0]
	v_pk_fma_f32 v[200:201], v[200:201], v[32:33], v[48:49]
	v_cvt_pk_bf16_f32 v92, v200, v201
	v_pk_mul_f32 v[202:203], v[194:195], v[210:211] op_sel_hi:[1,0]
	v_pk_fma_f32 v[202:203], v[202:203], v[34:35], v[50:51]
	v_cvt_pk_bf16_f32 v93, v202, v203
	v_pk_mul_f32 v[200:201], v[196:197], v[210:211] op_sel_hi:[1,0]
	v_pk_fma_f32 v[200:201], v[200:201], v[36:37], v[52:53]
	v_cvt_pk_bf16_f32 v94, v200, v201
	v_pk_mul_f32 v[202:203], v[198:199], v[210:211] op_sel_hi:[1,0]
	v_pk_fma_f32 v[202:203], v[202:203], v[38:39], v[54:55]
	v_cvt_pk_bf16_f32 v95, v202, v203
	global_store_dwordx4 v2, v[88:91], s[78:79]
	global_store_dwordx4 v2, v[92:95], s[78:79] offset:1024
	s_add_i32 s81, s82, 10
	s_cmp_lt_u32 s81, 32
	s_cbranch_scc0 .Lrw_MID_l6_d
	s_add_i32 s81, s80, 10
	s_add_i32 s81, s81, s82
	s_and_b32 s81, s81, 31
	s_lshl_b32 s83, s81, 11
	v_add_u32_e32 v2, s83, v1
	global_load_dwordx4 v[56:59], v2, s[72:73]
	global_load_dwordx4 v[60:63], v2, s[72:73] offset:1024
	global_load_dwordx4 v[64:67], v2, s[74:75]
	global_load_dwordx4 v[68:71], v2, s[74:75] offset:1024
	s_branch .Lrw_MID_l6_e

; __device__ __forceinline__ void phase_rowwise(const void* xsrc_, bool sbf, void* xdst_, bool dbf, const bf16_t* Y, bf16_t* H, const float* mods, int lprev, int iprev, const float* lnpost, float resw, ...
;     ...
;         for (int rr = 0; rr < 32; rr += 2) {
;             const size_t m = (size_t)ch * 32 + rr;
;             f32x4 x[2][4]; u32x2 yr[2][4];
; #pragma unroll
;             for (int r = 0; r < 2; ++r)
; #pragma unroll
;                 for (int j = 0; j < 4; ++j) { if (sbf) { const u32x2 u = xnb[r][j]; x[r][j] = (f32x4){bflo(u.x), bfhi(u.x), bflo(u.y), bfhi(u.y)}; } else x[r][j] = xn[r][j]; yr[r][j] = yn[r][j]; }
;             if (rr + 2 < 32) {
; #pragma unroll
;                 for (int r = 0; r < 2; ++r)
; #pragma unroll
;                     for (int j = 0; j < 4; ++j) { if (sbf) xnb[r][j] = *(const u32x2*)(xsrcb + (m + 2 + r) * DM + 4 * lane + 256 * j); else xn[r][j] = *(const f32x4*)(xsrc + (m + 2 + r) * DM + 4 * lane + 256 * j); if (hasprev) yn[r][j] = *(const u32x2*)(Y + (m + 2 + r) * DM + 4 * lane + 256 * j); } }
;             if (hasprev) {
;                 f32x4 y[2][4]; float ss[2] = {0.f, 0.f};
; #pragma unroll
;                 for (int r = 0; r < 2; ++r)
; #pragma unroll
;                     for (int j = 0; j < 4; ++j) { const u32x2 u = yr[r][j]; y[r][j] = (f32x4){bflo(u.x), bfhi(u.x), bflo(u.y), bfhi(u.y)};
;                         ss[r] += (y[r][j].x * y[r][j].x + y[r][j].y * y[r][j].y) + (y[r][j].z * y[r][j].z + y[r][j].w * y[r][j].w); }
; #pragma unroll
;                 for (int off = 1; off < 64; off <<= 1) { ss[0] += __shfl_xor(ss[0], off); ss[1] += __shfl_xor(ss[1], off); }
; #pragma unroll
;                 for (int r = 0; r < 2; ++r) { const float rs = __builtin_amdgcn_rsqf(ss[r] * (1.f / DM) + EPS);
; #pragma unroll
;                     for (int j = 0; j < 4; ++j) x[r][j] = x[r][j] + gp[j] * (y[r][j] * rs); }
;             }
; #pragma unroll
;             for (int r = 0; r < 2; ++r)
; #pragma unroll
;                 for (int j = 0; j < 4; ++j) { if (hasprev) { if (dbf) { u32x2 w; w.x = cvtpk(x[r][j].x, x[r][j].y); w.y = cvtpk(x[r][j].z, x[r][j].w); *(u32x2*)(xdstb + (m + r) * DM + 4 * lane + 256 * j) = w; } else *(f32x4*)(xdst + (m + r) * DM + 4 * lane + 256 * j) = x[r][j]; } }
;             if (hasnext) {
;                 float ss[2] = {0.f, 0.f};
; #pragma unroll
;                 for (int r = 0; r < 2; ++r)
.Lrw_MID_l6_e:
	s_waitcnt vmcnt(32)
	v_lshlrev_b32_e32 v200, 16, v112
	v_and_b32_e32 v201, 0xffff0000, v112
	v_pk_mul_f32 v[204:205], v[200:201], v[200:201]
	v_lshlrev_b32_e32 v202, 16, v113
	v_and_b32_e32 v203, 0xffff0000, v113
	v_pk_mul_f32 v[206:207], v[202:203], v[202:203]
	v_lshlrev_b32_e32 v200, 16, v114
	v_and_b32_e32 v201, 0xffff0000, v114
	v_pk_fma_f32 v[204:205], v[200:201], v[200:201], v[204:205]
	v_lshlrev_b32_e32 v202, 16, v115
	v_and_b32_e32 v203, 0xffff0000, v115
	v_pk_fma_f32 v[206:207], v[202:203], v[202:203], v[206:207]
	v_lshlrev_b32_e32 v200, 16, v116
	v_and_b32_e32 v201, 0xffff0000, v116
	v_pk_fma_f32 v[204:205], v[200:201], v[200:201], v[204:205]
	v_lshlrev_b32_e32 v202, 16, v117
	v_and_b32_e32 v203, 0xffff0000, v117
	v_pk_fma_f32 v[206:207], v[202:203], v[202:203], v[206:207]
	v_lshlrev_b32_e32 v200, 16, v118
	v_and_b32_e32 v201, 0xffff0000, v118
	v_pk_fma_f32 v[204:205], v[200:201], v[200:201], v[204:205]
	v_lshlrev_b32_e32 v202, 16, v119
	v_and_b32_e32 v203, 0xffff0000, v119
	v_pk_fma_f32 v[206:207], v[202:203], v[202:203], v[206:207]
	v_pk_add_f32 v[204:205], v[204:205], v[206:207]
	v_add_f32_e32 v208, v204, v205
	v_lshlrev_b32_e32 v184, 16, v104
	v_and_b32_e32 v185, 0xffff0000, v104
	v_add_f32_dpp v208, v208, v208 quad_perm:[1,0,3,2] row_mask:0xf bank_mask:0xf
	v_lshlrev_b32_e32 v186, 16, v105
	v_and_b32_e32 v187, 0xffff0000, v105
	v_add_f32_dpp v208, v208, v208 quad_perm:[2,3,0,1] row_mask:0xf bank_mask:0xf
	v_lshlrev_b32_e32 v188, 16, v106
	v_and_b32_e32 v189, 0xffff0000, v106
	v_add_f32_dpp v208, v208, v208 row_half_mirror row_mask:0xf bank_mask:0xf
	v_lshlrev_b32_e32 v190, 16, v107
	v_and_b32_e32 v191, 0xffff0000, v107
	v_add_f32_dpp v208, v208, v208 row_mirror row_mask:0xf bank_mask:0xf
	v_lshlrev_b32_e32 v192, 16, v108
	v_and_b32_e32 v193, 0xffff0000, v108
	v_add_f32_dpp v208, v208, v208 row_bcast:15 row_mask:0xa bank_mask:0xf
	v_lshlrev_b32_e32 v194, 16, v109
	v_and_b32_e32 v195, 0xffff0000, v109
	v_add_f32_dpp v208, v208, v208 row_bcast:31 row_mask:0xc bank_mask:0xf
	v_lshlrev_b32_e32 v196, 16, v110
	v_and_b32_e32 v197, 0xffff0000, v110
	v_readlane_b32 s60, v208, 63
	s_nop 1
	v_lshlrev_b32_e32 v198, 16, v111
	v_and_b32_e32 v199, 0xffff0000, v111
	v_mov_b32_e32 v210, s60
	v_fmaak_f32 v210, v210, v212, 0x358637bd
	v_rsq_f32_e32 v210, v210
	s_nop 0
	v_lshlrev_b32_e32 v200, 16, v112
	v_and_b32_e32 v201, 0xffff0000, v112
	v_pk_mul_f32 v[200:201], v[200:201], v[210:211] op_sel_hi:[1,0]
	v_pk_fma_f32 v[184:185], v[8:9], v[200:201], v[184:185]
	v_lshlrev_b32_e32 v202, 16, v113
	v_and_b32_e32 v203, 0xffff0000, v113
	v_pk_mul_f32 v[202:203], v[202:203], v[210:211] op_sel_hi:[1,0]
	v_pk_fma_f32 v[186:187], v[10:11], v[202:203], v[186:187]
	v_lshlrev_b32_e32 v200, 16, v114
	v_and_b32_e32 v201, 0xffff0000, v114
	v_pk_mul_f32 v[200:201], v[200:201], v[210:211] op_sel_hi:[1,0]
	v_pk_fma_f32 v[188:189], v[12:13], v[200:201], v[188:189]
	v_lshlrev_b32_e32 v202, 16, v115
	v_and_b32_e32 v203, 0xffff0000, v115
	v_pk_mul_f32 v[202:203], v[202:203], v[210:211] op_sel_hi:[1,0]
	v_pk_fma_f32 v[190:191], v[14:15], v[202:203], v[190:191]
	v_lshlrev_b32_e32 v200, 16, v116
	v_and_b32_e32 v201, 0xffff0000, v116
	v_pk_mul_f32 v[200:201], v[200:201], v[210:211] op_sel_hi:[1,0]
	v_pk_fma_f32 v[192:193], v[16:17], v[200:201], v[192:193]
	v_lshlrev_b32_e32 v202, 16, v117
	v_and_b32_e32 v203, 0xffff0000, v117
	v_pk_mul_f32 v[202:203], v[202:203], v[210:211] op_sel_hi:[1,0]
	v_pk_fma_f32 v[194:195], v[18:19], v[202:203], v[194:195]
	v_lshlrev_b32_e32 v200, 16, v118
	v_and_b32_e32 v201, 0xffff0000, v118
	v_pk_mul_f32 v[200:201], v[200:201], v[210:211] op_sel_hi:[1,0]
	v_pk_fma_f32 v[196:197], v[20:21], v[200:201], v[196:197]
	v_lshlrev_b32_e32 v202, 16, v119
	v_and_b32_e32 v203, 0xffff0000, v119
	v_pk_mul_f32 v[202:203], v[202:203], v[210:211] op_sel_hi:[1,0]
	v_pk_fma_f32 v[198:199], v[22:23], v[202:203], v[198:199]
	s_add_i32 s81, s80, 6
	s_add_i32 s81, s81, s82
	s_and_b32 s81, s81, 31
	s_lshl_b32 s83, s81, 11
	v_add_u32_e32 v2, s83, v1
	v_cvt_pk_bf16_f32 v112, v184, v185
	v_cvt_pk_bf16_f32 v113, v186, v187
	v_cvt_pk_bf16_f32 v114, v188, v189
	v_cvt_pk_bf16_f32 v115, v190, v191
	v_cvt_pk_bf16_f32 v116, v192, v193
	v_cvt_pk_bf16_f32 v117, v194, v195
	v_cvt_pk_bf16_f32 v118, v196, v197
	v_cvt_pk_bf16_f32 v119, v198, v199
	global_store_dwordx4 v2, v[112:115], s[76:77]
	global_store_dwordx4 v2, v[116:119], s[76:77] offset:1024
	v_pk_mul_f32 v[204:205], v[184:185], v[184:185]
	v_pk_mul_f32 v[206:207], v[186:187], v[186:187]
	v_pk_fma_f32 v[204:205], v[188:189], v[188:189], v[204:205]
	v_pk_fma_f32 v[206:207], v[190:191], v[190:191], v[206:207]
	v_pk_fma_f32 v[204:205], v[192:193], v[192:193], v[204:205]
	v_pk_fma_f32 v[206:207], v[194:195], v[194:195], v[206:207]
	v_pk_fma_f32 v[204:205], v[196:197], v[196:197], v[204:205]
	v_pk_fma_f32 v[206:207], v[198:199], v[198:199], v[206:207]
	v_pk_add_f32 v[204:205], v[204:205], v[206:207]
	v_add_f32_e32 v208, v204, v205
	s_nop 0
	s_nop 0
	v_add_f32_dpp v208, v208, v208 quad_perm:[1,0,3,2] row_mask:0xf bank_mask:0xf
	s_nop 0
	s_nop 0
	v_add_f32_dpp v208, v208, v208 quad_perm:[2,3,0,1] row_mask:0xf bank_mask:0xf
	s_nop 0
	s_nop 0
	v_add_f32_dpp v208, v208, v208 row_half_mirror row_mask:0xf bank_mask:0xf
	s_nop 0
	s_nop 0
	v_add_f32_dpp v208, v208, v208 row_mirror row_mask:0xf bank_mask:0xf
	s_nop 0
	s_nop 0
	v_add_f32_dpp v208, v208, v208 row_bcast:15 row_mask:0xa bank_mask:0xf
	s_nop 0
	s_nop 0
	v_add_f32_dpp v208, v208, v208 row_bcast:31 row_mask:0xc bank_mask:0xf
	s_nop 0
	s_nop 0
	v_readlane_b32 s60, v208, 63
	s_nop 1
	v_mov_b32_e32 v210, s60
	v_fmaak_f32 v210, v210, v212, 0x358637bd
; __device__ __forceinline__ void phase_rowwise(const void* xsrc_, bool sbf, void* xdst_, bool dbf, const bf16_t* Y, bf16_t* H, const float* mods, int lprev, int iprev, const float* lnpost, float resw, ...
;     ...
;     for (int ch = gw; ch < M / 32; ch += NGW) {
;         const int b = ch >> 6;
;         f32x4 gp[4], na[4], ns[4];
; #pragma unroll
;         for (int j = 0; j < 4; ++j) { const int c = 4 * lane + 256 * j;
;             if (hasprev) { const f32x4 g = *(const f32x4*)(mods + ((size_t)lprev * 32 + b) * 9216 + iprev * 3072 + 2048 + c); const f32x4 lp = *(const f32x4*)(lnpost + c); gp[j] = g * lp * resw; }
;             else gp[j] = (f32x4){0.f, 0.f, 0.f, 0.f};
;             if (hasnext) { const f32x4 sh = *(const f32x4*)(mods + ((size_t)lnext * 32 + b) * 9216 + inext * 3072 + c); const f32x4 scl = *(const f32x4*)(mods + ((size_t)lnext * 32 + b) * 9216 + inext * 3072 + 1024 + c);
;                 const f32x4 lp = *(const f32x4*)(lnpre + c); na[j] = lp * (scl + 1.0f); ns[j] = sh; }
;             else { na[j] = (f32x4){0.f, 0.f, 0.f, 0.f}; ns[j] = na[j]; } }
;         f32x4 xn[2][4]; u32x2 xnb[2][4]; u32x2 yn[2][4];
;         { const size_t m0 = (size_t)ch * 32;
; #pragma unroll
;           for (int r = 0; r < 2; ++r)
; #pragma unroll
;     ...
;                 for (int j = 0; j < 4; ++j) { if (hasprev) { if (dbf) { u32x2 w; w.x = cvtpk(x[r][j].x, x[r][j].y); w.y = cvtpk(x[r][j].z, x[r][j].w); *(u32x2*)(xdstb + (m + r) * DM + 4 * lane + 256 * j) = w; } else *(f32x4*)(xdst + (m + r) * DM + 4 * lane + 256 * j) = x[r][j]; } }
;             if (hasnext) {
;                 float ss[2] = {0.f, 0.f};
; #pragma unroll
;                 for (int r = 0; r < 2; ++r)
; #pragma unroll
;                     for (int j = 0; j < 4; ++j) ss[r] += (x[r][j].x * x[r][j].x + x[r][j].y * x[r][j].y) + (x[r][j].z * x[r][j].z + x[r][j].w * x[r][j].w);
; #pragma unroll
;                 for (int off = 1; off < 64; off <<= 1) { ss[0] += __shfl_xor(ss[0], off); ss[1] += __shfl_xor(ss[1], off); }
; #pragma unroll
;                 for (int r = 0; r < 2; ++r) { const float rs = __builtin_amdgcn_rsqf(ss[r] * (1.f / DM) + EPS);
; #pragma unroll
;                     for (int j = 0; j < 4; ++j) { const f32x4 h = (x[r][j] * rs) * na[j] + ns[j]; u32x2 w; w.x = cvtpk(h.x, h.y); w.y = cvtpk(h.z, h.w); *(u32x2*)(H + (m + r) * DM + 4 * lane + 256 * j) = w; } }
	v_rsq_f32_e32 v210, v210
	s_nop 0
	v_pk_mul_f32 v[200:201], v[184:185], v[210:211] op_sel_hi:[1,0]
	v_pk_fma_f32 v[200:201], v[200:201], v[24:25], v[40:41]
	v_cvt_pk_bf16_f32 v104, v200, v201
	v_pk_mul_f32 v[202:203], v[186:187], v[210:211] op_sel_hi:[1,0]
	v_pk_fma_f32 v[202:203], v[202:203], v[26:27], v[42:43]
	v_cvt_pk_bf16_f32 v105, v202, v203
	v_pk_mul_f32 v[200:201], v[188:189], v[210:211] op_sel_hi:[1,0]
	v_pk_fma_f32 v[200:201], v[200:201], v[28:29], v[44:45]
	v_cvt_pk_bf16_f32 v106, v200, v201
	v_pk_mul_f32 v[202:203], v[190:191], v[210:211] op_sel_hi:[1,0]
	v_pk_fma_f32 v[202:203], v[202:203], v[30:31], v[46:47]
	v_cvt_pk_bf16_f32 v107, v202, v203
	v_pk_mul_f32 v[200:201], v[192:193], v[210:211] op_sel_hi:[1,0]
	v_pk_fma_f32 v[200:201], v[200:201], v[32:33], v[48:49]
	v_cvt_pk_bf16_f32 v108, v200, v201
	v_pk_mul_f32 v[202:203], v[194:195], v[210:211] op_sel_hi:[1,0]
	v_pk_fma_f32 v[202:203], v[202:203], v[34:35], v[50:51]
	v_cvt_pk_bf16_f32 v109, v202, v203
	v_pk_mul_f32 v[200:201], v[196:197], v[210:211] op_sel_hi:[1,0]
	v_pk_fma_f32 v[200:201], v[200:201], v[36:37], v[52:53]
	v_cvt_pk_bf16_f32 v110, v200, v201
	v_pk_mul_f32 v[202:203], v[198:199], v[210:211] op_sel_hi:[1,0]
	v_pk_fma_f32 v[202:203], v[202:203], v[38:39], v[54:55]
	v_cvt_pk_bf16_f32 v111, v202, v203
	global_store_dwordx4 v2, v[104:107], s[78:79]
	global_store_dwordx4 v2, v[108:111], s[78:79] offset:1024
	s_add_i32 s82, s82, 7
	s_cmp_lt_u32 s82, 32
	s_cbranch_scc1 .Lrw_MID_loop
	s_branch .LBB0_1024
.Lrw_INIT:
	v_readfirstlane_b32 s40, v214
	v_readlane_b32 s41, v254, 46
	s_lshr_b32 s40, s40, 6
	s_add_i32 s40, s40, s41
	s_lshr_b32 s41, s40, 6
	v_and_b32_e32 v1, 63, v214
	v_lshlrev_b32_e32 v3, 5, v1
	v_lshlrev_b32_e32 v1, 4, v1
	v_mov_b32_e32 v212, 0x3a800000
	s_mov_b32 s42, 0
	s_mov_b32 s43, 0
	v_readlane_b32 s44, v255, 22
	v_readlane_b32 s45, v255, 23
	s_lshl_b32 s46, s42, 5
	s_add_i32 s46, s46, s41
	s_mul_i32 s46, s46, 0x9000
	s_mul_i32 s47, s43, 0x3000
	s_add_i32 s46, s46, s47
	s_add_u32 s50, s44, s46
	s_addc_u32 s51, s45, 0
	s_add_u32 s56, s50, 0x1000
	s_addc_u32 s57, s51, 0
	v_readlane_b32 s54, v255, 14
	v_readlane_b32 s55, v255, 15
	s_mul_i32 s46, s42, 3
	s_add_i32 s46, s46, s43
	s_lshl_b32 s46, s46, 12
	s_add_u32 s54, s54, s46
	s_addc_u32 s55, s55, 0
	global_load_dwordx4 v[24:27], v3, s[56:57]
	global_load_dwordx4 v[28:31], v3, s[56:57] offset:16
	global_load_dwordx4 v[32:35], v3, s[56:57] offset:2048
	global_load_dwordx4 v[36:39], v3, s[56:57] offset:2064
	global_load_dwordx4 v[72:75], v3, s[54:55]
	global_load_dwordx4 v[76:79], v3, s[54:55] offset:16
	global_load_dwordx4 v[80:83], v3, s[54:55] offset:2048
	global_load_dwordx4 v[84:87], v3, s[54:55] offset:2064
	global_load_dwordx4 v[40:43], v3, s[50:51]
	global_load_dwordx4 v[44:47], v3, s[50:51] offset:16
	global_load_dwordx4 v[48:51], v3, s[50:51] offset:2048
	global_load_dwordx4 v[52:55], v3, s[50:51] offset:2064
	s_lshl_b32 s46, s40, 16
	s_lshl_b32 s47, s40, 17
	v_readlane_b32 s72, v255, 4
	v_readlane_b32 s73, v255, 5
	s_add_u32 s72, s72, s47
	s_addc_u32 s73, s73, 0
	v_readlane_b32 s78, v252, 20
	v_readlane_b32 s79, v252, 21
	s_add_u32 s78, s78, s46
	s_addc_u32 s79, s79, 0
	s_and_b32 s80, s40, 15
	s_lshl_b32 s80, s80, 1
	s_waitcnt vmcnt(4)
	v_pk_add_f32 v[24:25], v[24:25], 1.0 op_sel_hi:[1,0]
	v_pk_add_f32 v[26:27], v[26:27], 1.0 op_sel_hi:[1,0]
	v_pk_add_f32 v[28:29], v[28:29], 1.0 op_sel_hi:[1,0]
	v_pk_add_f32 v[30:31], v[30:31], 1.0 op_sel_hi:[1,0]
	v_pk_add_f32 v[32:33], v[32:33], 1.0 op_sel_hi:[1,0]
	v_pk_add_f32 v[34:35], v[34:35], 1.0 op_sel_hi:[1,0]
	v_pk_add_f32 v[36:37], v[36:37], 1.0 op_sel_hi:[1,0]
	v_pk_add_f32 v[38:39], v[38:39], 1.0 op_sel_hi:[1,0]
	v_pk_mul_f32 v[24:25], v[72:73], v[24:25]
	v_pk_mul_f32 v[26:27], v[74:75], v[26:27]
	v_pk_mul_f32 v[28:29], v[76:77], v[28:29]
	v_pk_mul_f32 v[30:31], v[78:79], v[30:31]
	v_pk_mul_f32 v[32:33], v[80:81], v[32:33]
	v_pk_mul_f32 v[34:35], v[82:83], v[34:35]
	v_pk_mul_f32 v[36:37], v[84:85], v[36:37]
	v_pk_mul_f32 v[38:39], v[86:87], v[38:39]
	s_waitcnt vmcnt(0)
	s_mov_b32 s82, 0
	s_add_i32 s81, s80, 0
	s_add_i32 s81, s81, s82
	s_and_b32 s81, s81, 31
	s_lshl_b32 s83, s81, 12
	v_add_u32_e32 v213, s83, v3
	global_load_dwordx4 v[56:59], v213, s[72:73]
	global_load_dwordx4 v[60:63], v213, s[72:73] offset:16
	global_load_dwordx4 v[64:67], v213, s[72:73] offset:2048
	global_load_dwordx4 v[68:71], v213, s[72:73] offset:2064
	s_add_i32 s81, s80, 1
	s_add_i32 s81, s81, s82
	s_and_b32 s81, s81, 31
	s_lshl_b32 s83, s81, 12
	v_add_u32_e32 v213, s83, v3
	global_load_dwordx4 v[72:75], v213, s[72:73]
	global_load_dwordx4 v[76:79], v213, s[72:73] offset:16
	global_load_dwordx4 v[80:83], v213, s[72:73] offset:2048
	global_load_dwordx4 v[84:87], v213, s[72:73] offset:2064
	s_add_i32 s81, s80, 2
	s_add_i32 s81, s81, s82
	s_and_b32 s81, s81, 31
	s_lshl_b32 s83, s81, 12
	v_add_u32_e32 v213, s83, v3
	global_load_dwordx4 v[88:91], v213, s[72:73]
	global_load_dwordx4 v[92:95], v213, s[72:73] offset:16
	global_load_dwordx4 v[96:99], v213, s[72:73] offset:2048
	global_load_dwordx4 v[100:103], v213, s[72:73] offset:2064
	s_add_i32 s81, s80, 3
	s_add_i32 s81, s81, s82
	s_and_b32 s81, s81, 31
	s_lshl_b32 s83, s81, 12
	v_add_u32_e32 v213, s83, v3
	global_load_dwordx4 v[104:107], v213, s[72:73]
	global_load_dwordx4 v[108:111], v213, s[72:73] offset:16
	global_load_dwordx4 v[112:115], v213, s[72:73] offset:2048
	global_load_dwordx4 v[116:119], v213, s[72:73] offset:2064
	s_add_i32 s81, s80, 4
	s_add_i32 s81, s81, s82
	s_and_b32 s81, s81, 31
	s_lshl_b32 s83, s81, 12
	v_add_u32_e32 v213, s83, v3
	global_load_dwordx4 v[120:123], v213, s[72:73]
	global_load_dwordx4 v[124:127], v213, s[72:73] offset:16
	global_load_dwordx4 v[128:131], v213, s[72:73] offset:2048
	global_load_dwordx4 v[132:135], v213, s[72:73] offset:2064
	s_waitcnt vmcnt(16)
; __device__ __forceinline__ unsigned cvtpk(float lo, float hi) { f32x2 v = {lo, hi}; bf16x2_t b = __builtin_convertvector(v, bf16x2_t); return __builtin_bit_cast(unsigned, b); }
; __device__ __forceinline__ void phase_rowwise(const void* xsrc_, bool sbf, void* xdst_, bool dbf, const bf16_t* Y, bf16_t* H, const float* mods, int lprev, int iprev, const float* lnpost, float resw, ...
;     ...
;                     for (int j = 0; j < 4; ++j) { if (sbf) xnb[r][j] = *(const u32x2*)(xsrcb + (m + 2 + r) * DM + 4 * lane + 256 * j); else xn[r][j] = *(const f32x4*)(xsrc + (m + 2 + r) * DM + 4 * lane + 256 * j); if (hasprev) yn[r][j] = *(const u32x2*)(Y + (m + 2 + r) * DM + 4 * lane + 256 * j); } }
;     ...
;             if (hasnext) {
;                 float ss[2] = {0.f, 0.f};
; #pragma unroll
;                 for (int r = 0; r < 2; ++r)
; #pragma unroll
;                     for (int j = 0; j < 4; ++j) ss[r] += (x[r][j].x * x[r][j].x + x[r][j].y * x[r][j].y) + (x[r][j].z * x[r][j].z + x[r][j].w * x[r][j].w);
; #pragma unroll
;                 for (int off = 1; off < 64; off <<= 1) { ss[0] += __shfl_xor(ss[0], off); ss[1] += __shfl_xor(ss[1], off); }
; #pragma unroll
;                 for (int r = 0; r < 2; ++r) { const float rs = __builtin_amdgcn_rsqf(ss[r] * (1.f / DM) + EPS);
; #pragma unroll
;                     for (int j = 0; j < 4; ++j) { const f32x4 h = (x[r][j] * rs) * na[j] + ns[j]; u32x2 w; w.x = cvtpk(h.x, h.y); w.y = cvtpk(h.z, h.w); *(u32x2*)(H + (m + r) * DM + 4 * lane + 256 * j) = w; } }
;             }
	s_add_i32 s81, s80, 0
	s_add_i32 s81, s81, s82
	s_and_b32 s81, s81, 31
	s_lshl_b32 s83, s81, 11
	v_add_u32_e32 v2, s83, v1
	v_pk_mul_f32 v[204:205], v[56:57], v[56:57]
	v_pk_mul_f32 v[206:207], v[58:59], v[58:59]
	v_pk_fma_f32 v[204:205], v[60:61], v[60:61], v[204:205]
	v_pk_fma_f32 v[206:207], v[62:63], v[62:63], v[206:207]
	v_pk_fma_f32 v[204:205], v[64:65], v[64:65], v[204:205]
	v_pk_fma_f32 v[206:207], v[66:67], v[66:67], v[206:207]
	v_pk_fma_f32 v[204:205], v[68:69], v[68:69], v[204:205]
	v_pk_fma_f32 v[206:207], v[70:71], v[70:71], v[206:207]
	v_pk_add_f32 v[204:205], v[204:205], v[206:207]
	v_add_f32_e32 v208, v204, v205
	s_nop 0
	s_nop 0
	v_add_f32_dpp v208, v208, v208 quad_perm:[1,0,3,2] row_mask:0xf bank_mask:0xf
	s_nop 0
	s_nop 0
	v_add_f32_dpp v208, v208, v208 quad_perm:[2,3,0,1] row_mask:0xf bank_mask:0xf
	s_nop 0
	s_nop 0
	v_add_f32_dpp v208, v208, v208 row_half_mirror row_mask:0xf bank_mask:0xf
	s_nop 0
	s_nop 0
	v_add_f32_dpp v208, v208, v208 row_mirror row_mask:0xf bank_mask:0xf
	s_nop 0
	s_nop 0
	v_add_f32_dpp v208, v208, v208 row_bcast:15 row_mask:0xa bank_mask:0xf
	s_nop 0
	s_nop 0
	v_add_f32_dpp v208, v208, v208 row_bcast:31 row_mask:0xc bank_mask:0xf
	s_nop 0
	s_nop 0
	v_readlane_b32 s60, v208, 63
	s_nop 1
	v_mov_b32_e32 v210, s60
	v_fmaak_f32 v210, v210, v212, 0x358637bd
	v_rsq_f32_e32 v210, v210
	s_nop 0
	v_pk_mul_f32 v[200:201], v[56:57], v[210:211] op_sel_hi:[1,0]
	v_pk_fma_f32 v[200:201], v[200:201], v[24:25], v[40:41]
	v_cvt_pk_bf16_f32 v184, v200, v201
	v_pk_mul_f32 v[202:203], v[58:59], v[210:211] op_sel_hi:[1,0]
	v_pk_fma_f32 v[202:203], v[202:203], v[26:27], v[42:43]
	v_cvt_pk_bf16_f32 v185, v202, v203
	v_pk_mul_f32 v[200:201], v[60:61], v[210:211] op_sel_hi:[1,0]
	v_pk_fma_f32 v[200:201], v[200:201], v[28:29], v[44:45]
	v_cvt_pk_bf16_f32 v186, v200, v201
	v_pk_mul_f32 v[202:203], v[62:63], v[210:211] op_sel_hi:[1,0]
	v_pk_fma_f32 v[202:203], v[202:203], v[30:31], v[46:47]
	v_cvt_pk_bf16_f32 v187, v202, v203
	v_pk_mul_f32 v[200:201], v[64:65], v[210:211] op_sel_hi:[1,0]
	v_pk_fma_f32 v[200:201], v[200:201], v[32:33], v[48:49]
	v_cvt_pk_bf16_f32 v188, v200, v201
	v_pk_mul_f32 v[202:203], v[66:67], v[210:211] op_sel_hi:[1,0]
	v_pk_fma_f32 v[202:203], v[202:203], v[34:35], v[50:51]
	v_cvt_pk_bf16_f32 v189, v202, v203
	v_pk_mul_f32 v[200:201], v[68:69], v[210:211] op_sel_hi:[1,0]
	v_pk_fma_f32 v[200:201], v[200:201], v[36:37], v[52:53]
	v_cvt_pk_bf16_f32 v190, v200, v201
	v_pk_mul_f32 v[202:203], v[70:71], v[210:211] op_sel_hi:[1,0]
	v_pk_fma_f32 v[202:203], v[202:203], v[38:39], v[54:55]
	v_cvt_pk_bf16_f32 v191, v202, v203
	global_store_dwordx4 v2, v[184:187], s[78:79]
	global_store_dwordx4 v2, v[188:191], s[78:79] offset:1024
	s_add_i32 s81, s80, 5
	s_add_i32 s81, s81, s82
	s_and_b32 s81, s81, 31
	s_lshl_b32 s83, s81, 12
	v_add_u32_e32 v213, s83, v3
	global_load_dwordx4 v[136:139], v213, s[72:73]
	global_load_dwordx4 v[140:143], v213, s[72:73] offset:16
	global_load_dwordx4 v[144:147], v213, s[72:73] offset:2048
	global_load_dwordx4 v[148:151], v213, s[72:73] offset:2064
	s_waitcnt vmcnt(18)
	s_add_i32 s81, s80, 1
	s_add_i32 s81, s81, s82
	s_and_b32 s81, s81, 31
	s_lshl_b32 s83, s81, 11
	v_add_u32_e32 v2, s83, v1
	v_pk_mul_f32 v[204:205], v[72:73], v[72:73]
	v_pk_mul_f32 v[206:207], v[74:75], v[74:75]
	v_pk_fma_f32 v[204:205], v[76:77], v[76:77], v[204:205]
	v_pk_fma_f32 v[206:207], v[78:79], v[78:79], v[206:207]
	v_pk_fma_f32 v[204:205], v[80:81], v[80:81], v[204:205]
	v_pk_fma_f32 v[206:207], v[82:83], v[82:83], v[206:207]
	v_pk_fma_f32 v[204:205], v[84:85], v[84:85], v[204:205]
	v_pk_fma_f32 v[206:207], v[86:87], v[86:87], v[206:207]
	v_pk_add_f32 v[204:205], v[204:205], v[206:207]
	v_add_f32_e32 v208, v204, v205
	s_nop 0
	s_nop 0
	v_add_f32_dpp v208, v208, v208 quad_perm:[1,0,3,2] row_mask:0xf bank_mask:0xf
	s_nop 0
	s_nop 0
	v_add_f32_dpp v208, v208, v208 quad_perm:[2,3,0,1] row_mask:0xf bank_mask:0xf
	s_nop 0
	s_nop 0
	v_add_f32_dpp v208, v208, v208 row_half_mirror row_mask:0xf bank_mask:0xf
	s_nop 0
	s_nop 0
	v_add_f32_dpp v208, v208, v208 row_mirror row_mask:0xf bank_mask:0xf
	s_nop 0
	s_nop 0
	v_add_f32_dpp v208, v208, v208 row_bcast:15 row_mask:0xa bank_mask:0xf
	s_nop 0
	s_nop 0
	v_add_f32_dpp v208, v208, v208 row_bcast:31 row_mask:0xc bank_mask:0xf
	s_nop 0
	s_nop 0
	v_readlane_b32 s60, v208, 63
	s_nop 1
	v_mov_b32_e32 v210, s60
	v_fmaak_f32 v210, v210, v212, 0x358637bd
	v_rsq_f32_e32 v210, v210
	s_nop 0
	v_pk_mul_f32 v[200:201], v[72:73], v[210:211] op_sel_hi:[1,0]
	v_pk_fma_f32 v[200:201], v[200:201], v[24:25], v[40:41]
	v_cvt_pk_bf16_f32 v184, v200, v201
	v_pk_mul_f32 v[202:203], v[74:75], v[210:211] op_sel_hi:[1,0]
	v_pk_fma_f32 v[202:203], v[202:203], v[26:27], v[42:43]
	v_cvt_pk_bf16_f32 v185, v202, v203
	v_pk_mul_f32 v[200:201], v[76:77], v[210:211] op_sel_hi:[1,0]
	v_pk_fma_f32 v[200:201], v[200:201], v[28:29], v[44:45]
	v_cvt_pk_bf16_f32 v186, v200, v201
	v_pk_mul_f32 v[202:203], v[78:79], v[210:211] op_sel_hi:[1,0]
	v_pk_fma_f32 v[202:203], v[202:203], v[30:31], v[46:47]
	v_cvt_pk_bf16_f32 v187, v202, v203
	v_pk_mul_f32 v[200:201], v[80:81], v[210:211] op_sel_hi:[1,0]
	v_pk_fma_f32 v[200:201], v[200:201], v[32:33], v[48:49]
	v_cvt_pk_bf16_f32 v188, v200, v201
	v_pk_mul_f32 v[202:203], v[82:83], v[210:211] op_sel_hi:[1,0]
	v_pk_fma_f32 v[202:203], v[202:203], v[34:35], v[50:51]
	v_cvt_pk_bf16_f32 v189, v202, v203
	v_pk_mul_f32 v[200:201], v[84:85], v[210:211] op_sel_hi:[1,0]
	v_pk_fma_f32 v[200:201], v[200:201], v[36:37], v[52:53]
	v_cvt_pk_bf16_f32 v190, v200, v201
	v_pk_mul_f32 v[202:203], v[86:87], v[210:211] op_sel_hi:[1,0]
	v_pk_fma_f32 v[202:203], v[202:203], v[38:39], v[54:55]
	v_cvt_pk_bf16_f32 v191, v202, v203
	global_store_dwordx4 v2, v[184:187], s[78:79]
	global_store_dwordx4 v2, v[188:191], s[78:79] offset:1024
	s_add_i32 s81, s80, 6
	s_add_i32 s81, s81, s82
	s_and_b32 s81, s81, 31
	s_lshl_b32 s83, s81, 12
	v_add_u32_e32 v213, s83, v3
	global_load_dwordx4 v[152:155], v213, s[72:73]
	global_load_dwordx4 v[156:159], v213, s[72:73] offset:16
	global_load_dwordx4 v[160:163], v213, s[72:73] offset:2048
	global_load_dwordx4 v[164:167], v213, s[72:73] offset:2064
	s_waitcnt vmcnt(20)
; __device__ __forceinline__ unsigned cvtpk(float lo, float hi) { f32x2 v = {lo, hi}; bf16x2_t b = __builtin_convertvector(v, bf16x2_t); return __builtin_bit_cast(unsigned, b); }
; __device__ __forceinline__ void phase_rowwise(const void* xsrc_, bool sbf, void* xdst_, bool dbf, const bf16_t* Y, bf16_t* H, const float* mods, int lprev, int iprev, const float* lnpost, float resw, ...
;     ...
;                     for (int j = 0; j < 4; ++j) { if (sbf) xnb[r][j] = *(const u32x2*)(xsrcb + (m + 2 + r) * DM + 4 * lane + 256 * j); else xn[r][j] = *(const f32x4*)(xsrc + (m + 2 + r) * DM + 4 * lane + 256 * j); if (hasprev) yn[r][j] = *(const u32x2*)(Y + (m + 2 + r) * DM + 4 * lane + 256 * j); } }
;     ...
;             if (hasnext) {
;                 float ss[2] = {0.f, 0.f};
; #pragma unroll
;                 for (int r = 0; r < 2; ++r)
; #pragma unroll
;                     for (int j = 0; j < 4; ++j) ss[r] += (x[r][j].x * x[r][j].x + x[r][j].y * x[r][j].y) + (x[r][j].z * x[r][j].z + x[r][j].w * x[r][j].w);
; #pragma unroll
;                 for (int off = 1; off < 64; off <<= 1) { ss[0] += __shfl_xor(ss[0], off); ss[1] += __shfl_xor(ss[1], off); }
; #pragma unroll
;                 for (int r = 0; r < 2; ++r) { const float rs = __builtin_amdgcn_rsqf(ss[r] * (1.f / DM) + EPS);
; #pragma unroll
;                     for (int j = 0; j < 4; ++j) { const f32x4 h = (x[r][j] * rs) * na[j] + ns[j]; u32x2 w; w.x = cvtpk(h.x, h.y); w.y = cvtpk(h.z, h.w); *(u32x2*)(H + (m + r) * DM + 4 * lane + 256 * j) = w; } }
;             }
	s_add_i32 s81, s80, 2
	s_add_i32 s81, s81, s82
	s_and_b32 s81, s81, 31
	s_lshl_b32 s83, s81, 11
	v_add_u32_e32 v2, s83, v1
	v_pk_mul_f32 v[204:205], v[88:89], v[88:89]
	v_pk_mul_f32 v[206:207], v[90:91], v[90:91]
	v_pk_fma_f32 v[204:205], v[92:93], v[92:93], v[204:205]
	v_pk_fma_f32 v[206:207], v[94:95], v[94:95], v[206:207]
	v_pk_fma_f32 v[204:205], v[96:97], v[96:97], v[204:205]
	v_pk_fma_f32 v[206:207], v[98:99], v[98:99], v[206:207]
	v_pk_fma_f32 v[204:205], v[100:101], v[100:101], v[204:205]
	v_pk_fma_f32 v[206:207], v[102:103], v[102:103], v[206:207]
	v_pk_add_f32 v[204:205], v[204:205], v[206:207]
	v_add_f32_e32 v208, v204, v205
	s_nop 0
	s_nop 0
	v_add_f32_dpp v208, v208, v208 quad_perm:[1,0,3,2] row_mask:0xf bank_mask:0xf
	s_nop 0
	s_nop 0
	v_add_f32_dpp v208, v208, v208 quad_perm:[2,3,0,1] row_mask:0xf bank_mask:0xf
	s_nop 0
	s_nop 0
	v_add_f32_dpp v208, v208, v208 row_half_mirror row_mask:0xf bank_mask:0xf
	s_nop 0
	s_nop 0
	v_add_f32_dpp v208, v208, v208 row_mirror row_mask:0xf bank_mask:0xf
	s_nop 0
	s_nop 0
	v_add_f32_dpp v208, v208, v208 row_bcast:15 row_mask:0xa bank_mask:0xf
	s_nop 0
	s_nop 0
	v_add_f32_dpp v208, v208, v208 row_bcast:31 row_mask:0xc bank_mask:0xf
	s_nop 0
	s_nop 0
	v_readlane_b32 s60, v208, 63
	s_nop 1
	v_mov_b32_e32 v210, s60
	v_fmaak_f32 v210, v210, v212, 0x358637bd
	v_rsq_f32_e32 v210, v210
	s_nop 0
	v_pk_mul_f32 v[200:201], v[88:89], v[210:211] op_sel_hi:[1,0]
	v_pk_fma_f32 v[200:201], v[200:201], v[24:25], v[40:41]
	v_cvt_pk_bf16_f32 v184, v200, v201
	v_pk_mul_f32 v[202:203], v[90:91], v[210:211] op_sel_hi:[1,0]
	v_pk_fma_f32 v[202:203], v[202:203], v[26:27], v[42:43]
	v_cvt_pk_bf16_f32 v185, v202, v203
	v_pk_mul_f32 v[200:201], v[92:93], v[210:211] op_sel_hi:[1,0]
	v_pk_fma_f32 v[200:201], v[200:201], v[28:29], v[44:45]
	v_cvt_pk_bf16_f32 v186, v200, v201
	v_pk_mul_f32 v[202:203], v[94:95], v[210:211] op_sel_hi:[1,0]
	v_pk_fma_f32 v[202:203], v[202:203], v[30:31], v[46:47]
	v_cvt_pk_bf16_f32 v187, v202, v203
	v_pk_mul_f32 v[200:201], v[96:97], v[210:211] op_sel_hi:[1,0]
	v_pk_fma_f32 v[200:201], v[200:201], v[32:33], v[48:49]
	v_cvt_pk_bf16_f32 v188, v200, v201
	v_pk_mul_f32 v[202:203], v[98:99], v[210:211] op_sel_hi:[1,0]
	v_pk_fma_f32 v[202:203], v[202:203], v[34:35], v[50:51]
	v_cvt_pk_bf16_f32 v189, v202, v203
	v_pk_mul_f32 v[200:201], v[100:101], v[210:211] op_sel_hi:[1,0]
	v_pk_fma_f32 v[200:201], v[200:201], v[36:37], v[52:53]
	v_cvt_pk_bf16_f32 v190, v200, v201
	v_pk_mul_f32 v[202:203], v[102:103], v[210:211] op_sel_hi:[1,0]
	v_pk_fma_f32 v[202:203], v[202:203], v[38:39], v[54:55]
	v_cvt_pk_bf16_f32 v191, v202, v203
	global_store_dwordx4 v2, v[184:187], s[78:79]
	global_store_dwordx4 v2, v[188:191], s[78:79] offset:1024
	s_add_i32 s81, s80, 7
	s_add_i32 s81, s81, s82
	s_and_b32 s81, s81, 31
	s_lshl_b32 s83, s81, 12
	v_add_u32_e32 v213, s83, v3
	global_load_dwordx4 v[56:59], v213, s[72:73]
	global_load_dwordx4 v[60:63], v213, s[72:73] offset:16
	global_load_dwordx4 v[64:67], v213, s[72:73] offset:2048
	global_load_dwordx4 v[68:71], v213, s[72:73] offset:2064
	s_waitcnt vmcnt(22)
	s_add_i32 s81, s80, 3
	s_add_i32 s81, s81, s82
	s_and_b32 s81, s81, 31
	s_lshl_b32 s83, s81, 11
	v_add_u32_e32 v2, s83, v1
	v_pk_mul_f32 v[204:205], v[104:105], v[104:105]
	v_pk_mul_f32 v[206:207], v[106:107], v[106:107]
	v_pk_fma_f32 v[204:205], v[108:109], v[108:109], v[204:205]
	v_pk_fma_f32 v[206:207], v[110:111], v[110:111], v[206:207]
	v_pk_fma_f32 v[204:205], v[112:113], v[112:113], v[204:205]
	v_pk_fma_f32 v[206:207], v[114:115], v[114:115], v[206:207]
	v_pk_fma_f32 v[204:205], v[116:117], v[116:117], v[204:205]
	v_pk_fma_f32 v[206:207], v[118:119], v[118:119], v[206:207]
	v_pk_add_f32 v[204:205], v[204:205], v[206:207]
	v_add_f32_e32 v208, v204, v205
	s_nop 0
	s_nop 0
	v_add_f32_dpp v208, v208, v208 quad_perm:[1,0,3,2] row_mask:0xf bank_mask:0xf
	s_nop 0
	s_nop 0
	v_add_f32_dpp v208, v208, v208 quad_perm:[2,3,0,1] row_mask:0xf bank_mask:0xf
	s_nop 0
	s_nop 0
	v_add_f32_dpp v208, v208, v208 row_half_mirror row_mask:0xf bank_mask:0xf
	s_nop 0
	s_nop 0
	v_add_f32_dpp v208, v208, v208 row_mirror row_mask:0xf bank_mask:0xf
	s_nop 0
	s_nop 0
	v_add_f32_dpp v208, v208, v208 row_bcast:15 row_mask:0xa bank_mask:0xf
	s_nop 0
	s_nop 0
	v_add_f32_dpp v208, v208, v208 row_bcast:31 row_mask:0xc bank_mask:0xf
	s_nop 0
	s_nop 0
	v_readlane_b32 s60, v208, 63
	s_nop 1
	v_mov_b32_e32 v210, s60
	v_fmaak_f32 v210, v210, v212, 0x358637bd
	v_rsq_f32_e32 v210, v210
	s_nop 0
	v_pk_mul_f32 v[200:201], v[104:105], v[210:211] op_sel_hi:[1,0]
	v_pk_fma_f32 v[200:201], v[200:201], v[24:25], v[40:41]
	v_cvt_pk_bf16_f32 v184, v200, v201
	v_pk_mul_f32 v[202:203], v[106:107], v[210:211] op_sel_hi:[1,0]
	v_pk_fma_f32 v[202:203], v[202:203], v[26:27], v[42:43]
	v_cvt_pk_bf16_f32 v185, v202, v203
	v_pk_mul_f32 v[200:201], v[108:109], v[210:211] op_sel_hi:[1,0]
	v_pk_fma_f32 v[200:201], v[200:201], v[28:29], v[44:45]
	v_cvt_pk_bf16_f32 v186, v200, v201
	v_pk_mul_f32 v[202:203], v[110:111], v[210:211] op_sel_hi:[1,0]
	v_pk_fma_f32 v[202:203], v[202:203], v[30:31], v[46:47]
	v_cvt_pk_bf16_f32 v187, v202, v203
	v_pk_mul_f32 v[200:201], v[112:113], v[210:211] op_sel_hi:[1,0]
	v_pk_fma_f32 v[200:201], v[200:201], v[32:33], v[48:49]
	v_cvt_pk_bf16_f32 v188, v200, v201
	v_pk_mul_f32 v[202:203], v[114:115], v[210:211] op_sel_hi:[1,0]
	v_pk_fma_f32 v[202:203], v[202:203], v[34:35], v[50:51]
	v_cvt_pk_bf16_f32 v189, v202, v203
	v_pk_mul_f32 v[200:201], v[116:117], v[210:211] op_sel_hi:[1,0]
	v_pk_fma_f32 v[200:201], v[200:201], v[36:37], v[52:53]
	v_cvt_pk_bf16_f32 v190, v200, v201
	v_pk_mul_f32 v[202:203], v[118:119], v[210:211] op_sel_hi:[1,0]
	v_pk_fma_f32 v[202:203], v[202:203], v[38:39], v[54:55]
	v_cvt_pk_bf16_f32 v191, v202, v203
	global_store_dwordx4 v2, v[184:187], s[78:79]
	global_store_dwordx4 v2, v[188:191], s[78:79] offset:1024
	s_mov_b32 s82, 4
.Lrw_INIT_loop:
	s_add_i32 s81, s82, 4
	s_cmp_lt_u32 s81, 32
	s_cbranch_scc0 .Lrw_INIT_l0_d
	s_add_i32 s81, s80, 4
	s_add_i32 s81, s81, s82
	s_and_b32 s81, s81, 31
	s_lshl_b32 s83, s81, 12
	v_add_u32_e32 v213, s83, v3
	global_load_dwordx4 v[72:75], v213, s[72:73]
	global_load_dwordx4 v[76:79], v213, s[72:73] offset:16
	global_load_dwordx4 v[80:83], v213, s[72:73] offset:2048
	global_load_dwordx4 v[84:87], v213, s[72:73] offset:2064
	s_branch .Lrw_INIT_l0_e

; __device__ __forceinline__ unsigned cvtpk(float lo, float hi) { f32x2 v = {lo, hi}; bf16x2_t b = __builtin_convertvector(v, bf16x2_t); return __builtin_bit_cast(unsigned, b); }
; __device__ __forceinline__ void phase_rowwise(const void* xsrc_, bool sbf, void* xdst_, bool dbf, const bf16_t* Y, bf16_t* H, const float* mods, int lprev, int iprev, const float* lnpost, float resw, ...
;     ...
;                     for (int j = 0; j < 4; ++j) { if (sbf) xnb[r][j] = *(const u32x2*)(xsrcb + (m + 2 + r) * DM + 4 * lane + 256 * j); else xn[r][j] = *(const f32x4*)(xsrc + (m + 2 + r) * DM + 4 * lane + 256 * j); if (hasprev) yn[r][j] = *(const u32x2*)(Y + (m + 2 + r) * DM + 4 * lane + 256 * j); } }
;     ...
;             if (hasnext) {
;                 float ss[2] = {0.f, 0.f};
; #pragma unroll
;                 for (int r = 0; r < 2; ++r)
; #pragma unroll
;                     for (int j = 0; j < 4; ++j) ss[r] += (x[r][j].x * x[r][j].x + x[r][j].y * x[r][j].y) + (x[r][j].z * x[r][j].z + x[r][j].w * x[r][j].w);
; #pragma unroll
;                 for (int off = 1; off < 64; off <<= 1) { ss[0] += __shfl_xor(ss[0], off); ss[1] += __shfl_xor(ss[1], off); }
; #pragma unroll
;                 for (int r = 0; r < 2; ++r) { const float rs = __builtin_amdgcn_rsqf(ss[r] * (1.f / DM) + EPS);
; #pragma unroll
;                     for (int j = 0; j < 4; ++j) { const f32x4 h = (x[r][j] * rs) * na[j] + ns[j]; u32x2 w; w.x = cvtpk(h.x, h.y); w.y = cvtpk(h.z, h.w); *(u32x2*)(H + (m + r) * DM + 4 * lane + 256 * j) = w; } }
;             }
.Lrw_INIT_l0_e:
	s_waitcnt vmcnt(24)
	s_add_i32 s81, s80, 0
	s_add_i32 s81, s81, s82
	s_and_b32 s81, s81, 31
	s_lshl_b32 s83, s81, 11
	v_add_u32_e32 v2, s83, v1
	v_pk_mul_f32 v[204:205], v[120:121], v[120:121]
	v_pk_mul_f32 v[206:207], v[122:123], v[122:123]
	v_pk_fma_f32 v[204:205], v[124:125], v[124:125], v[204:205]
	v_pk_fma_f32 v[206:207], v[126:127], v[126:127], v[206:207]
	v_pk_fma_f32 v[204:205], v[128:129], v[128:129], v[204:205]
	v_pk_fma_f32 v[206:207], v[130:131], v[130:131], v[206:207]
	v_pk_fma_f32 v[204:205], v[132:133], v[132:133], v[204:205]
	v_pk_fma_f32 v[206:207], v[134:135], v[134:135], v[206:207]
	v_pk_add_f32 v[204:205], v[204:205], v[206:207]
	v_add_f32_e32 v208, v204, v205
	s_nop 0
	s_nop 0
	v_add_f32_dpp v208, v208, v208 quad_perm:[1,0,3,2] row_mask:0xf bank_mask:0xf
	s_nop 0
	s_nop 0
	v_add_f32_dpp v208, v208, v208 quad_perm:[2,3,0,1] row_mask:0xf bank_mask:0xf
	s_nop 0
	s_nop 0
	v_add_f32_dpp v208, v208, v208 row_half_mirror row_mask:0xf bank_mask:0xf
	s_nop 0
	s_nop 0
	v_add_f32_dpp v208, v208, v208 row_mirror row_mask:0xf bank_mask:0xf
	s_nop 0
	s_nop 0
	v_add_f32_dpp v208, v208, v208 row_bcast:15 row_mask:0xa bank_mask:0xf
	s_nop 0
	s_nop 0
	v_add_f32_dpp v208, v208, v208 row_bcast:31 row_mask:0xc bank_mask:0xf
	s_nop 0
	s_nop 0
	v_readlane_b32 s60, v208, 63
	s_nop 1
	v_mov_b32_e32 v210, s60
	v_fmaak_f32 v210, v210, v212, 0x358637bd
	v_rsq_f32_e32 v210, v210
	s_nop 0
	v_pk_mul_f32 v[200:201], v[120:121], v[210:211] op_sel_hi:[1,0]
	v_pk_fma_f32 v[200:201], v[200:201], v[24:25], v[40:41]
	v_cvt_pk_bf16_f32 v184, v200, v201
	v_pk_mul_f32 v[202:203], v[122:123], v[210:211] op_sel_hi:[1,0]
	v_pk_fma_f32 v[202:203], v[202:203], v[26:27], v[42:43]
	v_cvt_pk_bf16_f32 v185, v202, v203
	v_pk_mul_f32 v[200:201], v[124:125], v[210:211] op_sel_hi:[1,0]
	v_pk_fma_f32 v[200:201], v[200:201], v[28:29], v[44:45]
	v_cvt_pk_bf16_f32 v186, v200, v201
	v_pk_mul_f32 v[202:203], v[126:127], v[210:211] op_sel_hi:[1,0]
	v_pk_fma_f32 v[202:203], v[202:203], v[30:31], v[46:47]
	v_cvt_pk_bf16_f32 v187, v202, v203
	v_pk_mul_f32 v[200:201], v[128:129], v[210:211] op_sel_hi:[1,0]
	v_pk_fma_f32 v[200:201], v[200:201], v[32:33], v[48:49]
	v_cvt_pk_bf16_f32 v188, v200, v201
	v_pk_mul_f32 v[202:203], v[130:131], v[210:211] op_sel_hi:[1,0]
	v_pk_fma_f32 v[202:203], v[202:203], v[34:35], v[50:51]
	v_cvt_pk_bf16_f32 v189, v202, v203
	v_pk_mul_f32 v[200:201], v[132:133], v[210:211] op_sel_hi:[1,0]
	v_pk_fma_f32 v[200:201], v[200:201], v[36:37], v[52:53]
	v_cvt_pk_bf16_f32 v190, v200, v201
	v_pk_mul_f32 v[202:203], v[134:135], v[210:211] op_sel_hi:[1,0]
	v_pk_fma_f32 v[202:203], v[202:203], v[38:39], v[54:55]
	v_cvt_pk_bf16_f32 v191, v202, v203
	global_store_dwordx4 v2, v[184:187], s[78:79]
	global_store_dwordx4 v2, v[188:191], s[78:79] offset:1024
	s_add_i32 s81, s82, 5
	s_cmp_lt_u32 s81, 32
	s_cbranch_scc0 .Lrw_INIT_l1_d
	s_add_i32 s81, s80, 5
	s_add_i32 s81, s81, s82
	s_and_b32 s81, s81, 31
	s_lshl_b32 s83, s81, 12
	v_add_u32_e32 v213, s83, v3
	global_load_dwordx4 v[88:91], v213, s[72:73]
	global_load_dwordx4 v[92:95], v213, s[72:73] offset:16
	global_load_dwordx4 v[96:99], v213, s[72:73] offset:2048
	global_load_dwordx4 v[100:103], v213, s[72:73] offset:2064
	s_branch .Lrw_INIT_l1_e

; __device__ __forceinline__ unsigned cvtpk(float lo, float hi) { f32x2 v = {lo, hi}; bf16x2_t b = __builtin_convertvector(v, bf16x2_t); return __builtin_bit_cast(unsigned, b); }
; __device__ __forceinline__ void phase_rowwise(const void* xsrc_, bool sbf, void* xdst_, bool dbf, const bf16_t* Y, bf16_t* H, const float* mods, int lprev, int iprev, const float* lnpost, float resw, ...
;     ...
;                     for (int j = 0; j < 4; ++j) { if (sbf) xnb[r][j] = *(const u32x2*)(xsrcb + (m + 2 + r) * DM + 4 * lane + 256 * j); else xn[r][j] = *(const f32x4*)(xsrc + (m + 2 + r) * DM + 4 * lane + 256 * j); if (hasprev) yn[r][j] = *(const u32x2*)(Y + (m + 2 + r) * DM + 4 * lane + 256 * j); } }
;     ...
;             if (hasnext) {
;                 float ss[2] = {0.f, 0.f};
; #pragma unroll
;                 for (int r = 0; r < 2; ++r)
; #pragma unroll
;                     for (int j = 0; j < 4; ++j) ss[r] += (x[r][j].x * x[r][j].x + x[r][j].y * x[r][j].y) + (x[r][j].z * x[r][j].z + x[r][j].w * x[r][j].w);
; #pragma unroll
;                 for (int off = 1; off < 64; off <<= 1) { ss[0] += __shfl_xor(ss[0], off); ss[1] += __shfl_xor(ss[1], off); }
; #pragma unroll
;                 for (int r = 0; r < 2; ++r) { const float rs = __builtin_amdgcn_rsqf(ss[r] * (1.f / DM) + EPS);
; #pragma unroll
;                     for (int j = 0; j < 4; ++j) { const f32x4 h = (x[r][j] * rs) * na[j] + ns[j]; u32x2 w; w.x = cvtpk(h.x, h.y); w.y = cvtpk(h.z, h.w); *(u32x2*)(H + (m + r) * DM + 4 * lane + 256 * j) = w; } }
;             }
.Lrw_INIT_l1_e:
	s_waitcnt vmcnt(24)
	s_add_i32 s81, s80, 1
	s_add_i32 s81, s81, s82
	s_and_b32 s81, s81, 31
	s_lshl_b32 s83, s81, 11
	v_add_u32_e32 v2, s83, v1
	v_pk_mul_f32 v[204:205], v[136:137], v[136:137]
	v_pk_mul_f32 v[206:207], v[138:139], v[138:139]
	v_pk_fma_f32 v[204:205], v[140:141], v[140:141], v[204:205]
	v_pk_fma_f32 v[206:207], v[142:143], v[142:143], v[206:207]
	v_pk_fma_f32 v[204:205], v[144:145], v[144:145], v[204:205]
	v_pk_fma_f32 v[206:207], v[146:147], v[146:147], v[206:207]
	v_pk_fma_f32 v[204:205], v[148:149], v[148:149], v[204:205]
	v_pk_fma_f32 v[206:207], v[150:151], v[150:151], v[206:207]
	v_pk_add_f32 v[204:205], v[204:205], v[206:207]
	v_add_f32_e32 v208, v204, v205
	s_nop 0
	s_nop 0
	v_add_f32_dpp v208, v208, v208 quad_perm:[1,0,3,2] row_mask:0xf bank_mask:0xf
	s_nop 0
	s_nop 0
	v_add_f32_dpp v208, v208, v208 quad_perm:[2,3,0,1] row_mask:0xf bank_mask:0xf
	s_nop 0
	s_nop 0
	v_add_f32_dpp v208, v208, v208 row_half_mirror row_mask:0xf bank_mask:0xf
	s_nop 0
	s_nop 0
	v_add_f32_dpp v208, v208, v208 row_mirror row_mask:0xf bank_mask:0xf
	s_nop 0
	s_nop 0
	v_add_f32_dpp v208, v208, v208 row_bcast:15 row_mask:0xa bank_mask:0xf
	s_nop 0
	s_nop 0
	v_add_f32_dpp v208, v208, v208 row_bcast:31 row_mask:0xc bank_mask:0xf
	s_nop 0
	s_nop 0
	v_readlane_b32 s60, v208, 63
	s_nop 1
	v_mov_b32_e32 v210, s60
	v_fmaak_f32 v210, v210, v212, 0x358637bd
	v_rsq_f32_e32 v210, v210
	s_nop 0
	v_pk_mul_f32 v[200:201], v[136:137], v[210:211] op_sel_hi:[1,0]
	v_pk_fma_f32 v[200:201], v[200:201], v[24:25], v[40:41]
	v_cvt_pk_bf16_f32 v184, v200, v201
	v_pk_mul_f32 v[202:203], v[138:139], v[210:211] op_sel_hi:[1,0]
	v_pk_fma_f32 v[202:203], v[202:203], v[26:27], v[42:43]
	v_cvt_pk_bf16_f32 v185, v202, v203
	v_pk_mul_f32 v[200:201], v[140:141], v[210:211] op_sel_hi:[1,0]
	v_pk_fma_f32 v[200:201], v[200:201], v[28:29], v[44:45]
	v_cvt_pk_bf16_f32 v186, v200, v201
	v_pk_mul_f32 v[202:203], v[142:143], v[210:211] op_sel_hi:[1,0]
	v_pk_fma_f32 v[202:203], v[202:203], v[30:31], v[46:47]
	v_cvt_pk_bf16_f32 v187, v202, v203
	v_pk_mul_f32 v[200:201], v[144:145], v[210:211] op_sel_hi:[1,0]
	v_pk_fma_f32 v[200:201], v[200:201], v[32:33], v[48:49]
	v_cvt_pk_bf16_f32 v188, v200, v201
	v_pk_mul_f32 v[202:203], v[146:147], v[210:211] op_sel_hi:[1,0]
	v_pk_fma_f32 v[202:203], v[202:203], v[34:35], v[50:51]
	v_cvt_pk_bf16_f32 v189, v202, v203
	v_pk_mul_f32 v[200:201], v[148:149], v[210:211] op_sel_hi:[1,0]
	v_pk_fma_f32 v[200:201], v[200:201], v[36:37], v[52:53]
	v_cvt_pk_bf16_f32 v190, v200, v201
	v_pk_mul_f32 v[202:203], v[150:151], v[210:211] op_sel_hi:[1,0]
	v_pk_fma_f32 v[202:203], v[202:203], v[38:39], v[54:55]
	v_cvt_pk_bf16_f32 v191, v202, v203
	global_store_dwordx4 v2, v[184:187], s[78:79]
	global_store_dwordx4 v2, v[188:191], s[78:79] offset:1024
	s_add_i32 s81, s82, 6
	s_cmp_lt_u32 s81, 32
	s_cbranch_scc0 .Lrw_INIT_l2_d
	s_add_i32 s81, s80, 6
	s_add_i32 s81, s81, s82
	s_and_b32 s81, s81, 31
	s_lshl_b32 s83, s81, 12
	v_add_u32_e32 v213, s83, v3
	global_load_dwordx4 v[104:107], v213, s[72:73]
	global_load_dwordx4 v[108:111], v213, s[72:73] offset:16
	global_load_dwordx4 v[112:115], v213, s[72:73] offset:2048
	global_load_dwordx4 v[116:119], v213, s[72:73] offset:2064
	s_branch .Lrw_INIT_l2_e

; __device__ __forceinline__ unsigned cvtpk(float lo, float hi) { f32x2 v = {lo, hi}; bf16x2_t b = __builtin_convertvector(v, bf16x2_t); return __builtin_bit_cast(unsigned, b); }
; __device__ __forceinline__ void phase_rowwise(const void* xsrc_, bool sbf, void* xdst_, bool dbf, const bf16_t* Y, bf16_t* H, const float* mods, int lprev, int iprev, const float* lnpost, float resw, ...
;     ...
;                     for (int j = 0; j < 4; ++j) { if (sbf) xnb[r][j] = *(const u32x2*)(xsrcb + (m + 2 + r) * DM + 4 * lane + 256 * j); else xn[r][j] = *(const f32x4*)(xsrc + (m + 2 + r) * DM + 4 * lane + 256 * j); if (hasprev) yn[r][j] = *(const u32x2*)(Y + (m + 2 + r) * DM + 4 * lane + 256 * j); } }
;     ...
;             if (hasnext) {
;                 float ss[2] = {0.f, 0.f};
; #pragma unroll
;                 for (int r = 0; r < 2; ++r)
; #pragma unroll
;                     for (int j = 0; j < 4; ++j) ss[r] += (x[r][j].x * x[r][j].x + x[r][j].y * x[r][j].y) + (x[r][j].z * x[r][j].z + x[r][j].w * x[r][j].w);
; #pragma unroll
;                 for (int off = 1; off < 64; off <<= 1) { ss[0] += __shfl_xor(ss[0], off); ss[1] += __shfl_xor(ss[1], off); }
; #pragma unroll
;                 for (int r = 0; r < 2; ++r) { const float rs = __builtin_amdgcn_rsqf(ss[r] * (1.f / DM) + EPS);
; #pragma unroll
;                     for (int j = 0; j < 4; ++j) { const f32x4 h = (x[r][j] * rs) * na[j] + ns[j]; u32x2 w; w.x = cvtpk(h.x, h.y); w.y = cvtpk(h.z, h.w); *(u32x2*)(H + (m + r) * DM + 4 * lane + 256 * j) = w; } }
;             }
.Lrw_INIT_l2_e:
	s_waitcnt vmcnt(24)
	s_add_i32 s81, s80, 2
	s_add_i32 s81, s81, s82
	s_and_b32 s81, s81, 31
	s_lshl_b32 s83, s81, 11
	v_add_u32_e32 v2, s83, v1
	v_pk_mul_f32 v[204:205], v[152:153], v[152:153]
	v_pk_mul_f32 v[206:207], v[154:155], v[154:155]
	v_pk_fma_f32 v[204:205], v[156:157], v[156:157], v[204:205]
	v_pk_fma_f32 v[206:207], v[158:159], v[158:159], v[206:207]
	v_pk_fma_f32 v[204:205], v[160:161], v[160:161], v[204:205]
	v_pk_fma_f32 v[206:207], v[162:163], v[162:163], v[206:207]
	v_pk_fma_f32 v[204:205], v[164:165], v[164:165], v[204:205]
	v_pk_fma_f32 v[206:207], v[166:167], v[166:167], v[206:207]
	v_pk_add_f32 v[204:205], v[204:205], v[206:207]
	v_add_f32_e32 v208, v204, v205
	s_nop 0
	s_nop 0
	v_add_f32_dpp v208, v208, v208 quad_perm:[1,0,3,2] row_mask:0xf bank_mask:0xf
	s_nop 0
	s_nop 0
	v_add_f32_dpp v208, v208, v208 quad_perm:[2,3,0,1] row_mask:0xf bank_mask:0xf
	s_nop 0
	s_nop 0
	v_add_f32_dpp v208, v208, v208 row_half_mirror row_mask:0xf bank_mask:0xf
	s_nop 0
	s_nop 0
	v_add_f32_dpp v208, v208, v208 row_mirror row_mask:0xf bank_mask:0xf
	s_nop 0
	s_nop 0
	v_add_f32_dpp v208, v208, v208 row_bcast:15 row_mask:0xa bank_mask:0xf
	s_nop 0
	s_nop 0
	v_add_f32_dpp v208, v208, v208 row_bcast:31 row_mask:0xc bank_mask:0xf
	s_nop 0
	s_nop 0
	v_readlane_b32 s60, v208, 63
	s_nop 1
	v_mov_b32_e32 v210, s60
	v_fmaak_f32 v210, v210, v212, 0x358637bd
	v_rsq_f32_e32 v210, v210
	s_nop 0
	v_pk_mul_f32 v[200:201], v[152:153], v[210:211] op_sel_hi:[1,0]
	v_pk_fma_f32 v[200:201], v[200:201], v[24:25], v[40:41]
	v_cvt_pk_bf16_f32 v184, v200, v201
	v_pk_mul_f32 v[202:203], v[154:155], v[210:211] op_sel_hi:[1,0]
	v_pk_fma_f32 v[202:203], v[202:203], v[26:27], v[42:43]
	v_cvt_pk_bf16_f32 v185, v202, v203
	v_pk_mul_f32 v[200:201], v[156:157], v[210:211] op_sel_hi:[1,0]
	v_pk_fma_f32 v[200:201], v[200:201], v[28:29], v[44:45]
	v_cvt_pk_bf16_f32 v186, v200, v201
	v_pk_mul_f32 v[202:203], v[158:159], v[210:211] op_sel_hi:[1,0]
	v_pk_fma_f32 v[202:203], v[202:203], v[30:31], v[46:47]
	v_cvt_pk_bf16_f32 v187, v202, v203
	v_pk_mul_f32 v[200:201], v[160:161], v[210:211] op_sel_hi:[1,0]
	v_pk_fma_f32 v[200:201], v[200:201], v[32:33], v[48:49]
	v_cvt_pk_bf16_f32 v188, v200, v201
	v_pk_mul_f32 v[202:203], v[162:163], v[210:211] op_sel_hi:[1,0]
	v_pk_fma_f32 v[202:203], v[202:203], v[34:35], v[50:51]
	v_cvt_pk_bf16_f32 v189, v202, v203
	v_pk_mul_f32 v[200:201], v[164:165], v[210:211] op_sel_hi:[1,0]
	v_pk_fma_f32 v[200:201], v[200:201], v[36:37], v[52:53]
	v_cvt_pk_bf16_f32 v190, v200, v201
	v_pk_mul_f32 v[202:203], v[166:167], v[210:211] op_sel_hi:[1,0]
	v_pk_fma_f32 v[202:203], v[202:203], v[38:39], v[54:55]
	v_cvt_pk_bf16_f32 v191, v202, v203
	global_store_dwordx4 v2, v[184:187], s[78:79]
	global_store_dwordx4 v2, v[188:191], s[78:79] offset:1024
	s_add_i32 s81, s82, 7
	s_cmp_lt_u32 s81, 32
	s_cbranch_scc0 .Lrw_INIT_l3_d
	s_add_i32 s81, s80, 7
	s_add_i32 s81, s81, s82
	s_and_b32 s81, s81, 31
	s_lshl_b32 s83, s81, 12
	v_add_u32_e32 v213, s83, v3
	global_load_dwordx4 v[120:123], v213, s[72:73]
	global_load_dwordx4 v[124:127], v213, s[72:73] offset:16
	global_load_dwordx4 v[128:131], v213, s[72:73] offset:2048
	global_load_dwordx4 v[132:135], v213, s[72:73] offset:2064
	s_branch .Lrw_INIT_l3_e

; __device__ __forceinline__ unsigned cvtpk(float lo, float hi) { f32x2 v = {lo, hi}; bf16x2_t b = __builtin_convertvector(v, bf16x2_t); return __builtin_bit_cast(unsigned, b); }
; __device__ __forceinline__ void phase_rowwise(const void* xsrc_, bool sbf, void* xdst_, bool dbf, const bf16_t* Y, bf16_t* H, const float* mods, int lprev, int iprev, const float* lnpost, float resw, ...
;     ...
;                     for (int j = 0; j < 4; ++j) { if (sbf) xnb[r][j] = *(const u32x2*)(xsrcb + (m + 2 + r) * DM + 4 * lane + 256 * j); else xn[r][j] = *(const f32x4*)(xsrc + (m + 2 + r) * DM + 4 * lane + 256 * j); if (hasprev) yn[r][j] = *(const u32x2*)(Y + (m + 2 + r) * DM + 4 * lane + 256 * j); } }
;     ...
;             if (hasnext) {
;                 float ss[2] = {0.f, 0.f};
; #pragma unroll
;                 for (int r = 0; r < 2; ++r)
; #pragma unroll
;                     for (int j = 0; j < 4; ++j) ss[r] += (x[r][j].x * x[r][j].x + x[r][j].y * x[r][j].y) + (x[r][j].z * x[r][j].z + x[r][j].w * x[r][j].w);
; #pragma unroll
;                 for (int off = 1; off < 64; off <<= 1) { ss[0] += __shfl_xor(ss[0], off); ss[1] += __shfl_xor(ss[1], off); }
; #pragma unroll
;                 for (int r = 0; r < 2; ++r) { const float rs = __builtin_amdgcn_rsqf(ss[r] * (1.f / DM) + EPS);
; #pragma unroll
;                     for (int j = 0; j < 4; ++j) { const f32x4 h = (x[r][j] * rs) * na[j] + ns[j]; u32x2 w; w.x = cvtpk(h.x, h.y); w.y = cvtpk(h.z, h.w); *(u32x2*)(H + (m + r) * DM + 4 * lane + 256 * j) = w; } }
;             }
.Lrw_INIT_l3_e:
	s_waitcnt vmcnt(24)
	s_add_i32 s81, s80, 3
	s_add_i32 s81, s81, s82
	s_and_b32 s81, s81, 31
	s_lshl_b32 s83, s81, 11
	v_add_u32_e32 v2, s83, v1
	v_pk_mul_f32 v[204:205], v[56:57], v[56:57]
	v_pk_mul_f32 v[206:207], v[58:59], v[58:59]
	v_pk_fma_f32 v[204:205], v[60:61], v[60:61], v[204:205]
	v_pk_fma_f32 v[206:207], v[62:63], v[62:63], v[206:207]
	v_pk_fma_f32 v[204:205], v[64:65], v[64:65], v[204:205]
	v_pk_fma_f32 v[206:207], v[66:67], v[66:67], v[206:207]
	v_pk_fma_f32 v[204:205], v[68:69], v[68:69], v[204:205]
	v_pk_fma_f32 v[206:207], v[70:71], v[70:71], v[206:207]
	v_pk_add_f32 v[204:205], v[204:205], v[206:207]
	v_add_f32_e32 v208, v204, v205
	s_nop 0
	s_nop 0
	v_add_f32_dpp v208, v208, v208 quad_perm:[1,0,3,2] row_mask:0xf bank_mask:0xf
	s_nop 0
	s_nop 0
	v_add_f32_dpp v208, v208, v208 quad_perm:[2,3,0,1] row_mask:0xf bank_mask:0xf
	s_nop 0
	s_nop 0
	v_add_f32_dpp v208, v208, v208 row_half_mirror row_mask:0xf bank_mask:0xf
	s_nop 0
	s_nop 0
	v_add_f32_dpp v208, v208, v208 row_mirror row_mask:0xf bank_mask:0xf
	s_nop 0
	s_nop 0
	v_add_f32_dpp v208, v208, v208 row_bcast:15 row_mask:0xa bank_mask:0xf
	s_nop 0
	s_nop 0
	v_add_f32_dpp v208, v208, v208 row_bcast:31 row_mask:0xc bank_mask:0xf
	s_nop 0
	s_nop 0
	v_readlane_b32 s60, v208, 63
	s_nop 1
	v_mov_b32_e32 v210, s60
	v_fmaak_f32 v210, v210, v212, 0x358637bd
	v_rsq_f32_e32 v210, v210
	s_nop 0
	v_pk_mul_f32 v[200:201], v[56:57], v[210:211] op_sel_hi:[1,0]
	v_pk_fma_f32 v[200:201], v[200:201], v[24:25], v[40:41]
	v_cvt_pk_bf16_f32 v184, v200, v201
	v_pk_mul_f32 v[202:203], v[58:59], v[210:211] op_sel_hi:[1,0]
	v_pk_fma_f32 v[202:203], v[202:203], v[26:27], v[42:43]
	v_cvt_pk_bf16_f32 v185, v202, v203
	v_pk_mul_f32 v[200:201], v[60:61], v[210:211] op_sel_hi:[1,0]
	v_pk_fma_f32 v[200:201], v[200:201], v[28:29], v[44:45]
	v_cvt_pk_bf16_f32 v186, v200, v201
	v_pk_mul_f32 v[202:203], v[62:63], v[210:211] op_sel_hi:[1,0]
	v_pk_fma_f32 v[202:203], v[202:203], v[30:31], v[46:47]
	v_cvt_pk_bf16_f32 v187, v202, v203
	v_pk_mul_f32 v[200:201], v[64:65], v[210:211] op_sel_hi:[1,0]
	v_pk_fma_f32 v[200:201], v[200:201], v[32:33], v[48:49]
	v_cvt_pk_bf16_f32 v188, v200, v201
	v_pk_mul_f32 v[202:203], v[66:67], v[210:211] op_sel_hi:[1,0]
	v_pk_fma_f32 v[202:203], v[202:203], v[34:35], v[50:51]
	v_cvt_pk_bf16_f32 v189, v202, v203
	v_pk_mul_f32 v[200:201], v[68:69], v[210:211] op_sel_hi:[1,0]
	v_pk_fma_f32 v[200:201], v[200:201], v[36:37], v[52:53]
	v_cvt_pk_bf16_f32 v190, v200, v201
	v_pk_mul_f32 v[202:203], v[70:71], v[210:211] op_sel_hi:[1,0]
	v_pk_fma_f32 v[202:203], v[202:203], v[38:39], v[54:55]
	v_cvt_pk_bf16_f32 v191, v202, v203
	global_store_dwordx4 v2, v[184:187], s[78:79]
	global_store_dwordx4 v2, v[188:191], s[78:79] offset:1024
	s_add_i32 s81, s82, 8
	s_cmp_lt_u32 s81, 32
	s_cbranch_scc0 .Lrw_INIT_l4_d
	s_add_i32 s81, s80, 8
	s_add_i32 s81, s81, s82
	s_and_b32 s81, s81, 31
	s_lshl_b32 s83, s81, 12
	v_add_u32_e32 v213, s83, v3
	global_load_dwordx4 v[136:139], v213, s[72:73]
	global_load_dwordx4 v[140:143], v213, s[72:73] offset:16
	global_load_dwordx4 v[144:147], v213, s[72:73] offset:2048
	global_load_dwordx4 v[148:151], v213, s[72:73] offset:2064
	s_branch .Lrw_INIT_l4_e

; __device__ __forceinline__ unsigned cvtpk(float lo, float hi) { f32x2 v = {lo, hi}; bf16x2_t b = __builtin_convertvector(v, bf16x2_t); return __builtin_bit_cast(unsigned, b); }
; __device__ __forceinline__ void phase_rowwise(const void* xsrc_, bool sbf, void* xdst_, bool dbf, const bf16_t* Y, bf16_t* H, const float* mods, int lprev, int iprev, const float* lnpost, float resw, ...
;     ...
;                     for (int j = 0; j < 4; ++j) { if (sbf) xnb[r][j] = *(const u32x2*)(xsrcb + (m + 2 + r) * DM + 4 * lane + 256 * j); else xn[r][j] = *(const f32x4*)(xsrc + (m + 2 + r) * DM + 4 * lane + 256 * j); if (hasprev) yn[r][j] = *(const u32x2*)(Y + (m + 2 + r) * DM + 4 * lane + 256 * j); } }
;     ...
;             if (hasnext) {
;                 float ss[2] = {0.f, 0.f};
; #pragma unroll
;                 for (int r = 0; r < 2; ++r)
; #pragma unroll
;                     for (int j = 0; j < 4; ++j) ss[r] += (x[r][j].x * x[r][j].x + x[r][j].y * x[r][j].y) + (x[r][j].z * x[r][j].z + x[r][j].w * x[r][j].w);
; #pragma unroll
;                 for (int off = 1; off < 64; off <<= 1) { ss[0] += __shfl_xor(ss[0], off); ss[1] += __shfl_xor(ss[1], off); }
; #pragma unroll
;                 for (int r = 0; r < 2; ++r) { const float rs = __builtin_amdgcn_rsqf(ss[r] * (1.f / DM) + EPS);
; #pragma unroll
;                     for (int j = 0; j < 4; ++j) { const f32x4 h = (x[r][j] * rs) * na[j] + ns[j]; u32x2 w; w.x = cvtpk(h.x, h.y); w.y = cvtpk(h.z, h.w); *(u32x2*)(H + (m + r) * DM + 4 * lane + 256 * j) = w; } }
;             }
.Lrw_INIT_l4_e:
	s_waitcnt vmcnt(24)
	s_add_i32 s81, s80, 4
	s_add_i32 s81, s81, s82
	s_and_b32 s81, s81, 31
	s_lshl_b32 s83, s81, 11
	v_add_u32_e32 v2, s83, v1
	v_pk_mul_f32 v[204:205], v[72:73], v[72:73]
	v_pk_mul_f32 v[206:207], v[74:75], v[74:75]
	v_pk_fma_f32 v[204:205], v[76:77], v[76:77], v[204:205]
	v_pk_fma_f32 v[206:207], v[78:79], v[78:79], v[206:207]
	v_pk_fma_f32 v[204:205], v[80:81], v[80:81], v[204:205]
	v_pk_fma_f32 v[206:207], v[82:83], v[82:83], v[206:207]
	v_pk_fma_f32 v[204:205], v[84:85], v[84:85], v[204:205]
	v_pk_fma_f32 v[206:207], v[86:87], v[86:87], v[206:207]
	v_pk_add_f32 v[204:205], v[204:205], v[206:207]
	v_add_f32_e32 v208, v204, v205
	s_nop 0
	s_nop 0
	v_add_f32_dpp v208, v208, v208 quad_perm:[1,0,3,2] row_mask:0xf bank_mask:0xf
	s_nop 0
	s_nop 0
	v_add_f32_dpp v208, v208, v208 quad_perm:[2,3,0,1] row_mask:0xf bank_mask:0xf
	s_nop 0
	s_nop 0
	v_add_f32_dpp v208, v208, v208 row_half_mirror row_mask:0xf bank_mask:0xf
	s_nop 0
	s_nop 0
	v_add_f32_dpp v208, v208, v208 row_mirror row_mask:0xf bank_mask:0xf
	s_nop 0
	s_nop 0
	v_add_f32_dpp v208, v208, v208 row_bcast:15 row_mask:0xa bank_mask:0xf
	s_nop 0
	s_nop 0
	v_add_f32_dpp v208, v208, v208 row_bcast:31 row_mask:0xc bank_mask:0xf
	s_nop 0
	s_nop 0
	v_readlane_b32 s60, v208, 63
	s_nop 1
	v_mov_b32_e32 v210, s60
	v_fmaak_f32 v210, v210, v212, 0x358637bd
	v_rsq_f32_e32 v210, v210
	s_nop 0
	v_pk_mul_f32 v[200:201], v[72:73], v[210:211] op_sel_hi:[1,0]
	v_pk_fma_f32 v[200:201], v[200:201], v[24:25], v[40:41]
	v_cvt_pk_bf16_f32 v184, v200, v201
	v_pk_mul_f32 v[202:203], v[74:75], v[210:211] op_sel_hi:[1,0]
	v_pk_fma_f32 v[202:203], v[202:203], v[26:27], v[42:43]
	v_cvt_pk_bf16_f32 v185, v202, v203
	v_pk_mul_f32 v[200:201], v[76:77], v[210:211] op_sel_hi:[1,0]
	v_pk_fma_f32 v[200:201], v[200:201], v[28:29], v[44:45]
	v_cvt_pk_bf16_f32 v186, v200, v201
	v_pk_mul_f32 v[202:203], v[78:79], v[210:211] op_sel_hi:[1,0]
	v_pk_fma_f32 v[202:203], v[202:203], v[30:31], v[46:47]
	v_cvt_pk_bf16_f32 v187, v202, v203
	v_pk_mul_f32 v[200:201], v[80:81], v[210:211] op_sel_hi:[1,0]
	v_pk_fma_f32 v[200:201], v[200:201], v[32:33], v[48:49]
	v_cvt_pk_bf16_f32 v188, v200, v201
	v_pk_mul_f32 v[202:203], v[82:83], v[210:211] op_sel_hi:[1,0]
	v_pk_fma_f32 v[202:203], v[202:203], v[34:35], v[50:51]
	v_cvt_pk_bf16_f32 v189, v202, v203
	v_pk_mul_f32 v[200:201], v[84:85], v[210:211] op_sel_hi:[1,0]
	v_pk_fma_f32 v[200:201], v[200:201], v[36:37], v[52:53]
	v_cvt_pk_bf16_f32 v190, v200, v201
	v_pk_mul_f32 v[202:203], v[86:87], v[210:211] op_sel_hi:[1,0]
	v_pk_fma_f32 v[202:203], v[202:203], v[38:39], v[54:55]
	v_cvt_pk_bf16_f32 v191, v202, v203
	global_store_dwordx4 v2, v[184:187], s[78:79]
	global_store_dwordx4 v2, v[188:191], s[78:79] offset:1024
	s_add_i32 s81, s82, 9
	s_cmp_lt_u32 s81, 32
	s_cbranch_scc0 .Lrw_INIT_l5_d
	s_add_i32 s81, s80, 9
	s_add_i32 s81, s81, s82
	s_and_b32 s81, s81, 31
	s_lshl_b32 s83, s81, 12
	v_add_u32_e32 v213, s83, v3
	global_load_dwordx4 v[152:155], v213, s[72:73]
	global_load_dwordx4 v[156:159], v213, s[72:73] offset:16
	global_load_dwordx4 v[160:163], v213, s[72:73] offset:2048
	global_load_dwordx4 v[164:167], v213, s[72:73] offset:2064
	s_branch .Lrw_INIT_l5_e

; __device__ __forceinline__ unsigned cvtpk(float lo, float hi) { f32x2 v = {lo, hi}; bf16x2_t b = __builtin_convertvector(v, bf16x2_t); return __builtin_bit_cast(unsigned, b); }
; __device__ __forceinline__ void phase_rowwise(const void* xsrc_, bool sbf, void* xdst_, bool dbf, const bf16_t* Y, bf16_t* H, const float* mods, int lprev, int iprev, const float* lnpost, float resw, ...
;     ...
;                     for (int j = 0; j < 4; ++j) { if (sbf) xnb[r][j] = *(const u32x2*)(xsrcb + (m + 2 + r) * DM + 4 * lane + 256 * j); else xn[r][j] = *(const f32x4*)(xsrc + (m + 2 + r) * DM + 4 * lane + 256 * j); if (hasprev) yn[r][j] = *(const u32x2*)(Y + (m + 2 + r) * DM + 4 * lane + 256 * j); } }
;     ...
;             if (hasnext) {
;                 float ss[2] = {0.f, 0.f};
; #pragma unroll
;                 for (int r = 0; r < 2; ++r)
; #pragma unroll
;                     for (int j = 0; j < 4; ++j) ss[r] += (x[r][j].x * x[r][j].x + x[r][j].y * x[r][j].y) + (x[r][j].z * x[r][j].z + x[r][j].w * x[r][j].w);
; #pragma unroll
;                 for (int off = 1; off < 64; off <<= 1) { ss[0] += __shfl_xor(ss[0], off); ss[1] += __shfl_xor(ss[1], off); }
; #pragma unroll
;                 for (int r = 0; r < 2; ++r) { const float rs = __builtin_amdgcn_rsqf(ss[r] * (1.f / DM) + EPS);
; #pragma unroll
;                     for (int j = 0; j < 4; ++j) { const f32x4 h = (x[r][j] * rs) * na[j] + ns[j]; u32x2 w; w.x = cvtpk(h.x, h.y); w.y = cvtpk(h.z, h.w); *(u32x2*)(H + (m + r) * DM + 4 * lane + 256 * j) = w; } }
;             }
.Lrw_INIT_l5_e:
	s_waitcnt vmcnt(24)
	s_add_i32 s81, s80, 5
	s_add_i32 s81, s81, s82
	s_and_b32 s81, s81, 31
	s_lshl_b32 s83, s81, 11
	v_add_u32_e32 v2, s83, v1
	v_pk_mul_f32 v[204:205], v[88:89], v[88:89]
	v_pk_mul_f32 v[206:207], v[90:91], v[90:91]
	v_pk_fma_f32 v[204:205], v[92:93], v[92:93], v[204:205]
	v_pk_fma_f32 v[206:207], v[94:95], v[94:95], v[206:207]
	v_pk_fma_f32 v[204:205], v[96:97], v[96:97], v[204:205]
	v_pk_fma_f32 v[206:207], v[98:99], v[98:99], v[206:207]
	v_pk_fma_f32 v[204:205], v[100:101], v[100:101], v[204:205]
	v_pk_fma_f32 v[206:207], v[102:103], v[102:103], v[206:207]
	v_pk_add_f32 v[204:205], v[204:205], v[206:207]
	v_add_f32_e32 v208, v204, v205
	s_nop 0
	s_nop 0
	v_add_f32_dpp v208, v208, v208 quad_perm:[1,0,3,2] row_mask:0xf bank_mask:0xf
	s_nop 0
	s_nop 0
	v_add_f32_dpp v208, v208, v208 quad_perm:[2,3,0,1] row_mask:0xf bank_mask:0xf
	s_nop 0
	s_nop 0
	v_add_f32_dpp v208, v208, v208 row_half_mirror row_mask:0xf bank_mask:0xf
	s_nop 0
	s_nop 0
	v_add_f32_dpp v208, v208, v208 row_mirror row_mask:0xf bank_mask:0xf
	s_nop 0
	s_nop 0
	v_add_f32_dpp v208, v208, v208 row_bcast:15 row_mask:0xa bank_mask:0xf
	s_nop 0
	s_nop 0
	v_add_f32_dpp v208, v208, v208 row_bcast:31 row_mask:0xc bank_mask:0xf
	s_nop 0
	s_nop 0
	v_readlane_b32 s60, v208, 63
	s_nop 1
	v_mov_b32_e32 v210, s60
	v_fmaak_f32 v210, v210, v212, 0x358637bd
	v_rsq_f32_e32 v210, v210
	s_nop 0
	v_pk_mul_f32 v[200:201], v[88:89], v[210:211] op_sel_hi:[1,0]
	v_pk_fma_f32 v[200:201], v[200:201], v[24:25], v[40:41]
	v_cvt_pk_bf16_f32 v184, v200, v201
	v_pk_mul_f32 v[202:203], v[90:91], v[210:211] op_sel_hi:[1,0]
	v_pk_fma_f32 v[202:203], v[202:203], v[26:27], v[42:43]
	v_cvt_pk_bf16_f32 v185, v202, v203
	v_pk_mul_f32 v[200:201], v[92:93], v[210:211] op_sel_hi:[1,0]
	v_pk_fma_f32 v[200:201], v[200:201], v[28:29], v[44:45]
	v_cvt_pk_bf16_f32 v186, v200, v201
	v_pk_mul_f32 v[202:203], v[94:95], v[210:211] op_sel_hi:[1,0]
	v_pk_fma_f32 v[202:203], v[202:203], v[30:31], v[46:47]
	v_cvt_pk_bf16_f32 v187, v202, v203
	v_pk_mul_f32 v[200:201], v[96:97], v[210:211] op_sel_hi:[1,0]
	v_pk_fma_f32 v[200:201], v[200:201], v[32:33], v[48:49]
	v_cvt_pk_bf16_f32 v188, v200, v201
	v_pk_mul_f32 v[202:203], v[98:99], v[210:211] op_sel_hi:[1,0]
	v_pk_fma_f32 v[202:203], v[202:203], v[34:35], v[50:51]
	v_cvt_pk_bf16_f32 v189, v202, v203
	v_pk_mul_f32 v[200:201], v[100:101], v[210:211] op_sel_hi:[1,0]
	v_pk_fma_f32 v[200:201], v[200:201], v[36:37], v[52:53]
	v_cvt_pk_bf16_f32 v190, v200, v201
	v_pk_mul_f32 v[202:203], v[102:103], v[210:211] op_sel_hi:[1,0]
	v_pk_fma_f32 v[202:203], v[202:203], v[38:39], v[54:55]
	v_cvt_pk_bf16_f32 v191, v202, v203
	global_store_dwordx4 v2, v[184:187], s[78:79]
	global_store_dwordx4 v2, v[188:191], s[78:79] offset:1024
	s_add_i32 s81, s82, 10
	s_cmp_lt_u32 s81, 32
	s_cbranch_scc0 .Lrw_INIT_l6_d
	s_add_i32 s81, s80, 10
	s_add_i32 s81, s81, s82
	s_and_b32 s81, s81, 31
	s_lshl_b32 s83, s81, 12
	v_add_u32_e32 v213, s83, v3
	global_load_dwordx4 v[56:59], v213, s[72:73]
	global_load_dwordx4 v[60:63], v213, s[72:73] offset:16
	global_load_dwordx4 v[64:67], v213, s[72:73] offset:2048
	global_load_dwordx4 v[68:71], v213, s[72:73] offset:2064
	s_branch .Lrw_INIT_l6_e

; __device__ __forceinline__ void phase_rowwise(const void* xsrc_, bool sbf, void* xdst_, bool dbf, const bf16_t* Y, bf16_t* H, const float* mods, int lprev, int iprev, const float* lnpost, float resw, ...
;     ...
;     for (int ch = gw; ch < M / 32; ch += NGW) {
;         const int b = ch >> 6;
;         f32x4 gp[4], na[4], ns[4];
; #pragma unroll
;         for (int j = 0; j < 4; ++j) { const int c = 4 * lane + 256 * j;
;             if (hasprev) { const f32x4 g = *(const f32x4*)(mods + ((size_t)lprev * 32 + b) * 9216 + iprev * 3072 + 2048 + c); const f32x4 lp = *(const f32x4*)(lnpost + c); gp[j] = g * lp * resw; }
;             else gp[j] = (f32x4){0.f, 0.f, 0.f, 0.f};
;             if (hasnext) { const f32x4 sh = *(const f32x4*)(mods + ((size_t)lnext * 32 + b) * 9216 + inext * 3072 + c); const f32x4 scl = *(const f32x4*)(mods + ((size_t)lnext * 32 + b) * 9216 + inext * 3072 + 1024 + c);
;                 const f32x4 lp = *(const f32x4*)(lnpre + c); na[j] = lp * (scl + 1.0f); ns[j] = sh; }
;             else { na[j] = (f32x4){0.f, 0.f, 0.f, 0.f}; ns[j] = na[j]; } }
;         f32x4 xn[2][4]; u32x2 xnb[2][4]; u32x2 yn[2][4];
;         { const size_t m0 = (size_t)ch * 32;
; #pragma unroll
;           for (int r = 0; r < 2; ++r)
; #pragma unroll
;             for (int j = 0; j < 4; ++j) { if (sbf) { xnb[r][j] = *(const u32x2*)(xsrcb + (m0 + r) * DM + 4 * lane + 256 * j); xn[r][j] = (f32x4){0.f, 0.f, 0.f, 0.f}; } else { xn[r][j] = *(const f32x4*)(xsrc + (m0 + r) * DM + 4 * lane + 256 * j); xnb[r][j] = (u32x2){0u, 0u}; }
;     ...
;             if (hasnext) {
;                 float ss[2] = {0.f, 0.f};
; #pragma unroll
;                 for (int r = 0; r < 2; ++r)
; #pragma unroll
;                     for (int j = 0; j < 4; ++j) ss[r] += (x[r][j].x * x[r][j].x + x[r][j].y * x[r][j].y) + (x[r][j].z * x[r][j].z + x[r][j].w * x[r][j].w);
; #pragma unroll
;                 for (int off = 1; off < 64; off <<= 1) { ss[0] += __shfl_xor(ss[0], off); ss[1] += __shfl_xor(ss[1], off); }
; #pragma unroll
;                 for (int r = 0; r < 2; ++r) { const float rs = __builtin_amdgcn_rsqf(ss[r] * (1.f / DM) + EPS);
; #pragma unroll
;                     for (int j = 0; j < 4; ++j) { const f32x4 h = (x[r][j] * rs) * na[j] + ns[j]; u32x2 w; w.x = cvtpk(h.x, h.y); w.y = cvtpk(h.z, h.w); *(u32x2*)(H + (m + r) * DM + 4 * lane + 256 * j) = w; } }
;             }
.Lrw_INIT_l6_e:
	s_waitcnt vmcnt(24)
	s_add_i32 s81, s80, 6
	s_add_i32 s81, s81, s82
	s_and_b32 s81, s81, 31
	s_lshl_b32 s83, s81, 11
	v_add_u32_e32 v2, s83, v1
	v_pk_mul_f32 v[204:205], v[104:105], v[104:105]
	v_pk_mul_f32 v[206:207], v[106:107], v[106:107]
	v_pk_fma_f32 v[204:205], v[108:109], v[108:109], v[204:205]
	v_pk_fma_f32 v[206:207], v[110:111], v[110:111], v[206:207]
	v_pk_fma_f32 v[204:205], v[112:113], v[112:113], v[204:205]
	v_pk_fma_f32 v[206:207], v[114:115], v[114:115], v[206:207]
	v_pk_fma_f32 v[204:205], v[116:117], v[116:117], v[204:205]
	v_pk_fma_f32 v[206:207], v[118:119], v[118:119], v[206:207]
	v_pk_add_f32 v[204:205], v[204:205], v[206:207]
	v_add_f32_e32 v208, v204, v205
	s_nop 0
	s_nop 0
	v_add_f32_dpp v208, v208, v208 quad_perm:[1,0,3,2] row_mask:0xf bank_mask:0xf
	s_nop 0
	s_nop 0
	v_add_f32_dpp v208, v208, v208 quad_perm:[2,3,0,1] row_mask:0xf bank_mask:0xf
	s_nop 0
	s_nop 0
	v_add_f32_dpp v208, v208, v208 row_half_mirror row_mask:0xf bank_mask:0xf
	s_nop 0
	s_nop 0
	v_add_f32_dpp v208, v208, v208 row_mirror row_mask:0xf bank_mask:0xf
	s_nop 0
	s_nop 0
	v_add_f32_dpp v208, v208, v208 row_bcast:15 row_mask:0xa bank_mask:0xf
	s_nop 0
	s_nop 0
	v_add_f32_dpp v208, v208, v208 row_bcast:31 row_mask:0xc bank_mask:0xf
	s_nop 0
	s_nop 0
	v_readlane_b32 s60, v208, 63
	s_nop 1
	v_mov_b32_e32 v210, s60
	v_fmaak_f32 v210, v210, v212, 0x358637bd
	v_rsq_f32_e32 v210, v210
	s_nop 0
	v_pk_mul_f32 v[200:201], v[104:105], v[210:211] op_sel_hi:[1,0]
	v_pk_fma_f32 v[200:201], v[200:201], v[24:25], v[40:41]
	v_cvt_pk_bf16_f32 v184, v200, v201
	v_pk_mul_f32 v[202:203], v[106:107], v[210:211] op_sel_hi:[1,0]
	v_pk_fma_f32 v[202:203], v[202:203], v[26:27], v[42:43]
	v_cvt_pk_bf16_f32 v185, v202, v203
	v_pk_mul_f32 v[200:201], v[108:109], v[210:211] op_sel_hi:[1,0]
	v_pk_fma_f32 v[200:201], v[200:201], v[28:29], v[44:45]
	v_cvt_pk_bf16_f32 v186, v200, v201
	v_pk_mul_f32 v[202:203], v[110:111], v[210:211] op_sel_hi:[1,0]
	v_pk_fma_f32 v[202:203], v[202:203], v[30:31], v[46:47]
	v_cvt_pk_bf16_f32 v187, v202, v203
	v_pk_mul_f32 v[200:201], v[112:113], v[210:211] op_sel_hi:[1,0]
	v_pk_fma_f32 v[200:201], v[200:201], v[32:33], v[48:49]
	v_cvt_pk_bf16_f32 v188, v200, v201
	v_pk_mul_f32 v[202:203], v[114:115], v[210:211] op_sel_hi:[1,0]
	v_pk_fma_f32 v[202:203], v[202:203], v[34:35], v[50:51]
	v_cvt_pk_bf16_f32 v189, v202, v203
	v_pk_mul_f32 v[200:201], v[116:117], v[210:211] op_sel_hi:[1,0]
	v_pk_fma_f32 v[200:201], v[200:201], v[36:37], v[52:53]
	v_cvt_pk_bf16_f32 v190, v200, v201
	v_pk_mul_f32 v[202:203], v[118:119], v[210:211] op_sel_hi:[1,0]
	v_pk_fma_f32 v[202:203], v[202:203], v[38:39], v[54:55]
	v_cvt_pk_bf16_f32 v191, v202, v203
	global_store_dwordx4 v2, v[184:187], s[78:79]
	global_store_dwordx4 v2, v[188:191], s[78:79] offset:1024
	s_add_i32 s82, s82, 7
	s_cmp_lt_u32 s82, 32
	s_cbranch_scc1 .Lrw_INIT_loop
	s_branch .LBB0_1024
.Lrw_FIRST:
	v_readfirstlane_b32 s40, v214
	v_readlane_b32 s41, v254, 46
	s_lshr_b32 s40, s40, 6
	s_add_i32 s40, s40, s41
	s_lshr_b32 s41, s40, 6
	v_and_b32_e32 v1, 63, v214
	v_lshlrev_b32_e32 v3, 5, v1
	v_lshlrev_b32_e32 v1, 4, v1
	v_mov_b32_e32 v212, 0x3a800000
	s_cmp_eq_u32 s74, 2
	s_cselect_b32 s42, 1, 0
	s_add_i32 s42, s73, s42
	s_add_i32 s43, s74, 1
	s_cmp_eq_u32 s74, 2
	s_cselect_b32 s43, 0, s43
	s_cmp_eq_u32 s74, 1
	s_cselect_b32 s90, 1.0, 0.5
	s_mov_b32 s91, s90
	v_readlane_b32 s44, v255, 22
	v_readlane_b32 s45, v255, 23
	s_lshl_b32 s46, s73, 5
	s_add_i32 s46, s46, s41
	s_mul_i32 s46, s46, 0x9000
	s_mul_i32 s47, s74, 0x3000
	s_add_i32 s46, s46, s47
	s_add_i32 s46, s46, 0x2000
	s_add_u32 s48, s44, s46
	s_addc_u32 s49, s45, 0
	v_readlane_b32 s52, v255, 16
	v_readlane_b32 s53, v255, 17
	s_mul_i32 s46, s73, 3
	s_add_i32 s46, s46, s74
	s_lshl_b32 s46, s46, 12
	s_add_u32 s52, s52, s46
	s_addc_u32 s53, s53, 0
	global_load_dwordx4 v[8:11], v3, s[48:49]
	global_load_dwordx4 v[12:15], v3, s[48:49] offset:16
	global_load_dwordx4 v[16:19], v3, s[48:49] offset:2048
	global_load_dwordx4 v[20:23], v3, s[48:49] offset:2064
	global_load_dwordx4 v[56:59], v3, s[52:53]
	global_load_dwordx4 v[60:63], v3, s[52:53] offset:16
	global_load_dwordx4 v[64:67], v3, s[52:53] offset:2048
	global_load_dwordx4 v[68:71], v3, s[52:53] offset:2064
	s_lshl_b32 s46, s42, 5
	s_add_i32 s46, s46, s41
	s_mul_i32 s46, s46, 0x9000
	s_mul_i32 s47, s43, 0x3000
	s_add_i32 s46, s46, s47
	s_add_u32 s50, s44, s46
	s_addc_u32 s51, s45, 0
	s_add_u32 s56, s50, 0x1000
	s_addc_u32 s57, s51, 0
	v_readlane_b32 s54, v255, 14
	v_readlane_b32 s55, v255, 15
	s_mul_i32 s46, s42, 3
	s_add_i32 s46, s46, s43
	s_lshl_b32 s46, s46, 12
	s_add_u32 s54, s54, s46
	s_addc_u32 s55, s55, 0
	global_load_dwordx4 v[24:27], v3, s[56:57]
	global_load_dwordx4 v[28:31], v3, s[56:57] offset:16
	global_load_dwordx4 v[32:35], v3, s[56:57] offset:2048
	global_load_dwordx4 v[36:39], v3, s[56:57] offset:2064
	global_load_dwordx4 v[72:75], v3, s[54:55]
	global_load_dwordx4 v[76:79], v3, s[54:55] offset:16
	global_load_dwordx4 v[80:83], v3, s[54:55] offset:2048
	global_load_dwordx4 v[84:87], v3, s[54:55] offset:2064
	global_load_dwordx4 v[40:43], v3, s[50:51]
	global_load_dwordx4 v[44:47], v3, s[50:51] offset:16
	global_load_dwordx4 v[48:51], v3, s[50:51] offset:2048
	global_load_dwordx4 v[52:55], v3, s[50:51] offset:2064
	s_lshl_b32 s46, s40, 16
	s_lshl_b32 s47, s40, 17
	v_readlane_b32 s72, v255, 4
	v_readlane_b32 s73, v255, 5
	s_add_u32 s72, s72, s47
	s_addc_u32 s73, s73, 0
	v_readlane_b32 s74, v252, 22
	v_readlane_b32 s75, v252, 23
	s_add_u32 s74, s74, s46
	s_addc_u32 s75, s75, 0
	v_readlane_b32 s76, v252, 6
	v_readlane_b32 s77, v252, 7
	s_add_u32 s76, s76, s46
	s_addc_u32 s77, s77, 0
	v_readlane_b32 s78, v252, 20
	v_readlane_b32 s79, v252, 21
	s_add_u32 s78, s78, s46
	s_addc_u32 s79, s79, 0
	s_and_b32 s80, s40, 15
	s_lshl_b32 s80, s80, 1
	s_waitcnt vmcnt(12)
; __device__ __forceinline__ float bflo(unsigned u) { return __uint_as_float(u << 16); }
; __device__ __forceinline__ float bfhi(unsigned u) { return __uint_as_float(u & 0xffff0000u); }
; __device__ __forceinline__ void phase_rowwise(const void* xsrc_, bool sbf, void* xdst_, bool dbf, const bf16_t* Y, bf16_t* H, const float* mods, int lprev, int iprev, const float* lnpost, float resw, ...
;     ...
;         f32x4 gp[4], na[4], ns[4];
; #pragma unroll
;         for (int j = 0; j < 4; ++j) { const int c = 4 * lane + 256 * j;
;             if (hasprev) { const f32x4 g = *(const f32x4*)(mods + ((size_t)lprev * 32 + b) * 9216 + iprev * 3072 + 2048 + c); const f32x4 lp = *(const f32x4*)(lnpost + c); gp[j] = g * lp * resw; }
;             else gp[j] = (f32x4){0.f, 0.f, 0.f, 0.f};
;             if (hasnext) { const f32x4 sh = *(const f32x4*)(mods + ((size_t)lnext * 32 + b) * 9216 + inext * 3072 + c); const f32x4 scl = *(const f32x4*)(mods + ((size_t)lnext * 32 + b) * 9216 + inext * 3072 + 1024 + c);
;                 const f32x4 lp = *(const f32x4*)(lnpre + c); na[j] = lp * (scl + 1.0f); ns[j] = sh; }
;             else { na[j] = (f32x4){0.f, 0.f, 0.f, 0.f}; ns[j] = na[j]; } }
;         f32x4 xn[2][4]; u32x2 xnb[2][4]; u32x2 yn[2][4];
;         { const size_t m0 = (size_t)ch * 32;
; #pragma unroll
;           for (int r = 0; r < 2; ++r)
; #pragma unroll
;             for (int j = 0; j < 4; ++j) { if (sbf) { xnb[r][j] = *(const u32x2*)(xsrcb + (m0 + r) * DM + 4 * lane + 256 * j); xn[r][j] = (f32x4){0.f, 0.f, 0.f, 0.f}; } else { xn[r][j] = *(const f32x4*)(xsrc + (m0 + r) * DM + 4 * lane + 256 * j); xnb[r][j] = (u32x2){0u, 0u}; }
;                 yn[r][j] = hasprev ? *(const u32x2*)(Y + (m0 + r) * DM + 4 * lane + 256 * j) : (u32x2){0u, 0u}; } }
;         for (int rr = 0; rr < 32; rr += 2) {
;             const size_t m = (size_t)ch * 32 + rr;
;             f32x4 x[2][4]; u32x2 yr[2][4];
; #pragma unroll
;             for (int r = 0; r < 2; ++r)
; #pragma unroll
;                 for (int j = 0; j < 4; ++j) { if (sbf) { const u32x2 u = xnb[r][j]; x[r][j] = (f32x4){bflo(u.x), bfhi(u.x), bflo(u.y), bfhi(u.y)}; } else x[r][j] = xn[r][j]; yr[r][j] = yn[r][j]; }
;             if (rr + 2 < 32) {
; #pragma unroll
;                 for (int r = 0; r < 2; ++r)
; #pragma unroll
	v_pk_mul_f32 v[8:9], v[8:9], v[56:57]
	v_pk_mul_f32 v[10:11], v[10:11], v[58:59]
	v_pk_mul_f32 v[12:13], v[12:13], v[60:61]
	v_pk_mul_f32 v[14:15], v[14:15], v[62:63]
	v_pk_mul_f32 v[16:17], v[16:17], v[64:65]
	v_pk_mul_f32 v[18:19], v[18:19], v[66:67]
	v_pk_mul_f32 v[20:21], v[20:21], v[68:69]
	v_pk_mul_f32 v[22:23], v[22:23], v[70:71]
	v_pk_mul_f32 v[8:9], v[8:9], s[90:91]
	v_pk_mul_f32 v[10:11], v[10:11], s[90:91]
	v_pk_mul_f32 v[12:13], v[12:13], s[90:91]
	v_pk_mul_f32 v[14:15], v[14:15], s[90:91]
	v_pk_mul_f32 v[16:17], v[16:17], s[90:91]
	v_pk_mul_f32 v[18:19], v[18:19], s[90:91]
	v_pk_mul_f32 v[20:21], v[20:21], s[90:91]
	v_pk_mul_f32 v[22:23], v[22:23], s[90:91]
	s_waitcnt vmcnt(4)
	v_pk_add_f32 v[24:25], v[24:25], 1.0 op_sel_hi:[1,0]
	v_pk_add_f32 v[26:27], v[26:27], 1.0 op_sel_hi:[1,0]
	v_pk_add_f32 v[28:29], v[28:29], 1.0 op_sel_hi:[1,0]
	v_pk_add_f32 v[30:31], v[30:31], 1.0 op_sel_hi:[1,0]
	v_pk_add_f32 v[32:33], v[32:33], 1.0 op_sel_hi:[1,0]
	v_pk_add_f32 v[34:35], v[34:35], 1.0 op_sel_hi:[1,0]
	v_pk_add_f32 v[36:37], v[36:37], 1.0 op_sel_hi:[1,0]
	v_pk_add_f32 v[38:39], v[38:39], 1.0 op_sel_hi:[1,0]
	v_pk_mul_f32 v[24:25], v[72:73], v[24:25]
	v_pk_mul_f32 v[26:27], v[74:75], v[26:27]
	v_pk_mul_f32 v[28:29], v[76:77], v[28:29]
	v_pk_mul_f32 v[30:31], v[78:79], v[30:31]
	v_pk_mul_f32 v[32:33], v[80:81], v[32:33]
	v_pk_mul_f32 v[34:35], v[82:83], v[34:35]
	v_pk_mul_f32 v[36:37], v[84:85], v[36:37]
	v_pk_mul_f32 v[38:39], v[86:87], v[38:39]
	s_waitcnt vmcnt(0)
	s_mov_b32 s82, 0
	s_add_i32 s81, s80, 0
	s_add_i32 s81, s81, s82
	s_and_b32 s81, s81, 31
	s_lshl_b32 s83, s81, 11
	v_add_u32_e32 v2, s83, v1
	s_lshl_b32 s83, s81, 12
	v_add_u32_e32 v213, s83, v3
	global_load_dwordx4 v[56:59], v213, s[72:73]
	global_load_dwordx4 v[60:63], v213, s[72:73] offset:16
	global_load_dwordx4 v[64:67], v213, s[72:73] offset:2048
	global_load_dwordx4 v[68:71], v213, s[72:73] offset:2064
	global_load_dwordx4 v[72:75], v2, s[74:75]
	global_load_dwordx4 v[76:79], v2, s[74:75] offset:1024
	s_add_i32 s81, s80, 1
	s_add_i32 s81, s81, s82
	s_and_b32 s81, s81, 31
	s_lshl_b32 s83, s81, 11
	v_add_u32_e32 v2, s83, v1
	s_lshl_b32 s83, s81, 12
	v_add_u32_e32 v213, s83, v3
	global_load_dwordx4 v[80:83], v213, s[72:73]
	global_load_dwordx4 v[84:87], v213, s[72:73] offset:16
	global_load_dwordx4 v[88:91], v213, s[72:73] offset:2048
	global_load_dwordx4 v[92:95], v213, s[72:73] offset:2064
	global_load_dwordx4 v[96:99], v2, s[74:75]
	global_load_dwordx4 v[100:103], v2, s[74:75] offset:1024
	s_add_i32 s81, s80, 2
	s_add_i32 s81, s81, s82
	s_and_b32 s81, s81, 31
	s_lshl_b32 s83, s81, 11
	v_add_u32_e32 v2, s83, v1
	s_lshl_b32 s83, s81, 12
	v_add_u32_e32 v213, s83, v3
	global_load_dwordx4 v[104:107], v213, s[72:73]
	global_load_dwordx4 v[108:111], v213, s[72:73] offset:16
	global_load_dwordx4 v[112:115], v213, s[72:73] offset:2048
	global_load_dwordx4 v[116:119], v213, s[72:73] offset:2064
	global_load_dwordx4 v[120:123], v2, s[74:75]
	global_load_dwordx4 v[124:127], v2, s[74:75] offset:1024
	s_waitcnt vmcnt(12)
	v_lshlrev_b32_e32 v200, 16, v72
	v_and_b32_e32 v201, 0xffff0000, v72
	v_pk_mul_f32 v[204:205], v[200:201], v[200:201]
	v_lshlrev_b32_e32 v202, 16, v73
	v_and_b32_e32 v203, 0xffff0000, v73
	v_pk_mul_f32 v[206:207], v[202:203], v[202:203]
	v_lshlrev_b32_e32 v200, 16, v74
	v_and_b32_e32 v201, 0xffff0000, v74
	v_pk_fma_f32 v[204:205], v[200:201], v[200:201], v[204:205]
	v_lshlrev_b32_e32 v202, 16, v75
	v_and_b32_e32 v203, 0xffff0000, v75
	v_pk_fma_f32 v[206:207], v[202:203], v[202:203], v[206:207]
	v_lshlrev_b32_e32 v200, 16, v76
	v_and_b32_e32 v201, 0xffff0000, v76
	v_pk_fma_f32 v[204:205], v[200:201], v[200:201], v[204:205]
	v_lshlrev_b32_e32 v202, 16, v77
	v_and_b32_e32 v203, 0xffff0000, v77
	v_pk_fma_f32 v[206:207], v[202:203], v[202:203], v[206:207]
	v_lshlrev_b32_e32 v200, 16, v78
	v_and_b32_e32 v201, 0xffff0000, v78
	v_pk_fma_f32 v[204:205], v[200:201], v[200:201], v[204:205]
	v_lshlrev_b32_e32 v202, 16, v79
	v_and_b32_e32 v203, 0xffff0000, v79
	v_pk_fma_f32 v[206:207], v[202:203], v[202:203], v[206:207]
	v_pk_add_f32 v[204:205], v[204:205], v[206:207]
	v_add_f32_e32 v208, v204, v205
	s_nop 0
	s_nop 0
	v_add_f32_dpp v208, v208, v208 quad_perm:[1,0,3,2] row_mask:0xf bank_mask:0xf
	s_nop 0
	s_nop 0
	v_add_f32_dpp v208, v208, v208 quad_perm:[2,3,0,1] row_mask:0xf bank_mask:0xf
	s_nop 0
	s_nop 0
	v_add_f32_dpp v208, v208, v208 row_half_mirror row_mask:0xf bank_mask:0xf
	s_nop 0
	s_nop 0
	v_add_f32_dpp v208, v208, v208 row_mirror row_mask:0xf bank_mask:0xf
	s_nop 0
	s_nop 0
	v_add_f32_dpp v208, v208, v208 row_bcast:15 row_mask:0xa bank_mask:0xf
	s_nop 0
	s_nop 0
	v_add_f32_dpp v208, v208, v208 row_bcast:31 row_mask:0xc bank_mask:0xf
	s_nop 0
	s_nop 0
	v_readlane_b32 s60, v208, 63
	s_nop 1
	v_mov_b32_e32 v210, s60
	v_fmaak_f32 v210, v210, v212, 0x358637bd
	v_rsq_f32_e32 v210, v210
	s_nop 0
	v_lshlrev_b32_e32 v200, 16, v72
	v_and_b32_e32 v201, 0xffff0000, v72
	v_pk_mul_f32 v[200:201], v[200:201], v[210:211] op_sel_hi:[1,0]
	v_pk_fma_f32 v[56:57], v[8:9], v[200:201], v[56:57]
	v_lshlrev_b32_e32 v202, 16, v73
	v_and_b32_e32 v203, 0xffff0000, v73
	v_pk_mul_f32 v[202:203], v[202:203], v[210:211] op_sel_hi:[1,0]
	v_pk_fma_f32 v[58:59], v[10:11], v[202:203], v[58:59]
	v_lshlrev_b32_e32 v200, 16, v74
	v_and_b32_e32 v201, 0xffff0000, v74
	v_pk_mul_f32 v[200:201], v[200:201], v[210:211] op_sel_hi:[1,0]
	v_pk_fma_f32 v[60:61], v[12:13], v[200:201], v[60:61]
	v_lshlrev_b32_e32 v202, 16, v75
	v_and_b32_e32 v203, 0xffff0000, v75
	v_pk_mul_f32 v[202:203], v[202:203], v[210:211] op_sel_hi:[1,0]
	v_pk_fma_f32 v[62:63], v[14:15], v[202:203], v[62:63]
	v_lshlrev_b32_e32 v200, 16, v76
; __device__ __forceinline__ unsigned cvtpk(float lo, float hi) { f32x2 v = {lo, hi}; bf16x2_t b = __builtin_convertvector(v, bf16x2_t); return __builtin_bit_cast(unsigned, b); }
; __device__ __forceinline__ void phase_rowwise(const void* xsrc_, bool sbf, void* xdst_, bool dbf, const bf16_t* Y, bf16_t* H, const float* mods, int lprev, int iprev, const float* lnpost, float resw, ...
;     ...
; #pragma unroll
;             for (int r = 0; r < 2; ++r)
; #pragma unroll
;                 for (int j = 0; j < 4; ++j) { if (hasprev) { if (dbf) { u32x2 w; w.x = cvtpk(x[r][j].x, x[r][j].y); w.y = cvtpk(x[r][j].z, x[r][j].w); *(u32x2*)(xdstb + (m + r) * DM + 4 * lane + 256 * j) = w; } else *(f32x4*)(xdst + (m + r) * DM + 4 * lane + 256 * j) = x[r][j]; } }
;             if (hasnext) {
;                 float ss[2] = {0.f, 0.f};
; #pragma unroll
;                 for (int r = 0; r < 2; ++r)
; #pragma unroll
;                     for (int j = 0; j < 4; ++j) ss[r] += (x[r][j].x * x[r][j].x + x[r][j].y * x[r][j].y) + (x[r][j].z * x[r][j].z + x[r][j].w * x[r][j].w);
; #pragma unroll
;                 for (int off = 1; off < 64; off <<= 1) { ss[0] += __shfl_xor(ss[0], off); ss[1] += __shfl_xor(ss[1], off); }
; #pragma unroll
;                 for (int r = 0; r < 2; ++r) { const float rs = __builtin_amdgcn_rsqf(ss[r] * (1.f / DM) + EPS);
; #pragma unroll
;                     for (int j = 0; j < 4; ++j) { const f32x4 h = (x[r][j] * rs) * na[j] + ns[j]; u32x2 w; w.x = cvtpk(h.x, h.y); w.y = cvtpk(h.z, h.w); *(u32x2*)(H + (m + r) * DM + 4 * lane + 256 * j) = w; } }
;             }
	v_and_b32_e32 v201, 0xffff0000, v76
	v_pk_mul_f32 v[200:201], v[200:201], v[210:211] op_sel_hi:[1,0]
	v_pk_fma_f32 v[64:65], v[16:17], v[200:201], v[64:65]
	v_lshlrev_b32_e32 v202, 16, v77
	v_and_b32_e32 v203, 0xffff0000, v77
	v_pk_mul_f32 v[202:203], v[202:203], v[210:211] op_sel_hi:[1,0]
	v_pk_fma_f32 v[66:67], v[18:19], v[202:203], v[66:67]
	v_lshlrev_b32_e32 v200, 16, v78
	v_and_b32_e32 v201, 0xffff0000, v78
	v_pk_mul_f32 v[200:201], v[200:201], v[210:211] op_sel_hi:[1,0]
	v_pk_fma_f32 v[68:69], v[20:21], v[200:201], v[68:69]
	v_lshlrev_b32_e32 v202, 16, v79
	v_and_b32_e32 v203, 0xffff0000, v79
	v_pk_mul_f32 v[202:203], v[202:203], v[210:211] op_sel_hi:[1,0]
	v_pk_fma_f32 v[70:71], v[22:23], v[202:203], v[70:71]
	s_add_i32 s81, s80, 0
	s_add_i32 s81, s81, s82
	s_and_b32 s81, s81, 31
	s_lshl_b32 s83, s81, 11
	v_add_u32_e32 v2, s83, v1
	v_cvt_pk_bf16_f32 v72, v56, v57
	v_cvt_pk_bf16_f32 v73, v58, v59
	v_cvt_pk_bf16_f32 v74, v60, v61
	v_cvt_pk_bf16_f32 v75, v62, v63
	v_cvt_pk_bf16_f32 v76, v64, v65
	v_cvt_pk_bf16_f32 v77, v66, v67
	v_cvt_pk_bf16_f32 v78, v68, v69
	v_cvt_pk_bf16_f32 v79, v70, v71
	global_store_dwordx4 v2, v[72:75], s[76:77]
	global_store_dwordx4 v2, v[76:79], s[76:77] offset:1024
	v_pk_mul_f32 v[204:205], v[56:57], v[56:57]
	v_pk_mul_f32 v[206:207], v[58:59], v[58:59]
	v_pk_fma_f32 v[204:205], v[60:61], v[60:61], v[204:205]
	v_pk_fma_f32 v[206:207], v[62:63], v[62:63], v[206:207]
	v_pk_fma_f32 v[204:205], v[64:65], v[64:65], v[204:205]
	v_pk_fma_f32 v[206:207], v[66:67], v[66:67], v[206:207]
	v_pk_fma_f32 v[204:205], v[68:69], v[68:69], v[204:205]
	v_pk_fma_f32 v[206:207], v[70:71], v[70:71], v[206:207]
	v_pk_add_f32 v[204:205], v[204:205], v[206:207]
	v_add_f32_e32 v208, v204, v205
	s_nop 0
	s_nop 0
	v_add_f32_dpp v208, v208, v208 quad_perm:[1,0,3,2] row_mask:0xf bank_mask:0xf
	s_nop 0
	s_nop 0
	v_add_f32_dpp v208, v208, v208 quad_perm:[2,3,0,1] row_mask:0xf bank_mask:0xf
	s_nop 0
	s_nop 0
	v_add_f32_dpp v208, v208, v208 row_half_mirror row_mask:0xf bank_mask:0xf
	s_nop 0
	s_nop 0
	v_add_f32_dpp v208, v208, v208 row_mirror row_mask:0xf bank_mask:0xf
	s_nop 0
	s_nop 0
	v_add_f32_dpp v208, v208, v208 row_bcast:15 row_mask:0xa bank_mask:0xf
	s_nop 0
	s_nop 0
	v_add_f32_dpp v208, v208, v208 row_bcast:31 row_mask:0xc bank_mask:0xf
	s_nop 0
	s_nop 0
	v_readlane_b32 s60, v208, 63
	s_nop 1
	v_mov_b32_e32 v210, s60
	v_fmaak_f32 v210, v210, v212, 0x358637bd
	v_rsq_f32_e32 v210, v210
	s_nop 0
	v_pk_mul_f32 v[200:201], v[56:57], v[210:211] op_sel_hi:[1,0]
	v_pk_fma_f32 v[200:201], v[200:201], v[24:25], v[40:41]
	v_cvt_pk_bf16_f32 v72, v200, v201
	v_pk_mul_f32 v[202:203], v[58:59], v[210:211] op_sel_hi:[1,0]
	v_pk_fma_f32 v[202:203], v[202:203], v[26:27], v[42:43]
	v_cvt_pk_bf16_f32 v73, v202, v203
	v_pk_mul_f32 v[200:201], v[60:61], v[210:211] op_sel_hi:[1,0]
	v_pk_fma_f32 v[200:201], v[200:201], v[28:29], v[44:45]
	v_cvt_pk_bf16_f32 v74, v200, v201
	v_pk_mul_f32 v[202:203], v[62:63], v[210:211] op_sel_hi:[1,0]
	v_pk_fma_f32 v[202:203], v[202:203], v[30:31], v[46:47]
	v_cvt_pk_bf16_f32 v75, v202, v203
	v_pk_mul_f32 v[200:201], v[64:65], v[210:211] op_sel_hi:[1,0]
	v_pk_fma_f32 v[200:201], v[200:201], v[32:33], v[48:49]
	v_cvt_pk_bf16_f32 v76, v200, v201
	v_pk_mul_f32 v[202:203], v[66:67], v[210:211] op_sel_hi:[1,0]
	v_pk_fma_f32 v[202:203], v[202:203], v[34:35], v[50:51]
	v_cvt_pk_bf16_f32 v77, v202, v203
	v_pk_mul_f32 v[200:201], v[68:69], v[210:211] op_sel_hi:[1,0]
	v_pk_fma_f32 v[200:201], v[200:201], v[36:37], v[52:53]
	v_cvt_pk_bf16_f32 v78, v200, v201
	v_pk_mul_f32 v[202:203], v[70:71], v[210:211] op_sel_hi:[1,0]
	v_pk_fma_f32 v[202:203], v[202:203], v[38:39], v[54:55]
	v_cvt_pk_bf16_f32 v79, v202, v203
	global_store_dwordx4 v2, v[72:75], s[78:79]
	global_store_dwordx4 v2, v[76:79], s[78:79] offset:1024
	s_add_i32 s81, s80, 3
	s_add_i32 s81, s81, s82
	s_and_b32 s81, s81, 31
	s_lshl_b32 s83, s81, 11
	v_add_u32_e32 v2, s83, v1
	s_lshl_b32 s83, s81, 12
	v_add_u32_e32 v213, s83, v3
	global_load_dwordx4 v[128:131], v213, s[72:73]
	global_load_dwordx4 v[132:135], v213, s[72:73] offset:16
	global_load_dwordx4 v[136:139], v213, s[72:73] offset:2048
	global_load_dwordx4 v[140:143], v213, s[72:73] offset:2064
	global_load_dwordx4 v[144:147], v2, s[74:75]
	global_load_dwordx4 v[148:151], v2, s[74:75] offset:1024
	s_waitcnt vmcnt(16)
; __device__ __forceinline__ float bflo(unsigned u) { return __uint_as_float(u << 16); }
; __device__ __forceinline__ void phase_rowwise(const void* xsrc_, bool sbf, void* xdst_, bool dbf, const bf16_t* Y, bf16_t* H, const float* mods, int lprev, int iprev, const float* lnpost, float resw, ...
;     ...
;             if (hasprev) {
;                 f32x4 y[2][4]; float ss[2] = {0.f, 0.f};
; #pragma unroll
;                 for (int r = 0; r < 2; ++r)
; #pragma unroll
;                     for (int j = 0; j < 4; ++j) { const u32x2 u = yr[r][j]; y[r][j] = (f32x4){bflo(u.x), bfhi(u.x), bflo(u.y), bfhi(u.y)};
;                         ss[r] += (y[r][j].x * y[r][j].x + y[r][j].y * y[r][j].y) + (y[r][j].z * y[r][j].z + y[r][j].w * y[r][j].w); }
; #pragma unroll
;                 for (int off = 1; off < 64; off <<= 1) { ss[0] += __shfl_xor(ss[0], off); ss[1] += __shfl_xor(ss[1], off); }
; #pragma unroll
;                 for (int r = 0; r < 2; ++r) { const float rs = __builtin_amdgcn_rsqf(ss[r] * (1.f / DM) + EPS);
; #pragma unroll
;                     for (int j = 0; j < 4; ++j) x[r][j] = x[r][j] + gp[j] * (y[r][j] * rs); }
;             }
; #pragma unroll
;             for (int r = 0; r < 2; ++r)
; #pragma unroll
;                 for (int j = 0; j < 4; ++j) { if (hasprev) { if (dbf) { u32x2 w; w.x = cvtpk(x[r][j].x, x[r][j].y); w.y = cvtpk(x[r][j].z, x[r][j].w); *(u32x2*)(xdstb + (m + r) * DM + 4 * lane + 256 * j) = w; } else *(f32x4*)(xdst + (m + r) * DM + 4 * lane + 256 * j) = x[r][j]; } }
;             if (hasnext) {
;                 float ss[2] = {0.f, 0.f};
; #pragma unroll
;                 for (int r = 0; r < 2; ++r)
; #pragma unroll
;                     for (int j = 0; j < 4; ++j) ss[r] += (x[r][j].x * x[r][j].x + x[r][j].y * x[r][j].y) + (x[r][j].z * x[r][j].z + x[r][j].w * x[r][j].w);
; #pragma unroll
;                 for (int off = 1; off < 64; off <<= 1) { ss[0] += __shfl_xor(ss[0], off); ss[1] += __shfl_xor(ss[1], off); }
; #pragma unroll
;                 for (int r = 0; r < 2; ++r) { const float rs = __builtin_amdgcn_rsqf(ss[r] * (1.f / DM) + EPS);
; #pragma unroll
;                     for (int j = 0; j < 4; ++j) { const f32x4 h = (x[r][j] * rs) * na[j] + ns[j]; u32x2 w; w.x = cvtpk(h.x, h.y); w.y = cvtpk(h.z, h.w); *(u32x2*)(H + (m + r) * DM + 4 * lane + 256 * j) = w; } }
	v_lshlrev_b32_e32 v200, 16, v96
	v_and_b32_e32 v201, 0xffff0000, v96
	v_pk_mul_f32 v[204:205], v[200:201], v[200:201]
	v_lshlrev_b32_e32 v202, 16, v97
	v_and_b32_e32 v203, 0xffff0000, v97
	v_pk_mul_f32 v[206:207], v[202:203], v[202:203]
	v_lshlrev_b32_e32 v200, 16, v98
	v_and_b32_e32 v201, 0xffff0000, v98
	v_pk_fma_f32 v[204:205], v[200:201], v[200:201], v[204:205]
	v_lshlrev_b32_e32 v202, 16, v99
	v_and_b32_e32 v203, 0xffff0000, v99
	v_pk_fma_f32 v[206:207], v[202:203], v[202:203], v[206:207]
	v_lshlrev_b32_e32 v200, 16, v100
	v_and_b32_e32 v201, 0xffff0000, v100
	v_pk_fma_f32 v[204:205], v[200:201], v[200:201], v[204:205]
	v_lshlrev_b32_e32 v202, 16, v101
	v_and_b32_e32 v203, 0xffff0000, v101
	v_pk_fma_f32 v[206:207], v[202:203], v[202:203], v[206:207]
	v_lshlrev_b32_e32 v200, 16, v102
	v_and_b32_e32 v201, 0xffff0000, v102
	v_pk_fma_f32 v[204:205], v[200:201], v[200:201], v[204:205]
	v_lshlrev_b32_e32 v202, 16, v103
	v_and_b32_e32 v203, 0xffff0000, v103
	v_pk_fma_f32 v[206:207], v[202:203], v[202:203], v[206:207]
	v_pk_add_f32 v[204:205], v[204:205], v[206:207]
	v_add_f32_e32 v208, v204, v205
	s_nop 0
	s_nop 0
	v_add_f32_dpp v208, v208, v208 quad_perm:[1,0,3,2] row_mask:0xf bank_mask:0xf
	s_nop 0
	s_nop 0
	v_add_f32_dpp v208, v208, v208 quad_perm:[2,3,0,1] row_mask:0xf bank_mask:0xf
	s_nop 0
	s_nop 0
	v_add_f32_dpp v208, v208, v208 row_half_mirror row_mask:0xf bank_mask:0xf
	s_nop 0
	s_nop 0
	v_add_f32_dpp v208, v208, v208 row_mirror row_mask:0xf bank_mask:0xf
	s_nop 0
	s_nop 0
	v_add_f32_dpp v208, v208, v208 row_bcast:15 row_mask:0xa bank_mask:0xf
	s_nop 0
	s_nop 0
	v_add_f32_dpp v208, v208, v208 row_bcast:31 row_mask:0xc bank_mask:0xf
	s_nop 0
	s_nop 0
	v_readlane_b32 s60, v208, 63
	s_nop 1
	v_mov_b32_e32 v210, s60
	v_fmaak_f32 v210, v210, v212, 0x358637bd
	v_rsq_f32_e32 v210, v210
	s_nop 0
	v_lshlrev_b32_e32 v200, 16, v96
	v_and_b32_e32 v201, 0xffff0000, v96
	v_pk_mul_f32 v[200:201], v[200:201], v[210:211] op_sel_hi:[1,0]
	v_pk_fma_f32 v[80:81], v[8:9], v[200:201], v[80:81]
	v_lshlrev_b32_e32 v202, 16, v97
	v_and_b32_e32 v203, 0xffff0000, v97
	v_pk_mul_f32 v[202:203], v[202:203], v[210:211] op_sel_hi:[1,0]
	v_pk_fma_f32 v[82:83], v[10:11], v[202:203], v[82:83]
	v_lshlrev_b32_e32 v200, 16, v98
	v_and_b32_e32 v201, 0xffff0000, v98
	v_pk_mul_f32 v[200:201], v[200:201], v[210:211] op_sel_hi:[1,0]
	v_pk_fma_f32 v[84:85], v[12:13], v[200:201], v[84:85]
	v_lshlrev_b32_e32 v202, 16, v99
	v_and_b32_e32 v203, 0xffff0000, v99
	v_pk_mul_f32 v[202:203], v[202:203], v[210:211] op_sel_hi:[1,0]
	v_pk_fma_f32 v[86:87], v[14:15], v[202:203], v[86:87]
	v_lshlrev_b32_e32 v200, 16, v100
	v_and_b32_e32 v201, 0xffff0000, v100
	v_pk_mul_f32 v[200:201], v[200:201], v[210:211] op_sel_hi:[1,0]
	v_pk_fma_f32 v[88:89], v[16:17], v[200:201], v[88:89]
	v_lshlrev_b32_e32 v202, 16, v101
	v_and_b32_e32 v203, 0xffff0000, v101
	v_pk_mul_f32 v[202:203], v[202:203], v[210:211] op_sel_hi:[1,0]
	v_pk_fma_f32 v[90:91], v[18:19], v[202:203], v[90:91]
	v_lshlrev_b32_e32 v200, 16, v102
	v_and_b32_e32 v201, 0xffff0000, v102
	v_pk_mul_f32 v[200:201], v[200:201], v[210:211] op_sel_hi:[1,0]
	v_pk_fma_f32 v[92:93], v[20:21], v[200:201], v[92:93]
	v_lshlrev_b32_e32 v202, 16, v103
	v_and_b32_e32 v203, 0xffff0000, v103
	v_pk_mul_f32 v[202:203], v[202:203], v[210:211] op_sel_hi:[1,0]
	v_pk_fma_f32 v[94:95], v[22:23], v[202:203], v[94:95]
	s_add_i32 s81, s80, 1
	s_add_i32 s81, s81, s82
	s_and_b32 s81, s81, 31
	s_lshl_b32 s83, s81, 11
	v_add_u32_e32 v2, s83, v1
	v_cvt_pk_bf16_f32 v96, v80, v81
	v_cvt_pk_bf16_f32 v97, v82, v83
	v_cvt_pk_bf16_f32 v98, v84, v85
	v_cvt_pk_bf16_f32 v99, v86, v87
	v_cvt_pk_bf16_f32 v100, v88, v89
	v_cvt_pk_bf16_f32 v101, v90, v91
	v_cvt_pk_bf16_f32 v102, v92, v93
	v_cvt_pk_bf16_f32 v103, v94, v95
	global_store_dwordx4 v2, v[96:99], s[76:77]
	global_store_dwordx4 v2, v[100:103], s[76:77] offset:1024
	v_pk_mul_f32 v[204:205], v[80:81], v[80:81]
	v_pk_mul_f32 v[206:207], v[82:83], v[82:83]
	v_pk_fma_f32 v[204:205], v[84:85], v[84:85], v[204:205]
	v_pk_fma_f32 v[206:207], v[86:87], v[86:87], v[206:207]
	v_pk_fma_f32 v[204:205], v[88:89], v[88:89], v[204:205]
	v_pk_fma_f32 v[206:207], v[90:91], v[90:91], v[206:207]
	v_pk_fma_f32 v[204:205], v[92:93], v[92:93], v[204:205]
	v_pk_fma_f32 v[206:207], v[94:95], v[94:95], v[206:207]
	v_pk_add_f32 v[204:205], v[204:205], v[206:207]
	v_add_f32_e32 v208, v204, v205
	s_nop 0
	s_nop 0
	v_add_f32_dpp v208, v208, v208 quad_perm:[1,0,3,2] row_mask:0xf bank_mask:0xf
	s_nop 0
	s_nop 0
	v_add_f32_dpp v208, v208, v208 quad_perm:[2,3,0,1] row_mask:0xf bank_mask:0xf
	s_nop 0
	s_nop 0
	v_add_f32_dpp v208, v208, v208 row_half_mirror row_mask:0xf bank_mask:0xf
	s_nop 0
	s_nop 0
	v_add_f32_dpp v208, v208, v208 row_mirror row_mask:0xf bank_mask:0xf
	s_nop 0
	s_nop 0
	v_add_f32_dpp v208, v208, v208 row_bcast:15 row_mask:0xa bank_mask:0xf
	s_nop 0
	s_nop 0
	v_add_f32_dpp v208, v208, v208 row_bcast:31 row_mask:0xc bank_mask:0xf
	s_nop 0
	s_nop 0
	v_readlane_b32 s60, v208, 63
	s_nop 1
	v_mov_b32_e32 v210, s60
	v_fmaak_f32 v210, v210, v212, 0x358637bd
	v_rsq_f32_e32 v210, v210
	s_nop 0
	v_pk_mul_f32 v[200:201], v[80:81], v[210:211] op_sel_hi:[1,0]
	v_pk_fma_f32 v[200:201], v[200:201], v[24:25], v[40:41]
	v_cvt_pk_bf16_f32 v96, v200, v201
	v_pk_mul_f32 v[202:203], v[82:83], v[210:211] op_sel_hi:[1,0]
	v_pk_fma_f32 v[202:203], v[202:203], v[26:27], v[42:43]
	v_cvt_pk_bf16_f32 v97, v202, v203
	v_pk_mul_f32 v[200:201], v[84:85], v[210:211] op_sel_hi:[1,0]
	v_pk_fma_f32 v[200:201], v[200:201], v[28:29], v[44:45]
	v_cvt_pk_bf16_f32 v98, v200, v201
	v_pk_mul_f32 v[202:203], v[86:87], v[210:211] op_sel_hi:[1,0]
	v_pk_fma_f32 v[202:203], v[202:203], v[30:31], v[46:47]
	v_cvt_pk_bf16_f32 v99, v202, v203
	v_pk_mul_f32 v[200:201], v[88:89], v[210:211] op_sel_hi:[1,0]
	v_pk_fma_f32 v[200:201], v[200:201], v[32:33], v[48:49]
	v_cvt_pk_bf16_f32 v100, v200, v201
	v_pk_mul_f32 v[202:203], v[90:91], v[210:211] op_sel_hi:[1,0]
	v_pk_fma_f32 v[202:203], v[202:203], v[34:35], v[50:51]
	v_cvt_pk_bf16_f32 v101, v202, v203
	v_pk_mul_f32 v[200:201], v[92:93], v[210:211] op_sel_hi:[1,0]
	v_pk_fma_f32 v[200:201], v[200:201], v[36:37], v[52:53]
	v_cvt_pk_bf16_f32 v102, v200, v201
	v_pk_mul_f32 v[202:203], v[94:95], v[210:211] op_sel_hi:[1,0]
	v_pk_fma_f32 v[202:203], v[202:203], v[38:39], v[54:55]
	v_cvt_pk_bf16_f32 v103, v202, v203
	global_store_dwordx4 v2, v[96:99], s[78:79]
	global_store_dwordx4 v2, v[100:103], s[78:79] offset:1024
	s_mov_b32 s82, 2
; __device__ __forceinline__ float bflo(unsigned u) { return __uint_as_float(u << 16); }
; __device__ __forceinline__ float bfhi(unsigned u) { return __uint_as_float(u & 0xffff0000u); }
; __device__ __forceinline__ void phase_rowwise(const void* xsrc_, bool sbf, void* xdst_, bool dbf, const bf16_t* Y, bf16_t* H, const float* mods, int lprev, int iprev, const float* lnpost, float resw, ...
;     ...
;         for (int rr = 0; rr < 32; rr += 2) {
;             const size_t m = (size_t)ch * 32 + rr;
;             f32x4 x[2][4]; u32x2 yr[2][4];
; #pragma unroll
;             for (int r = 0; r < 2; ++r)
; #pragma unroll
;                 for (int j = 0; j < 4; ++j) { if (sbf) { const u32x2 u = xnb[r][j]; x[r][j] = (f32x4){bflo(u.x), bfhi(u.x), bflo(u.y), bfhi(u.y)}; } else x[r][j] = xn[r][j]; yr[r][j] = yn[r][j]; }
;             if (rr + 2 < 32) {
; #pragma unroll
;                 for (int r = 0; r < 2; ++r)
; #pragma unroll
;                     for (int j = 0; j < 4; ++j) { if (sbf) xnb[r][j] = *(const u32x2*)(xsrcb + (m + 2 + r) * DM + 4 * lane + 256 * j); else xn[r][j] = *(const f32x4*)(xsrc + (m + 2 + r) * DM + 4 * lane + 256 * j); if (hasprev) yn[r][j] = *(const u32x2*)(Y + (m + 2 + r) * DM + 4 * lane + 256 * j); } }
;             if (hasprev) {
;                 f32x4 y[2][4]; float ss[2] = {0.f, 0.f};
; #pragma unroll
;                 for (int r = 0; r < 2; ++r)
; #pragma unroll
;                     for (int j = 0; j < 4; ++j) { const u32x2 u = yr[r][j]; y[r][j] = (f32x4){bflo(u.x), bfhi(u.x), bflo(u.y), bfhi(u.y)};
;                         ss[r] += (y[r][j].x * y[r][j].x + y[r][j].y * y[r][j].y) + (y[r][j].z * y[r][j].z + y[r][j].w * y[r][j].w); }
; #pragma unroll
;                 for (int off = 1; off < 64; off <<= 1) { ss[0] += __shfl_xor(ss[0], off); ss[1] += __shfl_xor(ss[1], off); }
.Lrw_FIRST_loop:
	s_add_i32 s81, s82, 2
	s_cmp_lt_u32 s81, 32
	s_cbranch_scc0 .Lrw_FIRST_l0_d
	s_add_i32 s81, s80, 2
	s_add_i32 s81, s81, s82
	s_and_b32 s81, s81, 31
	s_lshl_b32 s83, s81, 11
	v_add_u32_e32 v2, s83, v1
	s_lshl_b32 s83, s81, 12
	v_add_u32_e32 v213, s83, v3
	global_load_dwordx4 v[152:155], v213, s[72:73]
	global_load_dwordx4 v[156:159], v213, s[72:73] offset:16
	global_load_dwordx4 v[160:163], v213, s[72:73] offset:2048
	global_load_dwordx4 v[164:167], v213, s[72:73] offset:2064
	global_load_dwordx4 v[168:171], v2, s[74:75]
	global_load_dwordx4 v[172:175], v2, s[74:75] offset:1024
	s_branch .Lrw_FIRST_l0_e
.Lrw_FIRST_l0_d:
	global_load_dword v209, v1, s[72:73]
	global_load_dword v209, v1, s[72:73]
	global_load_dword v209, v1, s[72:73]
	global_load_dword v209, v1, s[72:73]
	global_load_dword v209, v1, s[72:73]
	global_load_dword v209, v1, s[72:73]
.Lrw_FIRST_l0_e:
	s_waitcnt vmcnt(20)
	v_lshlrev_b32_e32 v200, 16, v120
	v_and_b32_e32 v201, 0xffff0000, v120
	v_pk_mul_f32 v[204:205], v[200:201], v[200:201]
	v_lshlrev_b32_e32 v202, 16, v121
	v_and_b32_e32 v203, 0xffff0000, v121
	v_pk_mul_f32 v[206:207], v[202:203], v[202:203]
	v_lshlrev_b32_e32 v200, 16, v122
	v_and_b32_e32 v201, 0xffff0000, v122
	v_pk_fma_f32 v[204:205], v[200:201], v[200:201], v[204:205]
	v_lshlrev_b32_e32 v202, 16, v123
	v_and_b32_e32 v203, 0xffff0000, v123
	v_pk_fma_f32 v[206:207], v[202:203], v[202:203], v[206:207]
	v_lshlrev_b32_e32 v200, 16, v124
	v_and_b32_e32 v201, 0xffff0000, v124
	v_pk_fma_f32 v[204:205], v[200:201], v[200:201], v[204:205]
	v_lshlrev_b32_e32 v202, 16, v125
	v_and_b32_e32 v203, 0xffff0000, v125
	v_pk_fma_f32 v[206:207], v[202:203], v[202:203], v[206:207]
	v_lshlrev_b32_e32 v200, 16, v126
	v_and_b32_e32 v201, 0xffff0000, v126
	v_pk_fma_f32 v[204:205], v[200:201], v[200:201], v[204:205]
	v_lshlrev_b32_e32 v202, 16, v127
	v_and_b32_e32 v203, 0xffff0000, v127
	v_pk_fma_f32 v[206:207], v[202:203], v[202:203], v[206:207]
	v_pk_add_f32 v[204:205], v[204:205], v[206:207]
	v_add_f32_e32 v208, v204, v205
	s_nop 0
	s_nop 0
	v_add_f32_dpp v208, v208, v208 quad_perm:[1,0,3,2] row_mask:0xf bank_mask:0xf
	s_nop 0
	s_nop 0
	v_add_f32_dpp v208, v208, v208 quad_perm:[2,3,0,1] row_mask:0xf bank_mask:0xf
	s_nop 0
	s_nop 0
	v_add_f32_dpp v208, v208, v208 row_half_mirror row_mask:0xf bank_mask:0xf
	s_nop 0
	s_nop 0
	v_add_f32_dpp v208, v208, v208 row_mirror row_mask:0xf bank_mask:0xf
	s_nop 0
	s_nop 0
	v_add_f32_dpp v208, v208, v208 row_bcast:15 row_mask:0xa bank_mask:0xf
	s_nop 0
	s_nop 0
	v_add_f32_dpp v208, v208, v208 row_bcast:31 row_mask:0xc bank_mask:0xf
	s_nop 0
	s_nop 0
	v_readlane_b32 s60, v208, 63
	s_nop 1
	v_mov_b32_e32 v210, s60
	v_fmaak_f32 v210, v210, v212, 0x358637bd
	v_rsq_f32_e32 v210, v210
	s_nop 0
	v_lshlrev_b32_e32 v200, 16, v120
	v_and_b32_e32 v201, 0xffff0000, v120
	v_pk_mul_f32 v[200:201], v[200:201], v[210:211] op_sel_hi:[1,0]
	v_pk_fma_f32 v[104:105], v[8:9], v[200:201], v[104:105]
	v_lshlrev_b32_e32 v202, 16, v121
	v_and_b32_e32 v203, 0xffff0000, v121
	v_pk_mul_f32 v[202:203], v[202:203], v[210:211] op_sel_hi:[1,0]
	v_pk_fma_f32 v[106:107], v[10:11], v[202:203], v[106:107]
	v_lshlrev_b32_e32 v200, 16, v122
	v_and_b32_e32 v201, 0xffff0000, v122
	v_pk_mul_f32 v[200:201], v[200:201], v[210:211] op_sel_hi:[1,0]
	v_pk_fma_f32 v[108:109], v[12:13], v[200:201], v[108:109]
	v_lshlrev_b32_e32 v202, 16, v123
	v_and_b32_e32 v203, 0xffff0000, v123
	v_pk_mul_f32 v[202:203], v[202:203], v[210:211] op_sel_hi:[1,0]
	v_pk_fma_f32 v[110:111], v[14:15], v[202:203], v[110:111]
	v_lshlrev_b32_e32 v200, 16, v124
	v_and_b32_e32 v201, 0xffff0000, v124
	v_pk_mul_f32 v[200:201], v[200:201], v[210:211] op_sel_hi:[1,0]
	v_pk_fma_f32 v[112:113], v[16:17], v[200:201], v[112:113]
	v_lshlrev_b32_e32 v202, 16, v125
	v_and_b32_e32 v203, 0xffff0000, v125
	v_pk_mul_f32 v[202:203], v[202:203], v[210:211] op_sel_hi:[1,0]
	v_pk_fma_f32 v[114:115], v[18:19], v[202:203], v[114:115]
	v_lshlrev_b32_e32 v200, 16, v126
	v_and_b32_e32 v201, 0xffff0000, v126
	v_pk_mul_f32 v[200:201], v[200:201], v[210:211] op_sel_hi:[1,0]
; __device__ __forceinline__ unsigned cvtpk(float lo, float hi) { f32x2 v = {lo, hi}; bf16x2_t b = __builtin_convertvector(v, bf16x2_t); return __builtin_bit_cast(unsigned, b); }
; __device__ __forceinline__ void phase_rowwise(const void* xsrc_, bool sbf, void* xdst_, bool dbf, const bf16_t* Y, bf16_t* H, const float* mods, int lprev, int iprev, const float* lnpost, float resw, ...
;     ...
;                     for (int j = 0; j < 4; ++j) x[r][j] = x[r][j] + gp[j] * (y[r][j] * rs); }
;             }
; #pragma unroll
;             for (int r = 0; r < 2; ++r)
; #pragma unroll
;                 for (int j = 0; j < 4; ++j) { if (hasprev) { if (dbf) { u32x2 w; w.x = cvtpk(x[r][j].x, x[r][j].y); w.y = cvtpk(x[r][j].z, x[r][j].w); *(u32x2*)(xdstb + (m + r) * DM + 4 * lane + 256 * j) = w; } else *(f32x4*)(xdst + (m + r) * DM + 4 * lane + 256 * j) = x[r][j]; } }
;             if (hasnext) {
;                 float ss[2] = {0.f, 0.f};
; #pragma unroll
;                 for (int r = 0; r < 2; ++r)
; #pragma unroll
;                     for (int j = 0; j < 4; ++j) ss[r] += (x[r][j].x * x[r][j].x + x[r][j].y * x[r][j].y) + (x[r][j].z * x[r][j].z + x[r][j].w * x[r][j].w);
; #pragma unroll
;                 for (int off = 1; off < 64; off <<= 1) { ss[0] += __shfl_xor(ss[0], off); ss[1] += __shfl_xor(ss[1], off); }
; #pragma unroll
;                 for (int r = 0; r < 2; ++r) { const float rs = __builtin_amdgcn_rsqf(ss[r] * (1.f / DM) + EPS);
; #pragma unroll
;                     for (int j = 0; j < 4; ++j) { const f32x4 h = (x[r][j] * rs) * na[j] + ns[j]; u32x2 w; w.x = cvtpk(h.x, h.y); w.y = cvtpk(h.z, h.w); *(u32x2*)(H + (m + r) * DM + 4 * lane + 256 * j) = w; } }
	v_pk_fma_f32 v[116:117], v[20:21], v[200:201], v[116:117]
	v_lshlrev_b32_e32 v202, 16, v127
	v_and_b32_e32 v203, 0xffff0000, v127
	v_pk_mul_f32 v[202:203], v[202:203], v[210:211] op_sel_hi:[1,0]
	v_pk_fma_f32 v[118:119], v[22:23], v[202:203], v[118:119]
	s_add_i32 s81, s80, 0
	s_add_i32 s81, s81, s82
	s_and_b32 s81, s81, 31
	s_lshl_b32 s83, s81, 11
	v_add_u32_e32 v2, s83, v1
	v_cvt_pk_bf16_f32 v120, v104, v105
	v_cvt_pk_bf16_f32 v121, v106, v107
	v_cvt_pk_bf16_f32 v122, v108, v109
	v_cvt_pk_bf16_f32 v123, v110, v111
	v_cvt_pk_bf16_f32 v124, v112, v113
	v_cvt_pk_bf16_f32 v125, v114, v115
	v_cvt_pk_bf16_f32 v126, v116, v117
	v_cvt_pk_bf16_f32 v127, v118, v119
	global_store_dwordx4 v2, v[120:123], s[76:77]
	global_store_dwordx4 v2, v[124:127], s[76:77] offset:1024
	v_pk_mul_f32 v[204:205], v[104:105], v[104:105]
	v_pk_mul_f32 v[206:207], v[106:107], v[106:107]
	v_pk_fma_f32 v[204:205], v[108:109], v[108:109], v[204:205]
	v_pk_fma_f32 v[206:207], v[110:111], v[110:111], v[206:207]
	v_pk_fma_f32 v[204:205], v[112:113], v[112:113], v[204:205]
	v_pk_fma_f32 v[206:207], v[114:115], v[114:115], v[206:207]
	v_pk_fma_f32 v[204:205], v[116:117], v[116:117], v[204:205]
	v_pk_fma_f32 v[206:207], v[118:119], v[118:119], v[206:207]
	v_pk_add_f32 v[204:205], v[204:205], v[206:207]
	v_add_f32_e32 v208, v204, v205
	s_nop 0
	s_nop 0
	v_add_f32_dpp v208, v208, v208 quad_perm:[1,0,3,2] row_mask:0xf bank_mask:0xf
	s_nop 0
	s_nop 0
	v_add_f32_dpp v208, v208, v208 quad_perm:[2,3,0,1] row_mask:0xf bank_mask:0xf
	s_nop 0
	s_nop 0
	v_add_f32_dpp v208, v208, v208 row_half_mirror row_mask:0xf bank_mask:0xf
	s_nop 0
	s_nop 0
	v_add_f32_dpp v208, v208, v208 row_mirror row_mask:0xf bank_mask:0xf
	s_nop 0
	s_nop 0
	v_add_f32_dpp v208, v208, v208 row_bcast:15 row_mask:0xa bank_mask:0xf
	s_nop 0
	s_nop 0
	v_add_f32_dpp v208, v208, v208 row_bcast:31 row_mask:0xc bank_mask:0xf
	s_nop 0
	s_nop 0
	v_readlane_b32 s60, v208, 63
	s_nop 1
	v_mov_b32_e32 v210, s60
	v_fmaak_f32 v210, v210, v212, 0x358637bd
	v_rsq_f32_e32 v210, v210
	s_nop 0
	v_pk_mul_f32 v[200:201], v[104:105], v[210:211] op_sel_hi:[1,0]
	v_pk_fma_f32 v[200:201], v[200:201], v[24:25], v[40:41]
	v_cvt_pk_bf16_f32 v120, v200, v201
	v_pk_mul_f32 v[202:203], v[106:107], v[210:211] op_sel_hi:[1,0]
	v_pk_fma_f32 v[202:203], v[202:203], v[26:27], v[42:43]
	v_cvt_pk_bf16_f32 v121, v202, v203
	v_pk_mul_f32 v[200:201], v[108:109], v[210:211] op_sel_hi:[1,0]
	v_pk_fma_f32 v[200:201], v[200:201], v[28:29], v[44:45]
	v_cvt_pk_bf16_f32 v122, v200, v201
	v_pk_mul_f32 v[202:203], v[110:111], v[210:211] op_sel_hi:[1,0]
	v_pk_fma_f32 v[202:203], v[202:203], v[30:31], v[46:47]
	v_cvt_pk_bf16_f32 v123, v202, v203
	v_pk_mul_f32 v[200:201], v[112:113], v[210:211] op_sel_hi:[1,0]
	v_pk_fma_f32 v[200:201], v[200:201], v[32:33], v[48:49]
	v_cvt_pk_bf16_f32 v124, v200, v201
	v_pk_mul_f32 v[202:203], v[114:115], v[210:211] op_sel_hi:[1,0]
	v_pk_fma_f32 v[202:203], v[202:203], v[34:35], v[50:51]
	v_cvt_pk_bf16_f32 v125, v202, v203
	v_pk_mul_f32 v[200:201], v[116:117], v[210:211] op_sel_hi:[1,0]
	v_pk_fma_f32 v[200:201], v[200:201], v[36:37], v[52:53]
	v_cvt_pk_bf16_f32 v126, v200, v201
	v_pk_mul_f32 v[202:203], v[118:119], v[210:211] op_sel_hi:[1,0]
	v_pk_fma_f32 v[202:203], v[202:203], v[38:39], v[54:55]
	v_cvt_pk_bf16_f32 v127, v202, v203
	global_store_dwordx4 v2, v[120:123], s[78:79]
	global_store_dwordx4 v2, v[124:127], s[78:79] offset:1024
	s_add_i32 s81, s82, 3
	s_cmp_lt_u32 s81, 32
	s_cbranch_scc0 .Lrw_FIRST_l1_d
	s_add_i32 s81, s80, 3
	s_add_i32 s81, s81, s82
	s_and_b32 s81, s81, 31
	s_lshl_b32 s83, s81, 11
	v_add_u32_e32 v2, s83, v1
	s_lshl_b32 s83, s81, 12
	v_add_u32_e32 v213, s83, v3
	global_load_dwordx4 v[56:59], v213, s[72:73]
	global_load_dwordx4 v[60:63], v213, s[72:73] offset:16
	global_load_dwordx4 v[64:67], v213, s[72:73] offset:2048
	global_load_dwordx4 v[68:71], v213, s[72:73] offset:2064
	global_load_dwordx4 v[72:75], v2, s[74:75]
	global_load_dwordx4 v[76:79], v2, s[74:75] offset:1024
	s_branch .Lrw_FIRST_l1_e

; __device__ __forceinline__ float bflo(unsigned u) { return __uint_as_float(u << 16); }
; __device__ __forceinline__ void phase_rowwise(const void* xsrc_, bool sbf, void* xdst_, bool dbf, const bf16_t* Y, bf16_t* H, const float* mods, int lprev, int iprev, const float* lnpost, float resw, ...
;     ...
;             if (hasprev) {
;                 f32x4 y[2][4]; float ss[2] = {0.f, 0.f};
; #pragma unroll
;                 for (int r = 0; r < 2; ++r)
; #pragma unroll
;                     for (int j = 0; j < 4; ++j) { const u32x2 u = yr[r][j]; y[r][j] = (f32x4){bflo(u.x), bfhi(u.x), bflo(u.y), bfhi(u.y)};
;                         ss[r] += (y[r][j].x * y[r][j].x + y[r][j].y * y[r][j].y) + (y[r][j].z * y[r][j].z + y[r][j].w * y[r][j].w); }
; #pragma unroll
;                 for (int off = 1; off < 64; off <<= 1) { ss[0] += __shfl_xor(ss[0], off); ss[1] += __shfl_xor(ss[1], off); }
; #pragma unroll
;                 for (int r = 0; r < 2; ++r) { const float rs = __builtin_amdgcn_rsqf(ss[r] * (1.f / DM) + EPS);
; #pragma unroll
;                     for (int j = 0; j < 4; ++j) x[r][j] = x[r][j] + gp[j] * (y[r][j] * rs); }
;             }
; #pragma unroll
;             for (int r = 0; r < 2; ++r)
; #pragma unroll
;                 for (int j = 0; j < 4; ++j) { if (hasprev) { if (dbf) { u32x2 w; w.x = cvtpk(x[r][j].x, x[r][j].y); w.y = cvtpk(x[r][j].z, x[r][j].w); *(u32x2*)(xdstb + (m + r) * DM + 4 * lane + 256 * j) = w; } else *(f32x4*)(xdst + (m + r) * DM + 4 * lane + 256 * j) = x[r][j]; } }
;             if (hasnext) {
;                 float ss[2] = {0.f, 0.f};
; #pragma unroll
;                 for (int r = 0; r < 2; ++r)
; #pragma unroll
;                     for (int j = 0; j < 4; ++j) ss[r] += (x[r][j].x * x[r][j].x + x[r][j].y * x[r][j].y) + (x[r][j].z * x[r][j].z + x[r][j].w * x[r][j].w);
; #pragma unroll
;                 for (int off = 1; off < 64; off <<= 1) { ss[0] += __shfl_xor(ss[0], off); ss[1] += __shfl_xor(ss[1], off); }
; #pragma unroll
;                 for (int r = 0; r < 2; ++r) { const float rs = __builtin_amdgcn_rsqf(ss[r] * (1.f / DM) + EPS);
; #pragma unroll
;                     for (int j = 0; j < 4; ++j) { const f32x4 h = (x[r][j] * rs) * na[j] + ns[j]; u32x2 w; w.x = cvtpk(h.x, h.y); w.y = cvtpk(h.z, h.w); *(u32x2*)(H + (m + r) * DM + 4 * lane + 256 * j) = w; } }
.Lrw_FIRST_l1_e:
	s_waitcnt vmcnt(20)
	v_lshlrev_b32_e32 v200, 16, v144
	v_and_b32_e32 v201, 0xffff0000, v144
	v_pk_mul_f32 v[204:205], v[200:201], v[200:201]
	v_lshlrev_b32_e32 v202, 16, v145
	v_and_b32_e32 v203, 0xffff0000, v145
	v_pk_mul_f32 v[206:207], v[202:203], v[202:203]
	v_lshlrev_b32_e32 v200, 16, v146
	v_and_b32_e32 v201, 0xffff0000, v146
	v_pk_fma_f32 v[204:205], v[200:201], v[200:201], v[204:205]
	v_lshlrev_b32_e32 v202, 16, v147
	v_and_b32_e32 v203, 0xffff0000, v147
	v_pk_fma_f32 v[206:207], v[202:203], v[202:203], v[206:207]
	v_lshlrev_b32_e32 v200, 16, v148
	v_and_b32_e32 v201, 0xffff0000, v148
	v_pk_fma_f32 v[204:205], v[200:201], v[200:201], v[204:205]
	v_lshlrev_b32_e32 v202, 16, v149
	v_and_b32_e32 v203, 0xffff0000, v149
	v_pk_fma_f32 v[206:207], v[202:203], v[202:203], v[206:207]
	v_lshlrev_b32_e32 v200, 16, v150
	v_and_b32_e32 v201, 0xffff0000, v150
	v_pk_fma_f32 v[204:205], v[200:201], v[200:201], v[204:205]
	v_lshlrev_b32_e32 v202, 16, v151
	v_and_b32_e32 v203, 0xffff0000, v151
	v_pk_fma_f32 v[206:207], v[202:203], v[202:203], v[206:207]
	v_pk_add_f32 v[204:205], v[204:205], v[206:207]
	v_add_f32_e32 v208, v204, v205
	s_nop 0
	s_nop 0
	v_add_f32_dpp v208, v208, v208 quad_perm:[1,0,3,2] row_mask:0xf bank_mask:0xf
	s_nop 0
	s_nop 0
	v_add_f32_dpp v208, v208, v208 quad_perm:[2,3,0,1] row_mask:0xf bank_mask:0xf
	s_nop 0
	s_nop 0
	v_add_f32_dpp v208, v208, v208 row_half_mirror row_mask:0xf bank_mask:0xf
	s_nop 0
	s_nop 0
	v_add_f32_dpp v208, v208, v208 row_mirror row_mask:0xf bank_mask:0xf
	s_nop 0
	s_nop 0
	v_add_f32_dpp v208, v208, v208 row_bcast:15 row_mask:0xa bank_mask:0xf
	s_nop 0
	s_nop 0
	v_add_f32_dpp v208, v208, v208 row_bcast:31 row_mask:0xc bank_mask:0xf
	s_nop 0
	s_nop 0
	v_readlane_b32 s60, v208, 63
	s_nop 1
	v_mov_b32_e32 v210, s60
	v_fmaak_f32 v210, v210, v212, 0x358637bd
	v_rsq_f32_e32 v210, v210
	s_nop 0
	v_lshlrev_b32_e32 v200, 16, v144
	v_and_b32_e32 v201, 0xffff0000, v144
	v_pk_mul_f32 v[200:201], v[200:201], v[210:211] op_sel_hi:[1,0]
	v_pk_fma_f32 v[128:129], v[8:9], v[200:201], v[128:129]
	v_lshlrev_b32_e32 v202, 16, v145
	v_and_b32_e32 v203, 0xffff0000, v145
	v_pk_mul_f32 v[202:203], v[202:203], v[210:211] op_sel_hi:[1,0]
	v_pk_fma_f32 v[130:131], v[10:11], v[202:203], v[130:131]
	v_lshlrev_b32_e32 v200, 16, v146
	v_and_b32_e32 v201, 0xffff0000, v146
	v_pk_mul_f32 v[200:201], v[200:201], v[210:211] op_sel_hi:[1,0]
	v_pk_fma_f32 v[132:133], v[12:13], v[200:201], v[132:133]
	v_lshlrev_b32_e32 v202, 16, v147
	v_and_b32_e32 v203, 0xffff0000, v147
	v_pk_mul_f32 v[202:203], v[202:203], v[210:211] op_sel_hi:[1,0]
	v_pk_fma_f32 v[134:135], v[14:15], v[202:203], v[134:135]
	v_lshlrev_b32_e32 v200, 16, v148
	v_and_b32_e32 v201, 0xffff0000, v148
	v_pk_mul_f32 v[200:201], v[200:201], v[210:211] op_sel_hi:[1,0]
	v_pk_fma_f32 v[136:137], v[16:17], v[200:201], v[136:137]
	v_lshlrev_b32_e32 v202, 16, v149
	v_and_b32_e32 v203, 0xffff0000, v149
	v_pk_mul_f32 v[202:203], v[202:203], v[210:211] op_sel_hi:[1,0]
	v_pk_fma_f32 v[138:139], v[18:19], v[202:203], v[138:139]
	v_lshlrev_b32_e32 v200, 16, v150
	v_and_b32_e32 v201, 0xffff0000, v150
	v_pk_mul_f32 v[200:201], v[200:201], v[210:211] op_sel_hi:[1,0]
	v_pk_fma_f32 v[140:141], v[20:21], v[200:201], v[140:141]
	v_lshlrev_b32_e32 v202, 16, v151
	v_and_b32_e32 v203, 0xffff0000, v151
	v_pk_mul_f32 v[202:203], v[202:203], v[210:211] op_sel_hi:[1,0]
	v_pk_fma_f32 v[142:143], v[22:23], v[202:203], v[142:143]
	s_add_i32 s81, s80, 1
	s_add_i32 s81, s81, s82
	s_and_b32 s81, s81, 31
	s_lshl_b32 s83, s81, 11
	v_add_u32_e32 v2, s83, v1
	v_cvt_pk_bf16_f32 v144, v128, v129
	v_cvt_pk_bf16_f32 v145, v130, v131
	v_cvt_pk_bf16_f32 v146, v132, v133
	v_cvt_pk_bf16_f32 v147, v134, v135
	v_cvt_pk_bf16_f32 v148, v136, v137
	v_cvt_pk_bf16_f32 v149, v138, v139
	v_cvt_pk_bf16_f32 v150, v140, v141
	v_cvt_pk_bf16_f32 v151, v142, v143
	global_store_dwordx4 v2, v[144:147], s[76:77]
	global_store_dwordx4 v2, v[148:151], s[76:77] offset:1024
	v_pk_mul_f32 v[204:205], v[128:129], v[128:129]
	v_pk_mul_f32 v[206:207], v[130:131], v[130:131]
	v_pk_fma_f32 v[204:205], v[132:133], v[132:133], v[204:205]
	v_pk_fma_f32 v[206:207], v[134:135], v[134:135], v[206:207]
	v_pk_fma_f32 v[204:205], v[136:137], v[136:137], v[204:205]
	v_pk_fma_f32 v[206:207], v[138:139], v[138:139], v[206:207]
	v_pk_fma_f32 v[204:205], v[140:141], v[140:141], v[204:205]
	v_pk_fma_f32 v[206:207], v[142:143], v[142:143], v[206:207]
	v_pk_add_f32 v[204:205], v[204:205], v[206:207]
	v_add_f32_e32 v208, v204, v205
	s_nop 0
	s_nop 0
	v_add_f32_dpp v208, v208, v208 quad_perm:[1,0,3,2] row_mask:0xf bank_mask:0xf
	s_nop 0
	s_nop 0
	v_add_f32_dpp v208, v208, v208 quad_perm:[2,3,0,1] row_mask:0xf bank_mask:0xf
	s_nop 0
	s_nop 0
	v_add_f32_dpp v208, v208, v208 row_half_mirror row_mask:0xf bank_mask:0xf
	s_nop 0
	s_nop 0
	v_add_f32_dpp v208, v208, v208 row_mirror row_mask:0xf bank_mask:0xf
	s_nop 0
	s_nop 0
	v_add_f32_dpp v208, v208, v208 row_bcast:15 row_mask:0xa bank_mask:0xf
	s_nop 0
	s_nop 0
	v_add_f32_dpp v208, v208, v208 row_bcast:31 row_mask:0xc bank_mask:0xf
	s_nop 0
	s_nop 0
	v_readlane_b32 s60, v208, 63
	s_nop 1
	v_mov_b32_e32 v210, s60
	v_fmaak_f32 v210, v210, v212, 0x358637bd
	v_rsq_f32_e32 v210, v210
	s_nop 0
	v_pk_mul_f32 v[200:201], v[128:129], v[210:211] op_sel_hi:[1,0]
	v_pk_fma_f32 v[200:201], v[200:201], v[24:25], v[40:41]
	v_cvt_pk_bf16_f32 v144, v200, v201
	v_pk_mul_f32 v[202:203], v[130:131], v[210:211] op_sel_hi:[1,0]
	v_pk_fma_f32 v[202:203], v[202:203], v[26:27], v[42:43]
	v_cvt_pk_bf16_f32 v145, v202, v203
	v_pk_mul_f32 v[200:201], v[132:133], v[210:211] op_sel_hi:[1,0]
	v_pk_fma_f32 v[200:201], v[200:201], v[28:29], v[44:45]
	v_cvt_pk_bf16_f32 v146, v200, v201
	v_pk_mul_f32 v[202:203], v[134:135], v[210:211] op_sel_hi:[1,0]
	v_pk_fma_f32 v[202:203], v[202:203], v[30:31], v[46:47]
	v_cvt_pk_bf16_f32 v147, v202, v203
	v_pk_mul_f32 v[200:201], v[136:137], v[210:211] op_sel_hi:[1,0]
	v_pk_fma_f32 v[200:201], v[200:201], v[32:33], v[48:49]
	v_cvt_pk_bf16_f32 v148, v200, v201
	v_pk_mul_f32 v[202:203], v[138:139], v[210:211] op_sel_hi:[1,0]
	v_pk_fma_f32 v[202:203], v[202:203], v[34:35], v[50:51]
	v_cvt_pk_bf16_f32 v149, v202, v203
	v_pk_mul_f32 v[200:201], v[140:141], v[210:211] op_sel_hi:[1,0]
	v_pk_fma_f32 v[200:201], v[200:201], v[36:37], v[52:53]
	v_cvt_pk_bf16_f32 v150, v200, v201
	v_pk_mul_f32 v[202:203], v[142:143], v[210:211] op_sel_hi:[1,0]
	v_pk_fma_f32 v[202:203], v[202:203], v[38:39], v[54:55]
	v_cvt_pk_bf16_f32 v151, v202, v203
	global_store_dwordx4 v2, v[144:147], s[78:79]
	global_store_dwordx4 v2, v[148:151], s[78:79] offset:1024
	s_add_i32 s81, s82, 4
	s_cmp_lt_u32 s81, 32
	s_cbranch_scc0 .Lrw_FIRST_l2_d
; __device__ __forceinline__ void phase_rowwise(const void* xsrc_, bool sbf, void* xdst_, bool dbf, const bf16_t* Y, bf16_t* H, const float* mods, int lprev, int iprev, const float* lnpost, float resw, ...
;     ...
;             if (rr + 2 < 32) {
; #pragma unroll
;                 for (int r = 0; r < 2; ++r)
; #pragma unroll
;                     for (int j = 0; j < 4; ++j) { if (sbf) xnb[r][j] = *(const u32x2*)(xsrcb + (m + 2 + r) * DM + 4 * lane + 256 * j); else xn[r][j] = *(const f32x4*)(xsrc + (m + 2 + r) * DM + 4 * lane + 256 * j); if (hasprev) yn[r][j] = *(const u32x2*)(Y + (m + 2 + r) * DM + 4 * lane + 256 * j); } }
	s_add_i32 s81, s80, 4
	s_add_i32 s81, s81, s82
	s_and_b32 s81, s81, 31
	s_lshl_b32 s83, s81, 11
	v_add_u32_e32 v2, s83, v1
	s_lshl_b32 s83, s81, 12
	v_add_u32_e32 v213, s83, v3
	global_load_dwordx4 v[80:83], v213, s[72:73]
	global_load_dwordx4 v[84:87], v213, s[72:73] offset:16
	global_load_dwordx4 v[88:91], v213, s[72:73] offset:2048
	global_load_dwordx4 v[92:95], v213, s[72:73] offset:2064
	global_load_dwordx4 v[96:99], v2, s[74:75]
	global_load_dwordx4 v[100:103], v2, s[74:75] offset:1024
	s_branch .Lrw_FIRST_l2_e

; __device__ __forceinline__ float bflo(unsigned u) { return __uint_as_float(u << 16); }
; __device__ __forceinline__ void phase_rowwise(const void* xsrc_, bool sbf, void* xdst_, bool dbf, const bf16_t* Y, bf16_t* H, const float* mods, int lprev, int iprev, const float* lnpost, float resw, ...
;     ...
;             if (hasprev) {
;                 f32x4 y[2][4]; float ss[2] = {0.f, 0.f};
; #pragma unroll
;                 for (int r = 0; r < 2; ++r)
; #pragma unroll
;                     for (int j = 0; j < 4; ++j) { const u32x2 u = yr[r][j]; y[r][j] = (f32x4){bflo(u.x), bfhi(u.x), bflo(u.y), bfhi(u.y)};
;                         ss[r] += (y[r][j].x * y[r][j].x + y[r][j].y * y[r][j].y) + (y[r][j].z * y[r][j].z + y[r][j].w * y[r][j].w); }
; #pragma unroll
;                 for (int off = 1; off < 64; off <<= 1) { ss[0] += __shfl_xor(ss[0], off); ss[1] += __shfl_xor(ss[1], off); }
; #pragma unroll
;                 for (int r = 0; r < 2; ++r) { const float rs = __builtin_amdgcn_rsqf(ss[r] * (1.f / DM) + EPS);
; #pragma unroll
;                     for (int j = 0; j < 4; ++j) x[r][j] = x[r][j] + gp[j] * (y[r][j] * rs); }
;             }
; #pragma unroll
;             for (int r = 0; r < 2; ++r)
; #pragma unroll
;                 for (int j = 0; j < 4; ++j) { if (hasprev) { if (dbf) { u32x2 w; w.x = cvtpk(x[r][j].x, x[r][j].y); w.y = cvtpk(x[r][j].z, x[r][j].w); *(u32x2*)(xdstb + (m + r) * DM + 4 * lane + 256 * j) = w; } else *(f32x4*)(xdst + (m + r) * DM + 4 * lane + 256 * j) = x[r][j]; } }
;             if (hasnext) {
;                 float ss[2] = {0.f, 0.f};
; #pragma unroll
;                 for (int r = 0; r < 2; ++r)
; #pragma unroll
;                     for (int j = 0; j < 4; ++j) ss[r] += (x[r][j].x * x[r][j].x + x[r][j].y * x[r][j].y) + (x[r][j].z * x[r][j].z + x[r][j].w * x[r][j].w);
; #pragma unroll
;                 for (int off = 1; off < 64; off <<= 1) { ss[0] += __shfl_xor(ss[0], off); ss[1] += __shfl_xor(ss[1], off); }
; #pragma unroll
;                 for (int r = 0; r < 2; ++r) { const float rs = __builtin_amdgcn_rsqf(ss[r] * (1.f / DM) + EPS);
; #pragma unroll
;                     for (int j = 0; j < 4; ++j) { const f32x4 h = (x[r][j] * rs) * na[j] + ns[j]; u32x2 w; w.x = cvtpk(h.x, h.y); w.y = cvtpk(h.z, h.w); *(u32x2*)(H + (m + r) * DM + 4 * lane + 256 * j) = w; } }
.Lrw_FIRST_l2_e:
	s_waitcnt vmcnt(20)
	v_lshlrev_b32_e32 v200, 16, v168
	v_and_b32_e32 v201, 0xffff0000, v168
	v_pk_mul_f32 v[204:205], v[200:201], v[200:201]
	v_lshlrev_b32_e32 v202, 16, v169
	v_and_b32_e32 v203, 0xffff0000, v169
	v_pk_mul_f32 v[206:207], v[202:203], v[202:203]
	v_lshlrev_b32_e32 v200, 16, v170
	v_and_b32_e32 v201, 0xffff0000, v170
	v_pk_fma_f32 v[204:205], v[200:201], v[200:201], v[204:205]
	v_lshlrev_b32_e32 v202, 16, v171
	v_and_b32_e32 v203, 0xffff0000, v171
	v_pk_fma_f32 v[206:207], v[202:203], v[202:203], v[206:207]
	v_lshlrev_b32_e32 v200, 16, v172
	v_and_b32_e32 v201, 0xffff0000, v172
	v_pk_fma_f32 v[204:205], v[200:201], v[200:201], v[204:205]
	v_lshlrev_b32_e32 v202, 16, v173
	v_and_b32_e32 v203, 0xffff0000, v173
	v_pk_fma_f32 v[206:207], v[202:203], v[202:203], v[206:207]
	v_lshlrev_b32_e32 v200, 16, v174
	v_and_b32_e32 v201, 0xffff0000, v174
	v_pk_fma_f32 v[204:205], v[200:201], v[200:201], v[204:205]
	v_lshlrev_b32_e32 v202, 16, v175
	v_and_b32_e32 v203, 0xffff0000, v175
	v_pk_fma_f32 v[206:207], v[202:203], v[202:203], v[206:207]
	v_pk_add_f32 v[204:205], v[204:205], v[206:207]
	v_add_f32_e32 v208, v204, v205
	s_nop 0
	s_nop 0
	v_add_f32_dpp v208, v208, v208 quad_perm:[1,0,3,2] row_mask:0xf bank_mask:0xf
	s_nop 0
	s_nop 0
	v_add_f32_dpp v208, v208, v208 quad_perm:[2,3,0,1] row_mask:0xf bank_mask:0xf
	s_nop 0
	s_nop 0
	v_add_f32_dpp v208, v208, v208 row_half_mirror row_mask:0xf bank_mask:0xf
	s_nop 0
	s_nop 0
	v_add_f32_dpp v208, v208, v208 row_mirror row_mask:0xf bank_mask:0xf
	s_nop 0
	s_nop 0
	v_add_f32_dpp v208, v208, v208 row_bcast:15 row_mask:0xa bank_mask:0xf
	s_nop 0
	s_nop 0
	v_add_f32_dpp v208, v208, v208 row_bcast:31 row_mask:0xc bank_mask:0xf
	s_nop 0
	s_nop 0
	v_readlane_b32 s60, v208, 63
	s_nop 1
	v_mov_b32_e32 v210, s60
	v_fmaak_f32 v210, v210, v212, 0x358637bd
	v_rsq_f32_e32 v210, v210
	s_nop 0
	v_lshlrev_b32_e32 v200, 16, v168
	v_and_b32_e32 v201, 0xffff0000, v168
	v_pk_mul_f32 v[200:201], v[200:201], v[210:211] op_sel_hi:[1,0]
	v_pk_fma_f32 v[152:153], v[8:9], v[200:201], v[152:153]
	v_lshlrev_b32_e32 v202, 16, v169
	v_and_b32_e32 v203, 0xffff0000, v169
	v_pk_mul_f32 v[202:203], v[202:203], v[210:211] op_sel_hi:[1,0]
	v_pk_fma_f32 v[154:155], v[10:11], v[202:203], v[154:155]
	v_lshlrev_b32_e32 v200, 16, v170
	v_and_b32_e32 v201, 0xffff0000, v170
	v_pk_mul_f32 v[200:201], v[200:201], v[210:211] op_sel_hi:[1,0]
	v_pk_fma_f32 v[156:157], v[12:13], v[200:201], v[156:157]
	v_lshlrev_b32_e32 v202, 16, v171
	v_and_b32_e32 v203, 0xffff0000, v171
	v_pk_mul_f32 v[202:203], v[202:203], v[210:211] op_sel_hi:[1,0]
	v_pk_fma_f32 v[158:159], v[14:15], v[202:203], v[158:159]
	v_lshlrev_b32_e32 v200, 16, v172
	v_and_b32_e32 v201, 0xffff0000, v172
	v_pk_mul_f32 v[200:201], v[200:201], v[210:211] op_sel_hi:[1,0]
	v_pk_fma_f32 v[160:161], v[16:17], v[200:201], v[160:161]
	v_lshlrev_b32_e32 v202, 16, v173
	v_and_b32_e32 v203, 0xffff0000, v173
	v_pk_mul_f32 v[202:203], v[202:203], v[210:211] op_sel_hi:[1,0]
	v_pk_fma_f32 v[162:163], v[18:19], v[202:203], v[162:163]
	v_lshlrev_b32_e32 v200, 16, v174
	v_and_b32_e32 v201, 0xffff0000, v174
	v_pk_mul_f32 v[200:201], v[200:201], v[210:211] op_sel_hi:[1,0]
	v_pk_fma_f32 v[164:165], v[20:21], v[200:201], v[164:165]
	v_lshlrev_b32_e32 v202, 16, v175
	v_and_b32_e32 v203, 0xffff0000, v175
	v_pk_mul_f32 v[202:203], v[202:203], v[210:211] op_sel_hi:[1,0]
	v_pk_fma_f32 v[166:167], v[22:23], v[202:203], v[166:167]
	s_add_i32 s81, s80, 2
	s_add_i32 s81, s81, s82
	s_and_b32 s81, s81, 31
	s_lshl_b32 s83, s81, 11
	v_add_u32_e32 v2, s83, v1
	v_cvt_pk_bf16_f32 v168, v152, v153
	v_cvt_pk_bf16_f32 v169, v154, v155
	v_cvt_pk_bf16_f32 v170, v156, v157
	v_cvt_pk_bf16_f32 v171, v158, v159
	v_cvt_pk_bf16_f32 v172, v160, v161
	v_cvt_pk_bf16_f32 v173, v162, v163
	v_cvt_pk_bf16_f32 v174, v164, v165
	v_cvt_pk_bf16_f32 v175, v166, v167
	global_store_dwordx4 v2, v[168:171], s[76:77]
	global_store_dwordx4 v2, v[172:175], s[76:77] offset:1024
	v_pk_mul_f32 v[204:205], v[152:153], v[152:153]
	v_pk_mul_f32 v[206:207], v[154:155], v[154:155]
	v_pk_fma_f32 v[204:205], v[156:157], v[156:157], v[204:205]
	v_pk_fma_f32 v[206:207], v[158:159], v[158:159], v[206:207]
	v_pk_fma_f32 v[204:205], v[160:161], v[160:161], v[204:205]
	v_pk_fma_f32 v[206:207], v[162:163], v[162:163], v[206:207]
	v_pk_fma_f32 v[204:205], v[164:165], v[164:165], v[204:205]
	v_pk_fma_f32 v[206:207], v[166:167], v[166:167], v[206:207]
	v_pk_add_f32 v[204:205], v[204:205], v[206:207]
	v_add_f32_e32 v208, v204, v205
	s_nop 0
	s_nop 0
	v_add_f32_dpp v208, v208, v208 quad_perm:[1,0,3,2] row_mask:0xf bank_mask:0xf
	s_nop 0
	s_nop 0
	v_add_f32_dpp v208, v208, v208 quad_perm:[2,3,0,1] row_mask:0xf bank_mask:0xf
	s_nop 0
	s_nop 0
	v_add_f32_dpp v208, v208, v208 row_half_mirror row_mask:0xf bank_mask:0xf
	s_nop 0
	s_nop 0
	v_add_f32_dpp v208, v208, v208 row_mirror row_mask:0xf bank_mask:0xf
	s_nop 0
	s_nop 0
	v_add_f32_dpp v208, v208, v208 row_bcast:15 row_mask:0xa bank_mask:0xf
	s_nop 0
	s_nop 0
	v_add_f32_dpp v208, v208, v208 row_bcast:31 row_mask:0xc bank_mask:0xf
	s_nop 0
	s_nop 0
	v_readlane_b32 s60, v208, 63
	s_nop 1
	v_mov_b32_e32 v210, s60
	v_fmaak_f32 v210, v210, v212, 0x358637bd
	v_rsq_f32_e32 v210, v210
	s_nop 0
	v_pk_mul_f32 v[200:201], v[152:153], v[210:211] op_sel_hi:[1,0]
	v_pk_fma_f32 v[200:201], v[200:201], v[24:25], v[40:41]
	v_cvt_pk_bf16_f32 v168, v200, v201
	v_pk_mul_f32 v[202:203], v[154:155], v[210:211] op_sel_hi:[1,0]
	v_pk_fma_f32 v[202:203], v[202:203], v[26:27], v[42:43]
	v_cvt_pk_bf16_f32 v169, v202, v203
	v_pk_mul_f32 v[200:201], v[156:157], v[210:211] op_sel_hi:[1,0]
	v_pk_fma_f32 v[200:201], v[200:201], v[28:29], v[44:45]
	v_cvt_pk_bf16_f32 v170, v200, v201
	v_pk_mul_f32 v[202:203], v[158:159], v[210:211] op_sel_hi:[1,0]
	v_pk_fma_f32 v[202:203], v[202:203], v[30:31], v[46:47]
	v_cvt_pk_bf16_f32 v171, v202, v203
	v_pk_mul_f32 v[200:201], v[160:161], v[210:211] op_sel_hi:[1,0]
	v_pk_fma_f32 v[200:201], v[200:201], v[32:33], v[48:49]
	v_cvt_pk_bf16_f32 v172, v200, v201
	v_pk_mul_f32 v[202:203], v[162:163], v[210:211] op_sel_hi:[1,0]
	v_pk_fma_f32 v[202:203], v[202:203], v[34:35], v[50:51]
	v_cvt_pk_bf16_f32 v173, v202, v203
	v_pk_mul_f32 v[200:201], v[164:165], v[210:211] op_sel_hi:[1,0]
	v_pk_fma_f32 v[200:201], v[200:201], v[36:37], v[52:53]
	v_cvt_pk_bf16_f32 v174, v200, v201
	v_pk_mul_f32 v[202:203], v[166:167], v[210:211] op_sel_hi:[1,0]
	v_pk_fma_f32 v[202:203], v[202:203], v[38:39], v[54:55]
	v_cvt_pk_bf16_f32 v175, v202, v203
	global_store_dwordx4 v2, v[168:171], s[78:79]
	global_store_dwordx4 v2, v[172:175], s[78:79] offset:1024
	s_add_i32 s81, s82, 5
	s_cmp_lt_u32 s81, 32
	s_cbranch_scc0 .Lrw_FIRST_l3_d
; __device__ __forceinline__ void phase_rowwise(const void* xsrc_, bool sbf, void* xdst_, bool dbf, const bf16_t* Y, bf16_t* H, const float* mods, int lprev, int iprev, const float* lnpost, float resw, ...
;     ...
;             if (rr + 2 < 32) {
; #pragma unroll
;                 for (int r = 0; r < 2; ++r)
; #pragma unroll
;                     for (int j = 0; j < 4; ++j) { if (sbf) xnb[r][j] = *(const u32x2*)(xsrcb + (m + 2 + r) * DM + 4 * lane + 256 * j); else xn[r][j] = *(const f32x4*)(xsrc + (m + 2 + r) * DM + 4 * lane + 256 * j); if (hasprev) yn[r][j] = *(const u32x2*)(Y + (m + 2 + r) * DM + 4 * lane + 256 * j); } }
	s_add_i32 s81, s80, 5
	s_add_i32 s81, s81, s82
	s_and_b32 s81, s81, 31
	s_lshl_b32 s83, s81, 11
	v_add_u32_e32 v2, s83, v1
	s_lshl_b32 s83, s81, 12
	v_add_u32_e32 v213, s83, v3
	global_load_dwordx4 v[104:107], v213, s[72:73]
	global_load_dwordx4 v[108:111], v213, s[72:73] offset:16
	global_load_dwordx4 v[112:115], v213, s[72:73] offset:2048
	global_load_dwordx4 v[116:119], v213, s[72:73] offset:2064
	global_load_dwordx4 v[120:123], v2, s[74:75]
	global_load_dwordx4 v[124:127], v2, s[74:75] offset:1024
	s_branch .Lrw_FIRST_l3_e

; __device__ __forceinline__ float bflo(unsigned u) { return __uint_as_float(u << 16); }
; __device__ __forceinline__ void phase_rowwise(const void* xsrc_, bool sbf, void* xdst_, bool dbf, const bf16_t* Y, bf16_t* H, const float* mods, int lprev, int iprev, const float* lnpost, float resw, ...
;     ...
;             if (hasprev) {
;                 f32x4 y[2][4]; float ss[2] = {0.f, 0.f};
; #pragma unroll
;                 for (int r = 0; r < 2; ++r)
; #pragma unroll
;                     for (int j = 0; j < 4; ++j) { const u32x2 u = yr[r][j]; y[r][j] = (f32x4){bflo(u.x), bfhi(u.x), bflo(u.y), bfhi(u.y)};
;                         ss[r] += (y[r][j].x * y[r][j].x + y[r][j].y * y[r][j].y) + (y[r][j].z * y[r][j].z + y[r][j].w * y[r][j].w); }
; #pragma unroll
;                 for (int off = 1; off < 64; off <<= 1) { ss[0] += __shfl_xor(ss[0], off); ss[1] += __shfl_xor(ss[1], off); }
; #pragma unroll
;                 for (int r = 0; r < 2; ++r) { const float rs = __builtin_amdgcn_rsqf(ss[r] * (1.f / DM) + EPS);
; #pragma unroll
;                     for (int j = 0; j < 4; ++j) x[r][j] = x[r][j] + gp[j] * (y[r][j] * rs); }
;             }
; #pragma unroll
;             for (int r = 0; r < 2; ++r)
; #pragma unroll
;                 for (int j = 0; j < 4; ++j) { if (hasprev) { if (dbf) { u32x2 w; w.x = cvtpk(x[r][j].x, x[r][j].y); w.y = cvtpk(x[r][j].z, x[r][j].w); *(u32x2*)(xdstb + (m + r) * DM + 4 * lane + 256 * j) = w; } else *(f32x4*)(xdst + (m + r) * DM + 4 * lane + 256 * j) = x[r][j]; } }
;             if (hasnext) {
;                 float ss[2] = {0.f, 0.f};
; #pragma unroll
;                 for (int r = 0; r < 2; ++r)
; #pragma unroll
;                     for (int j = 0; j < 4; ++j) ss[r] += (x[r][j].x * x[r][j].x + x[r][j].y * x[r][j].y) + (x[r][j].z * x[r][j].z + x[r][j].w * x[r][j].w);
; #pragma unroll
;                 for (int off = 1; off < 64; off <<= 1) { ss[0] += __shfl_xor(ss[0], off); ss[1] += __shfl_xor(ss[1], off); }
; #pragma unroll
;                 for (int r = 0; r < 2; ++r) { const float rs = __builtin_amdgcn_rsqf(ss[r] * (1.f / DM) + EPS);
; #pragma unroll
;                     for (int j = 0; j < 4; ++j) { const f32x4 h = (x[r][j] * rs) * na[j] + ns[j]; u32x2 w; w.x = cvtpk(h.x, h.y); w.y = cvtpk(h.z, h.w); *(u32x2*)(H + (m + r) * DM + 4 * lane + 256 * j) = w; } }
.Lrw_FIRST_l3_e:
	s_waitcnt vmcnt(20)
	v_lshlrev_b32_e32 v200, 16, v72
	v_and_b32_e32 v201, 0xffff0000, v72
	v_pk_mul_f32 v[204:205], v[200:201], v[200:201]
	v_lshlrev_b32_e32 v202, 16, v73
	v_and_b32_e32 v203, 0xffff0000, v73
	v_pk_mul_f32 v[206:207], v[202:203], v[202:203]
	v_lshlrev_b32_e32 v200, 16, v74
	v_and_b32_e32 v201, 0xffff0000, v74
	v_pk_fma_f32 v[204:205], v[200:201], v[200:201], v[204:205]
	v_lshlrev_b32_e32 v202, 16, v75
	v_and_b32_e32 v203, 0xffff0000, v75
	v_pk_fma_f32 v[206:207], v[202:203], v[202:203], v[206:207]
	v_lshlrev_b32_e32 v200, 16, v76
	v_and_b32_e32 v201, 0xffff0000, v76
	v_pk_fma_f32 v[204:205], v[200:201], v[200:201], v[204:205]
	v_lshlrev_b32_e32 v202, 16, v77
	v_and_b32_e32 v203, 0xffff0000, v77
	v_pk_fma_f32 v[206:207], v[202:203], v[202:203], v[206:207]
	v_lshlrev_b32_e32 v200, 16, v78
	v_and_b32_e32 v201, 0xffff0000, v78
	v_pk_fma_f32 v[204:205], v[200:201], v[200:201], v[204:205]
	v_lshlrev_b32_e32 v202, 16, v79
	v_and_b32_e32 v203, 0xffff0000, v79
	v_pk_fma_f32 v[206:207], v[202:203], v[202:203], v[206:207]
	v_pk_add_f32 v[204:205], v[204:205], v[206:207]
	v_add_f32_e32 v208, v204, v205
	s_nop 0
	s_nop 0
	v_add_f32_dpp v208, v208, v208 quad_perm:[1,0,3,2] row_mask:0xf bank_mask:0xf
	s_nop 0
	s_nop 0
	v_add_f32_dpp v208, v208, v208 quad_perm:[2,3,0,1] row_mask:0xf bank_mask:0xf
	s_nop 0
	s_nop 0
	v_add_f32_dpp v208, v208, v208 row_half_mirror row_mask:0xf bank_mask:0xf
	s_nop 0
	s_nop 0
	v_add_f32_dpp v208, v208, v208 row_mirror row_mask:0xf bank_mask:0xf
	s_nop 0
	s_nop 0
	v_add_f32_dpp v208, v208, v208 row_bcast:15 row_mask:0xa bank_mask:0xf
	s_nop 0
	s_nop 0
	v_add_f32_dpp v208, v208, v208 row_bcast:31 row_mask:0xc bank_mask:0xf
	s_nop 0
	s_nop 0
	v_readlane_b32 s60, v208, 63
	s_nop 1
	v_mov_b32_e32 v210, s60
	v_fmaak_f32 v210, v210, v212, 0x358637bd
	v_rsq_f32_e32 v210, v210
	s_nop 0
	v_lshlrev_b32_e32 v200, 16, v72
	v_and_b32_e32 v201, 0xffff0000, v72
	v_pk_mul_f32 v[200:201], v[200:201], v[210:211] op_sel_hi:[1,0]
	v_pk_fma_f32 v[56:57], v[8:9], v[200:201], v[56:57]
	v_lshlrev_b32_e32 v202, 16, v73
	v_and_b32_e32 v203, 0xffff0000, v73
	v_pk_mul_f32 v[202:203], v[202:203], v[210:211] op_sel_hi:[1,0]
	v_pk_fma_f32 v[58:59], v[10:11], v[202:203], v[58:59]
	v_lshlrev_b32_e32 v200, 16, v74
	v_and_b32_e32 v201, 0xffff0000, v74
	v_pk_mul_f32 v[200:201], v[200:201], v[210:211] op_sel_hi:[1,0]
	v_pk_fma_f32 v[60:61], v[12:13], v[200:201], v[60:61]
	v_lshlrev_b32_e32 v202, 16, v75
	v_and_b32_e32 v203, 0xffff0000, v75
	v_pk_mul_f32 v[202:203], v[202:203], v[210:211] op_sel_hi:[1,0]
	v_pk_fma_f32 v[62:63], v[14:15], v[202:203], v[62:63]
	v_lshlrev_b32_e32 v200, 16, v76
	v_and_b32_e32 v201, 0xffff0000, v76
	v_pk_mul_f32 v[200:201], v[200:201], v[210:211] op_sel_hi:[1,0]
	v_pk_fma_f32 v[64:65], v[16:17], v[200:201], v[64:65]
	v_lshlrev_b32_e32 v202, 16, v77
	v_and_b32_e32 v203, 0xffff0000, v77
	v_pk_mul_f32 v[202:203], v[202:203], v[210:211] op_sel_hi:[1,0]
	v_pk_fma_f32 v[66:67], v[18:19], v[202:203], v[66:67]
	v_lshlrev_b32_e32 v200, 16, v78
	v_and_b32_e32 v201, 0xffff0000, v78
	v_pk_mul_f32 v[200:201], v[200:201], v[210:211] op_sel_hi:[1,0]
	v_pk_fma_f32 v[68:69], v[20:21], v[200:201], v[68:69]
	v_lshlrev_b32_e32 v202, 16, v79
	v_and_b32_e32 v203, 0xffff0000, v79
	v_pk_mul_f32 v[202:203], v[202:203], v[210:211] op_sel_hi:[1,0]
	v_pk_fma_f32 v[70:71], v[22:23], v[202:203], v[70:71]
	s_add_i32 s81, s80, 3
	s_add_i32 s81, s81, s82
	s_and_b32 s81, s81, 31
	s_lshl_b32 s83, s81, 11
	v_add_u32_e32 v2, s83, v1
	v_cvt_pk_bf16_f32 v72, v56, v57
	v_cvt_pk_bf16_f32 v73, v58, v59
	v_cvt_pk_bf16_f32 v74, v60, v61
	v_cvt_pk_bf16_f32 v75, v62, v63
	v_cvt_pk_bf16_f32 v76, v64, v65
	v_cvt_pk_bf16_f32 v77, v66, v67
	v_cvt_pk_bf16_f32 v78, v68, v69
	v_cvt_pk_bf16_f32 v79, v70, v71
	global_store_dwordx4 v2, v[72:75], s[76:77]
	global_store_dwordx4 v2, v[76:79], s[76:77] offset:1024
	v_pk_mul_f32 v[204:205], v[56:57], v[56:57]
	v_pk_mul_f32 v[206:207], v[58:59], v[58:59]
	v_pk_fma_f32 v[204:205], v[60:61], v[60:61], v[204:205]
	v_pk_fma_f32 v[206:207], v[62:63], v[62:63], v[206:207]
	v_pk_fma_f32 v[204:205], v[64:65], v[64:65], v[204:205]
	v_pk_fma_f32 v[206:207], v[66:67], v[66:67], v[206:207]
	v_pk_fma_f32 v[204:205], v[68:69], v[68:69], v[204:205]
	v_pk_fma_f32 v[206:207], v[70:71], v[70:71], v[206:207]
	v_pk_add_f32 v[204:205], v[204:205], v[206:207]
	v_add_f32_e32 v208, v204, v205
	s_nop 0
	s_nop 0
	v_add_f32_dpp v208, v208, v208 quad_perm:[1,0,3,2] row_mask:0xf bank_mask:0xf
	s_nop 0
	s_nop 0
	v_add_f32_dpp v208, v208, v208 quad_perm:[2,3,0,1] row_mask:0xf bank_mask:0xf
	s_nop 0
	s_nop 0
	v_add_f32_dpp v208, v208, v208 row_half_mirror row_mask:0xf bank_mask:0xf
	s_nop 0
	s_nop 0
	v_add_f32_dpp v208, v208, v208 row_mirror row_mask:0xf bank_mask:0xf
	s_nop 0
	s_nop 0
	v_add_f32_dpp v208, v208, v208 row_bcast:15 row_mask:0xa bank_mask:0xf
	s_nop 0
	s_nop 0
	v_add_f32_dpp v208, v208, v208 row_bcast:31 row_mask:0xc bank_mask:0xf
	s_nop 0
	s_nop 0
	v_readlane_b32 s60, v208, 63
	s_nop 1
	v_mov_b32_e32 v210, s60
	v_fmaak_f32 v210, v210, v212, 0x358637bd
	v_rsq_f32_e32 v210, v210
	s_nop 0
	v_pk_mul_f32 v[200:201], v[56:57], v[210:211] op_sel_hi:[1,0]
	v_pk_fma_f32 v[200:201], v[200:201], v[24:25], v[40:41]
	v_cvt_pk_bf16_f32 v72, v200, v201
	v_pk_mul_f32 v[202:203], v[58:59], v[210:211] op_sel_hi:[1,0]
	v_pk_fma_f32 v[202:203], v[202:203], v[26:27], v[42:43]
	v_cvt_pk_bf16_f32 v73, v202, v203
	v_pk_mul_f32 v[200:201], v[60:61], v[210:211] op_sel_hi:[1,0]
	v_pk_fma_f32 v[200:201], v[200:201], v[28:29], v[44:45]
	v_cvt_pk_bf16_f32 v74, v200, v201
	v_pk_mul_f32 v[202:203], v[62:63], v[210:211] op_sel_hi:[1,0]
	v_pk_fma_f32 v[202:203], v[202:203], v[30:31], v[46:47]
	v_cvt_pk_bf16_f32 v75, v202, v203
	v_pk_mul_f32 v[200:201], v[64:65], v[210:211] op_sel_hi:[1,0]
	v_pk_fma_f32 v[200:201], v[200:201], v[32:33], v[48:49]
	v_cvt_pk_bf16_f32 v76, v200, v201
	v_pk_mul_f32 v[202:203], v[66:67], v[210:211] op_sel_hi:[1,0]
	v_pk_fma_f32 v[202:203], v[202:203], v[34:35], v[50:51]
	v_cvt_pk_bf16_f32 v77, v202, v203
	v_pk_mul_f32 v[200:201], v[68:69], v[210:211] op_sel_hi:[1,0]
	v_pk_fma_f32 v[200:201], v[200:201], v[36:37], v[52:53]
	v_cvt_pk_bf16_f32 v78, v200, v201
	v_pk_mul_f32 v[202:203], v[70:71], v[210:211] op_sel_hi:[1,0]
	v_pk_fma_f32 v[202:203], v[202:203], v[38:39], v[54:55]
	v_cvt_pk_bf16_f32 v79, v202, v203
	global_store_dwordx4 v2, v[72:75], s[78:79]
	global_store_dwordx4 v2, v[76:79], s[78:79] offset:1024
	s_add_i32 s81, s82, 6
	s_cmp_lt_u32 s81, 32
	s_cbranch_scc0 .Lrw_FIRST_l4_d
	s_add_i32 s81, s80, 6
	s_add_i32 s81, s81, s82
	s_and_b32 s81, s81, 31
	s_lshl_b32 s83, s81, 11
	v_add_u32_e32 v2, s83, v1
	s_lshl_b32 s83, s81, 12
	v_add_u32_e32 v213, s83, v3
	global_load_dwordx4 v[128:131], v213, s[72:73]
	global_load_dwordx4 v[132:135], v213, s[72:73] offset:16
	global_load_dwordx4 v[136:139], v213, s[72:73] offset:2048
	global_load_dwordx4 v[140:143], v213, s[72:73] offset:2064
	global_load_dwordx4 v[144:147], v2, s[74:75]
	global_load_dwordx4 v[148:151], v2, s[74:75] offset:1024
	s_branch .Lrw_FIRST_l4_e

; __device__ __forceinline__ void phase_rowwise(const void* xsrc_, bool sbf, void* xdst_, bool dbf, const bf16_t* Y, bf16_t* H, const float* mods, int lprev, int iprev, const float* lnpost, float resw, ...
;     ...
;         for (int rr = 0; rr < 32; rr += 2) {
;             const size_t m = (size_t)ch * 32 + rr;
;             f32x4 x[2][4]; u32x2 yr[2][4];
; #pragma unroll
;             for (int r = 0; r < 2; ++r)
; #pragma unroll
;                 for (int j = 0; j < 4; ++j) { if (sbf) { const u32x2 u = xnb[r][j]; x[r][j] = (f32x4){bflo(u.x), bfhi(u.x), bflo(u.y), bfhi(u.y)}; } else x[r][j] = xn[r][j]; yr[r][j] = yn[r][j]; }
;             if (rr + 2 < 32) {
; #pragma unroll
;                 for (int r = 0; r < 2; ++r)
; #pragma unroll
;                     for (int j = 0; j < 4; ++j) { if (sbf) xnb[r][j] = *(const u32x2*)(xsrcb + (m + 2 + r) * DM + 4 * lane + 256 * j); else xn[r][j] = *(const f32x4*)(xsrc + (m + 2 + r) * DM + 4 * lane + 256 * j); if (hasprev) yn[r][j] = *(const u32x2*)(Y + (m + 2 + r) * DM + 4 * lane + 256 * j); } }
;             if (hasprev) {
;                 f32x4 y[2][4]; float ss[2] = {0.f, 0.f};
; #pragma unroll
;                 for (int r = 0; r < 2; ++r)
; #pragma unroll
;                     for (int j = 0; j < 4; ++j) { const u32x2 u = yr[r][j]; y[r][j] = (f32x4){bflo(u.x), bfhi(u.x), bflo(u.y), bfhi(u.y)};
;                         ss[r] += (y[r][j].x * y[r][j].x + y[r][j].y * y[r][j].y) + (y[r][j].z * y[r][j].z + y[r][j].w * y[r][j].w); }
; #pragma unroll
;                 for (int off = 1; off < 64; off <<= 1) { ss[0] += __shfl_xor(ss[0], off); ss[1] += __shfl_xor(ss[1], off); }
; #pragma unroll
;                 for (int r = 0; r < 2; ++r) { const float rs = __builtin_amdgcn_rsqf(ss[r] * (1.f / DM) + EPS);
; #pragma unroll
;                     for (int j = 0; j < 4; ++j) x[r][j] = x[r][j] + gp[j] * (y[r][j] * rs); }
;             }
; #pragma unroll
;             for (int r = 0; r < 2; ++r)
; #pragma unroll
;                 for (int j = 0; j < 4; ++j) { if (hasprev) { if (dbf) { u32x2 w; w.x = cvtpk(x[r][j].x, x[r][j].y); w.y = cvtpk(x[r][j].z, x[r][j].w); *(u32x2*)(xdstb + (m + r) * DM + 4 * lane + 256 * j) = w; } else *(f32x4*)(xdst + (m + r) * DM + 4 * lane + 256 * j) = x[r][j]; } }
;             if (hasnext) {
;                 float ss[2] = {0.f, 0.f};
; #pragma unroll
;                 for (int r = 0; r < 2; ++r)
.Lrw_FIRST_l4_e:
	s_waitcnt vmcnt(20)
	v_lshlrev_b32_e32 v200, 16, v96
	v_and_b32_e32 v201, 0xffff0000, v96
	v_pk_mul_f32 v[204:205], v[200:201], v[200:201]
	v_lshlrev_b32_e32 v202, 16, v97
	v_and_b32_e32 v203, 0xffff0000, v97
	v_pk_mul_f32 v[206:207], v[202:203], v[202:203]
	v_lshlrev_b32_e32 v200, 16, v98
	v_and_b32_e32 v201, 0xffff0000, v98
	v_pk_fma_f32 v[204:205], v[200:201], v[200:201], v[204:205]
	v_lshlrev_b32_e32 v202, 16, v99
	v_and_b32_e32 v203, 0xffff0000, v99
	v_pk_fma_f32 v[206:207], v[202:203], v[202:203], v[206:207]
	v_lshlrev_b32_e32 v200, 16, v100
	v_and_b32_e32 v201, 0xffff0000, v100
	v_pk_fma_f32 v[204:205], v[200:201], v[200:201], v[204:205]
	v_lshlrev_b32_e32 v202, 16, v101
	v_and_b32_e32 v203, 0xffff0000, v101
	v_pk_fma_f32 v[206:207], v[202:203], v[202:203], v[206:207]
	v_lshlrev_b32_e32 v200, 16, v102
	v_and_b32_e32 v201, 0xffff0000, v102
	v_pk_fma_f32 v[204:205], v[200:201], v[200:201], v[204:205]
	v_lshlrev_b32_e32 v202, 16, v103
	v_and_b32_e32 v203, 0xffff0000, v103
	v_pk_fma_f32 v[206:207], v[202:203], v[202:203], v[206:207]
	v_pk_add_f32 v[204:205], v[204:205], v[206:207]
	v_add_f32_e32 v208, v204, v205
	s_nop 0
	s_nop 0
	v_add_f32_dpp v208, v208, v208 quad_perm:[1,0,3,2] row_mask:0xf bank_mask:0xf
	s_nop 0
	s_nop 0
	v_add_f32_dpp v208, v208, v208 quad_perm:[2,3,0,1] row_mask:0xf bank_mask:0xf
	s_nop 0
	s_nop 0
	v_add_f32_dpp v208, v208, v208 row_half_mirror row_mask:0xf bank_mask:0xf
	s_nop 0
	s_nop 0
	v_add_f32_dpp v208, v208, v208 row_mirror row_mask:0xf bank_mask:0xf
	s_nop 0
	s_nop 0
	v_add_f32_dpp v208, v208, v208 row_bcast:15 row_mask:0xa bank_mask:0xf
	s_nop 0
	s_nop 0
	v_add_f32_dpp v208, v208, v208 row_bcast:31 row_mask:0xc bank_mask:0xf
	s_nop 0
	s_nop 0
	v_readlane_b32 s60, v208, 63
	s_nop 1
	v_mov_b32_e32 v210, s60
	v_fmaak_f32 v210, v210, v212, 0x358637bd
	v_rsq_f32_e32 v210, v210
	s_nop 0
	v_lshlrev_b32_e32 v200, 16, v96
	v_and_b32_e32 v201, 0xffff0000, v96
	v_pk_mul_f32 v[200:201], v[200:201], v[210:211] op_sel_hi:[1,0]
	v_pk_fma_f32 v[80:81], v[8:9], v[200:201], v[80:81]
	v_lshlrev_b32_e32 v202, 16, v97
	v_and_b32_e32 v203, 0xffff0000, v97
	v_pk_mul_f32 v[202:203], v[202:203], v[210:211] op_sel_hi:[1,0]
	v_pk_fma_f32 v[82:83], v[10:11], v[202:203], v[82:83]
	v_lshlrev_b32_e32 v200, 16, v98
	v_and_b32_e32 v201, 0xffff0000, v98
	v_pk_mul_f32 v[200:201], v[200:201], v[210:211] op_sel_hi:[1,0]
	v_pk_fma_f32 v[84:85], v[12:13], v[200:201], v[84:85]
	v_lshlrev_b32_e32 v202, 16, v99
	v_and_b32_e32 v203, 0xffff0000, v99
	v_pk_mul_f32 v[202:203], v[202:203], v[210:211] op_sel_hi:[1,0]
	v_pk_fma_f32 v[86:87], v[14:15], v[202:203], v[86:87]
	v_lshlrev_b32_e32 v200, 16, v100
	v_and_b32_e32 v201, 0xffff0000, v100
	v_pk_mul_f32 v[200:201], v[200:201], v[210:211] op_sel_hi:[1,0]
	v_pk_fma_f32 v[88:89], v[16:17], v[200:201], v[88:89]
	v_lshlrev_b32_e32 v202, 16, v101
	v_and_b32_e32 v203, 0xffff0000, v101
	v_pk_mul_f32 v[202:203], v[202:203], v[210:211] op_sel_hi:[1,0]
	v_pk_fma_f32 v[90:91], v[18:19], v[202:203], v[90:91]
	v_lshlrev_b32_e32 v200, 16, v102
	v_and_b32_e32 v201, 0xffff0000, v102
	v_pk_mul_f32 v[200:201], v[200:201], v[210:211] op_sel_hi:[1,0]
	v_pk_fma_f32 v[92:93], v[20:21], v[200:201], v[92:93]
	v_lshlrev_b32_e32 v202, 16, v103
	v_and_b32_e32 v203, 0xffff0000, v103
	v_pk_mul_f32 v[202:203], v[202:203], v[210:211] op_sel_hi:[1,0]
	v_pk_fma_f32 v[94:95], v[22:23], v[202:203], v[94:95]
	s_add_i32 s81, s80, 4
	s_add_i32 s81, s81, s82
	s_and_b32 s81, s81, 31
	s_lshl_b32 s83, s81, 11
	v_add_u32_e32 v2, s83, v1
	v_cvt_pk_bf16_f32 v96, v80, v81
	v_cvt_pk_bf16_f32 v97, v82, v83
	v_cvt_pk_bf16_f32 v98, v84, v85
	v_cvt_pk_bf16_f32 v99, v86, v87
	v_cvt_pk_bf16_f32 v100, v88, v89
	v_cvt_pk_bf16_f32 v101, v90, v91
	v_cvt_pk_bf16_f32 v102, v92, v93
	v_cvt_pk_bf16_f32 v103, v94, v95
	global_store_dwordx4 v2, v[96:99], s[76:77]
	global_store_dwordx4 v2, v[100:103], s[76:77] offset:1024
	v_pk_mul_f32 v[204:205], v[80:81], v[80:81]
	v_pk_mul_f32 v[206:207], v[82:83], v[82:83]
	v_pk_fma_f32 v[204:205], v[84:85], v[84:85], v[204:205]
	v_pk_fma_f32 v[206:207], v[86:87], v[86:87], v[206:207]
	v_pk_fma_f32 v[204:205], v[88:89], v[88:89], v[204:205]
	v_pk_fma_f32 v[206:207], v[90:91], v[90:91], v[206:207]
	v_pk_fma_f32 v[204:205], v[92:93], v[92:93], v[204:205]
	v_pk_fma_f32 v[206:207], v[94:95], v[94:95], v[206:207]
	v_pk_add_f32 v[204:205], v[204:205], v[206:207]
	v_add_f32_e32 v208, v204, v205
	s_nop 0
	s_nop 0
	v_add_f32_dpp v208, v208, v208 quad_perm:[1,0,3,2] row_mask:0xf bank_mask:0xf
	s_nop 0
	s_nop 0
	v_add_f32_dpp v208, v208, v208 quad_perm:[2,3,0,1] row_mask:0xf bank_mask:0xf
	s_nop 0
	s_nop 0
	v_add_f32_dpp v208, v208, v208 row_half_mirror row_mask:0xf bank_mask:0xf
	s_nop 0
	s_nop 0
	v_add_f32_dpp v208, v208, v208 row_mirror row_mask:0xf bank_mask:0xf
	s_nop 0
	s_nop 0
	v_add_f32_dpp v208, v208, v208 row_bcast:15 row_mask:0xa bank_mask:0xf
	s_nop 0
	s_nop 0
	v_add_f32_dpp v208, v208, v208 row_bcast:31 row_mask:0xc bank_mask:0xf
	s_nop 0
	s_nop 0
	v_readlane_b32 s60, v208, 63
	s_nop 1
	v_mov_b32_e32 v210, s60
	v_fmaak_f32 v210, v210, v212, 0x358637bd
	v_rsq_f32_e32 v210, v210
	s_nop 0
	v_pk_mul_f32 v[200:201], v[80:81], v[210:211] op_sel_hi:[1,0]
	v_pk_fma_f32 v[200:201], v[200:201], v[24:25], v[40:41]
	v_cvt_pk_bf16_f32 v96, v200, v201
	v_pk_mul_f32 v[202:203], v[82:83], v[210:211] op_sel_hi:[1,0]
	v_pk_fma_f32 v[202:203], v[202:203], v[26:27], v[42:43]
	v_cvt_pk_bf16_f32 v97, v202, v203
	v_pk_mul_f32 v[200:201], v[84:85], v[210:211] op_sel_hi:[1,0]
	v_pk_fma_f32 v[200:201], v[200:201], v[28:29], v[44:45]
	v_cvt_pk_bf16_f32 v98, v200, v201
	v_pk_mul_f32 v[202:203], v[86:87], v[210:211] op_sel_hi:[1,0]
	v_pk_fma_f32 v[202:203], v[202:203], v[30:31], v[46:47]
	v_cvt_pk_bf16_f32 v99, v202, v203
	v_pk_mul_f32 v[200:201], v[88:89], v[210:211] op_sel_hi:[1,0]
	v_pk_fma_f32 v[200:201], v[200:201], v[32:33], v[48:49]
	v_cvt_pk_bf16_f32 v100, v200, v201
	v_pk_mul_f32 v[202:203], v[90:91], v[210:211] op_sel_hi:[1,0]
	v_pk_fma_f32 v[202:203], v[202:203], v[34:35], v[50:51]
	v_cvt_pk_bf16_f32 v101, v202, v203
	v_pk_mul_f32 v[200:201], v[92:93], v[210:211] op_sel_hi:[1,0]
	v_pk_fma_f32 v[200:201], v[200:201], v[36:37], v[52:53]
	v_cvt_pk_bf16_f32 v102, v200, v201
	v_pk_mul_f32 v[202:203], v[94:95], v[210:211] op_sel_hi:[1,0]
	v_pk_fma_f32 v[202:203], v[202:203], v[38:39], v[54:55]
	v_cvt_pk_bf16_f32 v103, v202, v203
	global_store_dwordx4 v2, v[96:99], s[78:79]
	global_store_dwordx4 v2, v[100:103], s[78:79] offset:1024
	s_add_i32 s82, s82, 5
	s_cmp_lt_u32 s82, 32
	s_cbranch_scc1 .Lrw_FIRST_loop
	s_branch .LBB0_1024
; __device__ __forceinline__ void phase_rowwise(const void* xsrc_, bool sbf, void* xdst_, bool dbf, const bf16_t* Y, bf16_t* H, const float* mods, int lprev, int iprev, const float* lnpost, float resw, ...
;     ...
;     const int lane = tid_ & 63, wid = __builtin_amdgcn_readfirstlane(tid_ >> 6), gw = blockIdx.x * 8 + wid, NGW = gridDim.x * 8;
;     const float* xsrc = (const float*)xsrc_; const bf16_t* xsrcb = (const bf16_t*)xsrc_; float* xdst = (float*)xdst_; bf16_t* xdstb = (bf16_t*)xdst_;
;     for (int ch = gw; ch < M / 32; ch += NGW) {
;         const int b = ch >> 6;
;         f32x4 gp[4], na[4], ns[4];
; #pragma unroll
;         for (int j = 0; j < 4; ++j) { const int c = 4 * lane + 256 * j;
;             if (hasprev) { const f32x4 g = *(const f32x4*)(mods + ((size_t)lprev * 32 + b) * 9216 + iprev * 3072 + 2048 + c); const f32x4 lp = *(const f32x4*)(lnpost + c); gp[j] = g * lp * resw; }
;             else gp[j] = (f32x4){0.f, 0.f, 0.f, 0.f};
;             if (hasnext) { const f32x4 sh = *(const f32x4*)(mods + ((size_t)lnext * 32 + b) * 9216 + inext * 3072 + c); const f32x4 scl = *(const f32x4*)(mods + ((size_t)lnext * 32 + b) * 9216 + inext * 3072 + 1024 + c);
;                 const f32x4 lp = *(const f32x4*)(lnpre + c); na[j] = lp * (scl + 1.0f); ns[j] = sh; }
;             else { na[j] = (f32x4){0.f, 0.f, 0.f, 0.f}; ns[j] = na[j]; } }
;         f32x4 xn[2][4]; u32x2 xnb[2][4]; u32x2 yn[2][4];
;         { const size_t m0 = (size_t)ch * 32;
; #pragma unroll
;           for (int r = 0; r < 2; ++r)
; #pragma unroll
;             for (int j = 0; j < 4; ++j) { if (sbf) { xnb[r][j] = *(const u32x2*)(xsrcb + (m0 + r) * DM + 4 * lane + 256 * j); xn[r][j] = (f32x4){0.f, 0.f, 0.f, 0.f}; } else { xn[r][j] = *(const f32x4*)(xsrc + (m0 + r) * DM + 4 * lane + 256 * j); xnb[r][j] = (u32x2){0u, 0u}; }
;                 yn[r][j] = hasprev ? *(const u32x2*)(Y + (m0 + r) * DM + 4 * lane + 256 * j) : (u32x2){0u, 0u}; } }
;     ...
;             if (hasprev) {
;                 f32x4 y[2][4]; float ss[2] = {0.f, 0.f};
; #pragma unroll
;                 for (int r = 0; r < 2; ++r)
; #pragma unroll
;                     for (int j = 0; j < 4; ++j) { const u32x2 u = yr[r][j]; y[r][j] = (f32x4){bflo(u.x), bfhi(u.x), bflo(u.y), bfhi(u.y)};
;                         ss[r] += (y[r][j].x * y[r][j].x + y[r][j].y * y[r][j].y) + (y[r][j].z * y[r][j].z + y[r][j].w * y[r][j].w); }
; #pragma unroll
.Lrw_LAST:
	v_readfirstlane_b32 s40, v214
	v_readlane_b32 s41, v254, 46
	s_lshr_b32 s40, s40, 6
	s_add_i32 s40, s40, s41
	s_lshr_b32 s41, s40, 6
	v_and_b32_e32 v1, 63, v214
	v_lshlrev_b32_e32 v3, 5, v1
	v_lshlrev_b32_e32 v1, 4, v1
	v_mov_b32_e32 v212, 0x3a800000
	s_cmp_eq_u32 s74, 2
	s_cselect_b32 s42, 1, 0
	s_add_i32 s42, s73, s42
	s_add_i32 s43, s74, 1
	s_cmp_eq_u32 s74, 2
	s_cselect_b32 s43, 0, s43
	s_cmp_eq_u32 s74, 1
	s_cselect_b32 s90, 1.0, 0.5
	s_mov_b32 s91, s90
	v_readlane_b32 s44, v255, 22
	v_readlane_b32 s45, v255, 23
	s_lshl_b32 s46, s73, 5
	s_add_i32 s46, s46, s41
	s_mul_i32 s46, s46, 0x9000
	s_mul_i32 s47, s74, 0x3000
	s_add_i32 s46, s46, s47
	s_add_i32 s46, s46, 0x2000
	s_add_u32 s48, s44, s46
	s_addc_u32 s49, s45, 0
	v_readlane_b32 s52, v255, 16
	v_readlane_b32 s53, v255, 17
	s_mul_i32 s46, s73, 3
	s_add_i32 s46, s46, s74
	s_lshl_b32 s46, s46, 12
	s_add_u32 s52, s52, s46
	s_addc_u32 s53, s53, 0
	global_load_dwordx4 v[8:11], v3, s[48:49]
	global_load_dwordx4 v[12:15], v3, s[48:49] offset:16
	global_load_dwordx4 v[16:19], v3, s[48:49] offset:2048
	global_load_dwordx4 v[20:23], v3, s[48:49] offset:2064
	global_load_dwordx4 v[56:59], v3, s[52:53]
	global_load_dwordx4 v[60:63], v3, s[52:53] offset:16
	global_load_dwordx4 v[64:67], v3, s[52:53] offset:2048
	global_load_dwordx4 v[68:71], v3, s[52:53] offset:2064
	s_lshl_b32 s46, s40, 16
	s_lshl_b32 s47, s40, 17
	v_readlane_b32 s72, v252, 26
	v_readlane_b32 s73, v252, 27
	s_add_u32 s72, s72, s46
	s_addc_u32 s73, s73, 0
	v_readlane_b32 s74, v252, 22
	v_readlane_b32 s75, v252, 23
	s_add_u32 s74, s74, s46
	s_addc_u32 s75, s75, 0
	v_readlane_b32 s76, v252, 6
	v_readlane_b32 s77, v252, 7
	s_add_u32 s76, s76, s47
	s_addc_u32 s77, s77, 0
	s_and_b32 s80, s40, 15
	s_lshl_b32 s80, s80, 1
	s_waitcnt vmcnt(0)
	v_pk_mul_f32 v[8:9], v[8:9], v[56:57]
	v_pk_mul_f32 v[10:11], v[10:11], v[58:59]
	v_pk_mul_f32 v[12:13], v[12:13], v[60:61]
	v_pk_mul_f32 v[14:15], v[14:15], v[62:63]
	v_pk_mul_f32 v[16:17], v[16:17], v[64:65]
	v_pk_mul_f32 v[18:19], v[18:19], v[66:67]
	v_pk_mul_f32 v[20:21], v[20:21], v[68:69]
	v_pk_mul_f32 v[22:23], v[22:23], v[70:71]
	v_pk_mul_f32 v[8:9], v[8:9], s[90:91]
	v_pk_mul_f32 v[10:11], v[10:11], s[90:91]
	v_pk_mul_f32 v[12:13], v[12:13], s[90:91]
	v_pk_mul_f32 v[14:15], v[14:15], s[90:91]
	v_pk_mul_f32 v[16:17], v[16:17], s[90:91]
	v_pk_mul_f32 v[18:19], v[18:19], s[90:91]
	v_pk_mul_f32 v[20:21], v[20:21], s[90:91]
	v_pk_mul_f32 v[22:23], v[22:23], s[90:91]
	s_waitcnt vmcnt(0)
	s_mov_b32 s82, 0
	s_add_i32 s81, s80, 0
	s_add_i32 s81, s81, s82
	s_and_b32 s81, s81, 31
	s_lshl_b32 s83, s81, 11
	v_add_u32_e32 v2, s83, v1
	global_load_dwordx4 v[56:59], v2, s[72:73]
	global_load_dwordx4 v[60:63], v2, s[72:73] offset:1024
	global_load_dwordx4 v[64:67], v2, s[74:75]
	global_load_dwordx4 v[68:71], v2, s[74:75] offset:1024
	s_add_i32 s81, s80, 1
	s_add_i32 s81, s81, s82
	s_and_b32 s81, s81, 31
	s_lshl_b32 s83, s81, 11
	v_add_u32_e32 v2, s83, v1
	global_load_dwordx4 v[72:75], v2, s[72:73]
	global_load_dwordx4 v[76:79], v2, s[72:73] offset:1024
	global_load_dwordx4 v[80:83], v2, s[74:75]
	global_load_dwordx4 v[84:87], v2, s[74:75] offset:1024
	s_add_i32 s81, s80, 2
	s_add_i32 s81, s81, s82
	s_and_b32 s81, s81, 31
	s_lshl_b32 s83, s81, 11
	v_add_u32_e32 v2, s83, v1
	global_load_dwordx4 v[88:91], v2, s[72:73]
	global_load_dwordx4 v[92:95], v2, s[72:73] offset:1024
	global_load_dwordx4 v[96:99], v2, s[74:75]
	global_load_dwordx4 v[100:103], v2, s[74:75] offset:1024
	s_add_i32 s81, s80, 3
	s_add_i32 s81, s81, s82
	s_and_b32 s81, s81, 31
	s_lshl_b32 s83, s81, 11
	v_add_u32_e32 v2, s83, v1
	global_load_dwordx4 v[104:107], v2, s[72:73]
	global_load_dwordx4 v[108:111], v2, s[72:73] offset:1024
	global_load_dwordx4 v[112:115], v2, s[74:75]
	global_load_dwordx4 v[116:119], v2, s[74:75] offset:1024
	s_add_i32 s81, s80, 4
	s_add_i32 s81, s81, s82
	s_and_b32 s81, s81, 31
	s_lshl_b32 s83, s81, 11
	v_add_u32_e32 v2, s83, v1
	global_load_dwordx4 v[120:123], v2, s[72:73]
	global_load_dwordx4 v[124:127], v2, s[72:73] offset:1024
	global_load_dwordx4 v[128:131], v2, s[74:75]
	global_load_dwordx4 v[132:135], v2, s[74:75] offset:1024
	s_waitcnt vmcnt(16)
	v_lshlrev_b32_e32 v200, 16, v64
	v_and_b32_e32 v201, 0xffff0000, v64
	v_pk_mul_f32 v[204:205], v[200:201], v[200:201]
	v_lshlrev_b32_e32 v202, 16, v65
	v_and_b32_e32 v203, 0xffff0000, v65
	v_pk_mul_f32 v[206:207], v[202:203], v[202:203]
	v_lshlrev_b32_e32 v200, 16, v66
	v_and_b32_e32 v201, 0xffff0000, v66
	v_pk_fma_f32 v[204:205], v[200:201], v[200:201], v[204:205]
	v_lshlrev_b32_e32 v202, 16, v67
	v_and_b32_e32 v203, 0xffff0000, v67
	v_pk_fma_f32 v[206:207], v[202:203], v[202:203], v[206:207]
	v_lshlrev_b32_e32 v200, 16, v68
	v_and_b32_e32 v201, 0xffff0000, v68
	v_pk_fma_f32 v[204:205], v[200:201], v[200:201], v[204:205]
	v_lshlrev_b32_e32 v202, 16, v69
	v_and_b32_e32 v203, 0xffff0000, v69
	v_pk_fma_f32 v[206:207], v[202:203], v[202:203], v[206:207]
	v_lshlrev_b32_e32 v200, 16, v70
	v_and_b32_e32 v201, 0xffff0000, v70
	v_pk_fma_f32 v[204:205], v[200:201], v[200:201], v[204:205]
	v_lshlrev_b32_e32 v202, 16, v71
	v_and_b32_e32 v203, 0xffff0000, v71
	v_pk_fma_f32 v[206:207], v[202:203], v[202:203], v[206:207]
	v_pk_add_f32 v[204:205], v[204:205], v[206:207]
	v_add_f32_e32 v208, v204, v205
	v_lshlrev_b32_e32 v184, 16, v56
	v_and_b32_e32 v185, 0xffff0000, v56
	v_add_f32_dpp v208, v208, v208 quad_perm:[1,0,3,2] row_mask:0xf bank_mask:0xf
	v_lshlrev_b32_e32 v186, 16, v57
	v_and_b32_e32 v187, 0xffff0000, v57
	v_add_f32_dpp v208, v208, v208 quad_perm:[2,3,0,1] row_mask:0xf bank_mask:0xf
	v_lshlrev_b32_e32 v188, 16, v58
	v_and_b32_e32 v189, 0xffff0000, v58
; __device__ __forceinline__ unsigned cvtpk(float lo, float hi) { f32x2 v = {lo, hi}; bf16x2_t b = __builtin_convertvector(v, bf16x2_t); return __builtin_bit_cast(unsigned, b); }
; __device__ __forceinline__ float bflo(unsigned u) { return __uint_as_float(u << 16); }
; __device__ __forceinline__ float bfhi(unsigned u) { return __uint_as_float(u & 0xffff0000u); }
; __device__ __forceinline__ void phase_rowwise(const void* xsrc_, bool sbf, void* xdst_, bool dbf, const bf16_t* Y, bf16_t* H, const float* mods, int lprev, int iprev, const float* lnpost, float resw, ...
;     ...
;             if (hasprev) {
;                 f32x4 y[2][4]; float ss[2] = {0.f, 0.f};
; #pragma unroll
;                 for (int r = 0; r < 2; ++r)
; #pragma unroll
;                     for (int j = 0; j < 4; ++j) { const u32x2 u = yr[r][j]; y[r][j] = (f32x4){bflo(u.x), bfhi(u.x), bflo(u.y), bfhi(u.y)};
;                         ss[r] += (y[r][j].x * y[r][j].x + y[r][j].y * y[r][j].y) + (y[r][j].z * y[r][j].z + y[r][j].w * y[r][j].w); }
; #pragma unroll
;                 for (int off = 1; off < 64; off <<= 1) { ss[0] += __shfl_xor(ss[0], off); ss[1] += __shfl_xor(ss[1], off); }
; #pragma unroll
;                 for (int r = 0; r < 2; ++r) { const float rs = __builtin_amdgcn_rsqf(ss[r] * (1.f / DM) + EPS);
; #pragma unroll
;                     for (int j = 0; j < 4; ++j) x[r][j] = x[r][j] + gp[j] * (y[r][j] * rs); }
;             }
; #pragma unroll
;             for (int r = 0; r < 2; ++r)
; #pragma unroll
;                 for (int j = 0; j < 4; ++j) { if (hasprev) { if (dbf) { u32x2 w; w.x = cvtpk(x[r][j].x, x[r][j].y); w.y = cvtpk(x[r][j].z, x[r][j].w); *(u32x2*)(xdstb + (m + r) * DM + 4 * lane + 256 * j) = w; } else *(f32x4*)(xdst + (m + r) * DM + 4 * lane + 256 * j) = x[r][j]; } }
	v_add_f32_dpp v208, v208, v208 row_half_mirror row_mask:0xf bank_mask:0xf
	v_lshlrev_b32_e32 v190, 16, v59
	v_and_b32_e32 v191, 0xffff0000, v59
	v_add_f32_dpp v208, v208, v208 row_mirror row_mask:0xf bank_mask:0xf
	v_lshlrev_b32_e32 v192, 16, v60
	v_and_b32_e32 v193, 0xffff0000, v60
	v_add_f32_dpp v208, v208, v208 row_bcast:15 row_mask:0xa bank_mask:0xf
	v_lshlrev_b32_e32 v194, 16, v61
	v_and_b32_e32 v195, 0xffff0000, v61
	v_add_f32_dpp v208, v208, v208 row_bcast:31 row_mask:0xc bank_mask:0xf
	v_lshlrev_b32_e32 v196, 16, v62
	v_and_b32_e32 v197, 0xffff0000, v62
	v_readlane_b32 s60, v208, 63
	s_nop 1
	v_lshlrev_b32_e32 v198, 16, v63
	v_and_b32_e32 v199, 0xffff0000, v63
	v_mov_b32_e32 v210, s60
	v_fmaak_f32 v210, v210, v212, 0x358637bd
	v_rsq_f32_e32 v210, v210
	s_nop 0
	v_lshlrev_b32_e32 v200, 16, v64
	v_and_b32_e32 v201, 0xffff0000, v64
	v_pk_mul_f32 v[200:201], v[200:201], v[210:211] op_sel_hi:[1,0]
	v_pk_fma_f32 v[184:185], v[8:9], v[200:201], v[184:185]
	v_lshlrev_b32_e32 v202, 16, v65
	v_and_b32_e32 v203, 0xffff0000, v65
	v_pk_mul_f32 v[202:203], v[202:203], v[210:211] op_sel_hi:[1,0]
	v_pk_fma_f32 v[186:187], v[10:11], v[202:203], v[186:187]
	v_lshlrev_b32_e32 v200, 16, v66
	v_and_b32_e32 v201, 0xffff0000, v66
	v_pk_mul_f32 v[200:201], v[200:201], v[210:211] op_sel_hi:[1,0]
	v_pk_fma_f32 v[188:189], v[12:13], v[200:201], v[188:189]
	v_lshlrev_b32_e32 v202, 16, v67
	v_and_b32_e32 v203, 0xffff0000, v67
	v_pk_mul_f32 v[202:203], v[202:203], v[210:211] op_sel_hi:[1,0]
	v_pk_fma_f32 v[190:191], v[14:15], v[202:203], v[190:191]
	v_lshlrev_b32_e32 v200, 16, v68
	v_and_b32_e32 v201, 0xffff0000, v68
	v_pk_mul_f32 v[200:201], v[200:201], v[210:211] op_sel_hi:[1,0]
	v_pk_fma_f32 v[192:193], v[16:17], v[200:201], v[192:193]
	v_lshlrev_b32_e32 v202, 16, v69
	v_and_b32_e32 v203, 0xffff0000, v69
	v_pk_mul_f32 v[202:203], v[202:203], v[210:211] op_sel_hi:[1,0]
	v_pk_fma_f32 v[194:195], v[18:19], v[202:203], v[194:195]
	v_lshlrev_b32_e32 v200, 16, v70
	v_and_b32_e32 v201, 0xffff0000, v70
	v_pk_mul_f32 v[200:201], v[200:201], v[210:211] op_sel_hi:[1,0]
	v_pk_fma_f32 v[196:197], v[20:21], v[200:201], v[196:197]
	v_lshlrev_b32_e32 v202, 16, v71
	v_and_b32_e32 v203, 0xffff0000, v71
	v_pk_mul_f32 v[202:203], v[202:203], v[210:211] op_sel_hi:[1,0]
	v_pk_fma_f32 v[198:199], v[22:23], v[202:203], v[198:199]
	s_add_i32 s81, s80, 0
	s_add_i32 s81, s81, s82
	s_and_b32 s81, s81, 31
	s_lshl_b32 s83, s81, 12
	v_add_u32_e32 v213, s83, v3
	global_store_dwordx4 v213, v[184:187], s[76:77]
	global_store_dwordx4 v213, v[188:191], s[76:77] offset:16
	global_store_dwordx4 v213, v[192:195], s[76:77] offset:2048
	global_store_dwordx4 v213, v[196:199], s[76:77] offset:2064
	s_add_i32 s81, s80, 5
	s_add_i32 s81, s81, s82
	s_and_b32 s81, s81, 31
	s_lshl_b32 s83, s81, 11
	v_add_u32_e32 v2, s83, v1
	global_load_dwordx4 v[136:139], v2, s[72:73]
	global_load_dwordx4 v[140:143], v2, s[72:73] offset:1024
	global_load_dwordx4 v[144:147], v2, s[74:75]
	global_load_dwordx4 v[148:151], v2, s[74:75] offset:1024
	s_waitcnt vmcnt(20)
	v_lshlrev_b32_e32 v200, 16, v80
	v_and_b32_e32 v201, 0xffff0000, v80
	v_pk_mul_f32 v[204:205], v[200:201], v[200:201]
	v_lshlrev_b32_e32 v202, 16, v81
	v_and_b32_e32 v203, 0xffff0000, v81
	v_pk_mul_f32 v[206:207], v[202:203], v[202:203]
	v_lshlrev_b32_e32 v200, 16, v82
	v_and_b32_e32 v201, 0xffff0000, v82
	v_pk_fma_f32 v[204:205], v[200:201], v[200:201], v[204:205]
	v_lshlrev_b32_e32 v202, 16, v83
	v_and_b32_e32 v203, 0xffff0000, v83
	v_pk_fma_f32 v[206:207], v[202:203], v[202:203], v[206:207]
	v_lshlrev_b32_e32 v200, 16, v84
	v_and_b32_e32 v201, 0xffff0000, v84
	v_pk_fma_f32 v[204:205], v[200:201], v[200:201], v[204:205]
	v_lshlrev_b32_e32 v202, 16, v85
	v_and_b32_e32 v203, 0xffff0000, v85
	v_pk_fma_f32 v[206:207], v[202:203], v[202:203], v[206:207]
	v_lshlrev_b32_e32 v200, 16, v86
	v_and_b32_e32 v201, 0xffff0000, v86
	v_pk_fma_f32 v[204:205], v[200:201], v[200:201], v[204:205]
	v_lshlrev_b32_e32 v202, 16, v87
	v_and_b32_e32 v203, 0xffff0000, v87
	v_pk_fma_f32 v[206:207], v[202:203], v[202:203], v[206:207]
	v_pk_add_f32 v[204:205], v[204:205], v[206:207]
	v_add_f32_e32 v208, v204, v205
	v_lshlrev_b32_e32 v184, 16, v72
	v_and_b32_e32 v185, 0xffff0000, v72
	v_add_f32_dpp v208, v208, v208 quad_perm:[1,0,3,2] row_mask:0xf bank_mask:0xf
	v_lshlrev_b32_e32 v186, 16, v73
	v_and_b32_e32 v187, 0xffff0000, v73
	v_add_f32_dpp v208, v208, v208 quad_perm:[2,3,0,1] row_mask:0xf bank_mask:0xf
	v_lshlrev_b32_e32 v188, 16, v74
	v_and_b32_e32 v189, 0xffff0000, v74
	v_add_f32_dpp v208, v208, v208 row_half_mirror row_mask:0xf bank_mask:0xf
	v_lshlrev_b32_e32 v190, 16, v75
	v_and_b32_e32 v191, 0xffff0000, v75
	v_add_f32_dpp v208, v208, v208 row_mirror row_mask:0xf bank_mask:0xf
	v_lshlrev_b32_e32 v192, 16, v76
	v_and_b32_e32 v193, 0xffff0000, v76
	v_add_f32_dpp v208, v208, v208 row_bcast:15 row_mask:0xa bank_mask:0xf
	v_lshlrev_b32_e32 v194, 16, v77
	v_and_b32_e32 v195, 0xffff0000, v77
	v_add_f32_dpp v208, v208, v208 row_bcast:31 row_mask:0xc bank_mask:0xf
	v_lshlrev_b32_e32 v196, 16, v78
	v_and_b32_e32 v197, 0xffff0000, v78
	v_readlane_b32 s60, v208, 63
	s_nop 1
	v_lshlrev_b32_e32 v198, 16, v79
	v_and_b32_e32 v199, 0xffff0000, v79
	v_mov_b32_e32 v210, s60
	v_fmaak_f32 v210, v210, v212, 0x358637bd
	v_rsq_f32_e32 v210, v210
	s_nop 0
	v_lshlrev_b32_e32 v200, 16, v80
	v_and_b32_e32 v201, 0xffff0000, v80
	v_pk_mul_f32 v[200:201], v[200:201], v[210:211] op_sel_hi:[1,0]
	v_pk_fma_f32 v[184:185], v[8:9], v[200:201], v[184:185]
	v_lshlrev_b32_e32 v202, 16, v81
	v_and_b32_e32 v203, 0xffff0000, v81
	v_pk_mul_f32 v[202:203], v[202:203], v[210:211] op_sel_hi:[1,0]
; __device__ __forceinline__ unsigned cvtpk(float lo, float hi) { f32x2 v = {lo, hi}; bf16x2_t b = __builtin_convertvector(v, bf16x2_t); return __builtin_bit_cast(unsigned, b); }
; __device__ __forceinline__ float bflo(unsigned u) { return __uint_as_float(u << 16); }
; __device__ __forceinline__ float bfhi(unsigned u) { return __uint_as_float(u & 0xffff0000u); }
; __device__ __forceinline__ void phase_rowwise(const void* xsrc_, bool sbf, void* xdst_, bool dbf, const bf16_t* Y, bf16_t* H, const float* mods, int lprev, int iprev, const float* lnpost, float resw, ...
;     ...
;             if (hasprev) {
;                 f32x4 y[2][4]; float ss[2] = {0.f, 0.f};
; #pragma unroll
;                 for (int r = 0; r < 2; ++r)
; #pragma unroll
;                     for (int j = 0; j < 4; ++j) { const u32x2 u = yr[r][j]; y[r][j] = (f32x4){bflo(u.x), bfhi(u.x), bflo(u.y), bfhi(u.y)};
;                         ss[r] += (y[r][j].x * y[r][j].x + y[r][j].y * y[r][j].y) + (y[r][j].z * y[r][j].z + y[r][j].w * y[r][j].w); }
; #pragma unroll
;                 for (int off = 1; off < 64; off <<= 1) { ss[0] += __shfl_xor(ss[0], off); ss[1] += __shfl_xor(ss[1], off); }
; #pragma unroll
;                 for (int r = 0; r < 2; ++r) { const float rs = __builtin_amdgcn_rsqf(ss[r] * (1.f / DM) + EPS);
; #pragma unroll
;                     for (int j = 0; j < 4; ++j) x[r][j] = x[r][j] + gp[j] * (y[r][j] * rs); }
;             }
; #pragma unroll
;             for (int r = 0; r < 2; ++r)
; #pragma unroll
;                 for (int j = 0; j < 4; ++j) { if (hasprev) { if (dbf) { u32x2 w; w.x = cvtpk(x[r][j].x, x[r][j].y); w.y = cvtpk(x[r][j].z, x[r][j].w); *(u32x2*)(xdstb + (m + r) * DM + 4 * lane + 256 * j) = w; } else *(f32x4*)(xdst + (m + r) * DM + 4 * lane + 256 * j) = x[r][j]; } }
	v_pk_fma_f32 v[186:187], v[10:11], v[202:203], v[186:187]
	v_lshlrev_b32_e32 v200, 16, v82
	v_and_b32_e32 v201, 0xffff0000, v82
	v_pk_mul_f32 v[200:201], v[200:201], v[210:211] op_sel_hi:[1,0]
	v_pk_fma_f32 v[188:189], v[12:13], v[200:201], v[188:189]
	v_lshlrev_b32_e32 v202, 16, v83
	v_and_b32_e32 v203, 0xffff0000, v83
	v_pk_mul_f32 v[202:203], v[202:203], v[210:211] op_sel_hi:[1,0]
	v_pk_fma_f32 v[190:191], v[14:15], v[202:203], v[190:191]
	v_lshlrev_b32_e32 v200, 16, v84
	v_and_b32_e32 v201, 0xffff0000, v84
	v_pk_mul_f32 v[200:201], v[200:201], v[210:211] op_sel_hi:[1,0]
	v_pk_fma_f32 v[192:193], v[16:17], v[200:201], v[192:193]
	v_lshlrev_b32_e32 v202, 16, v85
	v_and_b32_e32 v203, 0xffff0000, v85
	v_pk_mul_f32 v[202:203], v[202:203], v[210:211] op_sel_hi:[1,0]
	v_pk_fma_f32 v[194:195], v[18:19], v[202:203], v[194:195]
	v_lshlrev_b32_e32 v200, 16, v86
	v_and_b32_e32 v201, 0xffff0000, v86
	v_pk_mul_f32 v[200:201], v[200:201], v[210:211] op_sel_hi:[1,0]
	v_pk_fma_f32 v[196:197], v[20:21], v[200:201], v[196:197]
	v_lshlrev_b32_e32 v202, 16, v87
	v_and_b32_e32 v203, 0xffff0000, v87
	v_pk_mul_f32 v[202:203], v[202:203], v[210:211] op_sel_hi:[1,0]
	v_pk_fma_f32 v[198:199], v[22:23], v[202:203], v[198:199]
	s_add_i32 s81, s80, 1
	s_add_i32 s81, s81, s82
	s_and_b32 s81, s81, 31
	s_lshl_b32 s83, s81, 12
	v_add_u32_e32 v213, s83, v3
	global_store_dwordx4 v213, v[184:187], s[76:77]
	global_store_dwordx4 v213, v[188:191], s[76:77] offset:16
	global_store_dwordx4 v213, v[192:195], s[76:77] offset:2048
	global_store_dwordx4 v213, v[196:199], s[76:77] offset:2064
	s_add_i32 s81, s80, 6
	s_add_i32 s81, s81, s82
	s_and_b32 s81, s81, 31
	s_lshl_b32 s83, s81, 11
	v_add_u32_e32 v2, s83, v1
	global_load_dwordx4 v[152:155], v2, s[72:73]
	global_load_dwordx4 v[156:159], v2, s[72:73] offset:1024
	global_load_dwordx4 v[160:163], v2, s[74:75]
	global_load_dwordx4 v[164:167], v2, s[74:75] offset:1024
	s_waitcnt vmcnt(24)
	v_lshlrev_b32_e32 v200, 16, v96
	v_and_b32_e32 v201, 0xffff0000, v96
	v_pk_mul_f32 v[204:205], v[200:201], v[200:201]
	v_lshlrev_b32_e32 v202, 16, v97
	v_and_b32_e32 v203, 0xffff0000, v97
	v_pk_mul_f32 v[206:207], v[202:203], v[202:203]
	v_lshlrev_b32_e32 v200, 16, v98
	v_and_b32_e32 v201, 0xffff0000, v98
	v_pk_fma_f32 v[204:205], v[200:201], v[200:201], v[204:205]
	v_lshlrev_b32_e32 v202, 16, v99
	v_and_b32_e32 v203, 0xffff0000, v99
	v_pk_fma_f32 v[206:207], v[202:203], v[202:203], v[206:207]
	v_lshlrev_b32_e32 v200, 16, v100
	v_and_b32_e32 v201, 0xffff0000, v100
	v_pk_fma_f32 v[204:205], v[200:201], v[200:201], v[204:205]
	v_lshlrev_b32_e32 v202, 16, v101
	v_and_b32_e32 v203, 0xffff0000, v101
	v_pk_fma_f32 v[206:207], v[202:203], v[202:203], v[206:207]
	v_lshlrev_b32_e32 v200, 16, v102
	v_and_b32_e32 v201, 0xffff0000, v102
	v_pk_fma_f32 v[204:205], v[200:201], v[200:201], v[204:205]
	v_lshlrev_b32_e32 v202, 16, v103
	v_and_b32_e32 v203, 0xffff0000, v103
	v_pk_fma_f32 v[206:207], v[202:203], v[202:203], v[206:207]
	v_pk_add_f32 v[204:205], v[204:205], v[206:207]
	v_add_f32_e32 v208, v204, v205
	v_lshlrev_b32_e32 v184, 16, v88
	v_and_b32_e32 v185, 0xffff0000, v88
	v_add_f32_dpp v208, v208, v208 quad_perm:[1,0,3,2] row_mask:0xf bank_mask:0xf
	v_lshlrev_b32_e32 v186, 16, v89
	v_and_b32_e32 v187, 0xffff0000, v89
	v_add_f32_dpp v208, v208, v208 quad_perm:[2,3,0,1] row_mask:0xf bank_mask:0xf
	v_lshlrev_b32_e32 v188, 16, v90
	v_and_b32_e32 v189, 0xffff0000, v90
	v_add_f32_dpp v208, v208, v208 row_half_mirror row_mask:0xf bank_mask:0xf
	v_lshlrev_b32_e32 v190, 16, v91
	v_and_b32_e32 v191, 0xffff0000, v91
	v_add_f32_dpp v208, v208, v208 row_mirror row_mask:0xf bank_mask:0xf
	v_lshlrev_b32_e32 v192, 16, v92
	v_and_b32_e32 v193, 0xffff0000, v92
	v_add_f32_dpp v208, v208, v208 row_bcast:15 row_mask:0xa bank_mask:0xf
	v_lshlrev_b32_e32 v194, 16, v93
	v_and_b32_e32 v195, 0xffff0000, v93
	v_add_f32_dpp v208, v208, v208 row_bcast:31 row_mask:0xc bank_mask:0xf
	v_lshlrev_b32_e32 v196, 16, v94
	v_and_b32_e32 v197, 0xffff0000, v94
	v_readlane_b32 s60, v208, 63
	s_nop 1
	v_lshlrev_b32_e32 v198, 16, v95
	v_and_b32_e32 v199, 0xffff0000, v95
	v_mov_b32_e32 v210, s60
	v_fmaak_f32 v210, v210, v212, 0x358637bd
	v_rsq_f32_e32 v210, v210
	s_nop 0
	v_lshlrev_b32_e32 v200, 16, v96
	v_and_b32_e32 v201, 0xffff0000, v96
	v_pk_mul_f32 v[200:201], v[200:201], v[210:211] op_sel_hi:[1,0]
	v_pk_fma_f32 v[184:185], v[8:9], v[200:201], v[184:185]
	v_lshlrev_b32_e32 v202, 16, v97
	v_and_b32_e32 v203, 0xffff0000, v97
	v_pk_mul_f32 v[202:203], v[202:203], v[210:211] op_sel_hi:[1,0]
	v_pk_fma_f32 v[186:187], v[10:11], v[202:203], v[186:187]
	v_lshlrev_b32_e32 v200, 16, v98
	v_and_b32_e32 v201, 0xffff0000, v98
	v_pk_mul_f32 v[200:201], v[200:201], v[210:211] op_sel_hi:[1,0]
	v_pk_fma_f32 v[188:189], v[12:13], v[200:201], v[188:189]
	v_lshlrev_b32_e32 v202, 16, v99
	v_and_b32_e32 v203, 0xffff0000, v99
	v_pk_mul_f32 v[202:203], v[202:203], v[210:211] op_sel_hi:[1,0]
	v_pk_fma_f32 v[190:191], v[14:15], v[202:203], v[190:191]
	v_lshlrev_b32_e32 v200, 16, v100
	v_and_b32_e32 v201, 0xffff0000, v100
	v_pk_mul_f32 v[200:201], v[200:201], v[210:211] op_sel_hi:[1,0]
	v_pk_fma_f32 v[192:193], v[16:17], v[200:201], v[192:193]
	v_lshlrev_b32_e32 v202, 16, v101
	v_and_b32_e32 v203, 0xffff0000, v101
	v_pk_mul_f32 v[202:203], v[202:203], v[210:211] op_sel_hi:[1,0]
	v_pk_fma_f32 v[194:195], v[18:19], v[202:203], v[194:195]
	v_lshlrev_b32_e32 v200, 16, v102
	v_and_b32_e32 v201, 0xffff0000, v102
	v_pk_mul_f32 v[200:201], v[200:201], v[210:211] op_sel_hi:[1,0]
	v_pk_fma_f32 v[196:197], v[20:21], v[200:201], v[196:197]
	v_lshlrev_b32_e32 v202, 16, v103
	v_and_b32_e32 v203, 0xffff0000, v103
	v_pk_mul_f32 v[202:203], v[202:203], v[210:211] op_sel_hi:[1,0]
	v_pk_fma_f32 v[198:199], v[22:23], v[202:203], v[198:199]
	s_add_i32 s81, s80, 2
	s_add_i32 s81, s81, s82
	s_and_b32 s81, s81, 31
	s_lshl_b32 s83, s81, 12
	v_add_u32_e32 v213, s83, v3
	global_store_dwordx4 v213, v[184:187], s[76:77]
	global_store_dwordx4 v213, v[188:191], s[76:77] offset:16
	global_store_dwordx4 v213, v[192:195], s[76:77] offset:2048
	global_store_dwordx4 v213, v[196:199], s[76:77] offset:2064
	s_add_i32 s81, s80, 7
	s_add_i32 s81, s81, s82
	s_and_b32 s81, s81, 31
	s_lshl_b32 s83, s81, 11
	v_add_u32_e32 v2, s83, v1
	global_load_dwordx4 v[56:59], v2, s[72:73]
	global_load_dwordx4 v[60:63], v2, s[72:73] offset:1024
	global_load_dwordx4 v[64:67], v2, s[74:75]
	global_load_dwordx4 v[68:71], v2, s[74:75] offset:1024
	s_waitcnt vmcnt(28)
; __device__ __forceinline__ unsigned cvtpk(float lo, float hi) { f32x2 v = {lo, hi}; bf16x2_t b = __builtin_convertvector(v, bf16x2_t); return __builtin_bit_cast(unsigned, b); }
; __device__ __forceinline__ float bflo(unsigned u) { return __uint_as_float(u << 16); }
; __device__ __forceinline__ float bfhi(unsigned u) { return __uint_as_float(u & 0xffff0000u); }
; __device__ __forceinline__ void phase_rowwise(const void* xsrc_, bool sbf, void* xdst_, bool dbf, const bf16_t* Y, bf16_t* H, const float* mods, int lprev, int iprev, const float* lnpost, float resw, ...
;     ...
;             if (hasprev) {
;                 f32x4 y[2][4]; float ss[2] = {0.f, 0.f};
; #pragma unroll
;                 for (int r = 0; r < 2; ++r)
; #pragma unroll
;                     for (int j = 0; j < 4; ++j) { const u32x2 u = yr[r][j]; y[r][j] = (f32x4){bflo(u.x), bfhi(u.x), bflo(u.y), bfhi(u.y)};
;                         ss[r] += (y[r][j].x * y[r][j].x + y[r][j].y * y[r][j].y) + (y[r][j].z * y[r][j].z + y[r][j].w * y[r][j].w); }
; #pragma unroll
;                 for (int off = 1; off < 64; off <<= 1) { ss[0] += __shfl_xor(ss[0], off); ss[1] += __shfl_xor(ss[1], off); }
; #pragma unroll
;                 for (int r = 0; r < 2; ++r) { const float rs = __builtin_amdgcn_rsqf(ss[r] * (1.f / DM) + EPS);
; #pragma unroll
;                     for (int j = 0; j < 4; ++j) x[r][j] = x[r][j] + gp[j] * (y[r][j] * rs); }
;             }
; #pragma unroll
;             for (int r = 0; r < 2; ++r)
; #pragma unroll
;                 for (int j = 0; j < 4; ++j) { if (hasprev) { if (dbf) { u32x2 w; w.x = cvtpk(x[r][j].x, x[r][j].y); w.y = cvtpk(x[r][j].z, x[r][j].w); *(u32x2*)(xdstb + (m + r) * DM + 4 * lane + 256 * j) = w; } else *(f32x4*)(xdst + (m + r) * DM + 4 * lane + 256 * j) = x[r][j]; } }
	v_lshlrev_b32_e32 v200, 16, v112
	v_and_b32_e32 v201, 0xffff0000, v112
	v_pk_mul_f32 v[204:205], v[200:201], v[200:201]
	v_lshlrev_b32_e32 v202, 16, v113
	v_and_b32_e32 v203, 0xffff0000, v113
	v_pk_mul_f32 v[206:207], v[202:203], v[202:203]
	v_lshlrev_b32_e32 v200, 16, v114
	v_and_b32_e32 v201, 0xffff0000, v114
	v_pk_fma_f32 v[204:205], v[200:201], v[200:201], v[204:205]
	v_lshlrev_b32_e32 v202, 16, v115
	v_and_b32_e32 v203, 0xffff0000, v115
	v_pk_fma_f32 v[206:207], v[202:203], v[202:203], v[206:207]
	v_lshlrev_b32_e32 v200, 16, v116
	v_and_b32_e32 v201, 0xffff0000, v116
	v_pk_fma_f32 v[204:205], v[200:201], v[200:201], v[204:205]
	v_lshlrev_b32_e32 v202, 16, v117
	v_and_b32_e32 v203, 0xffff0000, v117
	v_pk_fma_f32 v[206:207], v[202:203], v[202:203], v[206:207]
	v_lshlrev_b32_e32 v200, 16, v118
	v_and_b32_e32 v201, 0xffff0000, v118
	v_pk_fma_f32 v[204:205], v[200:201], v[200:201], v[204:205]
	v_lshlrev_b32_e32 v202, 16, v119
	v_and_b32_e32 v203, 0xffff0000, v119
	v_pk_fma_f32 v[206:207], v[202:203], v[202:203], v[206:207]
	v_pk_add_f32 v[204:205], v[204:205], v[206:207]
	v_add_f32_e32 v208, v204, v205
	v_lshlrev_b32_e32 v184, 16, v104
	v_and_b32_e32 v185, 0xffff0000, v104
	v_add_f32_dpp v208, v208, v208 quad_perm:[1,0,3,2] row_mask:0xf bank_mask:0xf
	v_lshlrev_b32_e32 v186, 16, v105
	v_and_b32_e32 v187, 0xffff0000, v105
	v_add_f32_dpp v208, v208, v208 quad_perm:[2,3,0,1] row_mask:0xf bank_mask:0xf
	v_lshlrev_b32_e32 v188, 16, v106
	v_and_b32_e32 v189, 0xffff0000, v106
	v_add_f32_dpp v208, v208, v208 row_half_mirror row_mask:0xf bank_mask:0xf
	v_lshlrev_b32_e32 v190, 16, v107
	v_and_b32_e32 v191, 0xffff0000, v107
	v_add_f32_dpp v208, v208, v208 row_mirror row_mask:0xf bank_mask:0xf
	v_lshlrev_b32_e32 v192, 16, v108
	v_and_b32_e32 v193, 0xffff0000, v108
	v_add_f32_dpp v208, v208, v208 row_bcast:15 row_mask:0xa bank_mask:0xf
	v_lshlrev_b32_e32 v194, 16, v109
	v_and_b32_e32 v195, 0xffff0000, v109
	v_add_f32_dpp v208, v208, v208 row_bcast:31 row_mask:0xc bank_mask:0xf
	v_lshlrev_b32_e32 v196, 16, v110
	v_and_b32_e32 v197, 0xffff0000, v110
	v_readlane_b32 s60, v208, 63
	s_nop 1
	v_lshlrev_b32_e32 v198, 16, v111
	v_and_b32_e32 v199, 0xffff0000, v111
	v_mov_b32_e32 v210, s60
	v_fmaak_f32 v210, v210, v212, 0x358637bd
	v_rsq_f32_e32 v210, v210
	s_nop 0
	v_lshlrev_b32_e32 v200, 16, v112
	v_and_b32_e32 v201, 0xffff0000, v112
	v_pk_mul_f32 v[200:201], v[200:201], v[210:211] op_sel_hi:[1,0]
	v_pk_fma_f32 v[184:185], v[8:9], v[200:201], v[184:185]
	v_lshlrev_b32_e32 v202, 16, v113
	v_and_b32_e32 v203, 0xffff0000, v113
	v_pk_mul_f32 v[202:203], v[202:203], v[210:211] op_sel_hi:[1,0]
	v_pk_fma_f32 v[186:187], v[10:11], v[202:203], v[186:187]
	v_lshlrev_b32_e32 v200, 16, v114
	v_and_b32_e32 v201, 0xffff0000, v114
	v_pk_mul_f32 v[200:201], v[200:201], v[210:211] op_sel_hi:[1,0]
	v_pk_fma_f32 v[188:189], v[12:13], v[200:201], v[188:189]
	v_lshlrev_b32_e32 v202, 16, v115
	v_and_b32_e32 v203, 0xffff0000, v115
	v_pk_mul_f32 v[202:203], v[202:203], v[210:211] op_sel_hi:[1,0]
	v_pk_fma_f32 v[190:191], v[14:15], v[202:203], v[190:191]
	v_lshlrev_b32_e32 v200, 16, v116
	v_and_b32_e32 v201, 0xffff0000, v116
	v_pk_mul_f32 v[200:201], v[200:201], v[210:211] op_sel_hi:[1,0]
	v_pk_fma_f32 v[192:193], v[16:17], v[200:201], v[192:193]
	v_lshlrev_b32_e32 v202, 16, v117
	v_and_b32_e32 v203, 0xffff0000, v117
	v_pk_mul_f32 v[202:203], v[202:203], v[210:211] op_sel_hi:[1,0]
	v_pk_fma_f32 v[194:195], v[18:19], v[202:203], v[194:195]
	v_lshlrev_b32_e32 v200, 16, v118
	v_and_b32_e32 v201, 0xffff0000, v118
	v_pk_mul_f32 v[200:201], v[200:201], v[210:211] op_sel_hi:[1,0]
	v_pk_fma_f32 v[196:197], v[20:21], v[200:201], v[196:197]
	v_lshlrev_b32_e32 v202, 16, v119
	v_and_b32_e32 v203, 0xffff0000, v119
	v_pk_mul_f32 v[202:203], v[202:203], v[210:211] op_sel_hi:[1,0]
	v_pk_fma_f32 v[198:199], v[22:23], v[202:203], v[198:199]
	s_add_i32 s81, s80, 3
	s_add_i32 s81, s81, s82
	s_and_b32 s81, s81, 31
	s_lshl_b32 s83, s81, 12
	v_add_u32_e32 v213, s83, v3
	global_store_dwordx4 v213, v[184:187], s[76:77]
	global_store_dwordx4 v213, v[188:191], s[76:77] offset:16
	global_store_dwordx4 v213, v[192:195], s[76:77] offset:2048
	global_store_dwordx4 v213, v[196:199], s[76:77] offset:2064
	s_mov_b32 s82, 4

; __device__ __forceinline__ float bflo(unsigned u) { return __uint_as_float(u << 16); }
; __device__ __forceinline__ void phase_rowwise(const void* xsrc_, bool sbf, void* xdst_, bool dbf, const bf16_t* Y, bf16_t* H, const float* mods, int lprev, int iprev, const float* lnpost, float resw, ...
;     ...
;         for (int rr = 0; rr < 32; rr += 2) {
;             const size_t m = (size_t)ch * 32 + rr;
;             f32x4 x[2][4]; u32x2 yr[2][4];
; #pragma unroll
;             for (int r = 0; r < 2; ++r)
; #pragma unroll
;                 for (int j = 0; j < 4; ++j) { if (sbf) { const u32x2 u = xnb[r][j]; x[r][j] = (f32x4){bflo(u.x), bfhi(u.x), bflo(u.y), bfhi(u.y)}; } else x[r][j] = xn[r][j]; yr[r][j] = yn[r][j]; }
;             if (rr + 2 < 32) {
; #pragma unroll
;                 for (int r = 0; r < 2; ++r)
; #pragma unroll
;                     for (int j = 0; j < 4; ++j) { if (sbf) xnb[r][j] = *(const u32x2*)(xsrcb + (m + 2 + r) * DM + 4 * lane + 256 * j); else xn[r][j] = *(const f32x4*)(xsrc + (m + 2 + r) * DM + 4 * lane + 256 * j); if (hasprev) yn[r][j] = *(const u32x2*)(Y + (m + 2 + r) * DM + 4 * lane + 256 * j); } }
;             if (hasprev) {
;                 f32x4 y[2][4]; float ss[2] = {0.f, 0.f};
; #pragma unroll
;                 for (int r = 0; r < 2; ++r)
; #pragma unroll
;                     for (int j = 0; j < 4; ++j) { const u32x2 u = yr[r][j]; y[r][j] = (f32x4){bflo(u.x), bfhi(u.x), bflo(u.y), bfhi(u.y)};
;                         ss[r] += (y[r][j].x * y[r][j].x + y[r][j].y * y[r][j].y) + (y[r][j].z * y[r][j].z + y[r][j].w * y[r][j].w); }
; #pragma unroll
;                 for (int off = 1; off < 64; off <<= 1) { ss[0] += __shfl_xor(ss[0], off); ss[1] += __shfl_xor(ss[1], off); }
; #pragma unroll
;                 for (int r = 0; r < 2; ++r) { const float rs = __builtin_amdgcn_rsqf(ss[r] * (1.f / DM) + EPS);
; #pragma unroll
;                     for (int j = 0; j < 4; ++j) x[r][j] = x[r][j] + gp[j] * (y[r][j] * rs); }
;             }
; #pragma unroll
;             for (int r = 0; r < 2; ++r)
; #pragma unroll
;                 for (int j = 0; j < 4; ++j) { if (hasprev) { if (dbf) { u32x2 w; w.x = cvtpk(x[r][j].x, x[r][j].y); w.y = cvtpk(x[r][j].z, x[r][j].w); *(u32x2*)(xdstb + (m + r) * DM + 4 * lane + 256 * j) = w; } else *(f32x4*)(xdst + (m + r) * DM + 4 * lane + 256 * j) = x[r][j]; } }
.Lrw_LAST_l0_e:
	s_waitcnt vmcnt(32)
	v_lshlrev_b32_e32 v200, 16, v128
	v_and_b32_e32 v201, 0xffff0000, v128
	v_pk_mul_f32 v[204:205], v[200:201], v[200:201]
	v_lshlrev_b32_e32 v202, 16, v129
	v_and_b32_e32 v203, 0xffff0000, v129
	v_pk_mul_f32 v[206:207], v[202:203], v[202:203]
	v_lshlrev_b32_e32 v200, 16, v130
	v_and_b32_e32 v201, 0xffff0000, v130
	v_pk_fma_f32 v[204:205], v[200:201], v[200:201], v[204:205]
	v_lshlrev_b32_e32 v202, 16, v131
	v_and_b32_e32 v203, 0xffff0000, v131
	v_pk_fma_f32 v[206:207], v[202:203], v[202:203], v[206:207]
	v_lshlrev_b32_e32 v200, 16, v132
	v_and_b32_e32 v201, 0xffff0000, v132
	v_pk_fma_f32 v[204:205], v[200:201], v[200:201], v[204:205]
	v_lshlrev_b32_e32 v202, 16, v133
	v_and_b32_e32 v203, 0xffff0000, v133
	v_pk_fma_f32 v[206:207], v[202:203], v[202:203], v[206:207]
	v_lshlrev_b32_e32 v200, 16, v134
	v_and_b32_e32 v201, 0xffff0000, v134
	v_pk_fma_f32 v[204:205], v[200:201], v[200:201], v[204:205]
	v_lshlrev_b32_e32 v202, 16, v135
	v_and_b32_e32 v203, 0xffff0000, v135
	v_pk_fma_f32 v[206:207], v[202:203], v[202:203], v[206:207]
	v_pk_add_f32 v[204:205], v[204:205], v[206:207]
	v_add_f32_e32 v208, v204, v205
	v_lshlrev_b32_e32 v184, 16, v120
	v_and_b32_e32 v185, 0xffff0000, v120
	v_add_f32_dpp v208, v208, v208 quad_perm:[1,0,3,2] row_mask:0xf bank_mask:0xf
	v_lshlrev_b32_e32 v186, 16, v121
	v_and_b32_e32 v187, 0xffff0000, v121
	v_add_f32_dpp v208, v208, v208 quad_perm:[2,3,0,1] row_mask:0xf bank_mask:0xf
	v_lshlrev_b32_e32 v188, 16, v122
	v_and_b32_e32 v189, 0xffff0000, v122
	v_add_f32_dpp v208, v208, v208 row_half_mirror row_mask:0xf bank_mask:0xf
	v_lshlrev_b32_e32 v190, 16, v123
	v_and_b32_e32 v191, 0xffff0000, v123
	v_add_f32_dpp v208, v208, v208 row_mirror row_mask:0xf bank_mask:0xf
	v_lshlrev_b32_e32 v192, 16, v124
	v_and_b32_e32 v193, 0xffff0000, v124
	v_add_f32_dpp v208, v208, v208 row_bcast:15 row_mask:0xa bank_mask:0xf
	v_lshlrev_b32_e32 v194, 16, v125
	v_and_b32_e32 v195, 0xffff0000, v125
	v_add_f32_dpp v208, v208, v208 row_bcast:31 row_mask:0xc bank_mask:0xf
	v_lshlrev_b32_e32 v196, 16, v126
	v_and_b32_e32 v197, 0xffff0000, v126
	v_readlane_b32 s60, v208, 63
	s_nop 1
	v_lshlrev_b32_e32 v198, 16, v127
	v_and_b32_e32 v199, 0xffff0000, v127
	v_mov_b32_e32 v210, s60
	v_fmaak_f32 v210, v210, v212, 0x358637bd
	v_rsq_f32_e32 v210, v210
	s_nop 0
	v_lshlrev_b32_e32 v200, 16, v128
	v_and_b32_e32 v201, 0xffff0000, v128
	v_pk_mul_f32 v[200:201], v[200:201], v[210:211] op_sel_hi:[1,0]
	v_pk_fma_f32 v[184:185], v[8:9], v[200:201], v[184:185]
	v_lshlrev_b32_e32 v202, 16, v129
	v_and_b32_e32 v203, 0xffff0000, v129
	v_pk_mul_f32 v[202:203], v[202:203], v[210:211] op_sel_hi:[1,0]
	v_pk_fma_f32 v[186:187], v[10:11], v[202:203], v[186:187]
	v_lshlrev_b32_e32 v200, 16, v130
	v_and_b32_e32 v201, 0xffff0000, v130
	v_pk_mul_f32 v[200:201], v[200:201], v[210:211] op_sel_hi:[1,0]
	v_pk_fma_f32 v[188:189], v[12:13], v[200:201], v[188:189]
	v_lshlrev_b32_e32 v202, 16, v131
	v_and_b32_e32 v203, 0xffff0000, v131
	v_pk_mul_f32 v[202:203], v[202:203], v[210:211] op_sel_hi:[1,0]
	v_pk_fma_f32 v[190:191], v[14:15], v[202:203], v[190:191]
	v_lshlrev_b32_e32 v200, 16, v132
	v_and_b32_e32 v201, 0xffff0000, v132
	v_pk_mul_f32 v[200:201], v[200:201], v[210:211] op_sel_hi:[1,0]
	v_pk_fma_f32 v[192:193], v[16:17], v[200:201], v[192:193]
	v_lshlrev_b32_e32 v202, 16, v133
	v_and_b32_e32 v203, 0xffff0000, v133
	v_pk_mul_f32 v[202:203], v[202:203], v[210:211] op_sel_hi:[1,0]
	v_pk_fma_f32 v[194:195], v[18:19], v[202:203], v[194:195]
	v_lshlrev_b32_e32 v200, 16, v134
	v_and_b32_e32 v201, 0xffff0000, v134
	v_pk_mul_f32 v[200:201], v[200:201], v[210:211] op_sel_hi:[1,0]
	v_pk_fma_f32 v[196:197], v[20:21], v[200:201], v[196:197]
	v_lshlrev_b32_e32 v202, 16, v135
	v_and_b32_e32 v203, 0xffff0000, v135
	v_pk_mul_f32 v[202:203], v[202:203], v[210:211] op_sel_hi:[1,0]
	v_pk_fma_f32 v[198:199], v[22:23], v[202:203], v[198:199]
	s_add_i32 s81, s80, 0
	s_add_i32 s81, s81, s82
	s_and_b32 s81, s81, 31
	s_lshl_b32 s83, s81, 12
	v_add_u32_e32 v213, s83, v3
	global_store_dwordx4 v213, v[184:187], s[76:77]
	global_store_dwordx4 v213, v[188:191], s[76:77] offset:16
	global_store_dwordx4 v213, v[192:195], s[76:77] offset:2048
	global_store_dwordx4 v213, v[196:199], s[76:77] offset:2064
	s_add_i32 s81, s82, 5
	s_cmp_lt_u32 s81, 32
	s_cbranch_scc0 .Lrw_LAST_l1_d
	s_add_i32 s81, s80, 5
	s_add_i32 s81, s81, s82
	s_and_b32 s81, s81, 31
	s_lshl_b32 s83, s81, 11
	v_add_u32_e32 v2, s83, v1
	global_load_dwordx4 v[88:91], v2, s[72:73]
	global_load_dwordx4 v[92:95], v2, s[72:73] offset:1024
	global_load_dwordx4 v[96:99], v2, s[74:75]
	global_load_dwordx4 v[100:103], v2, s[74:75] offset:1024
	s_branch .Lrw_LAST_l1_e

; __device__ __forceinline__ float bflo(unsigned u) { return __uint_as_float(u << 16); }
; __device__ __forceinline__ void phase_rowwise(const void* xsrc_, bool sbf, void* xdst_, bool dbf, const bf16_t* Y, bf16_t* H, const float* mods, int lprev, int iprev, const float* lnpost, float resw, ...
;     ...
;         for (int rr = 0; rr < 32; rr += 2) {
;             const size_t m = (size_t)ch * 32 + rr;
;             f32x4 x[2][4]; u32x2 yr[2][4];
; #pragma unroll
;             for (int r = 0; r < 2; ++r)
; #pragma unroll
;                 for (int j = 0; j < 4; ++j) { if (sbf) { const u32x2 u = xnb[r][j]; x[r][j] = (f32x4){bflo(u.x), bfhi(u.x), bflo(u.y), bfhi(u.y)}; } else x[r][j] = xn[r][j]; yr[r][j] = yn[r][j]; }
;             if (rr + 2 < 32) {
; #pragma unroll
;                 for (int r = 0; r < 2; ++r)
; #pragma unroll
;                     for (int j = 0; j < 4; ++j) { if (sbf) xnb[r][j] = *(const u32x2*)(xsrcb + (m + 2 + r) * DM + 4 * lane + 256 * j); else xn[r][j] = *(const f32x4*)(xsrc + (m + 2 + r) * DM + 4 * lane + 256 * j); if (hasprev) yn[r][j] = *(const u32x2*)(Y + (m + 2 + r) * DM + 4 * lane + 256 * j); } }
;             if (hasprev) {
;                 f32x4 y[2][4]; float ss[2] = {0.f, 0.f};
; #pragma unroll
;                 for (int r = 0; r < 2; ++r)
; #pragma unroll
;                     for (int j = 0; j < 4; ++j) { const u32x2 u = yr[r][j]; y[r][j] = (f32x4){bflo(u.x), bfhi(u.x), bflo(u.y), bfhi(u.y)};
;                         ss[r] += (y[r][j].x * y[r][j].x + y[r][j].y * y[r][j].y) + (y[r][j].z * y[r][j].z + y[r][j].w * y[r][j].w); }
; #pragma unroll
;                 for (int off = 1; off < 64; off <<= 1) { ss[0] += __shfl_xor(ss[0], off); ss[1] += __shfl_xor(ss[1], off); }
; #pragma unroll
;                 for (int r = 0; r < 2; ++r) { const float rs = __builtin_amdgcn_rsqf(ss[r] * (1.f / DM) + EPS);
; #pragma unroll
;                     for (int j = 0; j < 4; ++j) x[r][j] = x[r][j] + gp[j] * (y[r][j] * rs); }
;             }
; #pragma unroll
;             for (int r = 0; r < 2; ++r)
; #pragma unroll
;                 for (int j = 0; j < 4; ++j) { if (hasprev) { if (dbf) { u32x2 w; w.x = cvtpk(x[r][j].x, x[r][j].y); w.y = cvtpk(x[r][j].z, x[r][j].w); *(u32x2*)(xdstb + (m + r) * DM + 4 * lane + 256 * j) = w; } else *(f32x4*)(xdst + (m + r) * DM + 4 * lane + 256 * j) = x[r][j]; } }
.Lrw_LAST_l1_e:
	s_waitcnt vmcnt(32)
	v_lshlrev_b32_e32 v200, 16, v144
	v_and_b32_e32 v201, 0xffff0000, v144
	v_pk_mul_f32 v[204:205], v[200:201], v[200:201]
	v_lshlrev_b32_e32 v202, 16, v145
	v_and_b32_e32 v203, 0xffff0000, v145
	v_pk_mul_f32 v[206:207], v[202:203], v[202:203]
	v_lshlrev_b32_e32 v200, 16, v146
	v_and_b32_e32 v201, 0xffff0000, v146
	v_pk_fma_f32 v[204:205], v[200:201], v[200:201], v[204:205]
	v_lshlrev_b32_e32 v202, 16, v147
	v_and_b32_e32 v203, 0xffff0000, v147
	v_pk_fma_f32 v[206:207], v[202:203], v[202:203], v[206:207]
	v_lshlrev_b32_e32 v200, 16, v148
	v_and_b32_e32 v201, 0xffff0000, v148
	v_pk_fma_f32 v[204:205], v[200:201], v[200:201], v[204:205]
	v_lshlrev_b32_e32 v202, 16, v149
	v_and_b32_e32 v203, 0xffff0000, v149
	v_pk_fma_f32 v[206:207], v[202:203], v[202:203], v[206:207]
	v_lshlrev_b32_e32 v200, 16, v150
	v_and_b32_e32 v201, 0xffff0000, v150
	v_pk_fma_f32 v[204:205], v[200:201], v[200:201], v[204:205]
	v_lshlrev_b32_e32 v202, 16, v151
	v_and_b32_e32 v203, 0xffff0000, v151
	v_pk_fma_f32 v[206:207], v[202:203], v[202:203], v[206:207]
	v_pk_add_f32 v[204:205], v[204:205], v[206:207]
	v_add_f32_e32 v208, v204, v205
	v_lshlrev_b32_e32 v184, 16, v136
	v_and_b32_e32 v185, 0xffff0000, v136
	v_add_f32_dpp v208, v208, v208 quad_perm:[1,0,3,2] row_mask:0xf bank_mask:0xf
	v_lshlrev_b32_e32 v186, 16, v137
	v_and_b32_e32 v187, 0xffff0000, v137
	v_add_f32_dpp v208, v208, v208 quad_perm:[2,3,0,1] row_mask:0xf bank_mask:0xf
	v_lshlrev_b32_e32 v188, 16, v138
	v_and_b32_e32 v189, 0xffff0000, v138
	v_add_f32_dpp v208, v208, v208 row_half_mirror row_mask:0xf bank_mask:0xf
	v_lshlrev_b32_e32 v190, 16, v139
	v_and_b32_e32 v191, 0xffff0000, v139
	v_add_f32_dpp v208, v208, v208 row_mirror row_mask:0xf bank_mask:0xf
	v_lshlrev_b32_e32 v192, 16, v140
	v_and_b32_e32 v193, 0xffff0000, v140
	v_add_f32_dpp v208, v208, v208 row_bcast:15 row_mask:0xa bank_mask:0xf
	v_lshlrev_b32_e32 v194, 16, v141
	v_and_b32_e32 v195, 0xffff0000, v141
	v_add_f32_dpp v208, v208, v208 row_bcast:31 row_mask:0xc bank_mask:0xf
	v_lshlrev_b32_e32 v196, 16, v142
	v_and_b32_e32 v197, 0xffff0000, v142
	v_readlane_b32 s60, v208, 63
	s_nop 1
	v_lshlrev_b32_e32 v198, 16, v143
	v_and_b32_e32 v199, 0xffff0000, v143
	v_mov_b32_e32 v210, s60
	v_fmaak_f32 v210, v210, v212, 0x358637bd
	v_rsq_f32_e32 v210, v210
	s_nop 0
	v_lshlrev_b32_e32 v200, 16, v144
	v_and_b32_e32 v201, 0xffff0000, v144
	v_pk_mul_f32 v[200:201], v[200:201], v[210:211] op_sel_hi:[1,0]
	v_pk_fma_f32 v[184:185], v[8:9], v[200:201], v[184:185]
	v_lshlrev_b32_e32 v202, 16, v145
	v_and_b32_e32 v203, 0xffff0000, v145
	v_pk_mul_f32 v[202:203], v[202:203], v[210:211] op_sel_hi:[1,0]
	v_pk_fma_f32 v[186:187], v[10:11], v[202:203], v[186:187]
	v_lshlrev_b32_e32 v200, 16, v146
	v_and_b32_e32 v201, 0xffff0000, v146
	v_pk_mul_f32 v[200:201], v[200:201], v[210:211] op_sel_hi:[1,0]
	v_pk_fma_f32 v[188:189], v[12:13], v[200:201], v[188:189]
	v_lshlrev_b32_e32 v202, 16, v147
	v_and_b32_e32 v203, 0xffff0000, v147
	v_pk_mul_f32 v[202:203], v[202:203], v[210:211] op_sel_hi:[1,0]
	v_pk_fma_f32 v[190:191], v[14:15], v[202:203], v[190:191]
	v_lshlrev_b32_e32 v200, 16, v148
	v_and_b32_e32 v201, 0xffff0000, v148
	v_pk_mul_f32 v[200:201], v[200:201], v[210:211] op_sel_hi:[1,0]
	v_pk_fma_f32 v[192:193], v[16:17], v[200:201], v[192:193]
	v_lshlrev_b32_e32 v202, 16, v149
	v_and_b32_e32 v203, 0xffff0000, v149
	v_pk_mul_f32 v[202:203], v[202:203], v[210:211] op_sel_hi:[1,0]
	v_pk_fma_f32 v[194:195], v[18:19], v[202:203], v[194:195]
	v_lshlrev_b32_e32 v200, 16, v150
	v_and_b32_e32 v201, 0xffff0000, v150
	v_pk_mul_f32 v[200:201], v[200:201], v[210:211] op_sel_hi:[1,0]
	v_pk_fma_f32 v[196:197], v[20:21], v[200:201], v[196:197]
	v_lshlrev_b32_e32 v202, 16, v151
	v_and_b32_e32 v203, 0xffff0000, v151
	v_pk_mul_f32 v[202:203], v[202:203], v[210:211] op_sel_hi:[1,0]
	v_pk_fma_f32 v[198:199], v[22:23], v[202:203], v[198:199]
	s_add_i32 s81, s80, 1
	s_add_i32 s81, s81, s82
	s_and_b32 s81, s81, 31
	s_lshl_b32 s83, s81, 12
	v_add_u32_e32 v213, s83, v3
	global_store_dwordx4 v213, v[184:187], s[76:77]
	global_store_dwordx4 v213, v[188:191], s[76:77] offset:16
	global_store_dwordx4 v213, v[192:195], s[76:77] offset:2048
	global_store_dwordx4 v213, v[196:199], s[76:77] offset:2064
	s_add_i32 s81, s82, 6
	s_cmp_lt_u32 s81, 32
	s_cbranch_scc0 .Lrw_LAST_l2_d
	s_add_i32 s81, s80, 6
	s_add_i32 s81, s81, s82
	s_and_b32 s81, s81, 31
	s_lshl_b32 s83, s81, 11
	v_add_u32_e32 v2, s83, v1
	global_load_dwordx4 v[104:107], v2, s[72:73]
	global_load_dwordx4 v[108:111], v2, s[72:73] offset:1024
	global_load_dwordx4 v[112:115], v2, s[74:75]
	global_load_dwordx4 v[116:119], v2, s[74:75] offset:1024
	s_branch .Lrw_LAST_l2_e

; __device__ __forceinline__ float bflo(unsigned u) { return __uint_as_float(u << 16); }
; __device__ __forceinline__ void phase_rowwise(const void* xsrc_, bool sbf, void* xdst_, bool dbf, const bf16_t* Y, bf16_t* H, const float* mods, int lprev, int iprev, const float* lnpost, float resw, ...
;     ...
;         for (int rr = 0; rr < 32; rr += 2) {
;             const size_t m = (size_t)ch * 32 + rr;
;             f32x4 x[2][4]; u32x2 yr[2][4];
; #pragma unroll
;             for (int r = 0; r < 2; ++r)
; #pragma unroll
;                 for (int j = 0; j < 4; ++j) { if (sbf) { const u32x2 u = xnb[r][j]; x[r][j] = (f32x4){bflo(u.x), bfhi(u.x), bflo(u.y), bfhi(u.y)}; } else x[r][j] = xn[r][j]; yr[r][j] = yn[r][j]; }
;             if (rr + 2 < 32) {
; #pragma unroll
;                 for (int r = 0; r < 2; ++r)
; #pragma unroll
;                     for (int j = 0; j < 4; ++j) { if (sbf) xnb[r][j] = *(const u32x2*)(xsrcb + (m + 2 + r) * DM + 4 * lane + 256 * j); else xn[r][j] = *(const f32x4*)(xsrc + (m + 2 + r) * DM + 4 * lane + 256 * j); if (hasprev) yn[r][j] = *(const u32x2*)(Y + (m + 2 + r) * DM + 4 * lane + 256 * j); } }
;             if (hasprev) {
;                 f32x4 y[2][4]; float ss[2] = {0.f, 0.f};
; #pragma unroll
;                 for (int r = 0; r < 2; ++r)
; #pragma unroll
;                     for (int j = 0; j < 4; ++j) { const u32x2 u = yr[r][j]; y[r][j] = (f32x4){bflo(u.x), bfhi(u.x), bflo(u.y), bfhi(u.y)};
;                         ss[r] += (y[r][j].x * y[r][j].x + y[r][j].y * y[r][j].y) + (y[r][j].z * y[r][j].z + y[r][j].w * y[r][j].w); }
; #pragma unroll
;                 for (int off = 1; off < 64; off <<= 1) { ss[0] += __shfl_xor(ss[0], off); ss[1] += __shfl_xor(ss[1], off); }
; #pragma unroll
;                 for (int r = 0; r < 2; ++r) { const float rs = __builtin_amdgcn_rsqf(ss[r] * (1.f / DM) + EPS);
; #pragma unroll
;                     for (int j = 0; j < 4; ++j) x[r][j] = x[r][j] + gp[j] * (y[r][j] * rs); }
;             }
; #pragma unroll
;             for (int r = 0; r < 2; ++r)
; #pragma unroll
;                 for (int j = 0; j < 4; ++j) { if (hasprev) { if (dbf) { u32x2 w; w.x = cvtpk(x[r][j].x, x[r][j].y); w.y = cvtpk(x[r][j].z, x[r][j].w); *(u32x2*)(xdstb + (m + r) * DM + 4 * lane + 256 * j) = w; } else *(f32x4*)(xdst + (m + r) * DM + 4 * lane + 256 * j) = x[r][j]; } }
.Lrw_LAST_l2_e:
	s_waitcnt vmcnt(32)
	v_lshlrev_b32_e32 v200, 16, v160
	v_and_b32_e32 v201, 0xffff0000, v160
	v_pk_mul_f32 v[204:205], v[200:201], v[200:201]
	v_lshlrev_b32_e32 v202, 16, v161
	v_and_b32_e32 v203, 0xffff0000, v161
	v_pk_mul_f32 v[206:207], v[202:203], v[202:203]
	v_lshlrev_b32_e32 v200, 16, v162
	v_and_b32_e32 v201, 0xffff0000, v162
	v_pk_fma_f32 v[204:205], v[200:201], v[200:201], v[204:205]
	v_lshlrev_b32_e32 v202, 16, v163
	v_and_b32_e32 v203, 0xffff0000, v163
	v_pk_fma_f32 v[206:207], v[202:203], v[202:203], v[206:207]
	v_lshlrev_b32_e32 v200, 16, v164
	v_and_b32_e32 v201, 0xffff0000, v164
	v_pk_fma_f32 v[204:205], v[200:201], v[200:201], v[204:205]
	v_lshlrev_b32_e32 v202, 16, v165
	v_and_b32_e32 v203, 0xffff0000, v165
	v_pk_fma_f32 v[206:207], v[202:203], v[202:203], v[206:207]
	v_lshlrev_b32_e32 v200, 16, v166
	v_and_b32_e32 v201, 0xffff0000, v166
	v_pk_fma_f32 v[204:205], v[200:201], v[200:201], v[204:205]
	v_lshlrev_b32_e32 v202, 16, v167
	v_and_b32_e32 v203, 0xffff0000, v167
	v_pk_fma_f32 v[206:207], v[202:203], v[202:203], v[206:207]
	v_pk_add_f32 v[204:205], v[204:205], v[206:207]
	v_add_f32_e32 v208, v204, v205
	v_lshlrev_b32_e32 v184, 16, v152
	v_and_b32_e32 v185, 0xffff0000, v152
	v_add_f32_dpp v208, v208, v208 quad_perm:[1,0,3,2] row_mask:0xf bank_mask:0xf
	v_lshlrev_b32_e32 v186, 16, v153
	v_and_b32_e32 v187, 0xffff0000, v153
	v_add_f32_dpp v208, v208, v208 quad_perm:[2,3,0,1] row_mask:0xf bank_mask:0xf
	v_lshlrev_b32_e32 v188, 16, v154
	v_and_b32_e32 v189, 0xffff0000, v154
	v_add_f32_dpp v208, v208, v208 row_half_mirror row_mask:0xf bank_mask:0xf
	v_lshlrev_b32_e32 v190, 16, v155
	v_and_b32_e32 v191, 0xffff0000, v155
	v_add_f32_dpp v208, v208, v208 row_mirror row_mask:0xf bank_mask:0xf
	v_lshlrev_b32_e32 v192, 16, v156
	v_and_b32_e32 v193, 0xffff0000, v156
	v_add_f32_dpp v208, v208, v208 row_bcast:15 row_mask:0xa bank_mask:0xf
	v_lshlrev_b32_e32 v194, 16, v157
	v_and_b32_e32 v195, 0xffff0000, v157
	v_add_f32_dpp v208, v208, v208 row_bcast:31 row_mask:0xc bank_mask:0xf
	v_lshlrev_b32_e32 v196, 16, v158
	v_and_b32_e32 v197, 0xffff0000, v158
	v_readlane_b32 s60, v208, 63
	s_nop 1
	v_lshlrev_b32_e32 v198, 16, v159
	v_and_b32_e32 v199, 0xffff0000, v159
	v_mov_b32_e32 v210, s60
	v_fmaak_f32 v210, v210, v212, 0x358637bd
	v_rsq_f32_e32 v210, v210
	s_nop 0
	v_lshlrev_b32_e32 v200, 16, v160
	v_and_b32_e32 v201, 0xffff0000, v160
	v_pk_mul_f32 v[200:201], v[200:201], v[210:211] op_sel_hi:[1,0]
	v_pk_fma_f32 v[184:185], v[8:9], v[200:201], v[184:185]
	v_lshlrev_b32_e32 v202, 16, v161
	v_and_b32_e32 v203, 0xffff0000, v161
	v_pk_mul_f32 v[202:203], v[202:203], v[210:211] op_sel_hi:[1,0]
	v_pk_fma_f32 v[186:187], v[10:11], v[202:203], v[186:187]
	v_lshlrev_b32_e32 v200, 16, v162
	v_and_b32_e32 v201, 0xffff0000, v162
	v_pk_mul_f32 v[200:201], v[200:201], v[210:211] op_sel_hi:[1,0]
	v_pk_fma_f32 v[188:189], v[12:13], v[200:201], v[188:189]
	v_lshlrev_b32_e32 v202, 16, v163
	v_and_b32_e32 v203, 0xffff0000, v163
	v_pk_mul_f32 v[202:203], v[202:203], v[210:211] op_sel_hi:[1,0]
	v_pk_fma_f32 v[190:191], v[14:15], v[202:203], v[190:191]
	v_lshlrev_b32_e32 v200, 16, v164
	v_and_b32_e32 v201, 0xffff0000, v164
	v_pk_mul_f32 v[200:201], v[200:201], v[210:211] op_sel_hi:[1,0]
	v_pk_fma_f32 v[192:193], v[16:17], v[200:201], v[192:193]
	v_lshlrev_b32_e32 v202, 16, v165
	v_and_b32_e32 v203, 0xffff0000, v165
	v_pk_mul_f32 v[202:203], v[202:203], v[210:211] op_sel_hi:[1,0]
	v_pk_fma_f32 v[194:195], v[18:19], v[202:203], v[194:195]
	v_lshlrev_b32_e32 v200, 16, v166
	v_and_b32_e32 v201, 0xffff0000, v166
	v_pk_mul_f32 v[200:201], v[200:201], v[210:211] op_sel_hi:[1,0]
	v_pk_fma_f32 v[196:197], v[20:21], v[200:201], v[196:197]
	v_lshlrev_b32_e32 v202, 16, v167
	v_and_b32_e32 v203, 0xffff0000, v167
	v_pk_mul_f32 v[202:203], v[202:203], v[210:211] op_sel_hi:[1,0]
	v_pk_fma_f32 v[198:199], v[22:23], v[202:203], v[198:199]
	s_add_i32 s81, s80, 2
	s_add_i32 s81, s81, s82
	s_and_b32 s81, s81, 31
	s_lshl_b32 s83, s81, 12
	v_add_u32_e32 v213, s83, v3
	global_store_dwordx4 v213, v[184:187], s[76:77]
	global_store_dwordx4 v213, v[188:191], s[76:77] offset:16
	global_store_dwordx4 v213, v[192:195], s[76:77] offset:2048
	global_store_dwordx4 v213, v[196:199], s[76:77] offset:2064
	s_add_i32 s81, s82, 7
	s_cmp_lt_u32 s81, 32
	s_cbranch_scc0 .Lrw_LAST_l3_d
	s_add_i32 s81, s80, 7
	s_add_i32 s81, s81, s82
	s_and_b32 s81, s81, 31
	s_lshl_b32 s83, s81, 11
	v_add_u32_e32 v2, s83, v1
	global_load_dwordx4 v[120:123], v2, s[72:73]
	global_load_dwordx4 v[124:127], v2, s[72:73] offset:1024
	global_load_dwordx4 v[128:131], v2, s[74:75]
	global_load_dwordx4 v[132:135], v2, s[74:75] offset:1024
	s_branch .Lrw_LAST_l3_e

; __device__ __forceinline__ float bflo(unsigned u) { return __uint_as_float(u << 16); }
; __device__ __forceinline__ void phase_rowwise(const void* xsrc_, bool sbf, void* xdst_, bool dbf, const bf16_t* Y, bf16_t* H, const float* mods, int lprev, int iprev, const float* lnpost, float resw, ...
;     ...
;         for (int rr = 0; rr < 32; rr += 2) {
;             const size_t m = (size_t)ch * 32 + rr;
;             f32x4 x[2][4]; u32x2 yr[2][4];
; #pragma unroll
;             for (int r = 0; r < 2; ++r)
; #pragma unroll
;                 for (int j = 0; j < 4; ++j) { if (sbf) { const u32x2 u = xnb[r][j]; x[r][j] = (f32x4){bflo(u.x), bfhi(u.x), bflo(u.y), bfhi(u.y)}; } else x[r][j] = xn[r][j]; yr[r][j] = yn[r][j]; }
;             if (rr + 2 < 32) {
; #pragma unroll
;                 for (int r = 0; r < 2; ++r)
; #pragma unroll
;                     for (int j = 0; j < 4; ++j) { if (sbf) xnb[r][j] = *(const u32x2*)(xsrcb + (m + 2 + r) * DM + 4 * lane + 256 * j); else xn[r][j] = *(const f32x4*)(xsrc + (m + 2 + r) * DM + 4 * lane + 256 * j); if (hasprev) yn[r][j] = *(const u32x2*)(Y + (m + 2 + r) * DM + 4 * lane + 256 * j); } }
;             if (hasprev) {
;                 f32x4 y[2][4]; float ss[2] = {0.f, 0.f};
; #pragma unroll
;                 for (int r = 0; r < 2; ++r)
; #pragma unroll
;                     for (int j = 0; j < 4; ++j) { const u32x2 u = yr[r][j]; y[r][j] = (f32x4){bflo(u.x), bfhi(u.x), bflo(u.y), bfhi(u.y)};
;                         ss[r] += (y[r][j].x * y[r][j].x + y[r][j].y * y[r][j].y) + (y[r][j].z * y[r][j].z + y[r][j].w * y[r][j].w); }
; #pragma unroll
;                 for (int off = 1; off < 64; off <<= 1) { ss[0] += __shfl_xor(ss[0], off); ss[1] += __shfl_xor(ss[1], off); }
; #pragma unroll
;                 for (int r = 0; r < 2; ++r) { const float rs = __builtin_amdgcn_rsqf(ss[r] * (1.f / DM) + EPS);
; #pragma unroll
;                     for (int j = 0; j < 4; ++j) x[r][j] = x[r][j] + gp[j] * (y[r][j] * rs); }
;             }
; #pragma unroll
;             for (int r = 0; r < 2; ++r)
; #pragma unroll
;                 for (int j = 0; j < 4; ++j) { if (hasprev) { if (dbf) { u32x2 w; w.x = cvtpk(x[r][j].x, x[r][j].y); w.y = cvtpk(x[r][j].z, x[r][j].w); *(u32x2*)(xdstb + (m + r) * DM + 4 * lane + 256 * j) = w; } else *(f32x4*)(xdst + (m + r) * DM + 4 * lane + 256 * j) = x[r][j]; } }
.Lrw_LAST_l3_e:
	s_waitcnt vmcnt(32)
	v_lshlrev_b32_e32 v200, 16, v64
	v_and_b32_e32 v201, 0xffff0000, v64
	v_pk_mul_f32 v[204:205], v[200:201], v[200:201]
	v_lshlrev_b32_e32 v202, 16, v65
	v_and_b32_e32 v203, 0xffff0000, v65
	v_pk_mul_f32 v[206:207], v[202:203], v[202:203]
	v_lshlrev_b32_e32 v200, 16, v66
	v_and_b32_e32 v201, 0xffff0000, v66
	v_pk_fma_f32 v[204:205], v[200:201], v[200:201], v[204:205]
	v_lshlrev_b32_e32 v202, 16, v67
	v_and_b32_e32 v203, 0xffff0000, v67
	v_pk_fma_f32 v[206:207], v[202:203], v[202:203], v[206:207]
	v_lshlrev_b32_e32 v200, 16, v68
	v_and_b32_e32 v201, 0xffff0000, v68
	v_pk_fma_f32 v[204:205], v[200:201], v[200:201], v[204:205]
	v_lshlrev_b32_e32 v202, 16, v69
	v_and_b32_e32 v203, 0xffff0000, v69
	v_pk_fma_f32 v[206:207], v[202:203], v[202:203], v[206:207]
	v_lshlrev_b32_e32 v200, 16, v70
	v_and_b32_e32 v201, 0xffff0000, v70
	v_pk_fma_f32 v[204:205], v[200:201], v[200:201], v[204:205]
	v_lshlrev_b32_e32 v202, 16, v71
	v_and_b32_e32 v203, 0xffff0000, v71
	v_pk_fma_f32 v[206:207], v[202:203], v[202:203], v[206:207]
	v_pk_add_f32 v[204:205], v[204:205], v[206:207]
	v_add_f32_e32 v208, v204, v205
	v_lshlrev_b32_e32 v184, 16, v56
	v_and_b32_e32 v185, 0xffff0000, v56
	v_add_f32_dpp v208, v208, v208 quad_perm:[1,0,3,2] row_mask:0xf bank_mask:0xf
	v_lshlrev_b32_e32 v186, 16, v57
	v_and_b32_e32 v187, 0xffff0000, v57
	v_add_f32_dpp v208, v208, v208 quad_perm:[2,3,0,1] row_mask:0xf bank_mask:0xf
	v_lshlrev_b32_e32 v188, 16, v58
	v_and_b32_e32 v189, 0xffff0000, v58
	v_add_f32_dpp v208, v208, v208 row_half_mirror row_mask:0xf bank_mask:0xf
	v_lshlrev_b32_e32 v190, 16, v59
	v_and_b32_e32 v191, 0xffff0000, v59
	v_add_f32_dpp v208, v208, v208 row_mirror row_mask:0xf bank_mask:0xf
	v_lshlrev_b32_e32 v192, 16, v60
	v_and_b32_e32 v193, 0xffff0000, v60
	v_add_f32_dpp v208, v208, v208 row_bcast:15 row_mask:0xa bank_mask:0xf
	v_lshlrev_b32_e32 v194, 16, v61
	v_and_b32_e32 v195, 0xffff0000, v61
	v_add_f32_dpp v208, v208, v208 row_bcast:31 row_mask:0xc bank_mask:0xf
	v_lshlrev_b32_e32 v196, 16, v62
	v_and_b32_e32 v197, 0xffff0000, v62
	v_readlane_b32 s60, v208, 63
	s_nop 1
	v_lshlrev_b32_e32 v198, 16, v63
	v_and_b32_e32 v199, 0xffff0000, v63
	v_mov_b32_e32 v210, s60
	v_fmaak_f32 v210, v210, v212, 0x358637bd
	v_rsq_f32_e32 v210, v210
	s_nop 0
	v_lshlrev_b32_e32 v200, 16, v64
	v_and_b32_e32 v201, 0xffff0000, v64
	v_pk_mul_f32 v[200:201], v[200:201], v[210:211] op_sel_hi:[1,0]
	v_pk_fma_f32 v[184:185], v[8:9], v[200:201], v[184:185]
	v_lshlrev_b32_e32 v202, 16, v65
	v_and_b32_e32 v203, 0xffff0000, v65
	v_pk_mul_f32 v[202:203], v[202:203], v[210:211] op_sel_hi:[1,0]
	v_pk_fma_f32 v[186:187], v[10:11], v[202:203], v[186:187]
	v_lshlrev_b32_e32 v200, 16, v66
	v_and_b32_e32 v201, 0xffff0000, v66
	v_pk_mul_f32 v[200:201], v[200:201], v[210:211] op_sel_hi:[1,0]
	v_pk_fma_f32 v[188:189], v[12:13], v[200:201], v[188:189]
	v_lshlrev_b32_e32 v202, 16, v67
	v_and_b32_e32 v203, 0xffff0000, v67
	v_pk_mul_f32 v[202:203], v[202:203], v[210:211] op_sel_hi:[1,0]
	v_pk_fma_f32 v[190:191], v[14:15], v[202:203], v[190:191]
	v_lshlrev_b32_e32 v200, 16, v68
	v_and_b32_e32 v201, 0xffff0000, v68
	v_pk_mul_f32 v[200:201], v[200:201], v[210:211] op_sel_hi:[1,0]
	v_pk_fma_f32 v[192:193], v[16:17], v[200:201], v[192:193]
	v_lshlrev_b32_e32 v202, 16, v69
	v_and_b32_e32 v203, 0xffff0000, v69
	v_pk_mul_f32 v[202:203], v[202:203], v[210:211] op_sel_hi:[1,0]
	v_pk_fma_f32 v[194:195], v[18:19], v[202:203], v[194:195]
	v_lshlrev_b32_e32 v200, 16, v70
	v_and_b32_e32 v201, 0xffff0000, v70
	v_pk_mul_f32 v[200:201], v[200:201], v[210:211] op_sel_hi:[1,0]
	v_pk_fma_f32 v[196:197], v[20:21], v[200:201], v[196:197]
	v_lshlrev_b32_e32 v202, 16, v71
	v_and_b32_e32 v203, 0xffff0000, v71
	v_pk_mul_f32 v[202:203], v[202:203], v[210:211] op_sel_hi:[1,0]
	v_pk_fma_f32 v[198:199], v[22:23], v[202:203], v[198:199]
	s_add_i32 s81, s80, 3
	s_add_i32 s81, s81, s82
	s_and_b32 s81, s81, 31
	s_lshl_b32 s83, s81, 12
	v_add_u32_e32 v213, s83, v3
	global_store_dwordx4 v213, v[184:187], s[76:77]
	global_store_dwordx4 v213, v[188:191], s[76:77] offset:16
	global_store_dwordx4 v213, v[192:195], s[76:77] offset:2048
	global_store_dwordx4 v213, v[196:199], s[76:77] offset:2064
	s_add_i32 s81, s82, 8
	s_cmp_lt_u32 s81, 32
	s_cbranch_scc0 .Lrw_LAST_l4_d
	s_add_i32 s81, s80, 8
	s_add_i32 s81, s81, s82
	s_and_b32 s81, s81, 31
	s_lshl_b32 s83, s81, 11
	v_add_u32_e32 v2, s83, v1
	global_load_dwordx4 v[136:139], v2, s[72:73]
	global_load_dwordx4 v[140:143], v2, s[72:73] offset:1024
	global_load_dwordx4 v[144:147], v2, s[74:75]
	global_load_dwordx4 v[148:151], v2, s[74:75] offset:1024
	s_branch .Lrw_LAST_l4_e

; __device__ __forceinline__ float bflo(unsigned u) { return __uint_as_float(u << 16); }
; __device__ __forceinline__ void phase_rowwise(const void* xsrc_, bool sbf, void* xdst_, bool dbf, const bf16_t* Y, bf16_t* H, const float* mods, int lprev, int iprev, const float* lnpost, float resw, ...
;     ...
;         for (int rr = 0; rr < 32; rr += 2) {
;             const size_t m = (size_t)ch * 32 + rr;
;             f32x4 x[2][4]; u32x2 yr[2][4];
; #pragma unroll
;             for (int r = 0; r < 2; ++r)
; #pragma unroll
;                 for (int j = 0; j < 4; ++j) { if (sbf) { const u32x2 u = xnb[r][j]; x[r][j] = (f32x4){bflo(u.x), bfhi(u.x), bflo(u.y), bfhi(u.y)}; } else x[r][j] = xn[r][j]; yr[r][j] = yn[r][j]; }
;             if (rr + 2 < 32) {
; #pragma unroll
;                 for (int r = 0; r < 2; ++r)
; #pragma unroll
;                     for (int j = 0; j < 4; ++j) { if (sbf) xnb[r][j] = *(const u32x2*)(xsrcb + (m + 2 + r) * DM + 4 * lane + 256 * j); else xn[r][j] = *(const f32x4*)(xsrc + (m + 2 + r) * DM + 4 * lane + 256 * j); if (hasprev) yn[r][j] = *(const u32x2*)(Y + (m + 2 + r) * DM + 4 * lane + 256 * j); } }
;             if (hasprev) {
;                 f32x4 y[2][4]; float ss[2] = {0.f, 0.f};
; #pragma unroll
;                 for (int r = 0; r < 2; ++r)
; #pragma unroll
;                     for (int j = 0; j < 4; ++j) { const u32x2 u = yr[r][j]; y[r][j] = (f32x4){bflo(u.x), bfhi(u.x), bflo(u.y), bfhi(u.y)};
;                         ss[r] += (y[r][j].x * y[r][j].x + y[r][j].y * y[r][j].y) + (y[r][j].z * y[r][j].z + y[r][j].w * y[r][j].w); }
; #pragma unroll
;                 for (int off = 1; off < 64; off <<= 1) { ss[0] += __shfl_xor(ss[0], off); ss[1] += __shfl_xor(ss[1], off); }
; #pragma unroll
;                 for (int r = 0; r < 2; ++r) { const float rs = __builtin_amdgcn_rsqf(ss[r] * (1.f / DM) + EPS);
; #pragma unroll
;                     for (int j = 0; j < 4; ++j) x[r][j] = x[r][j] + gp[j] * (y[r][j] * rs); }
;             }
; #pragma unroll
;             for (int r = 0; r < 2; ++r)
; #pragma unroll
;                 for (int j = 0; j < 4; ++j) { if (hasprev) { if (dbf) { u32x2 w; w.x = cvtpk(x[r][j].x, x[r][j].y); w.y = cvtpk(x[r][j].z, x[r][j].w); *(u32x2*)(xdstb + (m + r) * DM + 4 * lane + 256 * j) = w; } else *(f32x4*)(xdst + (m + r) * DM + 4 * lane + 256 * j) = x[r][j]; } }
.Lrw_LAST_l4_e:
	s_waitcnt vmcnt(32)
	v_lshlrev_b32_e32 v200, 16, v80
	v_and_b32_e32 v201, 0xffff0000, v80
	v_pk_mul_f32 v[204:205], v[200:201], v[200:201]
	v_lshlrev_b32_e32 v202, 16, v81
	v_and_b32_e32 v203, 0xffff0000, v81
	v_pk_mul_f32 v[206:207], v[202:203], v[202:203]
	v_lshlrev_b32_e32 v200, 16, v82
	v_and_b32_e32 v201, 0xffff0000, v82
	v_pk_fma_f32 v[204:205], v[200:201], v[200:201], v[204:205]
	v_lshlrev_b32_e32 v202, 16, v83
	v_and_b32_e32 v203, 0xffff0000, v83
	v_pk_fma_f32 v[206:207], v[202:203], v[202:203], v[206:207]
	v_lshlrev_b32_e32 v200, 16, v84
	v_and_b32_e32 v201, 0xffff0000, v84
	v_pk_fma_f32 v[204:205], v[200:201], v[200:201], v[204:205]
	v_lshlrev_b32_e32 v202, 16, v85
	v_and_b32_e32 v203, 0xffff0000, v85
	v_pk_fma_f32 v[206:207], v[202:203], v[202:203], v[206:207]
	v_lshlrev_b32_e32 v200, 16, v86
	v_and_b32_e32 v201, 0xffff0000, v86
	v_pk_fma_f32 v[204:205], v[200:201], v[200:201], v[204:205]
	v_lshlrev_b32_e32 v202, 16, v87
	v_and_b32_e32 v203, 0xffff0000, v87
	v_pk_fma_f32 v[206:207], v[202:203], v[202:203], v[206:207]
	v_pk_add_f32 v[204:205], v[204:205], v[206:207]
	v_add_f32_e32 v208, v204, v205
	v_lshlrev_b32_e32 v184, 16, v72
	v_and_b32_e32 v185, 0xffff0000, v72
	v_add_f32_dpp v208, v208, v208 quad_perm:[1,0,3,2] row_mask:0xf bank_mask:0xf
	v_lshlrev_b32_e32 v186, 16, v73
	v_and_b32_e32 v187, 0xffff0000, v73
	v_add_f32_dpp v208, v208, v208 quad_perm:[2,3,0,1] row_mask:0xf bank_mask:0xf
	v_lshlrev_b32_e32 v188, 16, v74
	v_and_b32_e32 v189, 0xffff0000, v74
	v_add_f32_dpp v208, v208, v208 row_half_mirror row_mask:0xf bank_mask:0xf
	v_lshlrev_b32_e32 v190, 16, v75
	v_and_b32_e32 v191, 0xffff0000, v75
	v_add_f32_dpp v208, v208, v208 row_mirror row_mask:0xf bank_mask:0xf
	v_lshlrev_b32_e32 v192, 16, v76
	v_and_b32_e32 v193, 0xffff0000, v76
	v_add_f32_dpp v208, v208, v208 row_bcast:15 row_mask:0xa bank_mask:0xf
	v_lshlrev_b32_e32 v194, 16, v77
	v_and_b32_e32 v195, 0xffff0000, v77
	v_add_f32_dpp v208, v208, v208 row_bcast:31 row_mask:0xc bank_mask:0xf
	v_lshlrev_b32_e32 v196, 16, v78
	v_and_b32_e32 v197, 0xffff0000, v78
	v_readlane_b32 s60, v208, 63
	s_nop 1
	v_lshlrev_b32_e32 v198, 16, v79
	v_and_b32_e32 v199, 0xffff0000, v79
	v_mov_b32_e32 v210, s60
	v_fmaak_f32 v210, v210, v212, 0x358637bd
	v_rsq_f32_e32 v210, v210
	s_nop 0
	v_lshlrev_b32_e32 v200, 16, v80
	v_and_b32_e32 v201, 0xffff0000, v80
	v_pk_mul_f32 v[200:201], v[200:201], v[210:211] op_sel_hi:[1,0]
	v_pk_fma_f32 v[184:185], v[8:9], v[200:201], v[184:185]
	v_lshlrev_b32_e32 v202, 16, v81
	v_and_b32_e32 v203, 0xffff0000, v81
	v_pk_mul_f32 v[202:203], v[202:203], v[210:211] op_sel_hi:[1,0]
	v_pk_fma_f32 v[186:187], v[10:11], v[202:203], v[186:187]
	v_lshlrev_b32_e32 v200, 16, v82
	v_and_b32_e32 v201, 0xffff0000, v82
	v_pk_mul_f32 v[200:201], v[200:201], v[210:211] op_sel_hi:[1,0]
	v_pk_fma_f32 v[188:189], v[12:13], v[200:201], v[188:189]
	v_lshlrev_b32_e32 v202, 16, v83
	v_and_b32_e32 v203, 0xffff0000, v83
	v_pk_mul_f32 v[202:203], v[202:203], v[210:211] op_sel_hi:[1,0]
	v_pk_fma_f32 v[190:191], v[14:15], v[202:203], v[190:191]
	v_lshlrev_b32_e32 v200, 16, v84
	v_and_b32_e32 v201, 0xffff0000, v84
	v_pk_mul_f32 v[200:201], v[200:201], v[210:211] op_sel_hi:[1,0]
	v_pk_fma_f32 v[192:193], v[16:17], v[200:201], v[192:193]
	v_lshlrev_b32_e32 v202, 16, v85
	v_and_b32_e32 v203, 0xffff0000, v85
	v_pk_mul_f32 v[202:203], v[202:203], v[210:211] op_sel_hi:[1,0]
	v_pk_fma_f32 v[194:195], v[18:19], v[202:203], v[194:195]
	v_lshlrev_b32_e32 v200, 16, v86
	v_and_b32_e32 v201, 0xffff0000, v86
	v_pk_mul_f32 v[200:201], v[200:201], v[210:211] op_sel_hi:[1,0]
	v_pk_fma_f32 v[196:197], v[20:21], v[200:201], v[196:197]
	v_lshlrev_b32_e32 v202, 16, v87
	v_and_b32_e32 v203, 0xffff0000, v87
	v_pk_mul_f32 v[202:203], v[202:203], v[210:211] op_sel_hi:[1,0]
	v_pk_fma_f32 v[198:199], v[22:23], v[202:203], v[198:199]
	s_add_i32 s81, s80, 4
	s_add_i32 s81, s81, s82
	s_and_b32 s81, s81, 31
	s_lshl_b32 s83, s81, 12
	v_add_u32_e32 v213, s83, v3
	global_store_dwordx4 v213, v[184:187], s[76:77]
	global_store_dwordx4 v213, v[188:191], s[76:77] offset:16
	global_store_dwordx4 v213, v[192:195], s[76:77] offset:2048
	global_store_dwordx4 v213, v[196:199], s[76:77] offset:2064
	s_add_i32 s81, s82, 9
	s_cmp_lt_u32 s81, 32
	s_cbranch_scc0 .Lrw_LAST_l5_d
	s_add_i32 s81, s80, 9
	s_add_i32 s81, s81, s82
	s_and_b32 s81, s81, 31
	s_lshl_b32 s83, s81, 11
	v_add_u32_e32 v2, s83, v1
	global_load_dwordx4 v[152:155], v2, s[72:73]
	global_load_dwordx4 v[156:159], v2, s[72:73] offset:1024
	global_load_dwordx4 v[160:163], v2, s[74:75]
	global_load_dwordx4 v[164:167], v2, s[74:75] offset:1024
	s_branch .Lrw_LAST_l5_e

; __device__ __forceinline__ float bflo(unsigned u) { return __uint_as_float(u << 16); }
; __device__ __forceinline__ void phase_rowwise(const void* xsrc_, bool sbf, void* xdst_, bool dbf, const bf16_t* Y, bf16_t* H, const float* mods, int lprev, int iprev, const float* lnpost, float resw, ...
;     ...
;         for (int rr = 0; rr < 32; rr += 2) {
;             const size_t m = (size_t)ch * 32 + rr;
;             f32x4 x[2][4]; u32x2 yr[2][4];
; #pragma unroll
;             for (int r = 0; r < 2; ++r)
; #pragma unroll
;                 for (int j = 0; j < 4; ++j) { if (sbf) { const u32x2 u = xnb[r][j]; x[r][j] = (f32x4){bflo(u.x), bfhi(u.x), bflo(u.y), bfhi(u.y)}; } else x[r][j] = xn[r][j]; yr[r][j] = yn[r][j]; }
;             if (rr + 2 < 32) {
; #pragma unroll
;                 for (int r = 0; r < 2; ++r)
; #pragma unroll
;                     for (int j = 0; j < 4; ++j) { if (sbf) xnb[r][j] = *(const u32x2*)(xsrcb + (m + 2 + r) * DM + 4 * lane + 256 * j); else xn[r][j] = *(const f32x4*)(xsrc + (m + 2 + r) * DM + 4 * lane + 256 * j); if (hasprev) yn[r][j] = *(const u32x2*)(Y + (m + 2 + r) * DM + 4 * lane + 256 * j); } }
;             if (hasprev) {
;                 f32x4 y[2][4]; float ss[2] = {0.f, 0.f};
; #pragma unroll
;                 for (int r = 0; r < 2; ++r)
; #pragma unroll
;                     for (int j = 0; j < 4; ++j) { const u32x2 u = yr[r][j]; y[r][j] = (f32x4){bflo(u.x), bfhi(u.x), bflo(u.y), bfhi(u.y)};
;                         ss[r] += (y[r][j].x * y[r][j].x + y[r][j].y * y[r][j].y) + (y[r][j].z * y[r][j].z + y[r][j].w * y[r][j].w); }
; #pragma unroll
;                 for (int off = 1; off < 64; off <<= 1) { ss[0] += __shfl_xor(ss[0], off); ss[1] += __shfl_xor(ss[1], off); }
; #pragma unroll
;                 for (int r = 0; r < 2; ++r) { const float rs = __builtin_amdgcn_rsqf(ss[r] * (1.f / DM) + EPS);
; #pragma unroll
;                     for (int j = 0; j < 4; ++j) x[r][j] = x[r][j] + gp[j] * (y[r][j] * rs); }
;             }
; #pragma unroll
;             for (int r = 0; r < 2; ++r)
; #pragma unroll
;                 for (int j = 0; j < 4; ++j) { if (hasprev) { if (dbf) { u32x2 w; w.x = cvtpk(x[r][j].x, x[r][j].y); w.y = cvtpk(x[r][j].z, x[r][j].w); *(u32x2*)(xdstb + (m + r) * DM + 4 * lane + 256 * j) = w; } else *(f32x4*)(xdst + (m + r) * DM + 4 * lane + 256 * j) = x[r][j]; } }
.Lrw_LAST_l5_e:
	s_waitcnt vmcnt(32)
	v_lshlrev_b32_e32 v200, 16, v96
	v_and_b32_e32 v201, 0xffff0000, v96
	v_pk_mul_f32 v[204:205], v[200:201], v[200:201]
	v_lshlrev_b32_e32 v202, 16, v97
	v_and_b32_e32 v203, 0xffff0000, v97
	v_pk_mul_f32 v[206:207], v[202:203], v[202:203]
	v_lshlrev_b32_e32 v200, 16, v98
	v_and_b32_e32 v201, 0xffff0000, v98
	v_pk_fma_f32 v[204:205], v[200:201], v[200:201], v[204:205]
	v_lshlrev_b32_e32 v202, 16, v99
	v_and_b32_e32 v203, 0xffff0000, v99
	v_pk_fma_f32 v[206:207], v[202:203], v[202:203], v[206:207]
	v_lshlrev_b32_e32 v200, 16, v100
	v_and_b32_e32 v201, 0xffff0000, v100
	v_pk_fma_f32 v[204:205], v[200:201], v[200:201], v[204:205]
	v_lshlrev_b32_e32 v202, 16, v101
	v_and_b32_e32 v203, 0xffff0000, v101
	v_pk_fma_f32 v[206:207], v[202:203], v[202:203], v[206:207]
	v_lshlrev_b32_e32 v200, 16, v102
	v_and_b32_e32 v201, 0xffff0000, v102
	v_pk_fma_f32 v[204:205], v[200:201], v[200:201], v[204:205]
	v_lshlrev_b32_e32 v202, 16, v103
	v_and_b32_e32 v203, 0xffff0000, v103
	v_pk_fma_f32 v[206:207], v[202:203], v[202:203], v[206:207]
	v_pk_add_f32 v[204:205], v[204:205], v[206:207]
	v_add_f32_e32 v208, v204, v205
	v_lshlrev_b32_e32 v184, 16, v88
	v_and_b32_e32 v185, 0xffff0000, v88
	v_add_f32_dpp v208, v208, v208 quad_perm:[1,0,3,2] row_mask:0xf bank_mask:0xf
	v_lshlrev_b32_e32 v186, 16, v89
	v_and_b32_e32 v187, 0xffff0000, v89
	v_add_f32_dpp v208, v208, v208 quad_perm:[2,3,0,1] row_mask:0xf bank_mask:0xf
	v_lshlrev_b32_e32 v188, 16, v90
	v_and_b32_e32 v189, 0xffff0000, v90
	v_add_f32_dpp v208, v208, v208 row_half_mirror row_mask:0xf bank_mask:0xf
	v_lshlrev_b32_e32 v190, 16, v91
	v_and_b32_e32 v191, 0xffff0000, v91
	v_add_f32_dpp v208, v208, v208 row_mirror row_mask:0xf bank_mask:0xf
	v_lshlrev_b32_e32 v192, 16, v92
	v_and_b32_e32 v193, 0xffff0000, v92
	v_add_f32_dpp v208, v208, v208 row_bcast:15 row_mask:0xa bank_mask:0xf
	v_lshlrev_b32_e32 v194, 16, v93
	v_and_b32_e32 v195, 0xffff0000, v93
	v_add_f32_dpp v208, v208, v208 row_bcast:31 row_mask:0xc bank_mask:0xf
	v_lshlrev_b32_e32 v196, 16, v94
	v_and_b32_e32 v197, 0xffff0000, v94
	v_readlane_b32 s60, v208, 63
	s_nop 1
	v_lshlrev_b32_e32 v198, 16, v95
	v_and_b32_e32 v199, 0xffff0000, v95
	v_mov_b32_e32 v210, s60
	v_fmaak_f32 v210, v210, v212, 0x358637bd
	v_rsq_f32_e32 v210, v210
	s_nop 0
	v_lshlrev_b32_e32 v200, 16, v96
	v_and_b32_e32 v201, 0xffff0000, v96
	v_pk_mul_f32 v[200:201], v[200:201], v[210:211] op_sel_hi:[1,0]
	v_pk_fma_f32 v[184:185], v[8:9], v[200:201], v[184:185]
	v_lshlrev_b32_e32 v202, 16, v97
	v_and_b32_e32 v203, 0xffff0000, v97
	v_pk_mul_f32 v[202:203], v[202:203], v[210:211] op_sel_hi:[1,0]
	v_pk_fma_f32 v[186:187], v[10:11], v[202:203], v[186:187]
	v_lshlrev_b32_e32 v200, 16, v98
	v_and_b32_e32 v201, 0xffff0000, v98
	v_pk_mul_f32 v[200:201], v[200:201], v[210:211] op_sel_hi:[1,0]
	v_pk_fma_f32 v[188:189], v[12:13], v[200:201], v[188:189]
	v_lshlrev_b32_e32 v202, 16, v99
	v_and_b32_e32 v203, 0xffff0000, v99
	v_pk_mul_f32 v[202:203], v[202:203], v[210:211] op_sel_hi:[1,0]
	v_pk_fma_f32 v[190:191], v[14:15], v[202:203], v[190:191]
	v_lshlrev_b32_e32 v200, 16, v100
	v_and_b32_e32 v201, 0xffff0000, v100
	v_pk_mul_f32 v[200:201], v[200:201], v[210:211] op_sel_hi:[1,0]
	v_pk_fma_f32 v[192:193], v[16:17], v[200:201], v[192:193]
	v_lshlrev_b32_e32 v202, 16, v101
	v_and_b32_e32 v203, 0xffff0000, v101
	v_pk_mul_f32 v[202:203], v[202:203], v[210:211] op_sel_hi:[1,0]
	v_pk_fma_f32 v[194:195], v[18:19], v[202:203], v[194:195]
	v_lshlrev_b32_e32 v200, 16, v102
	v_and_b32_e32 v201, 0xffff0000, v102
	v_pk_mul_f32 v[200:201], v[200:201], v[210:211] op_sel_hi:[1,0]
	v_pk_fma_f32 v[196:197], v[20:21], v[200:201], v[196:197]
	v_lshlrev_b32_e32 v202, 16, v103
	v_and_b32_e32 v203, 0xffff0000, v103
	v_pk_mul_f32 v[202:203], v[202:203], v[210:211] op_sel_hi:[1,0]
	v_pk_fma_f32 v[198:199], v[22:23], v[202:203], v[198:199]
	s_add_i32 s81, s80, 5
	s_add_i32 s81, s81, s82
	s_and_b32 s81, s81, 31
	s_lshl_b32 s83, s81, 12
	v_add_u32_e32 v213, s83, v3
	global_store_dwordx4 v213, v[184:187], s[76:77]
	global_store_dwordx4 v213, v[188:191], s[76:77] offset:16
	global_store_dwordx4 v213, v[192:195], s[76:77] offset:2048
	global_store_dwordx4 v213, v[196:199], s[76:77] offset:2064
	s_add_i32 s81, s82, 10
	s_cmp_lt_u32 s81, 32
	s_cbranch_scc0 .Lrw_LAST_l6_d
	s_add_i32 s81, s80, 10
	s_add_i32 s81, s81, s82
	s_and_b32 s81, s81, 31
	s_lshl_b32 s83, s81, 11
	v_add_u32_e32 v2, s83, v1
	global_load_dwordx4 v[56:59], v2, s[72:73]
	global_load_dwordx4 v[60:63], v2, s[72:73] offset:1024
	global_load_dwordx4 v[64:67], v2, s[74:75]
	global_load_dwordx4 v[68:71], v2, s[74:75] offset:1024
	s_branch .Lrw_LAST_l6_e

; __device__ __forceinline__ float bflo(unsigned u) { return __uint_as_float(u << 16); }
; __device__ __forceinline__ void phase_rowwise(const void* xsrc_, bool sbf, void* xdst_, bool dbf, const bf16_t* Y, bf16_t* H, const float* mods, int lprev, int iprev, const float* lnpost, float resw, ...
;     ...
;         for (int rr = 0; rr < 32; rr += 2) {
;             const size_t m = (size_t)ch * 32 + rr;
;             f32x4 x[2][4]; u32x2 yr[2][4];
; #pragma unroll
;             for (int r = 0; r < 2; ++r)
; #pragma unroll
;                 for (int j = 0; j < 4; ++j) { if (sbf) { const u32x2 u = xnb[r][j]; x[r][j] = (f32x4){bflo(u.x), bfhi(u.x), bflo(u.y), bfhi(u.y)}; } else x[r][j] = xn[r][j]; yr[r][j] = yn[r][j]; }
;             if (rr + 2 < 32) {
; #pragma unroll
;                 for (int r = 0; r < 2; ++r)
; #pragma unroll
;                     for (int j = 0; j < 4; ++j) { if (sbf) xnb[r][j] = *(const u32x2*)(xsrcb + (m + 2 + r) * DM + 4 * lane + 256 * j); else xn[r][j] = *(const f32x4*)(xsrc + (m + 2 + r) * DM + 4 * lane + 256 * j); if (hasprev) yn[r][j] = *(const u32x2*)(Y + (m + 2 + r) * DM + 4 * lane + 256 * j); } }
;             if (hasprev) {
;                 f32x4 y[2][4]; float ss[2] = {0.f, 0.f};
; #pragma unroll
;                 for (int r = 0; r < 2; ++r)
; #pragma unroll
;                     for (int j = 0; j < 4; ++j) { const u32x2 u = yr[r][j]; y[r][j] = (f32x4){bflo(u.x), bfhi(u.x), bflo(u.y), bfhi(u.y)};
;                         ss[r] += (y[r][j].x * y[r][j].x + y[r][j].y * y[r][j].y) + (y[r][j].z * y[r][j].z + y[r][j].w * y[r][j].w); }
; #pragma unroll
;                 for (int off = 1; off < 64; off <<= 1) { ss[0] += __shfl_xor(ss[0], off); ss[1] += __shfl_xor(ss[1], off); }
; #pragma unroll
;                 for (int r = 0; r < 2; ++r) { const float rs = __builtin_amdgcn_rsqf(ss[r] * (1.f / DM) + EPS);
; #pragma unroll
;                     for (int j = 0; j < 4; ++j) x[r][j] = x[r][j] + gp[j] * (y[r][j] * rs); }
;             }
; #pragma unroll
;             for (int r = 0; r < 2; ++r)
; #pragma unroll
;                 for (int j = 0; j < 4; ++j) { if (hasprev) { if (dbf) { u32x2 w; w.x = cvtpk(x[r][j].x, x[r][j].y); w.y = cvtpk(x[r][j].z, x[r][j].w); *(u32x2*)(xdstb + (m + r) * DM + 4 * lane + 256 * j) = w; } else *(f32x4*)(xdst + (m + r) * DM + 4 * lane + 256 * j) = x[r][j]; } }
.Lrw_LAST_l6_e:
	s_waitcnt vmcnt(32)
	v_lshlrev_b32_e32 v200, 16, v112
	v_and_b32_e32 v201, 0xffff0000, v112
	v_pk_mul_f32 v[204:205], v[200:201], v[200:201]
	v_lshlrev_b32_e32 v202, 16, v113
	v_and_b32_e32 v203, 0xffff0000, v113
	v_pk_mul_f32 v[206:207], v[202:203], v[202:203]
	v_lshlrev_b32_e32 v200, 16, v114
	v_and_b32_e32 v201, 0xffff0000, v114
	v_pk_fma_f32 v[204:205], v[200:201], v[200:201], v[204:205]
	v_lshlrev_b32_e32 v202, 16, v115
	v_and_b32_e32 v203, 0xffff0000, v115
	v_pk_fma_f32 v[206:207], v[202:203], v[202:203], v[206:207]
	v_lshlrev_b32_e32 v200, 16, v116
	v_and_b32_e32 v201, 0xffff0000, v116
	v_pk_fma_f32 v[204:205], v[200:201], v[200:201], v[204:205]
	v_lshlrev_b32_e32 v202, 16, v117
	v_and_b32_e32 v203, 0xffff0000, v117
	v_pk_fma_f32 v[206:207], v[202:203], v[202:203], v[206:207]
	v_lshlrev_b32_e32 v200, 16, v118
	v_and_b32_e32 v201, 0xffff0000, v118
	v_pk_fma_f32 v[204:205], v[200:201], v[200:201], v[204:205]
	v_lshlrev_b32_e32 v202, 16, v119
	v_and_b32_e32 v203, 0xffff0000, v119
	v_pk_fma_f32 v[206:207], v[202:203], v[202:203], v[206:207]
	v_pk_add_f32 v[204:205], v[204:205], v[206:207]
	v_add_f32_e32 v208, v204, v205
	v_lshlrev_b32_e32 v184, 16, v104
	v_and_b32_e32 v185, 0xffff0000, v104
	v_add_f32_dpp v208, v208, v208 quad_perm:[1,0,3,2] row_mask:0xf bank_mask:0xf
	v_lshlrev_b32_e32 v186, 16, v105
	v_and_b32_e32 v187, 0xffff0000, v105
	v_add_f32_dpp v208, v208, v208 quad_perm:[2,3,0,1] row_mask:0xf bank_mask:0xf
	v_lshlrev_b32_e32 v188, 16, v106
	v_and_b32_e32 v189, 0xffff0000, v106
	v_add_f32_dpp v208, v208, v208 row_half_mirror row_mask:0xf bank_mask:0xf
	v_lshlrev_b32_e32 v190, 16, v107
	v_and_b32_e32 v191, 0xffff0000, v107
	v_add_f32_dpp v208, v208, v208 row_mirror row_mask:0xf bank_mask:0xf
	v_lshlrev_b32_e32 v192, 16, v108
	v_and_b32_e32 v193, 0xffff0000, v108
	v_add_f32_dpp v208, v208, v208 row_bcast:15 row_mask:0xa bank_mask:0xf
	v_lshlrev_b32_e32 v194, 16, v109
	v_and_b32_e32 v195, 0xffff0000, v109
	v_add_f32_dpp v208, v208, v208 row_bcast:31 row_mask:0xc bank_mask:0xf
	v_lshlrev_b32_e32 v196, 16, v110
	v_and_b32_e32 v197, 0xffff0000, v110
	v_readlane_b32 s60, v208, 63
	s_nop 1
	v_lshlrev_b32_e32 v198, 16, v111
	v_and_b32_e32 v199, 0xffff0000, v111
	v_mov_b32_e32 v210, s60
	v_fmaak_f32 v210, v210, v212, 0x358637bd
	v_rsq_f32_e32 v210, v210
	s_nop 0
	v_lshlrev_b32_e32 v200, 16, v112
	v_and_b32_e32 v201, 0xffff0000, v112
	v_pk_mul_f32 v[200:201], v[200:201], v[210:211] op_sel_hi:[1,0]
	v_pk_fma_f32 v[184:185], v[8:9], v[200:201], v[184:185]
	v_lshlrev_b32_e32 v202, 16, v113
	v_and_b32_e32 v203, 0xffff0000, v113
	v_pk_mul_f32 v[202:203], v[202:203], v[210:211] op_sel_hi:[1,0]
	v_pk_fma_f32 v[186:187], v[10:11], v[202:203], v[186:187]
	v_lshlrev_b32_e32 v200, 16, v114
	v_and_b32_e32 v201, 0xffff0000, v114
	v_pk_mul_f32 v[200:201], v[200:201], v[210:211] op_sel_hi:[1,0]
	v_pk_fma_f32 v[188:189], v[12:13], v[200:201], v[188:189]
	v_lshlrev_b32_e32 v202, 16, v115
	v_and_b32_e32 v203, 0xffff0000, v115
	v_pk_mul_f32 v[202:203], v[202:203], v[210:211] op_sel_hi:[1,0]
	v_pk_fma_f32 v[190:191], v[14:15], v[202:203], v[190:191]
	v_lshlrev_b32_e32 v200, 16, v116
	v_and_b32_e32 v201, 0xffff0000, v116
	v_pk_mul_f32 v[200:201], v[200:201], v[210:211] op_sel_hi:[1,0]
	v_pk_fma_f32 v[192:193], v[16:17], v[200:201], v[192:193]
	v_lshlrev_b32_e32 v202, 16, v117
	v_and_b32_e32 v203, 0xffff0000, v117
	v_pk_mul_f32 v[202:203], v[202:203], v[210:211] op_sel_hi:[1,0]
	v_pk_fma_f32 v[194:195], v[18:19], v[202:203], v[194:195]
	v_lshlrev_b32_e32 v200, 16, v118
	v_and_b32_e32 v201, 0xffff0000, v118
	v_pk_mul_f32 v[200:201], v[200:201], v[210:211] op_sel_hi:[1,0]
	v_pk_fma_f32 v[196:197], v[20:21], v[200:201], v[196:197]
	v_lshlrev_b32_e32 v202, 16, v119
	v_and_b32_e32 v203, 0xffff0000, v119
	v_pk_mul_f32 v[202:203], v[202:203], v[210:211] op_sel_hi:[1,0]
	v_pk_fma_f32 v[198:199], v[22:23], v[202:203], v[198:199]
	s_add_i32 s81, s80, 6
	s_add_i32 s81, s81, s82
	s_and_b32 s81, s81, 31
	s_lshl_b32 s83, s81, 12
	v_add_u32_e32 v213, s83, v3
	global_store_dwordx4 v213, v[184:187], s[76:77]
	global_store_dwordx4 v213, v[188:191], s[76:77] offset:16
	global_store_dwordx4 v213, v[192:195], s[76:77] offset:2048
	global_store_dwordx4 v213, v[196:199], s[76:77] offset:2064
	s_add_i32 s82, s82, 7
	s_cmp_lt_u32 s82, 32
	s_cbranch_scc1 .Lrw_LAST_loop
	s_branch .LBB0_1024

; __global__ void __launch_bounds__(512, 2) mega_fwd(Args a) {
;     ...
;         if (ph + 1 < hi) { if (ph == 0) grid.sync(); else xcd_barrier(xbar); }
.LBB0_1390:
	s_sleep 1
	global_load_dword v2, v0, s[4:5] offset:32 sc1
	s_waitcnt vmcnt(0)
	v_and_b32_e32 v2, 0xffff0000, v2
	v_cmp_ne_u32_e32 vcc, v2, v1
	s_or_b64 s[6:7], vcc, s[6:7]
	s_andn2_b64 exec, exec, s[6:7]
	s_cbranch_execnz .LBB0_1390
	s_branch .LBB0_7
.LBB0_7:
	buffer_inv sc1

; __global__ void __launch_bounds__(512, 2) mega_fwd(Args a) {
;     ...
;     for (int ph = lo; ph < hi; ++ph) {
;     ...
;         if (ph + 1 < hi) { if (ph == 0) grid.sync(); else xcd_barrier(xbar); }
.LBB0_10:
	s_and_b64 vcc, exec, s[0:1]
	s_cbranch_vccnz .LBB0_1391
	s_branch .Ltramp_11
